# GEMM K-loops: per-segment s_setprio toggles removed (all waves at default priority), on top of v91
# speedup vs baseline: 1.0093x; 1.0093x over previous
; #define PG8_STAGE(bufoff, gbase, voff) do { _Pragma("unroll") for (int _i = 0; _i < 2; ++_i) \
;         __builtin_amdgcn_global_load_lds((const unsigned*)((const char*)(gbase) + (voff)[_i]), (PG8_LAS unsigned*)(lds + (bufoff) + ldsw + _i * 8192), 16, 0, 0); } while (0)
; #define PG8_LDA(dst, b, h) do { _Pragma("unroll") for (int m = 0; m < 4; ++m) _Pragma("unroll") for (int k = 0; k < 2; ++k) dst[m][k] = *(const PG8_LAS bf16x8*)(lds + PG8_SA(b, h) + aoff + m * 2048 + k * 1024); } while (0)
; #define PG8_LDB(dst, b, h) do { _Pragma("unroll") for (int n = 0; n < 2; ++n) _Pragma("unroll") for (int k = 0; k < 2; ++k) dst[n][k] = *(const PG8_LAS bf16x8*)(lds + PG8_SB(b, h) + boff + n * 2048 + k * 1024); } while (0)
; #define PG8_MMA(ai, bj, At, Bt) do { __builtin_amdgcn_s_setprio(1); _Pragma("unroll") for (int m = 0; m < 4; ++m) _Pragma("unroll") for (int n = 0; n < 2; ++n) _Pragma("unroll") for (int k = 0; k < 2; ++k) \
;         acc[ai][bj][m][n] = __builtin_amdgcn_mfma_f32_16x16x32_bf16(Bt[n][k], At[m][k], acc[ai][bj][m][n], 0, 0, 0); __builtin_amdgcn_s_setprio(0); } while (0)
; #define PG8_WAIT_V(n) asm volatile("s_waitcnt vmcnt(" #n ")" ::: "memory")
; #define PG8_WAIT_L(n) asm volatile("s_waitcnt lgkmcnt(" #n ")" ::: "memory")
; #define PG8_BAR __builtin_amdgcn_s_barrier()
; #define PG8_SCHED __builtin_amdgcn_sched_barrier(0)
; template <class Epi, class Sched, bool ALIGN_EPI = false, bool SP2 = false>
; __device__ __forceinline__ void gemm_phase(PG8_LAS unsigned char* lds, const Gemm g, const Sched& S, const Epi& E) {
;     ...
;             PG8_LDB(B0, 0, 0); PG8_LDB(B1, 0, 1); PG8_SCHED; PG8_LDA(At, 0, 0); PG8_STAGE(PG8_SA(1, 1), a1 + hstep, voffA);
;             PG8_WAIT_V(8); PG8_WAIT_L(0); PG8_BAR; PG8_MMA(0, 0, At, B0); PG8_MMA(0, 1, At, B1); PG8_BAR; PG8_SCHED;
;             PG8_LDA(At, 0, 1); PG8_STAGE(PG8_SB(0, 0), b2, voffB); PG8_STAGE(PG8_SB(0, 1), b2 + hstep, voffB); PG8_STAGE(PG8_SA(0, 0), a2, voffA);
;             PG8_WAIT_V(8); PG8_WAIT_L(0); PG8_BAR; PG8_MMA(1, 0, At, B0); PG8_MMA(1, 1, At, B1); PG8_BAR; PG8_SCHED;
.LBB0_371:
	s_andn2_b64 vcc, exec, s[14:15]
	s_cbranch_vccnz .LBB0_374
	s_add_u32 s24, s24, 0x80
	s_addc_u32 s25, s25, 0
	s_add_u32 s62, s26, 0x100
	s_addc_u32 s63, s27, 0
	s_mov_b32 s26, 0
	ds_read_b128 v[154:157], v149
	ds_read_b128 v[158:161], v149 offset:1024
	ds_read_b128 v[162:165], v149 offset:2048
	ds_read_b128 v[166:169], v149 offset:3072
	ds_read_b128 v[170:173], v150
	ds_read_b128 v[174:177], v150 offset:1024
	ds_read_b128 v[180:183], v150 offset:2048
	ds_read_b128 v[184:187], v150 offset:3072
	s_add_i32 s64, s26, 2
	s_add_u32 s65, s24, 0x80
	s_addc_u32 s27, s25, 0
	s_cmp_eq_u32 s37, s26
	s_cselect_b32 s26, s0, s65
	s_cselect_b32 s27, s1, s27
	s_cselect_b32 s67, s23, s63
	s_cselect_b32 s66, s22, s62
	v_lshl_add_u64 v[144:145], s[24:25], 0, v[136:137]
	s_add_i32 m0, s28, 0xc000
	ds_read_b128 v[188:191], v151
	ds_read_b128 v[192:195], v151 offset:1024
	ds_read_b128 v[196:199], v151 offset:2048
	ds_read_b128 v[200:203], v151 offset:3072
	ds_read_b128 v[204:207], v151 offset:4096
	ds_read_b128 v[208:211], v151 offset:5120
	ds_read_b128 v[212:215], v151 offset:6144
	ds_read_b128 v[216:219], v151 offset:7168
	global_load_lds_dwordx4 v[144:145], off
	v_lshl_add_u64 v[144:145], s[24:25], 0, v[138:139]
	s_add_i32 m0, s28, 0xe000
	s_nop 0
	global_load_lds_dwordx4 v[144:145], off
	s_waitcnt vmcnt(8)
	s_waitcnt lgkmcnt(0)
	s_barrier
	s_waitcnt lgkmcnt(0)
	v_mfma_f32_16x16x32_bf16 v[116:119], v[154:157], v[188:191], 0
	v_mfma_f32_16x16x32_bf16 v[112:115], v[162:165], v[188:191], 0
	v_mfma_f32_16x16x32_bf16 v[100:103], v[154:157], v[196:199], 0
	v_mfma_f32_16x16x32_bf16 v[96:99], v[162:165], v[196:199], 0
	v_mfma_f32_16x16x32_bf16 v[84:87], v[154:157], v[204:207], 0
	v_mfma_f32_16x16x32_bf16 v[80:83], v[162:165], v[204:207], 0
	v_mfma_f32_16x16x32_bf16 v[68:71], v[154:157], v[212:215], 0
	v_mfma_f32_16x16x32_bf16 v[64:67], v[162:165], v[212:215], 0
	v_mfma_f32_16x16x32_bf16 v[116:119], v[158:161], v[192:195], v[116:119]
	v_mfma_f32_16x16x32_bf16 v[112:115], v[166:169], v[192:195], v[112:115]
	v_mfma_f32_16x16x32_bf16 v[100:103], v[158:161], v[200:203], v[100:103]
	v_mfma_f32_16x16x32_bf16 v[96:99], v[166:169], v[200:203], v[96:99]
	v_mfma_f32_16x16x32_bf16 v[84:87], v[158:161], v[208:211], v[84:87]
	v_mfma_f32_16x16x32_bf16 v[80:83], v[166:169], v[208:211], v[80:83]
	v_mfma_f32_16x16x32_bf16 v[68:71], v[158:161], v[216:219], v[68:71]
	v_mfma_f32_16x16x32_bf16 v[64:67], v[166:169], v[216:219], v[64:67]
	v_mfma_f32_16x16x32_bf16 v[124:127], v[170:173], v[188:191], 0
	v_mfma_f32_16x16x32_bf16 v[120:123], v[180:183], v[188:191], 0
	v_mfma_f32_16x16x32_bf16 v[108:111], v[170:173], v[196:199], 0
	v_mfma_f32_16x16x32_bf16 v[104:107], v[180:183], v[196:199], 0
	v_mfma_f32_16x16x32_bf16 v[92:95], v[170:173], v[204:207], 0
	v_mfma_f32_16x16x32_bf16 v[88:91], v[180:183], v[204:207], 0
	v_mfma_f32_16x16x32_bf16 v[76:79], v[170:173], v[212:215], 0
	v_mfma_f32_16x16x32_bf16 v[72:75], v[180:183], v[212:215], 0
	v_mfma_f32_16x16x32_bf16 v[124:127], v[174:177], v[192:195], v[124:127]
	v_mfma_f32_16x16x32_bf16 v[120:123], v[184:187], v[192:195], v[120:123]
	v_mfma_f32_16x16x32_bf16 v[108:111], v[174:177], v[200:203], v[108:111]
	v_mfma_f32_16x16x32_bf16 v[104:107], v[184:187], v[200:203], v[104:107]
	v_mfma_f32_16x16x32_bf16 v[92:95], v[174:177], v[208:211], v[92:95]
	v_mfma_f32_16x16x32_bf16 v[88:91], v[184:187], v[208:211], v[88:91]
	v_mfma_f32_16x16x32_bf16 v[76:79], v[174:177], v[216:219], v[76:79]
	v_mfma_f32_16x16x32_bf16 v[72:75], v[184:187], v[216:219], v[72:75]
	s_barrier
	s_add_i32 s65, s40, s16
	v_lshl_add_u64 v[144:145], s[66:67], 0, v[132:133]
	s_mov_b32 m0, s65
	ds_read_b128 v[188:191], v151 offset:16384
	ds_read_b128 v[192:195], v151 offset:17408
	ds_read_b128 v[196:199], v151 offset:18432
	ds_read_b128 v[200:203], v151 offset:19456
	ds_read_b128 v[204:207], v151 offset:20480
	ds_read_b128 v[208:211], v151 offset:21504
	ds_read_b128 v[212:215], v151 offset:22528
	ds_read_b128 v[216:219], v151 offset:23552
	global_load_lds_dwordx4 v[144:145], off
	s_add_i32 m0, s65, 0x2000
	v_lshl_add_u64 v[178:179], s[66:67], 0, v[128:129]
	s_add_u32 s66, s66, s6
	s_addc_u32 s67, s67, s7
	s_add_i32 s65, s41, s16
	global_load_lds_dwordx4 v[178:179], off
	v_lshl_add_u64 v[220:221], s[66:67], 0, v[132:133]
	s_mov_b32 m0, s65
	v_lshl_add_u64 v[222:223], s[66:67], 0, v[128:129]
	global_load_lds_dwordx4 v[220:221], off
	s_add_i32 m0, s65, 0x2000
	v_lshl_add_u64 v[224:225], s[26:27], 0, v[134:135]
	global_load_lds_dwordx4 v[222:223], off
	s_mov_b32 m0, s28
	v_lshl_add_u64 v[226:227], s[26:27], 0, v[130:131]
	global_load_lds_dwordx4 v[224:225], off
	s_mov_b32 m0, s29
	s_nop 0
	global_load_lds_dwordx4 v[226:227], off
	s_waitcnt vmcnt(8)
	s_waitcnt lgkmcnt(0)
	s_barrier
; #define PG8_STAGE(bufoff, gbase, voff) do { _Pragma("unroll") for (int _i = 0; _i < 2; ++_i) \
;         __builtin_amdgcn_global_load_lds((const unsigned*)((const char*)(gbase) + (voff)[_i]), (PG8_LAS unsigned*)(lds + (bufoff) + ldsw + _i * 8192), 16, 0, 0); } while (0)
; #define PG8_LDA(dst, b, h) do { _Pragma("unroll") for (int m = 0; m < 4; ++m) _Pragma("unroll") for (int k = 0; k < 2; ++k) dst[m][k] = *(const PG8_LAS bf16x8*)(lds + PG8_SA(b, h) + aoff + m * 2048 + k * 1024); } while (0)
; #define PG8_LDB(dst, b, h) do { _Pragma("unroll") for (int n = 0; n < 2; ++n) _Pragma("unroll") for (int k = 0; k < 2; ++k) dst[n][k] = *(const PG8_LAS bf16x8*)(lds + PG8_SB(b, h) + boff + n * 2048 + k * 1024); } while (0)
; #define PG8_MMA(ai, bj, At, Bt) do { __builtin_amdgcn_s_setprio(1); _Pragma("unroll") for (int m = 0; m < 4; ++m) _Pragma("unroll") for (int n = 0; n < 2; ++n) _Pragma("unroll") for (int k = 0; k < 2; ++k) \
;         acc[ai][bj][m][n] = __builtin_amdgcn_mfma_f32_16x16x32_bf16(Bt[n][k], At[m][k], acc[ai][bj][m][n], 0, 0, 0); __builtin_amdgcn_s_setprio(0); } while (0)
; #define PG8_WAIT_V(n) asm volatile("s_waitcnt vmcnt(" #n ")" ::: "memory")
; #define PG8_WAIT_L(n) asm volatile("s_waitcnt lgkmcnt(" #n ")" ::: "memory")
; #define PG8_BAR __builtin_amdgcn_s_barrier()
; #define PG8_SCHED __builtin_amdgcn_sched_barrier(0)
; template <class Epi, class Sched, bool ALIGN_EPI = false, bool SP2 = false>
; __device__ __forceinline__ void gemm_phase(PG8_LAS unsigned char* lds, const Gemm g, const Sched& S, const Epi& E) {
;     ...
;             PG8_WAIT_V(8); PG8_WAIT_L(0); PG8_BAR; PG8_MMA(1, 0, At, B0); PG8_MMA(1, 1, At, B1); PG8_BAR; PG8_SCHED;
;             PG8_LDB(B0, 1, 0); PG8_LDB(B1, 1, 1); PG8_SCHED; PG8_LDA(At, 1, 0); PG8_STAGE(PG8_SA(0, 1), a2 + hstep, voffA);
;             PG8_WAIT_V(8); PG8_WAIT_L(0); PG8_BAR; PG8_MMA(0, 0, At, B0); PG8_MMA(0, 1, At, B1); PG8_BAR; PG8_SCHED;
	s_waitcnt lgkmcnt(0)
	v_mfma_f32_16x16x32_bf16 v[52:55], v[154:157], v[188:191], 0
	v_mfma_f32_16x16x32_bf16 v[48:51], v[162:165], v[188:191], 0
	v_mfma_f32_16x16x32_bf16 v[36:39], v[154:157], v[196:199], 0
	v_mfma_f32_16x16x32_bf16 v[32:35], v[162:165], v[196:199], 0
	v_mfma_f32_16x16x32_bf16 v[20:23], v[154:157], v[204:207], 0
	v_mfma_f32_16x16x32_bf16 v[16:19], v[162:165], v[204:207], 0
	v_mfma_f32_16x16x32_bf16 v[4:7], v[154:157], v[212:215], 0
	v_mfma_f32_16x16x32_bf16 v[0:3], v[162:165], v[212:215], 0
	v_mfma_f32_16x16x32_bf16 v[52:55], v[158:161], v[192:195], v[52:55]
	v_mfma_f32_16x16x32_bf16 v[48:51], v[166:169], v[192:195], v[48:51]
	v_mfma_f32_16x16x32_bf16 v[36:39], v[158:161], v[200:203], v[36:39]
	v_mfma_f32_16x16x32_bf16 v[32:35], v[166:169], v[200:203], v[32:35]
	v_mfma_f32_16x16x32_bf16 v[20:23], v[158:161], v[208:211], v[20:23]
	v_mfma_f32_16x16x32_bf16 v[16:19], v[166:169], v[208:211], v[16:19]
	v_mfma_f32_16x16x32_bf16 v[4:7], v[158:161], v[216:219], v[4:7]
	v_mfma_f32_16x16x32_bf16 v[0:3], v[166:169], v[216:219], v[0:3]
	v_mfma_f32_16x16x32_bf16 v[60:63], v[170:173], v[188:191], 0
	v_mfma_f32_16x16x32_bf16 v[56:59], v[180:183], v[188:191], 0
	v_mfma_f32_16x16x32_bf16 v[44:47], v[170:173], v[196:199], 0
	v_mfma_f32_16x16x32_bf16 v[40:43], v[180:183], v[196:199], 0
	v_mfma_f32_16x16x32_bf16 v[28:31], v[170:173], v[204:207], 0
	v_mfma_f32_16x16x32_bf16 v[24:27], v[180:183], v[204:207], 0
	v_mfma_f32_16x16x32_bf16 v[12:15], v[170:173], v[212:215], 0
	v_mfma_f32_16x16x32_bf16 v[8:11], v[180:183], v[212:215], 0
	v_mfma_f32_16x16x32_bf16 v[60:63], v[174:177], v[192:195], v[60:63]
	v_mfma_f32_16x16x32_bf16 v[56:59], v[184:187], v[192:195], v[56:59]
	v_mfma_f32_16x16x32_bf16 v[44:47], v[174:177], v[200:203], v[44:47]
	v_mfma_f32_16x16x32_bf16 v[40:43], v[184:187], v[200:203], v[40:43]
	v_mfma_f32_16x16x32_bf16 v[28:31], v[174:177], v[208:211], v[28:31]
	v_mfma_f32_16x16x32_bf16 v[24:27], v[184:187], v[208:211], v[24:27]
	v_mfma_f32_16x16x32_bf16 v[12:15], v[174:177], v[216:219], v[12:15]
	v_mfma_f32_16x16x32_bf16 v[8:11], v[184:187], v[216:219], v[8:11]
	s_barrier
	s_add_i32 s65, 0, 0x18000
	v_add_u32_e32 v153, s65, v147
	s_add_i32 s66, 0, 0x1c000
	ds_read_b128 v[154:157], v153
	ds_read_b128 v[158:161], v153 offset:1024
	ds_read_b128 v[162:165], v153 offset:2048
	ds_read_b128 v[166:169], v153 offset:3072
	v_add_u32_e32 v153, s66, v147
	ds_read_b128 v[170:173], v153
	ds_read_b128 v[174:177], v153 offset:1024
	ds_read_b128 v[180:183], v153 offset:2048
	ds_read_b128 v[184:187], v153 offset:3072
	s_add_u32 s26, s26, s6
	s_addc_u32 s27, s27, s7
	s_mov_b32 m0, s30
	v_lshl_add_u64 v[228:229], s[26:27], 0, v[134:135]
	ds_read_b128 v[188:191], v151 offset:32768
	ds_read_b128 v[192:195], v151 offset:33792
	ds_read_b128 v[196:199], v151 offset:34816
	ds_read_b128 v[200:203], v151 offset:35840
	ds_read_b128 v[204:207], v151 offset:36864
	ds_read_b128 v[208:211], v151 offset:37888
	ds_read_b128 v[212:215], v151 offset:38912
	ds_read_b128 v[216:219], v151 offset:39936
	global_load_lds_dwordx4 v[228:229], off
	v_lshl_add_u64 v[228:229], s[26:27], 0, v[130:131]
	s_mov_b32 m0, s31
	s_nop 0
	global_load_lds_dwordx4 v[228:229], off
	s_waitcnt vmcnt(8)
	s_waitcnt lgkmcnt(0)
	s_barrier
	s_waitcnt lgkmcnt(0)
	v_mfma_f32_16x16x32_bf16 v[116:119], v[154:157], v[188:191], v[116:119]
	v_mfma_f32_16x16x32_bf16 v[112:115], v[162:165], v[188:191], v[112:115]
	v_mfma_f32_16x16x32_bf16 v[100:103], v[154:157], v[196:199], v[100:103]
	v_mfma_f32_16x16x32_bf16 v[96:99], v[162:165], v[196:199], v[96:99]
	v_mfma_f32_16x16x32_bf16 v[84:87], v[154:157], v[204:207], v[84:87]
	v_mfma_f32_16x16x32_bf16 v[80:83], v[162:165], v[204:207], v[80:83]
	v_mfma_f32_16x16x32_bf16 v[68:71], v[154:157], v[212:215], v[68:71]
	v_mfma_f32_16x16x32_bf16 v[64:67], v[162:165], v[212:215], v[64:67]
	v_mfma_f32_16x16x32_bf16 v[116:119], v[158:161], v[192:195], v[116:119]
	v_mfma_f32_16x16x32_bf16 v[112:115], v[166:169], v[192:195], v[112:115]
	v_mfma_f32_16x16x32_bf16 v[100:103], v[158:161], v[200:203], v[100:103]
	v_mfma_f32_16x16x32_bf16 v[96:99], v[166:169], v[200:203], v[96:99]
	v_mfma_f32_16x16x32_bf16 v[84:87], v[158:161], v[208:211], v[84:87]
	v_mfma_f32_16x16x32_bf16 v[80:83], v[166:169], v[208:211], v[80:83]
	v_mfma_f32_16x16x32_bf16 v[68:71], v[158:161], v[216:219], v[68:71]
	v_mfma_f32_16x16x32_bf16 v[64:67], v[166:169], v[216:219], v[64:67]
	v_mfma_f32_16x16x32_bf16 v[124:127], v[170:173], v[188:191], v[124:127]
	v_mfma_f32_16x16x32_bf16 v[120:123], v[180:183], v[188:191], v[120:123]
	v_mfma_f32_16x16x32_bf16 v[108:111], v[170:173], v[196:199], v[108:111]
	v_mfma_f32_16x16x32_bf16 v[104:107], v[180:183], v[196:199], v[104:107]
	v_mfma_f32_16x16x32_bf16 v[92:95], v[170:173], v[204:207], v[92:95]
	v_mfma_f32_16x16x32_bf16 v[88:91], v[180:183], v[204:207], v[88:91]
	v_mfma_f32_16x16x32_bf16 v[76:79], v[170:173], v[212:215], v[76:79]
	v_mfma_f32_16x16x32_bf16 v[72:75], v[180:183], v[212:215], v[72:75]
	v_mfma_f32_16x16x32_bf16 v[124:127], v[174:177], v[192:195], v[124:127]
	v_mfma_f32_16x16x32_bf16 v[120:123], v[184:187], v[192:195], v[120:123]
	v_mfma_f32_16x16x32_bf16 v[108:111], v[174:177], v[200:203], v[108:111]
	v_mfma_f32_16x16x32_bf16 v[104:107], v[184:187], v[200:203], v[104:107]
	v_mfma_f32_16x16x32_bf16 v[92:95], v[174:177], v[208:211], v[92:95]
	v_mfma_f32_16x16x32_bf16 v[88:91], v[184:187], v[208:211], v[88:91]
	v_mfma_f32_16x16x32_bf16 v[76:79], v[174:177], v[216:219], v[76:79]
	v_mfma_f32_16x16x32_bf16 v[72:75], v[184:187], v[216:219], v[72:75]
	s_barrier
; #define PG8_STAGE(bufoff, gbase, voff) do { _Pragma("unroll") for (int _i = 0; _i < 2; ++_i) \
;         __builtin_amdgcn_global_load_lds((const unsigned*)((const char*)(gbase) + (voff)[_i]), (PG8_LAS unsigned*)(lds + (bufoff) + ldsw + _i * 8192), 16, 0, 0); } while (0)
; #define PG8_LDA(dst, b, h) do { _Pragma("unroll") for (int m = 0; m < 4; ++m) _Pragma("unroll") for (int k = 0; k < 2; ++k) dst[m][k] = *(const PG8_LAS bf16x8*)(lds + PG8_SA(b, h) + aoff + m * 2048 + k * 1024); } while (0)
; #define PG8_LDB(dst, b, h) do { _Pragma("unroll") for (int n = 0; n < 2; ++n) _Pragma("unroll") for (int k = 0; k < 2; ++k) dst[n][k] = *(const PG8_LAS bf16x8*)(lds + PG8_SB(b, h) + boff + n * 2048 + k * 1024); } while (0)
; #define PG8_MMA(ai, bj, At, Bt) do { __builtin_amdgcn_s_setprio(1); _Pragma("unroll") for (int m = 0; m < 4; ++m) _Pragma("unroll") for (int n = 0; n < 2; ++n) _Pragma("unroll") for (int k = 0; k < 2; ++k) \
;         acc[ai][bj][m][n] = __builtin_amdgcn_mfma_f32_16x16x32_bf16(Bt[n][k], At[m][k], acc[ai][bj][m][n], 0, 0, 0); __builtin_amdgcn_s_setprio(0); } while (0)
; #define PG8_WAIT_V(n) asm volatile("s_waitcnt vmcnt(" #n ")" ::: "memory")
; #define PG8_WAIT_L(n) asm volatile("s_waitcnt lgkmcnt(" #n ")" ::: "memory")
; #define PG8_BAR __builtin_amdgcn_s_barrier()
; #define PG8_SCHED __builtin_amdgcn_sched_barrier(0)
; template <class Epi, class Sched, bool ALIGN_EPI = false, bool SP2 = false>
; __device__ __forceinline__ void gemm_phase(PG8_LAS unsigned char* lds, const Gemm g, const Sched& S, const Epi& E) {
;     ...
;             PG8_LDB(B0, 0, 0); PG8_LDB(B1, 0, 1); PG8_SCHED; PG8_LDA(At, 0, 0); PG8_STAGE(PG8_SA(1, 1), a1 + hstep, voffA);
;             PG8_WAIT_V(8); PG8_WAIT_L(0); PG8_BAR; PG8_MMA(0, 0, At, B0); PG8_MMA(0, 1, At, B1); PG8_BAR; PG8_SCHED;
;     ...
;             PG8_LDA(At, 1, 1); PG8_STAGE(PG8_SB(1, 0), b3, voffB); PG8_STAGE(PG8_SB(1, 1), b3 + hstep, voffB); PG8_STAGE(PG8_SA(1, 0), a3, voffA);
;             PG8_WAIT_V(8); PG8_WAIT_L(0); PG8_BAR; PG8_MMA(1, 0, At, B0); PG8_MMA(1, 1, At, B1); PG8_BAR; PG8_SCHED;
	s_add_i32 s26, s65, s16
	v_lshl_add_u64 v[144:145], v[144:145], 0, s[12:13]
	s_mov_b32 m0, s26
	ds_read_b128 v[188:191], v151 offset:49152
	ds_read_b128 v[192:195], v151 offset:50176
	ds_read_b128 v[196:199], v151 offset:51200
	ds_read_b128 v[200:203], v151 offset:52224
	ds_read_b128 v[204:207], v151 offset:53248
	ds_read_b128 v[208:211], v151 offset:54272
	ds_read_b128 v[212:215], v151 offset:55296
	ds_read_b128 v[216:219], v151 offset:56320
	global_load_lds_dwordx4 v[144:145], off
	v_lshl_add_u64 v[144:145], v[178:179], 0, s[12:13]
	s_add_i32 m0, s26, 0x2000
	s_add_i32 s26, s66, s16
	global_load_lds_dwordx4 v[144:145], off
	v_lshl_add_u64 v[144:145], v[220:221], 0, s[12:13]
	s_mov_b32 m0, s26
	s_nop 0
	global_load_lds_dwordx4 v[144:145], off
	v_lshl_add_u64 v[144:145], v[222:223], 0, s[12:13]
	s_add_i32 m0, s26, 0x2000
	s_nop 0
	global_load_lds_dwordx4 v[144:145], off
	v_lshl_add_u64 v[144:145], v[224:225], 0, s[12:13]
	s_mov_b32 m0, s34
	s_nop 0
	global_load_lds_dwordx4 v[144:145], off
	v_lshl_add_u64 v[144:145], v[226:227], 0, s[12:13]
	s_mov_b32 m0, s35
	s_nop 0
	global_load_lds_dwordx4 v[144:145], off
	s_waitcnt vmcnt(8)
	s_waitcnt lgkmcnt(0)
	s_barrier
	s_waitcnt lgkmcnt(0)
	v_mfma_f32_16x16x32_bf16 v[52:55], v[154:157], v[188:191], v[52:55]
	v_mfma_f32_16x16x32_bf16 v[48:51], v[162:165], v[188:191], v[48:51]
	v_mfma_f32_16x16x32_bf16 v[36:39], v[154:157], v[196:199], v[36:39]
	v_mfma_f32_16x16x32_bf16 v[32:35], v[162:165], v[196:199], v[32:35]
	v_mfma_f32_16x16x32_bf16 v[20:23], v[154:157], v[204:207], v[20:23]
	v_mfma_f32_16x16x32_bf16 v[16:19], v[162:165], v[204:207], v[16:19]
	v_mfma_f32_16x16x32_bf16 v[4:7], v[154:157], v[212:215], v[4:7]
	v_mfma_f32_16x16x32_bf16 v[0:3], v[162:165], v[212:215], v[0:3]
	v_mfma_f32_16x16x32_bf16 v[52:55], v[158:161], v[192:195], v[52:55]
	v_mfma_f32_16x16x32_bf16 v[48:51], v[166:169], v[192:195], v[48:51]
	v_mfma_f32_16x16x32_bf16 v[36:39], v[158:161], v[200:203], v[36:39]
	v_mfma_f32_16x16x32_bf16 v[32:35], v[166:169], v[200:203], v[32:35]
	v_mfma_f32_16x16x32_bf16 v[20:23], v[158:161], v[208:211], v[20:23]
	v_mfma_f32_16x16x32_bf16 v[16:19], v[166:169], v[208:211], v[16:19]
	v_mfma_f32_16x16x32_bf16 v[4:7], v[158:161], v[216:219], v[4:7]
	v_mfma_f32_16x16x32_bf16 v[0:3], v[166:169], v[216:219], v[0:3]
	v_mfma_f32_16x16x32_bf16 v[60:63], v[170:173], v[188:191], v[60:63]
	v_mfma_f32_16x16x32_bf16 v[56:59], v[180:183], v[188:191], v[56:59]
	v_mfma_f32_16x16x32_bf16 v[44:47], v[170:173], v[196:199], v[44:47]
	v_mfma_f32_16x16x32_bf16 v[40:43], v[180:183], v[196:199], v[40:43]
	v_mfma_f32_16x16x32_bf16 v[28:31], v[170:173], v[204:207], v[28:31]
	v_mfma_f32_16x16x32_bf16 v[24:27], v[180:183], v[204:207], v[24:27]
	v_mfma_f32_16x16x32_bf16 v[12:15], v[170:173], v[212:215], v[12:15]
	v_mfma_f32_16x16x32_bf16 v[8:11], v[180:183], v[212:215], v[8:11]
	v_mfma_f32_16x16x32_bf16 v[60:63], v[174:177], v[192:195], v[60:63]
	v_mfma_f32_16x16x32_bf16 v[56:59], v[184:187], v[192:195], v[56:59]
	v_mfma_f32_16x16x32_bf16 v[44:47], v[174:177], v[200:203], v[44:47]
	v_mfma_f32_16x16x32_bf16 v[40:43], v[184:187], v[200:203], v[40:43]
	v_mfma_f32_16x16x32_bf16 v[28:31], v[174:177], v[208:211], v[28:31]
	v_mfma_f32_16x16x32_bf16 v[24:27], v[184:187], v[208:211], v[24:27]
	v_mfma_f32_16x16x32_bf16 v[12:15], v[174:177], v[216:219], v[12:15]
	v_mfma_f32_16x16x32_bf16 v[8:11], v[184:187], v[216:219], v[8:11]
	s_barrier
	s_add_u32 s24, s24, 0x100
	s_addc_u32 s25, s25, 0
	s_add_u32 s62, s62, 0x100
	s_addc_u32 s63, s63, 0
	s_cmp_ge_i32 s64, s36
	s_mov_b32 s26, s64
	s_cbranch_scc0 .LBB0_373
	s_branch .Lpeel_x0
.LBB0_373:
	ds_read_b128 v[154:157], v149
	ds_read_b128 v[158:161], v149 offset:1024
	ds_read_b128 v[162:165], v149 offset:2048
	ds_read_b128 v[166:169], v149 offset:3072
	ds_read_b128 v[170:173], v150
	ds_read_b128 v[174:177], v150 offset:1024
	ds_read_b128 v[180:183], v150 offset:2048
	ds_read_b128 v[184:187], v150 offset:3072
	s_add_i32 s64, s26, 2
	s_add_u32 s65, s24, 0x80
	s_addc_u32 s27, s25, 0
	s_cmp_eq_u32 s37, s26
	s_cselect_b32 s26, s0, s65
	s_cselect_b32 s27, s1, s27
	s_cselect_b32 s67, s23, s63
	s_cselect_b32 s66, s22, s62
	v_lshl_add_u64 v[144:145], s[24:25], 0, v[136:137]
	s_add_i32 m0, s28, 0xc000
	ds_read_b128 v[188:191], v151
	ds_read_b128 v[192:195], v151 offset:1024
	ds_read_b128 v[196:199], v151 offset:2048
	ds_read_b128 v[200:203], v151 offset:3072
	ds_read_b128 v[204:207], v151 offset:4096
	ds_read_b128 v[208:211], v151 offset:5120
	ds_read_b128 v[212:215], v151 offset:6144
	ds_read_b128 v[216:219], v151 offset:7168
	global_load_lds_dwordx4 v[144:145], off
	v_lshl_add_u64 v[144:145], s[24:25], 0, v[138:139]
	s_add_i32 m0, s28, 0xe000
	s_nop 0
	global_load_lds_dwordx4 v[144:145], off
	s_waitcnt vmcnt(8)
	s_waitcnt lgkmcnt(0)
	s_barrier
; #define PG8_STAGE(bufoff, gbase, voff) do { _Pragma("unroll") for (int _i = 0; _i < 2; ++_i) \
;         __builtin_amdgcn_global_load_lds((const unsigned*)((const char*)(gbase) + (voff)[_i]), (PG8_LAS unsigned*)(lds + (bufoff) + ldsw + _i * 8192), 16, 0, 0); } while (0)
; #define PG8_LDA(dst, b, h) do { _Pragma("unroll") for (int m = 0; m < 4; ++m) _Pragma("unroll") for (int k = 0; k < 2; ++k) dst[m][k] = *(const PG8_LAS bf16x8*)(lds + PG8_SA(b, h) + aoff + m * 2048 + k * 1024); } while (0)
; #define PG8_MMA(ai, bj, At, Bt) do { __builtin_amdgcn_s_setprio(1); _Pragma("unroll") for (int m = 0; m < 4; ++m) _Pragma("unroll") for (int n = 0; n < 2; ++n) _Pragma("unroll") for (int k = 0; k < 2; ++k) \
;         acc[ai][bj][m][n] = __builtin_amdgcn_mfma_f32_16x16x32_bf16(Bt[n][k], At[m][k], acc[ai][bj][m][n], 0, 0, 0); __builtin_amdgcn_s_setprio(0); } while (0)
; #define PG8_WAIT_V(n) asm volatile("s_waitcnt vmcnt(" #n ")" ::: "memory")
; #define PG8_WAIT_L(n) asm volatile("s_waitcnt lgkmcnt(" #n ")" ::: "memory")
; #define PG8_BAR __builtin_amdgcn_s_barrier()
; #define PG8_SCHED __builtin_amdgcn_sched_barrier(0)
; template <class Epi, class Sched, bool ALIGN_EPI = false, bool SP2 = false>
; __device__ __forceinline__ void gemm_phase(PG8_LAS unsigned char* lds, const Gemm g, const Sched& S, const Epi& E) {
;     ...
;             PG8_WAIT_V(8); PG8_WAIT_L(0); PG8_BAR; PG8_MMA(0, 0, At, B0); PG8_MMA(0, 1, At, B1); PG8_BAR; PG8_SCHED;
;             PG8_LDA(At, 0, 1); PG8_STAGE(PG8_SB(0, 0), b2, voffB); PG8_STAGE(PG8_SB(0, 1), b2 + hstep, voffB); PG8_STAGE(PG8_SA(0, 0), a2, voffA);
;             PG8_WAIT_V(8); PG8_WAIT_L(0); PG8_BAR; PG8_MMA(1, 0, At, B0); PG8_MMA(1, 1, At, B1); PG8_BAR; PG8_SCHED;
	s_waitcnt lgkmcnt(0)
	v_mfma_f32_16x16x32_bf16 v[116:119], v[154:157], v[188:191], v[116:119]
	v_mfma_f32_16x16x32_bf16 v[112:115], v[162:165], v[188:191], v[112:115]
	v_mfma_f32_16x16x32_bf16 v[100:103], v[154:157], v[196:199], v[100:103]
	v_mfma_f32_16x16x32_bf16 v[96:99], v[162:165], v[196:199], v[96:99]
	v_mfma_f32_16x16x32_bf16 v[84:87], v[154:157], v[204:207], v[84:87]
	v_mfma_f32_16x16x32_bf16 v[80:83], v[162:165], v[204:207], v[80:83]
	v_mfma_f32_16x16x32_bf16 v[68:71], v[154:157], v[212:215], v[68:71]
	v_mfma_f32_16x16x32_bf16 v[64:67], v[162:165], v[212:215], v[64:67]
	v_mfma_f32_16x16x32_bf16 v[116:119], v[158:161], v[192:195], v[116:119]
	v_mfma_f32_16x16x32_bf16 v[112:115], v[166:169], v[192:195], v[112:115]
	v_mfma_f32_16x16x32_bf16 v[100:103], v[158:161], v[200:203], v[100:103]
	v_mfma_f32_16x16x32_bf16 v[96:99], v[166:169], v[200:203], v[96:99]
	v_mfma_f32_16x16x32_bf16 v[84:87], v[158:161], v[208:211], v[84:87]
	v_mfma_f32_16x16x32_bf16 v[80:83], v[166:169], v[208:211], v[80:83]
	v_mfma_f32_16x16x32_bf16 v[68:71], v[158:161], v[216:219], v[68:71]
	v_mfma_f32_16x16x32_bf16 v[64:67], v[166:169], v[216:219], v[64:67]
	v_mfma_f32_16x16x32_bf16 v[124:127], v[170:173], v[188:191], v[124:127]
	v_mfma_f32_16x16x32_bf16 v[120:123], v[180:183], v[188:191], v[120:123]
	v_mfma_f32_16x16x32_bf16 v[108:111], v[170:173], v[196:199], v[108:111]
	v_mfma_f32_16x16x32_bf16 v[104:107], v[180:183], v[196:199], v[104:107]
	v_mfma_f32_16x16x32_bf16 v[92:95], v[170:173], v[204:207], v[92:95]
	v_mfma_f32_16x16x32_bf16 v[88:91], v[180:183], v[204:207], v[88:91]
	v_mfma_f32_16x16x32_bf16 v[76:79], v[170:173], v[212:215], v[76:79]
	v_mfma_f32_16x16x32_bf16 v[72:75], v[180:183], v[212:215], v[72:75]
	v_mfma_f32_16x16x32_bf16 v[124:127], v[174:177], v[192:195], v[124:127]
	v_mfma_f32_16x16x32_bf16 v[120:123], v[184:187], v[192:195], v[120:123]
	v_mfma_f32_16x16x32_bf16 v[108:111], v[174:177], v[200:203], v[108:111]
	v_mfma_f32_16x16x32_bf16 v[104:107], v[184:187], v[200:203], v[104:107]
	v_mfma_f32_16x16x32_bf16 v[92:95], v[174:177], v[208:211], v[92:95]
	v_mfma_f32_16x16x32_bf16 v[88:91], v[184:187], v[208:211], v[88:91]
	v_mfma_f32_16x16x32_bf16 v[76:79], v[174:177], v[216:219], v[76:79]
	v_mfma_f32_16x16x32_bf16 v[72:75], v[184:187], v[216:219], v[72:75]
	s_barrier
	s_add_i32 s65, s40, s16
	v_lshl_add_u64 v[144:145], s[66:67], 0, v[132:133]
	s_mov_b32 m0, s65
	ds_read_b128 v[188:191], v151 offset:16384
	ds_read_b128 v[192:195], v151 offset:17408
	ds_read_b128 v[196:199], v151 offset:18432
	ds_read_b128 v[200:203], v151 offset:19456
	ds_read_b128 v[204:207], v151 offset:20480
	ds_read_b128 v[208:211], v151 offset:21504
	ds_read_b128 v[212:215], v151 offset:22528
	ds_read_b128 v[216:219], v151 offset:23552
	global_load_lds_dwordx4 v[144:145], off
	s_add_i32 m0, s65, 0x2000
	v_lshl_add_u64 v[178:179], s[66:67], 0, v[128:129]
	s_add_u32 s66, s66, s6
	s_addc_u32 s67, s67, s7
	s_add_i32 s65, s41, s16
	global_load_lds_dwordx4 v[178:179], off
	v_lshl_add_u64 v[220:221], s[66:67], 0, v[132:133]
	s_mov_b32 m0, s65
	v_lshl_add_u64 v[222:223], s[66:67], 0, v[128:129]
	global_load_lds_dwordx4 v[220:221], off
	s_add_i32 m0, s65, 0x2000
	v_lshl_add_u64 v[224:225], s[26:27], 0, v[134:135]
	global_load_lds_dwordx4 v[222:223], off
	s_mov_b32 m0, s28
	v_lshl_add_u64 v[226:227], s[26:27], 0, v[130:131]
	global_load_lds_dwordx4 v[224:225], off
	s_mov_b32 m0, s29
	s_nop 0
	global_load_lds_dwordx4 v[226:227], off
	s_waitcnt vmcnt(8)
	s_waitcnt lgkmcnt(0)
	s_barrier
	s_waitcnt lgkmcnt(0)
	v_mfma_f32_16x16x32_bf16 v[52:55], v[154:157], v[188:191], v[52:55]
	v_mfma_f32_16x16x32_bf16 v[48:51], v[162:165], v[188:191], v[48:51]
	v_mfma_f32_16x16x32_bf16 v[36:39], v[154:157], v[196:199], v[36:39]
	v_mfma_f32_16x16x32_bf16 v[32:35], v[162:165], v[196:199], v[32:35]
	v_mfma_f32_16x16x32_bf16 v[20:23], v[154:157], v[204:207], v[20:23]
	v_mfma_f32_16x16x32_bf16 v[16:19], v[162:165], v[204:207], v[16:19]
	v_mfma_f32_16x16x32_bf16 v[4:7], v[154:157], v[212:215], v[4:7]
	v_mfma_f32_16x16x32_bf16 v[0:3], v[162:165], v[212:215], v[0:3]
	v_mfma_f32_16x16x32_bf16 v[52:55], v[158:161], v[192:195], v[52:55]
	v_mfma_f32_16x16x32_bf16 v[48:51], v[166:169], v[192:195], v[48:51]
	v_mfma_f32_16x16x32_bf16 v[36:39], v[158:161], v[200:203], v[36:39]
	v_mfma_f32_16x16x32_bf16 v[32:35], v[166:169], v[200:203], v[32:35]
	v_mfma_f32_16x16x32_bf16 v[20:23], v[158:161], v[208:211], v[20:23]
	v_mfma_f32_16x16x32_bf16 v[16:19], v[166:169], v[208:211], v[16:19]
	v_mfma_f32_16x16x32_bf16 v[4:7], v[158:161], v[216:219], v[4:7]
	v_mfma_f32_16x16x32_bf16 v[0:3], v[166:169], v[216:219], v[0:3]
	v_mfma_f32_16x16x32_bf16 v[60:63], v[170:173], v[188:191], v[60:63]
	v_mfma_f32_16x16x32_bf16 v[56:59], v[180:183], v[188:191], v[56:59]
	v_mfma_f32_16x16x32_bf16 v[44:47], v[170:173], v[196:199], v[44:47]
	v_mfma_f32_16x16x32_bf16 v[40:43], v[180:183], v[196:199], v[40:43]
	v_mfma_f32_16x16x32_bf16 v[28:31], v[170:173], v[204:207], v[28:31]
	v_mfma_f32_16x16x32_bf16 v[24:27], v[180:183], v[204:207], v[24:27]
	v_mfma_f32_16x16x32_bf16 v[12:15], v[170:173], v[212:215], v[12:15]
	v_mfma_f32_16x16x32_bf16 v[8:11], v[180:183], v[212:215], v[8:11]
	v_mfma_f32_16x16x32_bf16 v[60:63], v[174:177], v[192:195], v[60:63]
	v_mfma_f32_16x16x32_bf16 v[56:59], v[184:187], v[192:195], v[56:59]
	v_mfma_f32_16x16x32_bf16 v[44:47], v[174:177], v[200:203], v[44:47]
	v_mfma_f32_16x16x32_bf16 v[40:43], v[184:187], v[200:203], v[40:43]
	v_mfma_f32_16x16x32_bf16 v[28:31], v[174:177], v[208:211], v[28:31]
	v_mfma_f32_16x16x32_bf16 v[24:27], v[184:187], v[208:211], v[24:27]
	v_mfma_f32_16x16x32_bf16 v[12:15], v[174:177], v[216:219], v[12:15]
	v_mfma_f32_16x16x32_bf16 v[8:11], v[184:187], v[216:219], v[8:11]
	s_barrier
; #define PG8_STAGE(bufoff, gbase, voff) do { _Pragma("unroll") for (int _i = 0; _i < 2; ++_i) \
;         __builtin_amdgcn_global_load_lds((const unsigned*)((const char*)(gbase) + (voff)[_i]), (PG8_LAS unsigned*)(lds + (bufoff) + ldsw + _i * 8192), 16, 0, 0); } while (0)
; #define PG8_LDA(dst, b, h) do { _Pragma("unroll") for (int m = 0; m < 4; ++m) _Pragma("unroll") for (int k = 0; k < 2; ++k) dst[m][k] = *(const PG8_LAS bf16x8*)(lds + PG8_SA(b, h) + aoff + m * 2048 + k * 1024); } while (0)
; #define PG8_LDB(dst, b, h) do { _Pragma("unroll") for (int n = 0; n < 2; ++n) _Pragma("unroll") for (int k = 0; k < 2; ++k) dst[n][k] = *(const PG8_LAS bf16x8*)(lds + PG8_SB(b, h) + boff + n * 2048 + k * 1024); } while (0)
; #define PG8_MMA(ai, bj, At, Bt) do { __builtin_amdgcn_s_setprio(1); _Pragma("unroll") for (int m = 0; m < 4; ++m) _Pragma("unroll") for (int n = 0; n < 2; ++n) _Pragma("unroll") for (int k = 0; k < 2; ++k) \
;         acc[ai][bj][m][n] = __builtin_amdgcn_mfma_f32_16x16x32_bf16(Bt[n][k], At[m][k], acc[ai][bj][m][n], 0, 0, 0); __builtin_amdgcn_s_setprio(0); } while (0)
; #define PG8_WAIT_V(n) asm volatile("s_waitcnt vmcnt(" #n ")" ::: "memory")
; #define PG8_WAIT_L(n) asm volatile("s_waitcnt lgkmcnt(" #n ")" ::: "memory")
; #define PG8_BAR __builtin_amdgcn_s_barrier()
; #define PG8_SCHED __builtin_amdgcn_sched_barrier(0)
; template <class Epi, class Sched, bool ALIGN_EPI = false, bool SP2 = false>
; __device__ __forceinline__ void gemm_phase(PG8_LAS unsigned char* lds, const Gemm g, const Sched& S, const Epi& E) {
;     ...
;             PG8_LDB(B0, 1, 0); PG8_LDB(B1, 1, 1); PG8_SCHED; PG8_LDA(At, 1, 0); PG8_STAGE(PG8_SA(0, 1), a2 + hstep, voffA);
;             PG8_WAIT_V(8); PG8_WAIT_L(0); PG8_BAR; PG8_MMA(0, 0, At, B0); PG8_MMA(0, 1, At, B1); PG8_BAR; PG8_SCHED;
;             PG8_LDA(At, 1, 1); PG8_STAGE(PG8_SB(1, 0), b3, voffB); PG8_STAGE(PG8_SB(1, 1), b3 + hstep, voffB); PG8_STAGE(PG8_SA(1, 0), a3, voffA);
;             PG8_WAIT_V(8); PG8_WAIT_L(0); PG8_BAR; PG8_MMA(1, 0, At, B0); PG8_MMA(1, 1, At, B1); PG8_BAR; PG8_SCHED;
	s_add_i32 s65, 0, 0x18000
	v_add_u32_e32 v153, s65, v147
	s_add_i32 s66, 0, 0x1c000
	ds_read_b128 v[154:157], v153
	ds_read_b128 v[158:161], v153 offset:1024
	ds_read_b128 v[162:165], v153 offset:2048
	ds_read_b128 v[166:169], v153 offset:3072
	v_add_u32_e32 v153, s66, v147
	ds_read_b128 v[170:173], v153
	ds_read_b128 v[174:177], v153 offset:1024
	ds_read_b128 v[180:183], v153 offset:2048
	ds_read_b128 v[184:187], v153 offset:3072
	s_add_u32 s26, s26, s6
	s_addc_u32 s27, s27, s7
	s_mov_b32 m0, s30
	v_lshl_add_u64 v[228:229], s[26:27], 0, v[134:135]
	ds_read_b128 v[188:191], v151 offset:32768
	ds_read_b128 v[192:195], v151 offset:33792
	ds_read_b128 v[196:199], v151 offset:34816
	ds_read_b128 v[200:203], v151 offset:35840
	ds_read_b128 v[204:207], v151 offset:36864
	ds_read_b128 v[208:211], v151 offset:37888
	ds_read_b128 v[212:215], v151 offset:38912
	ds_read_b128 v[216:219], v151 offset:39936
	global_load_lds_dwordx4 v[228:229], off
	v_lshl_add_u64 v[228:229], s[26:27], 0, v[130:131]
	s_mov_b32 m0, s31
	s_nop 0
	global_load_lds_dwordx4 v[228:229], off
	s_waitcnt vmcnt(8)
	s_waitcnt lgkmcnt(0)
	s_barrier
	s_waitcnt lgkmcnt(0)
	v_mfma_f32_16x16x32_bf16 v[116:119], v[154:157], v[188:191], v[116:119]
	v_mfma_f32_16x16x32_bf16 v[112:115], v[162:165], v[188:191], v[112:115]
	v_mfma_f32_16x16x32_bf16 v[100:103], v[154:157], v[196:199], v[100:103]
	v_mfma_f32_16x16x32_bf16 v[96:99], v[162:165], v[196:199], v[96:99]
	v_mfma_f32_16x16x32_bf16 v[84:87], v[154:157], v[204:207], v[84:87]
	v_mfma_f32_16x16x32_bf16 v[80:83], v[162:165], v[204:207], v[80:83]
	v_mfma_f32_16x16x32_bf16 v[68:71], v[154:157], v[212:215], v[68:71]
	v_mfma_f32_16x16x32_bf16 v[64:67], v[162:165], v[212:215], v[64:67]
	v_mfma_f32_16x16x32_bf16 v[116:119], v[158:161], v[192:195], v[116:119]
	v_mfma_f32_16x16x32_bf16 v[112:115], v[166:169], v[192:195], v[112:115]
	v_mfma_f32_16x16x32_bf16 v[100:103], v[158:161], v[200:203], v[100:103]
	v_mfma_f32_16x16x32_bf16 v[96:99], v[166:169], v[200:203], v[96:99]
	v_mfma_f32_16x16x32_bf16 v[84:87], v[158:161], v[208:211], v[84:87]
	v_mfma_f32_16x16x32_bf16 v[80:83], v[166:169], v[208:211], v[80:83]
	v_mfma_f32_16x16x32_bf16 v[68:71], v[158:161], v[216:219], v[68:71]
	v_mfma_f32_16x16x32_bf16 v[64:67], v[166:169], v[216:219], v[64:67]
	v_mfma_f32_16x16x32_bf16 v[124:127], v[170:173], v[188:191], v[124:127]
	v_mfma_f32_16x16x32_bf16 v[120:123], v[180:183], v[188:191], v[120:123]
	v_mfma_f32_16x16x32_bf16 v[108:111], v[170:173], v[196:199], v[108:111]
	v_mfma_f32_16x16x32_bf16 v[104:107], v[180:183], v[196:199], v[104:107]
	v_mfma_f32_16x16x32_bf16 v[92:95], v[170:173], v[204:207], v[92:95]
	v_mfma_f32_16x16x32_bf16 v[88:91], v[180:183], v[204:207], v[88:91]
	v_mfma_f32_16x16x32_bf16 v[76:79], v[170:173], v[212:215], v[76:79]
	v_mfma_f32_16x16x32_bf16 v[72:75], v[180:183], v[212:215], v[72:75]
	v_mfma_f32_16x16x32_bf16 v[124:127], v[174:177], v[192:195], v[124:127]
	v_mfma_f32_16x16x32_bf16 v[120:123], v[184:187], v[192:195], v[120:123]
	v_mfma_f32_16x16x32_bf16 v[108:111], v[174:177], v[200:203], v[108:111]
	v_mfma_f32_16x16x32_bf16 v[104:107], v[184:187], v[200:203], v[104:107]
	v_mfma_f32_16x16x32_bf16 v[92:95], v[174:177], v[208:211], v[92:95]
	v_mfma_f32_16x16x32_bf16 v[88:91], v[184:187], v[208:211], v[88:91]
	v_mfma_f32_16x16x32_bf16 v[76:79], v[174:177], v[216:219], v[76:79]
	v_mfma_f32_16x16x32_bf16 v[72:75], v[184:187], v[216:219], v[72:75]
	s_barrier
	s_add_i32 s26, s65, s16
	v_lshl_add_u64 v[144:145], v[144:145], 0, s[12:13]
	s_mov_b32 m0, s26
	ds_read_b128 v[188:191], v151 offset:49152
	ds_read_b128 v[192:195], v151 offset:50176
	ds_read_b128 v[196:199], v151 offset:51200
	ds_read_b128 v[200:203], v151 offset:52224
	ds_read_b128 v[204:207], v151 offset:53248
	ds_read_b128 v[208:211], v151 offset:54272
	ds_read_b128 v[212:215], v151 offset:55296
	ds_read_b128 v[216:219], v151 offset:56320
	global_load_lds_dwordx4 v[144:145], off
	v_lshl_add_u64 v[144:145], v[178:179], 0, s[12:13]
	s_add_i32 m0, s26, 0x2000
	s_add_i32 s26, s66, s16
	global_load_lds_dwordx4 v[144:145], off
	v_lshl_add_u64 v[144:145], v[220:221], 0, s[12:13]
	s_mov_b32 m0, s26
	s_nop 0
	global_load_lds_dwordx4 v[144:145], off
	v_lshl_add_u64 v[144:145], v[222:223], 0, s[12:13]
	s_add_i32 m0, s26, 0x2000
	s_nop 0
	global_load_lds_dwordx4 v[144:145], off
	v_lshl_add_u64 v[144:145], v[224:225], 0, s[12:13]
	s_mov_b32 m0, s34
	s_nop 0
	global_load_lds_dwordx4 v[144:145], off
	v_lshl_add_u64 v[144:145], v[226:227], 0, s[12:13]
	s_mov_b32 m0, s35
	s_nop 0
	global_load_lds_dwordx4 v[144:145], off
	s_waitcnt vmcnt(8)
	s_waitcnt lgkmcnt(0)
	s_barrier
	s_waitcnt lgkmcnt(0)
	v_mfma_f32_16x16x32_bf16 v[52:55], v[154:157], v[188:191], v[52:55]
	v_mfma_f32_16x16x32_bf16 v[48:51], v[162:165], v[188:191], v[48:51]
	v_mfma_f32_16x16x32_bf16 v[36:39], v[154:157], v[196:199], v[36:39]
	v_mfma_f32_16x16x32_bf16 v[32:35], v[162:165], v[196:199], v[32:35]
	v_mfma_f32_16x16x32_bf16 v[20:23], v[154:157], v[204:207], v[20:23]
	v_mfma_f32_16x16x32_bf16 v[16:19], v[162:165], v[204:207], v[16:19]
	v_mfma_f32_16x16x32_bf16 v[4:7], v[154:157], v[212:215], v[4:7]
	v_mfma_f32_16x16x32_bf16 v[0:3], v[162:165], v[212:215], v[0:3]
	v_mfma_f32_16x16x32_bf16 v[52:55], v[158:161], v[192:195], v[52:55]
	v_mfma_f32_16x16x32_bf16 v[48:51], v[166:169], v[192:195], v[48:51]
	v_mfma_f32_16x16x32_bf16 v[36:39], v[158:161], v[200:203], v[36:39]
	v_mfma_f32_16x16x32_bf16 v[32:35], v[166:169], v[200:203], v[32:35]
	v_mfma_f32_16x16x32_bf16 v[20:23], v[158:161], v[208:211], v[20:23]
	v_mfma_f32_16x16x32_bf16 v[16:19], v[166:169], v[208:211], v[16:19]
	v_mfma_f32_16x16x32_bf16 v[4:7], v[158:161], v[216:219], v[4:7]
	v_mfma_f32_16x16x32_bf16 v[0:3], v[166:169], v[216:219], v[0:3]
	v_mfma_f32_16x16x32_bf16 v[60:63], v[170:173], v[188:191], v[60:63]
	v_mfma_f32_16x16x32_bf16 v[56:59], v[180:183], v[188:191], v[56:59]
	v_mfma_f32_16x16x32_bf16 v[44:47], v[170:173], v[196:199], v[44:47]
	v_mfma_f32_16x16x32_bf16 v[40:43], v[180:183], v[196:199], v[40:43]
	v_mfma_f32_16x16x32_bf16 v[28:31], v[170:173], v[204:207], v[28:31]
	v_mfma_f32_16x16x32_bf16 v[24:27], v[180:183], v[204:207], v[24:27]
	v_mfma_f32_16x16x32_bf16 v[12:15], v[170:173], v[212:215], v[12:15]
	v_mfma_f32_16x16x32_bf16 v[8:11], v[180:183], v[212:215], v[8:11]
	v_mfma_f32_16x16x32_bf16 v[60:63], v[174:177], v[192:195], v[60:63]
	v_mfma_f32_16x16x32_bf16 v[56:59], v[184:187], v[192:195], v[56:59]
	v_mfma_f32_16x16x32_bf16 v[44:47], v[174:177], v[200:203], v[44:47]
	v_mfma_f32_16x16x32_bf16 v[40:43], v[184:187], v[200:203], v[40:43]
	v_mfma_f32_16x16x32_bf16 v[28:31], v[174:177], v[208:211], v[28:31]
	v_mfma_f32_16x16x32_bf16 v[24:27], v[184:187], v[208:211], v[24:27]
	v_mfma_f32_16x16x32_bf16 v[12:15], v[174:177], v[216:219], v[12:15]
	v_mfma_f32_16x16x32_bf16 v[8:11], v[184:187], v[216:219], v[8:11]
	s_barrier
	s_add_u32 s24, s24, 0x100
	s_addc_u32 s25, s25, 0
	s_add_u32 s62, s62, 0x100
	s_addc_u32 s63, s63, 0
	s_cmp_ge_i32 s64, s36
	s_mov_b32 s26, s64
	s_cbranch_scc0 .LBB0_373

; #define PG8_STAGE(bufoff, gbase, voff) do { _Pragma("unroll") for (int _i = 0; _i < 2; ++_i) \
;         __builtin_amdgcn_global_load_lds((const unsigned*)((const char*)(gbase) + (voff)[_i]), (PG8_LAS unsigned*)(lds + (bufoff) + ldsw + _i * 8192), 16, 0, 0); } while (0)
; #define PG8_LDA(dst, b, h) do { _Pragma("unroll") for (int m = 0; m < 4; ++m) _Pragma("unroll") for (int k = 0; k < 2; ++k) dst[m][k] = *(const PG8_LAS bf16x8*)(lds + PG8_SA(b, h) + aoff + m * 2048 + k * 1024); } while (0)
; #define PG8_LDB(dst, b, h) do { _Pragma("unroll") for (int n = 0; n < 2; ++n) _Pragma("unroll") for (int k = 0; k < 2; ++k) dst[n][k] = *(const PG8_LAS bf16x8*)(lds + PG8_SB(b, h) + boff + n * 2048 + k * 1024); } while (0)
; #define PG8_MMA(ai, bj, At, Bt) do { __builtin_amdgcn_s_setprio(1); _Pragma("unroll") for (int m = 0; m < 4; ++m) _Pragma("unroll") for (int n = 0; n < 2; ++n) _Pragma("unroll") for (int k = 0; k < 2; ++k) \
;         acc[ai][bj][m][n] = __builtin_amdgcn_mfma_f32_16x16x32_bf16(Bt[n][k], At[m][k], acc[ai][bj][m][n], 0, 0, 0); __builtin_amdgcn_s_setprio(0); } while (0)
; #define PG8_WAIT_V(n) asm volatile("s_waitcnt vmcnt(" #n ")" ::: "memory")
; #define PG8_WAIT_L(n) asm volatile("s_waitcnt lgkmcnt(" #n ")" ::: "memory")
; #define PG8_BAR __builtin_amdgcn_s_barrier()
; #define PG8_SCHED __builtin_amdgcn_sched_barrier(0)
; template <class Epi, class Sched, bool ALIGN_EPI = false, bool SP2 = false>
; __device__ __forceinline__ void gemm_phase(PG8_LAS unsigned char* lds, const Gemm g, const Sched& S, const Epi& E) {
;     ...
;             PG8_LDB(B0, 0, 0); PG8_LDB(B1, 0, 1); PG8_SCHED; PG8_LDA(At, 0, 0); PG8_STAGE(PG8_SA(1, 1), a1 + hstep, voffA);
;             PG8_WAIT_V(8); PG8_WAIT_L(0); PG8_BAR; PG8_MMA(0, 0, At, B0); PG8_MMA(0, 1, At, B1); PG8_BAR; PG8_SCHED;
;             PG8_LDA(At, 0, 1); PG8_STAGE(PG8_SB(0, 0), b2, voffB); PG8_STAGE(PG8_SB(0, 1), b2 + hstep, voffB); PG8_STAGE(PG8_SA(0, 0), a2, voffA);
;             PG8_WAIT_V(8); PG8_WAIT_L(0); PG8_BAR; PG8_MMA(1, 0, At, B0); PG8_MMA(1, 1, At, B1); PG8_BAR; PG8_SCHED;
.LBB0_465:
	v_mov_b32_e32 v151, 0
	s_andn2_b64 vcc, exec, s[24:25]
	v_mov_b32_e32 v150, 0
	v_mov_b32_e32 v155, 0
	v_mov_b32_e32 v154, 0
	v_mov_b32_e32 v153, 0
	v_mov_b32_e32 v152, 0
	v_mov_b32_e32 v149, 0
	v_mov_b32_e32 v148, 0
	v_mov_b32_e32 v145, 0
	v_mov_b32_e32 v144, 0
	v_mov_b32_e32 v147, 0
	v_mov_b32_e32 v146, 0
	s_waitcnt lgkmcnt(0)
	s_cbranch_vccnz .LBB0_469
	s_add_u32 s30, s30, 0x80
	s_addc_u32 s31, s31, 0
	s_add_u32 s65, s34, 0x100
	s_addc_u32 s66, s35, 0
	s_mov_b32 s34, 0
	ds_read_b128 v[144:147], v159
	ds_read_b128 v[148:151], v159 offset:1024
	ds_read_b128 v[152:155], v159 offset:2048
	ds_read_b128 v[164:167], v159 offset:3072
	ds_read_b128 v[168:171], v160
	ds_read_b128 v[172:175], v160 offset:1024
	ds_read_b128 v[180:183], v160 offset:2048
	ds_read_b128 v[184:187], v160 offset:3072
	s_add_i32 s67, s34, 2
	s_add_u32 s68, s30, 0x80
	s_addc_u32 s35, s31, 0
	s_cmp_eq_u32 s41, s34
	s_cselect_b32 s34, s0, s68
	s_cselect_b32 s35, s1, s35
	s_cselect_b32 s69, s29, s66
	s_cselect_b32 s68, s28, s65
	v_lshl_add_u64 v[176:177], s[30:31], 0, v[136:137]
	s_add_i32 m0, s17, 0xc000
	ds_read_b128 v[188:191], v161
	ds_read_b128 v[192:195], v161 offset:1024
	ds_read_b128 v[196:199], v161 offset:2048
	ds_read_b128 v[200:203], v161 offset:3072
	ds_read_b128 v[204:207], v161 offset:4096
	ds_read_b128 v[208:211], v161 offset:5120
	ds_read_b128 v[212:215], v161 offset:6144
	ds_read_b128 v[216:219], v161 offset:7168
	global_load_lds_dwordx4 v[176:177], off
	v_lshl_add_u64 v[176:177], s[30:31], 0, v[138:139]
	s_add_i32 m0, s17, 0xe000
	s_nop 0
	global_load_lds_dwordx4 v[176:177], off
	s_waitcnt vmcnt(8)
	s_waitcnt lgkmcnt(0)
	s_barrier
	s_waitcnt lgkmcnt(0)
	v_mfma_f32_16x16x32_bf16 v[124:127], v[144:147], v[188:191], 0
	v_mfma_f32_16x16x32_bf16 v[120:123], v[152:155], v[188:191], 0
	v_mfma_f32_16x16x32_bf16 v[116:119], v[144:147], v[196:199], 0
	v_mfma_f32_16x16x32_bf16 v[112:115], v[152:155], v[196:199], 0
	v_mfma_f32_16x16x32_bf16 v[104:107], v[144:147], v[204:207], 0
	v_mfma_f32_16x16x32_bf16 v[96:99], v[152:155], v[204:207], 0
	v_mfma_f32_16x16x32_bf16 v[88:91], v[144:147], v[212:215], 0
	v_mfma_f32_16x16x32_bf16 v[80:83], v[152:155], v[212:215], 0
	v_mfma_f32_16x16x32_bf16 v[124:127], v[148:151], v[192:195], v[124:127]
	v_mfma_f32_16x16x32_bf16 v[120:123], v[164:167], v[192:195], v[120:123]
	v_mfma_f32_16x16x32_bf16 v[116:119], v[148:151], v[200:203], v[116:119]
	v_mfma_f32_16x16x32_bf16 v[112:115], v[164:167], v[200:203], v[112:115]
	v_mfma_f32_16x16x32_bf16 v[104:107], v[148:151], v[208:211], v[104:107]
	v_mfma_f32_16x16x32_bf16 v[96:99], v[164:167], v[208:211], v[96:99]
	v_mfma_f32_16x16x32_bf16 v[88:91], v[148:151], v[216:219], v[88:91]
	v_mfma_f32_16x16x32_bf16 v[80:83], v[164:167], v[216:219], v[80:83]
	v_mfma_f32_16x16x32_bf16 v[108:111], v[168:171], v[188:191], 0
	v_mfma_f32_16x16x32_bf16 v[100:103], v[180:183], v[188:191], 0
	v_mfma_f32_16x16x32_bf16 v[92:95], v[168:171], v[196:199], 0
	v_mfma_f32_16x16x32_bf16 v[84:87], v[180:183], v[196:199], 0
	v_mfma_f32_16x16x32_bf16 v[76:79], v[168:171], v[204:207], 0
	v_mfma_f32_16x16x32_bf16 v[72:75], v[180:183], v[204:207], 0
	v_mfma_f32_16x16x32_bf16 v[68:71], v[168:171], v[212:215], 0
	v_mfma_f32_16x16x32_bf16 v[64:67], v[180:183], v[212:215], 0
	v_mfma_f32_16x16x32_bf16 v[108:111], v[172:175], v[192:195], v[108:111]
	v_mfma_f32_16x16x32_bf16 v[100:103], v[184:187], v[192:195], v[100:103]
	v_mfma_f32_16x16x32_bf16 v[92:95], v[172:175], v[200:203], v[92:95]
	v_mfma_f32_16x16x32_bf16 v[84:87], v[184:187], v[200:203], v[84:87]
	v_mfma_f32_16x16x32_bf16 v[76:79], v[172:175], v[208:211], v[76:79]
	v_mfma_f32_16x16x32_bf16 v[72:75], v[184:187], v[208:211], v[72:75]
	v_mfma_f32_16x16x32_bf16 v[68:71], v[172:175], v[216:219], v[68:71]
	v_mfma_f32_16x16x32_bf16 v[64:67], v[184:187], v[216:219], v[64:67]
	s_barrier
	s_add_i32 s70, s59, s16
	v_lshl_add_u64 v[176:177], s[68:69], 0, v[130:131]
	s_mov_b32 m0, s70
	ds_read_b128 v[188:191], v161 offset:16384
	ds_read_b128 v[192:195], v161 offset:17408
	ds_read_b128 v[196:199], v161 offset:18432
	ds_read_b128 v[200:203], v161 offset:19456
	ds_read_b128 v[204:207], v161 offset:20480
	ds_read_b128 v[208:211], v161 offset:21504
	ds_read_b128 v[212:215], v161 offset:22528
	ds_read_b128 v[216:219], v161 offset:23552
	global_load_lds_dwordx4 v[176:177], off
	s_add_i32 m0, s70, 0x2000
	v_lshl_add_u64 v[178:179], s[68:69], 0, v[134:135]
	s_add_u32 s68, s68, s6
	s_addc_u32 s69, s69, s7
	s_add_i32 s70, s60, s16
	global_load_lds_dwordx4 v[178:179], off
	v_lshl_add_u64 v[220:221], s[68:69], 0, v[130:131]
	s_mov_b32 m0, s70
	v_lshl_add_u64 v[222:223], s[68:69], 0, v[134:135]
	global_load_lds_dwordx4 v[220:221], off
	s_add_i32 m0, s70, 0x2000
	v_lshl_add_u64 v[224:225], s[34:35], 0, v[128:129]
	global_load_lds_dwordx4 v[222:223], off
	s_mov_b32 m0, s17
	v_lshl_add_u64 v[226:227], s[34:35], 0, v[132:133]
	global_load_lds_dwordx4 v[224:225], off
	s_mov_b32 m0, s19
	s_nop 0
	global_load_lds_dwordx4 v[226:227], off
	s_waitcnt vmcnt(8)
	s_waitcnt lgkmcnt(0)
	s_barrier
; #define PG8_STAGE(bufoff, gbase, voff) do { _Pragma("unroll") for (int _i = 0; _i < 2; ++_i) \
;         __builtin_amdgcn_global_load_lds((const unsigned*)((const char*)(gbase) + (voff)[_i]), (PG8_LAS unsigned*)(lds + (bufoff) + ldsw + _i * 8192), 16, 0, 0); } while (0)
; #define PG8_LDA(dst, b, h) do { _Pragma("unroll") for (int m = 0; m < 4; ++m) _Pragma("unroll") for (int k = 0; k < 2; ++k) dst[m][k] = *(const PG8_LAS bf16x8*)(lds + PG8_SA(b, h) + aoff + m * 2048 + k * 1024); } while (0)
; #define PG8_LDB(dst, b, h) do { _Pragma("unroll") for (int n = 0; n < 2; ++n) _Pragma("unroll") for (int k = 0; k < 2; ++k) dst[n][k] = *(const PG8_LAS bf16x8*)(lds + PG8_SB(b, h) + boff + n * 2048 + k * 1024); } while (0)
; #define PG8_MMA(ai, bj, At, Bt) do { __builtin_amdgcn_s_setprio(1); _Pragma("unroll") for (int m = 0; m < 4; ++m) _Pragma("unroll") for (int n = 0; n < 2; ++n) _Pragma("unroll") for (int k = 0; k < 2; ++k) \
;         acc[ai][bj][m][n] = __builtin_amdgcn_mfma_f32_16x16x32_bf16(Bt[n][k], At[m][k], acc[ai][bj][m][n], 0, 0, 0); __builtin_amdgcn_s_setprio(0); } while (0)
; #define PG8_WAIT_V(n) asm volatile("s_waitcnt vmcnt(" #n ")" ::: "memory")
; #define PG8_WAIT_L(n) asm volatile("s_waitcnt lgkmcnt(" #n ")" ::: "memory")
; #define PG8_BAR __builtin_amdgcn_s_barrier()
; #define PG8_SCHED __builtin_amdgcn_sched_barrier(0)
; template <class Epi, class Sched, bool ALIGN_EPI = false, bool SP2 = false>
; __device__ __forceinline__ void gemm_phase(PG8_LAS unsigned char* lds, const Gemm g, const Sched& S, const Epi& E) {
;     ...
;             PG8_WAIT_V(8); PG8_WAIT_L(0); PG8_BAR; PG8_MMA(1, 0, At, B0); PG8_MMA(1, 1, At, B1); PG8_BAR; PG8_SCHED;
;             PG8_LDB(B0, 1, 0); PG8_LDB(B1, 1, 1); PG8_SCHED; PG8_LDA(At, 1, 0); PG8_STAGE(PG8_SA(0, 1), a2 + hstep, voffA);
;             PG8_WAIT_V(8); PG8_WAIT_L(0); PG8_BAR; PG8_MMA(0, 0, At, B0); PG8_MMA(0, 1, At, B1); PG8_BAR; PG8_SCHED;
	s_waitcnt lgkmcnt(0)
	v_mfma_f32_16x16x32_bf16 v[60:63], v[144:147], v[188:191], 0
	v_mfma_f32_16x16x32_bf16 v[56:59], v[152:155], v[188:191], 0
	v_mfma_f32_16x16x32_bf16 v[52:55], v[144:147], v[196:199], 0
	v_mfma_f32_16x16x32_bf16 v[48:51], v[152:155], v[196:199], 0
	v_mfma_f32_16x16x32_bf16 v[40:43], v[144:147], v[204:207], 0
	v_mfma_f32_16x16x32_bf16 v[32:35], v[152:155], v[204:207], 0
	v_mfma_f32_16x16x32_bf16 v[24:27], v[144:147], v[212:215], 0
	v_mfma_f32_16x16x32_bf16 v[16:19], v[152:155], v[212:215], 0
	v_mfma_f32_16x16x32_bf16 v[60:63], v[148:151], v[192:195], v[60:63]
	v_mfma_f32_16x16x32_bf16 v[56:59], v[164:167], v[192:195], v[56:59]
	v_mfma_f32_16x16x32_bf16 v[52:55], v[148:151], v[200:203], v[52:55]
	v_mfma_f32_16x16x32_bf16 v[48:51], v[164:167], v[200:203], v[48:51]
	v_mfma_f32_16x16x32_bf16 v[40:43], v[148:151], v[208:211], v[40:43]
	v_mfma_f32_16x16x32_bf16 v[32:35], v[164:167], v[208:211], v[32:35]
	v_mfma_f32_16x16x32_bf16 v[24:27], v[148:151], v[216:219], v[24:27]
	v_mfma_f32_16x16x32_bf16 v[16:19], v[164:167], v[216:219], v[16:19]
	v_mfma_f32_16x16x32_bf16 v[44:47], v[168:171], v[188:191], 0
	v_mfma_f32_16x16x32_bf16 v[36:39], v[180:183], v[188:191], 0
	v_mfma_f32_16x16x32_bf16 v[28:31], v[168:171], v[196:199], 0
	v_mfma_f32_16x16x32_bf16 v[20:23], v[180:183], v[196:199], 0
	v_mfma_f32_16x16x32_bf16 v[12:15], v[168:171], v[204:207], 0
	v_mfma_f32_16x16x32_bf16 v[8:11], v[180:183], v[204:207], 0
	v_mfma_f32_16x16x32_bf16 v[4:7], v[168:171], v[212:215], 0
	v_mfma_f32_16x16x32_bf16 v[0:3], v[180:183], v[212:215], 0
	v_mfma_f32_16x16x32_bf16 v[44:47], v[172:175], v[192:195], v[44:47]
	v_mfma_f32_16x16x32_bf16 v[36:39], v[184:187], v[192:195], v[36:39]
	v_mfma_f32_16x16x32_bf16 v[28:31], v[172:175], v[200:203], v[28:31]
	v_mfma_f32_16x16x32_bf16 v[20:23], v[184:187], v[200:203], v[20:23]
	v_mfma_f32_16x16x32_bf16 v[12:15], v[172:175], v[208:211], v[12:15]
	v_mfma_f32_16x16x32_bf16 v[8:11], v[184:187], v[208:211], v[8:11]
	v_mfma_f32_16x16x32_bf16 v[4:7], v[172:175], v[216:219], v[4:7]
	v_mfma_f32_16x16x32_bf16 v[0:3], v[184:187], v[216:219], v[0:3]
	s_barrier
	s_add_i32 s68, 0, 0x18000
	v_add_u32_e32 v163, s68, v157
	s_add_i32 s69, 0, 0x1c000
	ds_read_b128 v[144:147], v163
	ds_read_b128 v[148:151], v163 offset:1024
	ds_read_b128 v[152:155], v163 offset:2048
	ds_read_b128 v[164:167], v163 offset:3072
	v_add_u32_e32 v163, s69, v157
	ds_read_b128 v[168:171], v163
	ds_read_b128 v[172:175], v163 offset:1024
	ds_read_b128 v[180:183], v163 offset:2048
	ds_read_b128 v[184:187], v163 offset:3072
	s_add_u32 s34, s34, s6
	s_addc_u32 s35, s35, s7
	s_mov_b32 m0, s33
	v_lshl_add_u64 v[228:229], s[34:35], 0, v[128:129]
	ds_read_b128 v[188:191], v161 offset:32768
	ds_read_b128 v[192:195], v161 offset:33792
	ds_read_b128 v[196:199], v161 offset:34816
	ds_read_b128 v[200:203], v161 offset:35840
	ds_read_b128 v[204:207], v161 offset:36864
	ds_read_b128 v[208:211], v161 offset:37888
	ds_read_b128 v[212:215], v161 offset:38912
	ds_read_b128 v[216:219], v161 offset:39936
	global_load_lds_dwordx4 v[228:229], off
	v_lshl_add_u64 v[228:229], s[34:35], 0, v[132:133]
	s_mov_b32 m0, s36
	s_nop 0
	global_load_lds_dwordx4 v[228:229], off
	s_waitcnt vmcnt(8)
	s_waitcnt lgkmcnt(0)
	s_barrier
	s_waitcnt lgkmcnt(0)
	v_mfma_f32_16x16x32_bf16 v[124:127], v[144:147], v[188:191], v[124:127]
	v_mfma_f32_16x16x32_bf16 v[120:123], v[152:155], v[188:191], v[120:123]
	v_mfma_f32_16x16x32_bf16 v[116:119], v[144:147], v[196:199], v[116:119]
	v_mfma_f32_16x16x32_bf16 v[112:115], v[152:155], v[196:199], v[112:115]
	v_mfma_f32_16x16x32_bf16 v[104:107], v[144:147], v[204:207], v[104:107]
	v_mfma_f32_16x16x32_bf16 v[96:99], v[152:155], v[204:207], v[96:99]
	v_mfma_f32_16x16x32_bf16 v[88:91], v[144:147], v[212:215], v[88:91]
	v_mfma_f32_16x16x32_bf16 v[80:83], v[152:155], v[212:215], v[80:83]
	v_mfma_f32_16x16x32_bf16 v[124:127], v[148:151], v[192:195], v[124:127]
	v_mfma_f32_16x16x32_bf16 v[120:123], v[164:167], v[192:195], v[120:123]
	v_mfma_f32_16x16x32_bf16 v[116:119], v[148:151], v[200:203], v[116:119]
	v_mfma_f32_16x16x32_bf16 v[112:115], v[164:167], v[200:203], v[112:115]
	v_mfma_f32_16x16x32_bf16 v[104:107], v[148:151], v[208:211], v[104:107]
	v_mfma_f32_16x16x32_bf16 v[96:99], v[164:167], v[208:211], v[96:99]
	v_mfma_f32_16x16x32_bf16 v[88:91], v[148:151], v[216:219], v[88:91]
	v_mfma_f32_16x16x32_bf16 v[80:83], v[164:167], v[216:219], v[80:83]
	v_mfma_f32_16x16x32_bf16 v[108:111], v[168:171], v[188:191], v[108:111]
	v_mfma_f32_16x16x32_bf16 v[100:103], v[180:183], v[188:191], v[100:103]
	v_mfma_f32_16x16x32_bf16 v[92:95], v[168:171], v[196:199], v[92:95]
	v_mfma_f32_16x16x32_bf16 v[84:87], v[180:183], v[196:199], v[84:87]
	v_mfma_f32_16x16x32_bf16 v[76:79], v[168:171], v[204:207], v[76:79]
	v_mfma_f32_16x16x32_bf16 v[72:75], v[180:183], v[204:207], v[72:75]
	v_mfma_f32_16x16x32_bf16 v[68:71], v[168:171], v[212:215], v[68:71]
	v_mfma_f32_16x16x32_bf16 v[64:67], v[180:183], v[212:215], v[64:67]
	v_mfma_f32_16x16x32_bf16 v[108:111], v[172:175], v[192:195], v[108:111]
	v_mfma_f32_16x16x32_bf16 v[100:103], v[184:187], v[192:195], v[100:103]
	v_mfma_f32_16x16x32_bf16 v[92:95], v[172:175], v[200:203], v[92:95]
	v_mfma_f32_16x16x32_bf16 v[84:87], v[184:187], v[200:203], v[84:87]
	v_mfma_f32_16x16x32_bf16 v[76:79], v[172:175], v[208:211], v[76:79]
	v_mfma_f32_16x16x32_bf16 v[72:75], v[184:187], v[208:211], v[72:75]
	v_mfma_f32_16x16x32_bf16 v[68:71], v[172:175], v[216:219], v[68:71]
	v_mfma_f32_16x16x32_bf16 v[64:67], v[184:187], v[216:219], v[64:67]
	s_barrier
; #define PG8_STAGE(bufoff, gbase, voff) do { _Pragma("unroll") for (int _i = 0; _i < 2; ++_i) \
;         __builtin_amdgcn_global_load_lds((const unsigned*)((const char*)(gbase) + (voff)[_i]), (PG8_LAS unsigned*)(lds + (bufoff) + ldsw + _i * 8192), 16, 0, 0); } while (0)
; #define PG8_LDA(dst, b, h) do { _Pragma("unroll") for (int m = 0; m < 4; ++m) _Pragma("unroll") for (int k = 0; k < 2; ++k) dst[m][k] = *(const PG8_LAS bf16x8*)(lds + PG8_SA(b, h) + aoff + m * 2048 + k * 1024); } while (0)
; #define PG8_LDB(dst, b, h) do { _Pragma("unroll") for (int n = 0; n < 2; ++n) _Pragma("unroll") for (int k = 0; k < 2; ++k) dst[n][k] = *(const PG8_LAS bf16x8*)(lds + PG8_SB(b, h) + boff + n * 2048 + k * 1024); } while (0)
; #define PG8_MMA(ai, bj, At, Bt) do { __builtin_amdgcn_s_setprio(1); _Pragma("unroll") for (int m = 0; m < 4; ++m) _Pragma("unroll") for (int n = 0; n < 2; ++n) _Pragma("unroll") for (int k = 0; k < 2; ++k) \
;         acc[ai][bj][m][n] = __builtin_amdgcn_mfma_f32_16x16x32_bf16(Bt[n][k], At[m][k], acc[ai][bj][m][n], 0, 0, 0); __builtin_amdgcn_s_setprio(0); } while (0)
; #define PG8_WAIT_V(n) asm volatile("s_waitcnt vmcnt(" #n ")" ::: "memory")
; #define PG8_WAIT_L(n) asm volatile("s_waitcnt lgkmcnt(" #n ")" ::: "memory")
; #define PG8_BAR __builtin_amdgcn_s_barrier()
; #define PG8_SCHED __builtin_amdgcn_sched_barrier(0)
; template <class Epi, class Sched, bool ALIGN_EPI = false, bool SP2 = false>
; __device__ __forceinline__ void gemm_phase(PG8_LAS unsigned char* lds, const Gemm g, const Sched& S, const Epi& E) {
;     ...
;             PG8_LDB(B0, 0, 0); PG8_LDB(B1, 0, 1); PG8_SCHED; PG8_LDA(At, 0, 0); PG8_STAGE(PG8_SA(1, 1), a1 + hstep, voffA);
;             PG8_WAIT_V(8); PG8_WAIT_L(0); PG8_BAR; PG8_MMA(0, 0, At, B0); PG8_MMA(0, 1, At, B1); PG8_BAR; PG8_SCHED;
;     ...
;             PG8_LDA(At, 1, 1); PG8_STAGE(PG8_SB(1, 0), b3, voffB); PG8_STAGE(PG8_SB(1, 1), b3 + hstep, voffB); PG8_STAGE(PG8_SA(1, 0), a3, voffA);
;             PG8_WAIT_V(8); PG8_WAIT_L(0); PG8_BAR; PG8_MMA(1, 0, At, B0); PG8_MMA(1, 1, At, B1); PG8_BAR; PG8_SCHED;
	s_add_i32 s34, s68, s16
	v_lshl_add_u64 v[176:177], v[176:177], 0, s[22:23]
	s_mov_b32 m0, s34
	ds_read_b128 v[188:191], v161 offset:49152
	ds_read_b128 v[192:195], v161 offset:50176
	ds_read_b128 v[196:199], v161 offset:51200
	ds_read_b128 v[200:203], v161 offset:52224
	ds_read_b128 v[204:207], v161 offset:53248
	ds_read_b128 v[208:211], v161 offset:54272
	ds_read_b128 v[212:215], v161 offset:55296
	ds_read_b128 v[216:219], v161 offset:56320
	global_load_lds_dwordx4 v[176:177], off
	v_lshl_add_u64 v[176:177], v[178:179], 0, s[22:23]
	s_add_i32 m0, s34, 0x2000
	s_add_i32 s34, s69, s16
	global_load_lds_dwordx4 v[176:177], off
	v_lshl_add_u64 v[176:177], v[220:221], 0, s[22:23]
	s_mov_b32 m0, s34
	s_nop 0
	global_load_lds_dwordx4 v[176:177], off
	v_lshl_add_u64 v[176:177], v[222:223], 0, s[22:23]
	s_add_i32 m0, s34, 0x2000
	s_nop 0
	global_load_lds_dwordx4 v[176:177], off
	v_lshl_add_u64 v[176:177], v[224:225], 0, s[22:23]
	s_mov_b32 m0, s37
	s_nop 0
	global_load_lds_dwordx4 v[176:177], off
	v_lshl_add_u64 v[176:177], v[226:227], 0, s[22:23]
	s_mov_b32 m0, s38
	s_nop 0
	global_load_lds_dwordx4 v[176:177], off
	s_waitcnt vmcnt(8)
	s_waitcnt lgkmcnt(0)
	s_barrier
	s_waitcnt lgkmcnt(0)
	v_mfma_f32_16x16x32_bf16 v[60:63], v[144:147], v[188:191], v[60:63]
	v_mfma_f32_16x16x32_bf16 v[56:59], v[152:155], v[188:191], v[56:59]
	v_mfma_f32_16x16x32_bf16 v[52:55], v[144:147], v[196:199], v[52:55]
	v_mfma_f32_16x16x32_bf16 v[48:51], v[152:155], v[196:199], v[48:51]
	v_mfma_f32_16x16x32_bf16 v[40:43], v[144:147], v[204:207], v[40:43]
	v_mfma_f32_16x16x32_bf16 v[32:35], v[152:155], v[204:207], v[32:35]
	v_mfma_f32_16x16x32_bf16 v[24:27], v[144:147], v[212:215], v[24:27]
	v_mfma_f32_16x16x32_bf16 v[16:19], v[152:155], v[212:215], v[16:19]
	v_mfma_f32_16x16x32_bf16 v[60:63], v[148:151], v[192:195], v[60:63]
	v_mfma_f32_16x16x32_bf16 v[56:59], v[164:167], v[192:195], v[56:59]
	v_mfma_f32_16x16x32_bf16 v[52:55], v[148:151], v[200:203], v[52:55]
	v_mfma_f32_16x16x32_bf16 v[48:51], v[164:167], v[200:203], v[48:51]
	v_mfma_f32_16x16x32_bf16 v[40:43], v[148:151], v[208:211], v[40:43]
	v_mfma_f32_16x16x32_bf16 v[32:35], v[164:167], v[208:211], v[32:35]
	v_mfma_f32_16x16x32_bf16 v[24:27], v[148:151], v[216:219], v[24:27]
	v_mfma_f32_16x16x32_bf16 v[16:19], v[164:167], v[216:219], v[16:19]
	v_mfma_f32_16x16x32_bf16 v[44:47], v[168:171], v[188:191], v[44:47]
	v_mfma_f32_16x16x32_bf16 v[36:39], v[180:183], v[188:191], v[36:39]
	v_mfma_f32_16x16x32_bf16 v[28:31], v[168:171], v[196:199], v[28:31]
	v_mfma_f32_16x16x32_bf16 v[20:23], v[180:183], v[196:199], v[20:23]
	v_mfma_f32_16x16x32_bf16 v[12:15], v[168:171], v[204:207], v[12:15]
	v_mfma_f32_16x16x32_bf16 v[8:11], v[180:183], v[204:207], v[8:11]
	v_mfma_f32_16x16x32_bf16 v[4:7], v[168:171], v[212:215], v[4:7]
	v_mfma_f32_16x16x32_bf16 v[0:3], v[180:183], v[212:215], v[0:3]
	v_mfma_f32_16x16x32_bf16 v[44:47], v[172:175], v[192:195], v[44:47]
	v_mfma_f32_16x16x32_bf16 v[36:39], v[184:187], v[192:195], v[36:39]
	v_mfma_f32_16x16x32_bf16 v[28:31], v[172:175], v[200:203], v[28:31]
	v_mfma_f32_16x16x32_bf16 v[20:23], v[184:187], v[200:203], v[20:23]
	v_mfma_f32_16x16x32_bf16 v[12:15], v[172:175], v[208:211], v[12:15]
	v_mfma_f32_16x16x32_bf16 v[8:11], v[184:187], v[208:211], v[8:11]
	v_mfma_f32_16x16x32_bf16 v[4:7], v[172:175], v[216:219], v[4:7]
	v_mfma_f32_16x16x32_bf16 v[0:3], v[184:187], v[216:219], v[0:3]
	s_barrier
	s_add_u32 s30, s30, 0x100
	s_addc_u32 s31, s31, 0
	s_add_u32 s65, s65, 0x100
	s_addc_u32 s66, s66, 0
	s_cmp_ge_i32 s67, s40
	s_mov_b32 s34, s67
	s_cbranch_scc0 .LBB0_467
	s_branch .Lpeel_x1
.LBB0_467:
	ds_read_b128 v[144:147], v159
	ds_read_b128 v[148:151], v159 offset:1024
	ds_read_b128 v[152:155], v159 offset:2048
	ds_read_b128 v[164:167], v159 offset:3072
	ds_read_b128 v[168:171], v160
	ds_read_b128 v[172:175], v160 offset:1024
	ds_read_b128 v[180:183], v160 offset:2048
	ds_read_b128 v[184:187], v160 offset:3072
	s_add_i32 s67, s34, 2
	s_add_u32 s68, s30, 0x80
	s_addc_u32 s35, s31, 0
	s_cmp_eq_u32 s41, s34
	s_cselect_b32 s34, s0, s68
	s_cselect_b32 s35, s1, s35
	s_cselect_b32 s69, s29, s66
	s_cselect_b32 s68, s28, s65
	v_lshl_add_u64 v[176:177], s[30:31], 0, v[136:137]
	s_add_i32 m0, s17, 0xc000
	ds_read_b128 v[188:191], v161
	ds_read_b128 v[192:195], v161 offset:1024
	ds_read_b128 v[196:199], v161 offset:2048
	ds_read_b128 v[200:203], v161 offset:3072
	ds_read_b128 v[204:207], v161 offset:4096
	ds_read_b128 v[208:211], v161 offset:5120
	ds_read_b128 v[212:215], v161 offset:6144
	ds_read_b128 v[216:219], v161 offset:7168
	global_load_lds_dwordx4 v[176:177], off
	v_lshl_add_u64 v[176:177], s[30:31], 0, v[138:139]
	s_add_i32 m0, s17, 0xe000
	s_nop 0
	global_load_lds_dwordx4 v[176:177], off
	s_waitcnt vmcnt(8)
	s_waitcnt lgkmcnt(0)
	s_barrier
; #define PG8_STAGE(bufoff, gbase, voff) do { _Pragma("unroll") for (int _i = 0; _i < 2; ++_i) \
;         __builtin_amdgcn_global_load_lds((const unsigned*)((const char*)(gbase) + (voff)[_i]), (PG8_LAS unsigned*)(lds + (bufoff) + ldsw + _i * 8192), 16, 0, 0); } while (0)
; #define PG8_LDA(dst, b, h) do { _Pragma("unroll") for (int m = 0; m < 4; ++m) _Pragma("unroll") for (int k = 0; k < 2; ++k) dst[m][k] = *(const PG8_LAS bf16x8*)(lds + PG8_SA(b, h) + aoff + m * 2048 + k * 1024); } while (0)
; #define PG8_MMA(ai, bj, At, Bt) do { __builtin_amdgcn_s_setprio(1); _Pragma("unroll") for (int m = 0; m < 4; ++m) _Pragma("unroll") for (int n = 0; n < 2; ++n) _Pragma("unroll") for (int k = 0; k < 2; ++k) \
;         acc[ai][bj][m][n] = __builtin_amdgcn_mfma_f32_16x16x32_bf16(Bt[n][k], At[m][k], acc[ai][bj][m][n], 0, 0, 0); __builtin_amdgcn_s_setprio(0); } while (0)
; #define PG8_WAIT_V(n) asm volatile("s_waitcnt vmcnt(" #n ")" ::: "memory")
; #define PG8_WAIT_L(n) asm volatile("s_waitcnt lgkmcnt(" #n ")" ::: "memory")
; #define PG8_BAR __builtin_amdgcn_s_barrier()
; #define PG8_SCHED __builtin_amdgcn_sched_barrier(0)
; template <class Epi, class Sched, bool ALIGN_EPI = false, bool SP2 = false>
; __device__ __forceinline__ void gemm_phase(PG8_LAS unsigned char* lds, const Gemm g, const Sched& S, const Epi& E) {
;     ...
;             PG8_WAIT_V(8); PG8_WAIT_L(0); PG8_BAR; PG8_MMA(0, 0, At, B0); PG8_MMA(0, 1, At, B1); PG8_BAR; PG8_SCHED;
;             PG8_LDA(At, 0, 1); PG8_STAGE(PG8_SB(0, 0), b2, voffB); PG8_STAGE(PG8_SB(0, 1), b2 + hstep, voffB); PG8_STAGE(PG8_SA(0, 0), a2, voffA);
;             PG8_WAIT_V(8); PG8_WAIT_L(0); PG8_BAR; PG8_MMA(1, 0, At, B0); PG8_MMA(1, 1, At, B1); PG8_BAR; PG8_SCHED;
	s_waitcnt lgkmcnt(0)
	v_mfma_f32_16x16x32_bf16 v[124:127], v[144:147], v[188:191], v[124:127]
	v_mfma_f32_16x16x32_bf16 v[120:123], v[152:155], v[188:191], v[120:123]
	v_mfma_f32_16x16x32_bf16 v[116:119], v[144:147], v[196:199], v[116:119]
	v_mfma_f32_16x16x32_bf16 v[112:115], v[152:155], v[196:199], v[112:115]
	v_mfma_f32_16x16x32_bf16 v[104:107], v[144:147], v[204:207], v[104:107]
	v_mfma_f32_16x16x32_bf16 v[96:99], v[152:155], v[204:207], v[96:99]
	v_mfma_f32_16x16x32_bf16 v[88:91], v[144:147], v[212:215], v[88:91]
	v_mfma_f32_16x16x32_bf16 v[80:83], v[152:155], v[212:215], v[80:83]
	v_mfma_f32_16x16x32_bf16 v[124:127], v[148:151], v[192:195], v[124:127]
	v_mfma_f32_16x16x32_bf16 v[120:123], v[164:167], v[192:195], v[120:123]
	v_mfma_f32_16x16x32_bf16 v[116:119], v[148:151], v[200:203], v[116:119]
	v_mfma_f32_16x16x32_bf16 v[112:115], v[164:167], v[200:203], v[112:115]
	v_mfma_f32_16x16x32_bf16 v[104:107], v[148:151], v[208:211], v[104:107]
	v_mfma_f32_16x16x32_bf16 v[96:99], v[164:167], v[208:211], v[96:99]
	v_mfma_f32_16x16x32_bf16 v[88:91], v[148:151], v[216:219], v[88:91]
	v_mfma_f32_16x16x32_bf16 v[80:83], v[164:167], v[216:219], v[80:83]
	v_mfma_f32_16x16x32_bf16 v[108:111], v[168:171], v[188:191], v[108:111]
	v_mfma_f32_16x16x32_bf16 v[100:103], v[180:183], v[188:191], v[100:103]
	v_mfma_f32_16x16x32_bf16 v[92:95], v[168:171], v[196:199], v[92:95]
	v_mfma_f32_16x16x32_bf16 v[84:87], v[180:183], v[196:199], v[84:87]
	v_mfma_f32_16x16x32_bf16 v[76:79], v[168:171], v[204:207], v[76:79]
	v_mfma_f32_16x16x32_bf16 v[72:75], v[180:183], v[204:207], v[72:75]
	v_mfma_f32_16x16x32_bf16 v[68:71], v[168:171], v[212:215], v[68:71]
	v_mfma_f32_16x16x32_bf16 v[64:67], v[180:183], v[212:215], v[64:67]
	v_mfma_f32_16x16x32_bf16 v[108:111], v[172:175], v[192:195], v[108:111]
	v_mfma_f32_16x16x32_bf16 v[100:103], v[184:187], v[192:195], v[100:103]
	v_mfma_f32_16x16x32_bf16 v[92:95], v[172:175], v[200:203], v[92:95]
	v_mfma_f32_16x16x32_bf16 v[84:87], v[184:187], v[200:203], v[84:87]
	v_mfma_f32_16x16x32_bf16 v[76:79], v[172:175], v[208:211], v[76:79]
	v_mfma_f32_16x16x32_bf16 v[72:75], v[184:187], v[208:211], v[72:75]
	v_mfma_f32_16x16x32_bf16 v[68:71], v[172:175], v[216:219], v[68:71]
	v_mfma_f32_16x16x32_bf16 v[64:67], v[184:187], v[216:219], v[64:67]
	s_barrier
	s_add_i32 s70, s59, s16
	v_lshl_add_u64 v[176:177], s[68:69], 0, v[130:131]
	s_mov_b32 m0, s70
	ds_read_b128 v[188:191], v161 offset:16384
	ds_read_b128 v[192:195], v161 offset:17408
	ds_read_b128 v[196:199], v161 offset:18432
	ds_read_b128 v[200:203], v161 offset:19456
	ds_read_b128 v[204:207], v161 offset:20480
	ds_read_b128 v[208:211], v161 offset:21504
	ds_read_b128 v[212:215], v161 offset:22528
	ds_read_b128 v[216:219], v161 offset:23552
	global_load_lds_dwordx4 v[176:177], off
	s_add_i32 m0, s70, 0x2000
	v_lshl_add_u64 v[178:179], s[68:69], 0, v[134:135]
	s_add_u32 s68, s68, s6
	s_addc_u32 s69, s69, s7
	s_add_i32 s70, s60, s16
	global_load_lds_dwordx4 v[178:179], off
	v_lshl_add_u64 v[220:221], s[68:69], 0, v[130:131]
	s_mov_b32 m0, s70
	v_lshl_add_u64 v[222:223], s[68:69], 0, v[134:135]
	global_load_lds_dwordx4 v[220:221], off
	s_add_i32 m0, s70, 0x2000
	v_lshl_add_u64 v[224:225], s[34:35], 0, v[128:129]
	global_load_lds_dwordx4 v[222:223], off
	s_mov_b32 m0, s17
	v_lshl_add_u64 v[226:227], s[34:35], 0, v[132:133]
	global_load_lds_dwordx4 v[224:225], off
	s_mov_b32 m0, s19
	s_nop 0
	global_load_lds_dwordx4 v[226:227], off
	s_waitcnt vmcnt(8)
	s_waitcnt lgkmcnt(0)
	s_barrier
	s_waitcnt lgkmcnt(0)
	v_mfma_f32_16x16x32_bf16 v[60:63], v[144:147], v[188:191], v[60:63]
	v_mfma_f32_16x16x32_bf16 v[56:59], v[152:155], v[188:191], v[56:59]
	v_mfma_f32_16x16x32_bf16 v[52:55], v[144:147], v[196:199], v[52:55]
	v_mfma_f32_16x16x32_bf16 v[48:51], v[152:155], v[196:199], v[48:51]
	v_mfma_f32_16x16x32_bf16 v[40:43], v[144:147], v[204:207], v[40:43]
	v_mfma_f32_16x16x32_bf16 v[32:35], v[152:155], v[204:207], v[32:35]
	v_mfma_f32_16x16x32_bf16 v[24:27], v[144:147], v[212:215], v[24:27]
	v_mfma_f32_16x16x32_bf16 v[16:19], v[152:155], v[212:215], v[16:19]
	v_mfma_f32_16x16x32_bf16 v[60:63], v[148:151], v[192:195], v[60:63]
	v_mfma_f32_16x16x32_bf16 v[56:59], v[164:167], v[192:195], v[56:59]
	v_mfma_f32_16x16x32_bf16 v[52:55], v[148:151], v[200:203], v[52:55]
	v_mfma_f32_16x16x32_bf16 v[48:51], v[164:167], v[200:203], v[48:51]
	v_mfma_f32_16x16x32_bf16 v[40:43], v[148:151], v[208:211], v[40:43]
	v_mfma_f32_16x16x32_bf16 v[32:35], v[164:167], v[208:211], v[32:35]
	v_mfma_f32_16x16x32_bf16 v[24:27], v[148:151], v[216:219], v[24:27]
	v_mfma_f32_16x16x32_bf16 v[16:19], v[164:167], v[216:219], v[16:19]
	v_mfma_f32_16x16x32_bf16 v[44:47], v[168:171], v[188:191], v[44:47]
	v_mfma_f32_16x16x32_bf16 v[36:39], v[180:183], v[188:191], v[36:39]
	v_mfma_f32_16x16x32_bf16 v[28:31], v[168:171], v[196:199], v[28:31]
	v_mfma_f32_16x16x32_bf16 v[20:23], v[180:183], v[196:199], v[20:23]
	v_mfma_f32_16x16x32_bf16 v[12:15], v[168:171], v[204:207], v[12:15]
	v_mfma_f32_16x16x32_bf16 v[8:11], v[180:183], v[204:207], v[8:11]
	v_mfma_f32_16x16x32_bf16 v[4:7], v[168:171], v[212:215], v[4:7]
	v_mfma_f32_16x16x32_bf16 v[0:3], v[180:183], v[212:215], v[0:3]
	v_mfma_f32_16x16x32_bf16 v[44:47], v[172:175], v[192:195], v[44:47]
	v_mfma_f32_16x16x32_bf16 v[36:39], v[184:187], v[192:195], v[36:39]
	v_mfma_f32_16x16x32_bf16 v[28:31], v[172:175], v[200:203], v[28:31]
	v_mfma_f32_16x16x32_bf16 v[20:23], v[184:187], v[200:203], v[20:23]
	v_mfma_f32_16x16x32_bf16 v[12:15], v[172:175], v[208:211], v[12:15]
	v_mfma_f32_16x16x32_bf16 v[8:11], v[184:187], v[208:211], v[8:11]
	v_mfma_f32_16x16x32_bf16 v[4:7], v[172:175], v[216:219], v[4:7]
	v_mfma_f32_16x16x32_bf16 v[0:3], v[184:187], v[216:219], v[0:3]
	s_barrier
; #define PG8_STAGE(bufoff, gbase, voff) do { _Pragma("unroll") for (int _i = 0; _i < 2; ++_i) \
;         __builtin_amdgcn_global_load_lds((const unsigned*)((const char*)(gbase) + (voff)[_i]), (PG8_LAS unsigned*)(lds + (bufoff) + ldsw + _i * 8192), 16, 0, 0); } while (0)
; #define PG8_LDA(dst, b, h) do { _Pragma("unroll") for (int m = 0; m < 4; ++m) _Pragma("unroll") for (int k = 0; k < 2; ++k) dst[m][k] = *(const PG8_LAS bf16x8*)(lds + PG8_SA(b, h) + aoff + m * 2048 + k * 1024); } while (0)
; #define PG8_LDB(dst, b, h) do { _Pragma("unroll") for (int n = 0; n < 2; ++n) _Pragma("unroll") for (int k = 0; k < 2; ++k) dst[n][k] = *(const PG8_LAS bf16x8*)(lds + PG8_SB(b, h) + boff + n * 2048 + k * 1024); } while (0)
; #define PG8_MMA(ai, bj, At, Bt) do { __builtin_amdgcn_s_setprio(1); _Pragma("unroll") for (int m = 0; m < 4; ++m) _Pragma("unroll") for (int n = 0; n < 2; ++n) _Pragma("unroll") for (int k = 0; k < 2; ++k) \
;         acc[ai][bj][m][n] = __builtin_amdgcn_mfma_f32_16x16x32_bf16(Bt[n][k], At[m][k], acc[ai][bj][m][n], 0, 0, 0); __builtin_amdgcn_s_setprio(0); } while (0)
; #define PG8_WAIT_V(n) asm volatile("s_waitcnt vmcnt(" #n ")" ::: "memory")
; #define PG8_WAIT_L(n) asm volatile("s_waitcnt lgkmcnt(" #n ")" ::: "memory")
; #define PG8_BAR __builtin_amdgcn_s_barrier()
; #define PG8_SCHED __builtin_amdgcn_sched_barrier(0)
; template <class Epi, class Sched, bool ALIGN_EPI = false, bool SP2 = false>
; __device__ __forceinline__ void gemm_phase(PG8_LAS unsigned char* lds, const Gemm g, const Sched& S, const Epi& E) {
;     ...
;             PG8_LDB(B0, 1, 0); PG8_LDB(B1, 1, 1); PG8_SCHED; PG8_LDA(At, 1, 0); PG8_STAGE(PG8_SA(0, 1), a2 + hstep, voffA);
;             PG8_WAIT_V(8); PG8_WAIT_L(0); PG8_BAR; PG8_MMA(0, 0, At, B0); PG8_MMA(0, 1, At, B1); PG8_BAR; PG8_SCHED;
;             PG8_LDA(At, 1, 1); PG8_STAGE(PG8_SB(1, 0), b3, voffB); PG8_STAGE(PG8_SB(1, 1), b3 + hstep, voffB); PG8_STAGE(PG8_SA(1, 0), a3, voffA);
;             PG8_WAIT_V(8); PG8_WAIT_L(0); PG8_BAR; PG8_MMA(1, 0, At, B0); PG8_MMA(1, 1, At, B1); PG8_BAR; PG8_SCHED;
	s_add_i32 s68, 0, 0x18000
	v_add_u32_e32 v163, s68, v157
	s_add_i32 s69, 0, 0x1c000
	ds_read_b128 v[144:147], v163
	ds_read_b128 v[148:151], v163 offset:1024
	ds_read_b128 v[152:155], v163 offset:2048
	ds_read_b128 v[164:167], v163 offset:3072
	v_add_u32_e32 v163, s69, v157
	ds_read_b128 v[168:171], v163
	ds_read_b128 v[172:175], v163 offset:1024
	ds_read_b128 v[180:183], v163 offset:2048
	ds_read_b128 v[184:187], v163 offset:3072
	s_add_u32 s34, s34, s6
	s_addc_u32 s35, s35, s7
	s_mov_b32 m0, s33
	v_lshl_add_u64 v[228:229], s[34:35], 0, v[128:129]
	ds_read_b128 v[188:191], v161 offset:32768
	ds_read_b128 v[192:195], v161 offset:33792
	ds_read_b128 v[196:199], v161 offset:34816
	ds_read_b128 v[200:203], v161 offset:35840
	ds_read_b128 v[204:207], v161 offset:36864
	ds_read_b128 v[208:211], v161 offset:37888
	ds_read_b128 v[212:215], v161 offset:38912
	ds_read_b128 v[216:219], v161 offset:39936
	global_load_lds_dwordx4 v[228:229], off
	v_lshl_add_u64 v[228:229], s[34:35], 0, v[132:133]
	s_mov_b32 m0, s36
	s_nop 0
	global_load_lds_dwordx4 v[228:229], off
	s_waitcnt vmcnt(8)
	s_waitcnt lgkmcnt(0)
	s_barrier
	s_waitcnt lgkmcnt(0)
	v_mfma_f32_16x16x32_bf16 v[124:127], v[144:147], v[188:191], v[124:127]
	v_mfma_f32_16x16x32_bf16 v[120:123], v[152:155], v[188:191], v[120:123]
	v_mfma_f32_16x16x32_bf16 v[116:119], v[144:147], v[196:199], v[116:119]
	v_mfma_f32_16x16x32_bf16 v[112:115], v[152:155], v[196:199], v[112:115]
	v_mfma_f32_16x16x32_bf16 v[104:107], v[144:147], v[204:207], v[104:107]
	v_mfma_f32_16x16x32_bf16 v[96:99], v[152:155], v[204:207], v[96:99]
	v_mfma_f32_16x16x32_bf16 v[88:91], v[144:147], v[212:215], v[88:91]
	v_mfma_f32_16x16x32_bf16 v[80:83], v[152:155], v[212:215], v[80:83]
	v_mfma_f32_16x16x32_bf16 v[124:127], v[148:151], v[192:195], v[124:127]
	v_mfma_f32_16x16x32_bf16 v[120:123], v[164:167], v[192:195], v[120:123]
	v_mfma_f32_16x16x32_bf16 v[116:119], v[148:151], v[200:203], v[116:119]
	v_mfma_f32_16x16x32_bf16 v[112:115], v[164:167], v[200:203], v[112:115]
	v_mfma_f32_16x16x32_bf16 v[104:107], v[148:151], v[208:211], v[104:107]
	v_mfma_f32_16x16x32_bf16 v[96:99], v[164:167], v[208:211], v[96:99]
	v_mfma_f32_16x16x32_bf16 v[88:91], v[148:151], v[216:219], v[88:91]
	v_mfma_f32_16x16x32_bf16 v[80:83], v[164:167], v[216:219], v[80:83]
	v_mfma_f32_16x16x32_bf16 v[108:111], v[168:171], v[188:191], v[108:111]
	v_mfma_f32_16x16x32_bf16 v[100:103], v[180:183], v[188:191], v[100:103]
	v_mfma_f32_16x16x32_bf16 v[92:95], v[168:171], v[196:199], v[92:95]
	v_mfma_f32_16x16x32_bf16 v[84:87], v[180:183], v[196:199], v[84:87]
	v_mfma_f32_16x16x32_bf16 v[76:79], v[168:171], v[204:207], v[76:79]
	v_mfma_f32_16x16x32_bf16 v[72:75], v[180:183], v[204:207], v[72:75]
	v_mfma_f32_16x16x32_bf16 v[68:71], v[168:171], v[212:215], v[68:71]
	v_mfma_f32_16x16x32_bf16 v[64:67], v[180:183], v[212:215], v[64:67]
	v_mfma_f32_16x16x32_bf16 v[108:111], v[172:175], v[192:195], v[108:111]
	v_mfma_f32_16x16x32_bf16 v[100:103], v[184:187], v[192:195], v[100:103]
	v_mfma_f32_16x16x32_bf16 v[92:95], v[172:175], v[200:203], v[92:95]
	v_mfma_f32_16x16x32_bf16 v[84:87], v[184:187], v[200:203], v[84:87]
	v_mfma_f32_16x16x32_bf16 v[76:79], v[172:175], v[208:211], v[76:79]
	v_mfma_f32_16x16x32_bf16 v[72:75], v[184:187], v[208:211], v[72:75]
	v_mfma_f32_16x16x32_bf16 v[68:71], v[172:175], v[216:219], v[68:71]
	v_mfma_f32_16x16x32_bf16 v[64:67], v[184:187], v[216:219], v[64:67]
	s_barrier
	s_add_i32 s34, s68, s16
	v_lshl_add_u64 v[176:177], v[176:177], 0, s[22:23]
	s_mov_b32 m0, s34
	ds_read_b128 v[188:191], v161 offset:49152
	ds_read_b128 v[192:195], v161 offset:50176
	ds_read_b128 v[196:199], v161 offset:51200
	ds_read_b128 v[200:203], v161 offset:52224
	ds_read_b128 v[204:207], v161 offset:53248
	ds_read_b128 v[208:211], v161 offset:54272
	ds_read_b128 v[212:215], v161 offset:55296
	ds_read_b128 v[216:219], v161 offset:56320
	global_load_lds_dwordx4 v[176:177], off
	v_lshl_add_u64 v[176:177], v[178:179], 0, s[22:23]
	s_add_i32 m0, s34, 0x2000
	s_add_i32 s34, s69, s16
	global_load_lds_dwordx4 v[176:177], off
	v_lshl_add_u64 v[176:177], v[220:221], 0, s[22:23]
	s_mov_b32 m0, s34
	s_nop 0
	global_load_lds_dwordx4 v[176:177], off
	v_lshl_add_u64 v[176:177], v[222:223], 0, s[22:23]
	s_add_i32 m0, s34, 0x2000
	s_nop 0
	global_load_lds_dwordx4 v[176:177], off
	v_lshl_add_u64 v[176:177], v[224:225], 0, s[22:23]
	s_mov_b32 m0, s37
	s_nop 0
	global_load_lds_dwordx4 v[176:177], off
	v_lshl_add_u64 v[176:177], v[226:227], 0, s[22:23]
	s_mov_b32 m0, s38
	s_nop 0
	global_load_lds_dwordx4 v[176:177], off
	s_waitcnt vmcnt(8)
	s_waitcnt lgkmcnt(0)
	s_barrier
	s_waitcnt lgkmcnt(0)
	v_mfma_f32_16x16x32_bf16 v[60:63], v[144:147], v[188:191], v[60:63]
	v_mfma_f32_16x16x32_bf16 v[56:59], v[152:155], v[188:191], v[56:59]
	v_mfma_f32_16x16x32_bf16 v[52:55], v[144:147], v[196:199], v[52:55]
	v_mfma_f32_16x16x32_bf16 v[48:51], v[152:155], v[196:199], v[48:51]
	v_mfma_f32_16x16x32_bf16 v[40:43], v[144:147], v[204:207], v[40:43]
	v_mfma_f32_16x16x32_bf16 v[32:35], v[152:155], v[204:207], v[32:35]
	v_mfma_f32_16x16x32_bf16 v[24:27], v[144:147], v[212:215], v[24:27]
	v_mfma_f32_16x16x32_bf16 v[16:19], v[152:155], v[212:215], v[16:19]
	v_mfma_f32_16x16x32_bf16 v[60:63], v[148:151], v[192:195], v[60:63]
	v_mfma_f32_16x16x32_bf16 v[56:59], v[164:167], v[192:195], v[56:59]
	v_mfma_f32_16x16x32_bf16 v[52:55], v[148:151], v[200:203], v[52:55]
	v_mfma_f32_16x16x32_bf16 v[48:51], v[164:167], v[200:203], v[48:51]
	v_mfma_f32_16x16x32_bf16 v[40:43], v[148:151], v[208:211], v[40:43]
	v_mfma_f32_16x16x32_bf16 v[32:35], v[164:167], v[208:211], v[32:35]
	v_mfma_f32_16x16x32_bf16 v[24:27], v[148:151], v[216:219], v[24:27]
	v_mfma_f32_16x16x32_bf16 v[16:19], v[164:167], v[216:219], v[16:19]
	v_mfma_f32_16x16x32_bf16 v[44:47], v[168:171], v[188:191], v[44:47]
	v_mfma_f32_16x16x32_bf16 v[36:39], v[180:183], v[188:191], v[36:39]
	v_mfma_f32_16x16x32_bf16 v[28:31], v[168:171], v[196:199], v[28:31]
	v_mfma_f32_16x16x32_bf16 v[20:23], v[180:183], v[196:199], v[20:23]
	v_mfma_f32_16x16x32_bf16 v[12:15], v[168:171], v[204:207], v[12:15]
	v_mfma_f32_16x16x32_bf16 v[8:11], v[180:183], v[204:207], v[8:11]
	v_mfma_f32_16x16x32_bf16 v[4:7], v[168:171], v[212:215], v[4:7]
	v_mfma_f32_16x16x32_bf16 v[0:3], v[180:183], v[212:215], v[0:3]
	v_mfma_f32_16x16x32_bf16 v[44:47], v[172:175], v[192:195], v[44:47]
	v_mfma_f32_16x16x32_bf16 v[36:39], v[184:187], v[192:195], v[36:39]
	v_mfma_f32_16x16x32_bf16 v[28:31], v[172:175], v[200:203], v[28:31]
	v_mfma_f32_16x16x32_bf16 v[20:23], v[184:187], v[200:203], v[20:23]
	v_mfma_f32_16x16x32_bf16 v[12:15], v[172:175], v[208:211], v[12:15]
	v_mfma_f32_16x16x32_bf16 v[8:11], v[184:187], v[208:211], v[8:11]
	v_mfma_f32_16x16x32_bf16 v[4:7], v[172:175], v[216:219], v[4:7]
	v_mfma_f32_16x16x32_bf16 v[0:3], v[184:187], v[216:219], v[0:3]
	s_barrier
	s_add_u32 s30, s30, 0x100
	s_addc_u32 s31, s31, 0
	s_add_u32 s65, s65, 0x100
	s_addc_u32 s66, s66, 0
	s_cmp_ge_i32 s67, s40
	s_mov_b32 s34, s67
	s_cbranch_scc0 .LBB0_467

; #define PG8_STAGE(bufoff, gbase, voff) do { _Pragma("unroll") for (int _i = 0; _i < 2; ++_i) \
;         __builtin_amdgcn_global_load_lds((const unsigned*)((const char*)(gbase) + (voff)[_i]), (PG8_LAS unsigned*)(lds + (bufoff) + ldsw + _i * 8192), 16, 0, 0); } while (0)
; #define PG8_LDA(dst, b, h) do { _Pragma("unroll") for (int m = 0; m < 4; ++m) _Pragma("unroll") for (int k = 0; k < 2; ++k) dst[m][k] = *(const PG8_LAS bf16x8*)(lds + PG8_SA(b, h) + aoff + m * 2048 + k * 1024); } while (0)
; #define PG8_LDB(dst, b, h) do { _Pragma("unroll") for (int n = 0; n < 2; ++n) _Pragma("unroll") for (int k = 0; k < 2; ++k) dst[n][k] = *(const PG8_LAS bf16x8*)(lds + PG8_SB(b, h) + boff + n * 2048 + k * 1024); } while (0)
; #define PG8_MMA(ai, bj, At, Bt) do { __builtin_amdgcn_s_setprio(1); _Pragma("unroll") for (int m = 0; m < 4; ++m) _Pragma("unroll") for (int n = 0; n < 2; ++n) _Pragma("unroll") for (int k = 0; k < 2; ++k) \
;         acc[ai][bj][m][n] = __builtin_amdgcn_mfma_f32_16x16x32_bf16(Bt[n][k], At[m][k], acc[ai][bj][m][n], 0, 0, 0); __builtin_amdgcn_s_setprio(0); } while (0)
; #define PG8_WAIT_V(n) asm volatile("s_waitcnt vmcnt(" #n ")" ::: "memory")
; #define PG8_WAIT_L(n) asm volatile("s_waitcnt lgkmcnt(" #n ")" ::: "memory")
; #define PG8_BAR __builtin_amdgcn_s_barrier()
; #define PG8_SCHED __builtin_amdgcn_sched_barrier(0)
; template <class Epi, class Sched, bool ALIGN_EPI = false, bool SP2 = false>
; __device__ __forceinline__ void gemm_phase(PG8_LAS unsigned char* lds, const Gemm g, const Sched& S, const Epi& E) {
;     ...
;             PG8_LDB(B0, 0, 0); PG8_LDB(B1, 0, 1); PG8_SCHED; PG8_LDA(At, 0, 0); PG8_STAGE(PG8_SA(1, 1), a1 + hstep, voffA);
;             PG8_WAIT_V(8); PG8_WAIT_L(0); PG8_BAR; PG8_MMA(0, 0, At, B0); PG8_MMA(0, 1, At, B1); PG8_BAR; PG8_SCHED;
;             PG8_LDA(At, 0, 1); PG8_STAGE(PG8_SB(0, 0), b2, voffB); PG8_STAGE(PG8_SB(0, 1), b2 + hstep, voffB); PG8_STAGE(PG8_SA(0, 0), a2, voffA);
;             PG8_WAIT_V(8); PG8_WAIT_L(0); PG8_BAR; PG8_MMA(1, 0, At, B0); PG8_MMA(1, 1, At, B1); PG8_BAR; PG8_SCHED;
.LBB0_595:
	s_andn2_b64 vcc, exec, s[78:79]
	s_cbranch_vccnz .LBB0_598
	s_add_u32 s4, s4, 0x80
	s_addc_u32 s5, s5, 0
	s_add_u32 s9, s6, 0x100
	s_addc_u32 s27, s7, 0
	s_mov_b32 s6, 0
	ds_read_b128 v[128:131], v177
	ds_read_b128 v[154:157], v177 offset:1024
	ds_read_b128 v[158:161], v177 offset:2048
	ds_read_b128 v[162:165], v177 offset:3072
	ds_read_b128 v[166:169], v179
	ds_read_b128 v[170:173], v179 offset:1024
	ds_read_b128 v[184:187], v179 offset:2048
	ds_read_b128 v[188:191], v179 offset:3072
	s_add_i32 s28, s6, 2
	s_add_u32 s29, s4, 0x80
	s_addc_u32 s7, s5, 0
	s_cmp_eq_u32 s86, s6
	s_cselect_b32 s6, s0, s29
	s_cselect_b32 s7, s1, s7
	s_cselect_b32 s39, s37, s27
	s_cselect_b32 s38, s36, s9
	v_lshl_add_u64 v[224:225], s[4:5], 0, v[146:147]
	s_add_i32 m0, s67, 0xc000
	ds_read_b128 v[192:195], v180
	ds_read_b128 v[196:199], v180 offset:1024
	ds_read_b128 v[200:203], v180 offset:2048
	ds_read_b128 v[204:207], v180 offset:3072
	ds_read_b128 v[208:211], v180 offset:4096
	ds_read_b128 v[212:215], v180 offset:5120
	ds_read_b128 v[216:219], v180 offset:6144
	ds_read_b128 v[220:223], v180 offset:7168
	global_load_lds_dwordx4 v[224:225], off
	v_lshl_add_u64 v[224:225], s[4:5], 0, v[148:149]
	s_add_i32 m0, s67, 0xe000
	s_nop 0
	global_load_lds_dwordx4 v[224:225], off
	s_waitcnt vmcnt(8)
	s_waitcnt lgkmcnt(0)
	s_barrier
	s_waitcnt lgkmcnt(0)
	v_mfma_f32_16x16x32_bf16 v[120:123], v[128:131], v[192:195], 0
	v_mfma_f32_16x16x32_bf16 v[124:127], v[158:161], v[192:195], 0
	v_mfma_f32_16x16x32_bf16 v[108:111], v[128:131], v[200:203], 0
	v_mfma_f32_16x16x32_bf16 v[104:107], v[158:161], v[200:203], 0
	v_mfma_f32_16x16x32_bf16 v[92:95], v[128:131], v[208:211], 0
	v_mfma_f32_16x16x32_bf16 v[88:91], v[158:161], v[208:211], 0
	v_mfma_f32_16x16x32_bf16 v[76:79], v[128:131], v[216:219], 0
	v_mfma_f32_16x16x32_bf16 v[72:75], v[158:161], v[216:219], 0
	v_mfma_f32_16x16x32_bf16 v[120:123], v[154:157], v[196:199], v[120:123]
	v_mfma_f32_16x16x32_bf16 v[124:127], v[162:165], v[196:199], v[124:127]
	v_mfma_f32_16x16x32_bf16 v[108:111], v[154:157], v[204:207], v[108:111]
	v_mfma_f32_16x16x32_bf16 v[104:107], v[162:165], v[204:207], v[104:107]
	v_mfma_f32_16x16x32_bf16 v[92:95], v[154:157], v[212:215], v[92:95]
	v_mfma_f32_16x16x32_bf16 v[88:91], v[162:165], v[212:215], v[88:91]
	v_mfma_f32_16x16x32_bf16 v[76:79], v[154:157], v[220:223], v[76:79]
	v_mfma_f32_16x16x32_bf16 v[72:75], v[162:165], v[220:223], v[72:75]
	v_mfma_f32_16x16x32_bf16 v[116:119], v[166:169], v[192:195], 0
	v_mfma_f32_16x16x32_bf16 v[112:115], v[184:187], v[192:195], 0
	v_mfma_f32_16x16x32_bf16 v[100:103], v[166:169], v[200:203], 0
	v_mfma_f32_16x16x32_bf16 v[96:99], v[184:187], v[200:203], 0
	v_mfma_f32_16x16x32_bf16 v[84:87], v[166:169], v[208:211], 0
	v_mfma_f32_16x16x32_bf16 v[80:83], v[184:187], v[208:211], 0
	v_mfma_f32_16x16x32_bf16 v[68:71], v[166:169], v[216:219], 0
	v_mfma_f32_16x16x32_bf16 v[64:67], v[184:187], v[216:219], 0
	v_mfma_f32_16x16x32_bf16 v[116:119], v[170:173], v[196:199], v[116:119]
	v_mfma_f32_16x16x32_bf16 v[112:115], v[188:191], v[196:199], v[112:115]
	v_mfma_f32_16x16x32_bf16 v[100:103], v[170:173], v[204:207], v[100:103]
	v_mfma_f32_16x16x32_bf16 v[96:99], v[188:191], v[204:207], v[96:99]
	v_mfma_f32_16x16x32_bf16 v[84:87], v[170:173], v[212:215], v[84:87]
	v_mfma_f32_16x16x32_bf16 v[80:83], v[188:191], v[212:215], v[80:83]
	v_mfma_f32_16x16x32_bf16 v[68:71], v[170:173], v[220:223], v[68:71]
	v_mfma_f32_16x16x32_bf16 v[64:67], v[188:191], v[220:223], v[64:67]
	s_barrier
	s_add_i32 s29, s11, s66
	v_lshl_add_u64 v[224:225], s[38:39], 0, v[134:135]
	s_mov_b32 m0, s29
	ds_read_b128 v[192:195], v180 offset:16384
	ds_read_b128 v[196:199], v180 offset:17408
	ds_read_b128 v[200:203], v180 offset:18432
	ds_read_b128 v[204:207], v180 offset:19456
	ds_read_b128 v[208:211], v180 offset:20480
	ds_read_b128 v[212:215], v180 offset:21504
	ds_read_b128 v[216:219], v180 offset:22528
	ds_read_b128 v[220:223], v180 offset:23552
	global_load_lds_dwordx4 v[224:225], off
	s_add_i32 m0, s29, 0x2000
	v_lshl_add_u64 v[226:227], s[38:39], 0, v[138:139]
	s_add_u32 s38, s38, s14
	s_addc_u32 s39, s39, s15
	s_add_i32 s29, s19, s66
	global_load_lds_dwordx4 v[226:227], off
	v_lshl_add_u64 v[228:229], s[38:39], 0, v[134:135]
	s_mov_b32 m0, s29
	v_lshl_add_u64 v[230:231], s[38:39], 0, v[138:139]
	global_load_lds_dwordx4 v[228:229], off
	s_add_i32 m0, s29, 0x2000
	v_lshl_add_u64 v[232:233], s[6:7], 0, v[132:133]
	global_load_lds_dwordx4 v[230:231], off
	s_mov_b32 m0, s67
	v_lshl_add_u64 v[234:235], s[6:7], 0, v[136:137]
	global_load_lds_dwordx4 v[232:233], off
	s_mov_b32 m0, s68
	s_nop 0
	global_load_lds_dwordx4 v[234:235], off
	s_waitcnt vmcnt(8)
	s_waitcnt lgkmcnt(0)
	s_barrier
; #define PG8_STAGE(bufoff, gbase, voff) do { _Pragma("unroll") for (int _i = 0; _i < 2; ++_i) \
;         __builtin_amdgcn_global_load_lds((const unsigned*)((const char*)(gbase) + (voff)[_i]), (PG8_LAS unsigned*)(lds + (bufoff) + ldsw + _i * 8192), 16, 0, 0); } while (0)
; #define PG8_LDA(dst, b, h) do { _Pragma("unroll") for (int m = 0; m < 4; ++m) _Pragma("unroll") for (int k = 0; k < 2; ++k) dst[m][k] = *(const PG8_LAS bf16x8*)(lds + PG8_SA(b, h) + aoff + m * 2048 + k * 1024); } while (0)
; #define PG8_LDB(dst, b, h) do { _Pragma("unroll") for (int n = 0; n < 2; ++n) _Pragma("unroll") for (int k = 0; k < 2; ++k) dst[n][k] = *(const PG8_LAS bf16x8*)(lds + PG8_SB(b, h) + boff + n * 2048 + k * 1024); } while (0)
; #define PG8_MMA(ai, bj, At, Bt) do { __builtin_amdgcn_s_setprio(1); _Pragma("unroll") for (int m = 0; m < 4; ++m) _Pragma("unroll") for (int n = 0; n < 2; ++n) _Pragma("unroll") for (int k = 0; k < 2; ++k) \
;         acc[ai][bj][m][n] = __builtin_amdgcn_mfma_f32_16x16x32_bf16(Bt[n][k], At[m][k], acc[ai][bj][m][n], 0, 0, 0); __builtin_amdgcn_s_setprio(0); } while (0)
; #define PG8_WAIT_V(n) asm volatile("s_waitcnt vmcnt(" #n ")" ::: "memory")
; #define PG8_WAIT_L(n) asm volatile("s_waitcnt lgkmcnt(" #n ")" ::: "memory")
; #define PG8_BAR __builtin_amdgcn_s_barrier()
; #define PG8_SCHED __builtin_amdgcn_sched_barrier(0)
; template <class Epi, class Sched, bool ALIGN_EPI = false, bool SP2 = false>
; __device__ __forceinline__ void gemm_phase(PG8_LAS unsigned char* lds, const Gemm g, const Sched& S, const Epi& E) {
;     ...
;             PG8_WAIT_V(8); PG8_WAIT_L(0); PG8_BAR; PG8_MMA(1, 0, At, B0); PG8_MMA(1, 1, At, B1); PG8_BAR; PG8_SCHED;
;             PG8_LDB(B0, 1, 0); PG8_LDB(B1, 1, 1); PG8_SCHED; PG8_LDA(At, 1, 0); PG8_STAGE(PG8_SA(0, 1), a2 + hstep, voffA);
;             PG8_WAIT_V(8); PG8_WAIT_L(0); PG8_BAR; PG8_MMA(0, 0, At, B0); PG8_MMA(0, 1, At, B1); PG8_BAR; PG8_SCHED;
	s_waitcnt lgkmcnt(0)
	v_mfma_f32_16x16x32_bf16 v[60:63], v[128:131], v[192:195], 0
	v_mfma_f32_16x16x32_bf16 v[56:59], v[158:161], v[192:195], 0
	v_mfma_f32_16x16x32_bf16 v[44:47], v[128:131], v[200:203], 0
	v_mfma_f32_16x16x32_bf16 v[40:43], v[158:161], v[200:203], 0
	v_mfma_f32_16x16x32_bf16 v[28:31], v[128:131], v[208:211], 0
	v_mfma_f32_16x16x32_bf16 v[24:27], v[158:161], v[208:211], 0
	v_mfma_f32_16x16x32_bf16 v[12:15], v[128:131], v[216:219], 0
	v_mfma_f32_16x16x32_bf16 v[8:11], v[158:161], v[216:219], 0
	v_mfma_f32_16x16x32_bf16 v[60:63], v[154:157], v[196:199], v[60:63]
	v_mfma_f32_16x16x32_bf16 v[56:59], v[162:165], v[196:199], v[56:59]
	v_mfma_f32_16x16x32_bf16 v[44:47], v[154:157], v[204:207], v[44:47]
	v_mfma_f32_16x16x32_bf16 v[40:43], v[162:165], v[204:207], v[40:43]
	v_mfma_f32_16x16x32_bf16 v[28:31], v[154:157], v[212:215], v[28:31]
	v_mfma_f32_16x16x32_bf16 v[24:27], v[162:165], v[212:215], v[24:27]
	v_mfma_f32_16x16x32_bf16 v[12:15], v[154:157], v[220:223], v[12:15]
	v_mfma_f32_16x16x32_bf16 v[8:11], v[162:165], v[220:223], v[8:11]
	v_mfma_f32_16x16x32_bf16 v[52:55], v[166:169], v[192:195], 0
	v_mfma_f32_16x16x32_bf16 v[48:51], v[184:187], v[192:195], 0
	v_mfma_f32_16x16x32_bf16 v[36:39], v[166:169], v[200:203], 0
	v_mfma_f32_16x16x32_bf16 v[32:35], v[184:187], v[200:203], 0
	v_mfma_f32_16x16x32_bf16 v[20:23], v[166:169], v[208:211], 0
	v_mfma_f32_16x16x32_bf16 v[16:19], v[184:187], v[208:211], 0
	v_mfma_f32_16x16x32_bf16 v[4:7], v[166:169], v[216:219], 0
	v_mfma_f32_16x16x32_bf16 v[0:3], v[184:187], v[216:219], 0
	v_mfma_f32_16x16x32_bf16 v[52:55], v[170:173], v[196:199], v[52:55]
	v_mfma_f32_16x16x32_bf16 v[48:51], v[188:191], v[196:199], v[48:51]
	v_mfma_f32_16x16x32_bf16 v[36:39], v[170:173], v[204:207], v[36:39]
	v_mfma_f32_16x16x32_bf16 v[32:35], v[188:191], v[204:207], v[32:35]
	v_mfma_f32_16x16x32_bf16 v[20:23], v[170:173], v[212:215], v[20:23]
	v_mfma_f32_16x16x32_bf16 v[16:19], v[188:191], v[212:215], v[16:19]
	v_mfma_f32_16x16x32_bf16 v[4:7], v[170:173], v[220:223], v[4:7]
	v_mfma_f32_16x16x32_bf16 v[0:3], v[188:191], v[220:223], v[0:3]
	s_barrier
	s_add_i32 s29, 0, 0x18000
	v_add_u32_e32 v140, s29, v175
	s_add_i32 s38, 0, 0x1c000
	ds_read_b128 v[128:131], v140
	ds_read_b128 v[154:157], v140 offset:1024
	ds_read_b128 v[158:161], v140 offset:2048
	ds_read_b128 v[162:165], v140 offset:3072
	v_add_u32_e32 v140, s38, v175
	ds_read_b128 v[166:169], v140
	ds_read_b128 v[170:173], v140 offset:1024
	ds_read_b128 v[184:187], v140 offset:2048
	ds_read_b128 v[188:191], v140 offset:3072
	s_add_u32 s6, s6, s14
	s_addc_u32 s7, s7, s15
	s_mov_b32 m0, s69
	v_lshl_add_u64 v[236:237], s[6:7], 0, v[132:133]
	ds_read_b128 v[192:195], v180 offset:32768
	ds_read_b128 v[196:199], v180 offset:33792
	ds_read_b128 v[200:203], v180 offset:34816
	ds_read_b128 v[204:207], v180 offset:35840
	ds_read_b128 v[208:211], v180 offset:36864
	ds_read_b128 v[212:215], v180 offset:37888
	ds_read_b128 v[216:219], v180 offset:38912
	ds_read_b128 v[220:223], v180 offset:39936
	global_load_lds_dwordx4 v[236:237], off
	v_lshl_add_u64 v[236:237], s[6:7], 0, v[136:137]
	s_mov_b32 m0, s70
	s_nop 0
	global_load_lds_dwordx4 v[236:237], off
	s_waitcnt vmcnt(8)
	s_waitcnt lgkmcnt(0)
	s_barrier
	s_waitcnt lgkmcnt(0)
	v_mfma_f32_16x16x32_bf16 v[120:123], v[128:131], v[192:195], v[120:123]
	v_mfma_f32_16x16x32_bf16 v[124:127], v[158:161], v[192:195], v[124:127]
	v_mfma_f32_16x16x32_bf16 v[108:111], v[128:131], v[200:203], v[108:111]
	v_mfma_f32_16x16x32_bf16 v[104:107], v[158:161], v[200:203], v[104:107]
	v_mfma_f32_16x16x32_bf16 v[92:95], v[128:131], v[208:211], v[92:95]
	v_mfma_f32_16x16x32_bf16 v[88:91], v[158:161], v[208:211], v[88:91]
	v_mfma_f32_16x16x32_bf16 v[76:79], v[128:131], v[216:219], v[76:79]
	v_mfma_f32_16x16x32_bf16 v[72:75], v[158:161], v[216:219], v[72:75]
	v_mfma_f32_16x16x32_bf16 v[120:123], v[154:157], v[196:199], v[120:123]
	v_mfma_f32_16x16x32_bf16 v[124:127], v[162:165], v[196:199], v[124:127]
	v_mfma_f32_16x16x32_bf16 v[108:111], v[154:157], v[204:207], v[108:111]
	v_mfma_f32_16x16x32_bf16 v[104:107], v[162:165], v[204:207], v[104:107]
	v_mfma_f32_16x16x32_bf16 v[92:95], v[154:157], v[212:215], v[92:95]
	v_mfma_f32_16x16x32_bf16 v[88:91], v[162:165], v[212:215], v[88:91]
	v_mfma_f32_16x16x32_bf16 v[76:79], v[154:157], v[220:223], v[76:79]
	v_mfma_f32_16x16x32_bf16 v[72:75], v[162:165], v[220:223], v[72:75]
	v_mfma_f32_16x16x32_bf16 v[116:119], v[166:169], v[192:195], v[116:119]
	v_mfma_f32_16x16x32_bf16 v[112:115], v[184:187], v[192:195], v[112:115]
	v_mfma_f32_16x16x32_bf16 v[100:103], v[166:169], v[200:203], v[100:103]
	v_mfma_f32_16x16x32_bf16 v[96:99], v[184:187], v[200:203], v[96:99]
	v_mfma_f32_16x16x32_bf16 v[84:87], v[166:169], v[208:211], v[84:87]
	v_mfma_f32_16x16x32_bf16 v[80:83], v[184:187], v[208:211], v[80:83]
	v_mfma_f32_16x16x32_bf16 v[68:71], v[166:169], v[216:219], v[68:71]
	v_mfma_f32_16x16x32_bf16 v[64:67], v[184:187], v[216:219], v[64:67]
	v_mfma_f32_16x16x32_bf16 v[116:119], v[170:173], v[196:199], v[116:119]
	v_mfma_f32_16x16x32_bf16 v[112:115], v[188:191], v[196:199], v[112:115]
	v_mfma_f32_16x16x32_bf16 v[100:103], v[170:173], v[204:207], v[100:103]
	v_mfma_f32_16x16x32_bf16 v[96:99], v[188:191], v[204:207], v[96:99]
	v_mfma_f32_16x16x32_bf16 v[84:87], v[170:173], v[212:215], v[84:87]
	v_mfma_f32_16x16x32_bf16 v[80:83], v[188:191], v[212:215], v[80:83]
	v_mfma_f32_16x16x32_bf16 v[68:71], v[170:173], v[220:223], v[68:71]
	v_mfma_f32_16x16x32_bf16 v[64:67], v[188:191], v[220:223], v[64:67]
	s_barrier
; #define PG8_STAGE(bufoff, gbase, voff) do { _Pragma("unroll") for (int _i = 0; _i < 2; ++_i) \
;         __builtin_amdgcn_global_load_lds((const unsigned*)((const char*)(gbase) + (voff)[_i]), (PG8_LAS unsigned*)(lds + (bufoff) + ldsw + _i * 8192), 16, 0, 0); } while (0)
; #define PG8_LDA(dst, b, h) do { _Pragma("unroll") for (int m = 0; m < 4; ++m) _Pragma("unroll") for (int k = 0; k < 2; ++k) dst[m][k] = *(const PG8_LAS bf16x8*)(lds + PG8_SA(b, h) + aoff + m * 2048 + k * 1024); } while (0)
; #define PG8_LDB(dst, b, h) do { _Pragma("unroll") for (int n = 0; n < 2; ++n) _Pragma("unroll") for (int k = 0; k < 2; ++k) dst[n][k] = *(const PG8_LAS bf16x8*)(lds + PG8_SB(b, h) + boff + n * 2048 + k * 1024); } while (0)
; #define PG8_MMA(ai, bj, At, Bt) do { __builtin_amdgcn_s_setprio(1); _Pragma("unroll") for (int m = 0; m < 4; ++m) _Pragma("unroll") for (int n = 0; n < 2; ++n) _Pragma("unroll") for (int k = 0; k < 2; ++k) \
;         acc[ai][bj][m][n] = __builtin_amdgcn_mfma_f32_16x16x32_bf16(Bt[n][k], At[m][k], acc[ai][bj][m][n], 0, 0, 0); __builtin_amdgcn_s_setprio(0); } while (0)
; #define PG8_WAIT_V(n) asm volatile("s_waitcnt vmcnt(" #n ")" ::: "memory")
; #define PG8_WAIT_L(n) asm volatile("s_waitcnt lgkmcnt(" #n ")" ::: "memory")
; #define PG8_BAR __builtin_amdgcn_s_barrier()
; #define PG8_SCHED __builtin_amdgcn_sched_barrier(0)
; template <class Epi, class Sched, bool ALIGN_EPI = false, bool SP2 = false>
; __device__ __forceinline__ void gemm_phase(PG8_LAS unsigned char* lds, const Gemm g, const Sched& S, const Epi& E) {
;     ...
;             PG8_LDB(B0, 0, 0); PG8_LDB(B1, 0, 1); PG8_SCHED; PG8_LDA(At, 0, 0); PG8_STAGE(PG8_SA(1, 1), a1 + hstep, voffA);
;             PG8_WAIT_V(8); PG8_WAIT_L(0); PG8_BAR; PG8_MMA(0, 0, At, B0); PG8_MMA(0, 1, At, B1); PG8_BAR; PG8_SCHED;
;     ...
;             PG8_LDA(At, 1, 1); PG8_STAGE(PG8_SB(1, 0), b3, voffB); PG8_STAGE(PG8_SB(1, 1), b3 + hstep, voffB); PG8_STAGE(PG8_SA(1, 0), a3, voffA);
;             PG8_WAIT_V(8); PG8_WAIT_L(0); PG8_BAR; PG8_MMA(1, 0, At, B0); PG8_MMA(1, 1, At, B1); PG8_BAR; PG8_SCHED;
	s_add_i32 s6, s29, s66
	v_lshl_add_u64 v[224:225], v[224:225], 0, s[24:25]
	s_mov_b32 m0, s6
	ds_read_b128 v[192:195], v180 offset:49152
	ds_read_b128 v[196:199], v180 offset:50176
	ds_read_b128 v[200:203], v180 offset:51200
	ds_read_b128 v[204:207], v180 offset:52224
	ds_read_b128 v[208:211], v180 offset:53248
	ds_read_b128 v[212:215], v180 offset:54272
	ds_read_b128 v[216:219], v180 offset:55296
	ds_read_b128 v[220:223], v180 offset:56320
	global_load_lds_dwordx4 v[224:225], off
	v_lshl_add_u64 v[224:225], v[226:227], 0, s[24:25]
	s_add_i32 m0, s6, 0x2000
	s_add_i32 s6, s38, s66
	global_load_lds_dwordx4 v[224:225], off
	v_lshl_add_u64 v[224:225], v[228:229], 0, s[24:25]
	s_mov_b32 m0, s6
	s_nop 0
	global_load_lds_dwordx4 v[224:225], off
	v_lshl_add_u64 v[224:225], v[230:231], 0, s[24:25]
	s_add_i32 m0, s6, 0x2000
	s_nop 0
	global_load_lds_dwordx4 v[224:225], off
	v_lshl_add_u64 v[224:225], v[232:233], 0, s[24:25]
	s_mov_b32 m0, s72
	s_nop 0
	global_load_lds_dwordx4 v[224:225], off
	v_lshl_add_u64 v[224:225], v[234:235], 0, s[24:25]
	s_mov_b32 m0, s73
	s_nop 0
	global_load_lds_dwordx4 v[224:225], off
	s_waitcnt vmcnt(8)
	s_waitcnt lgkmcnt(0)
	s_barrier
	s_waitcnt lgkmcnt(0)
	v_mfma_f32_16x16x32_bf16 v[60:63], v[128:131], v[192:195], v[60:63]
	v_mfma_f32_16x16x32_bf16 v[56:59], v[158:161], v[192:195], v[56:59]
	v_mfma_f32_16x16x32_bf16 v[44:47], v[128:131], v[200:203], v[44:47]
	v_mfma_f32_16x16x32_bf16 v[40:43], v[158:161], v[200:203], v[40:43]
	v_mfma_f32_16x16x32_bf16 v[28:31], v[128:131], v[208:211], v[28:31]
	v_mfma_f32_16x16x32_bf16 v[24:27], v[158:161], v[208:211], v[24:27]
	v_mfma_f32_16x16x32_bf16 v[12:15], v[128:131], v[216:219], v[12:15]
	v_mfma_f32_16x16x32_bf16 v[8:11], v[158:161], v[216:219], v[8:11]
	v_mfma_f32_16x16x32_bf16 v[60:63], v[154:157], v[196:199], v[60:63]
	v_mfma_f32_16x16x32_bf16 v[56:59], v[162:165], v[196:199], v[56:59]
	v_mfma_f32_16x16x32_bf16 v[44:47], v[154:157], v[204:207], v[44:47]
	v_mfma_f32_16x16x32_bf16 v[40:43], v[162:165], v[204:207], v[40:43]
	v_mfma_f32_16x16x32_bf16 v[28:31], v[154:157], v[212:215], v[28:31]
	v_mfma_f32_16x16x32_bf16 v[24:27], v[162:165], v[212:215], v[24:27]
	v_mfma_f32_16x16x32_bf16 v[12:15], v[154:157], v[220:223], v[12:15]
	v_mfma_f32_16x16x32_bf16 v[8:11], v[162:165], v[220:223], v[8:11]
	v_mfma_f32_16x16x32_bf16 v[52:55], v[166:169], v[192:195], v[52:55]
	v_mfma_f32_16x16x32_bf16 v[48:51], v[184:187], v[192:195], v[48:51]
	v_mfma_f32_16x16x32_bf16 v[36:39], v[166:169], v[200:203], v[36:39]
	v_mfma_f32_16x16x32_bf16 v[32:35], v[184:187], v[200:203], v[32:35]
	v_mfma_f32_16x16x32_bf16 v[20:23], v[166:169], v[208:211], v[20:23]
	v_mfma_f32_16x16x32_bf16 v[16:19], v[184:187], v[208:211], v[16:19]
	v_mfma_f32_16x16x32_bf16 v[4:7], v[166:169], v[216:219], v[4:7]
	v_mfma_f32_16x16x32_bf16 v[0:3], v[184:187], v[216:219], v[0:3]
	v_mfma_f32_16x16x32_bf16 v[52:55], v[170:173], v[196:199], v[52:55]
	v_mfma_f32_16x16x32_bf16 v[48:51], v[188:191], v[196:199], v[48:51]
	v_mfma_f32_16x16x32_bf16 v[36:39], v[170:173], v[204:207], v[36:39]
	v_mfma_f32_16x16x32_bf16 v[32:35], v[188:191], v[204:207], v[32:35]
	v_mfma_f32_16x16x32_bf16 v[20:23], v[170:173], v[212:215], v[20:23]
	v_mfma_f32_16x16x32_bf16 v[16:19], v[188:191], v[212:215], v[16:19]
	v_mfma_f32_16x16x32_bf16 v[4:7], v[170:173], v[220:223], v[4:7]
	v_mfma_f32_16x16x32_bf16 v[0:3], v[188:191], v[220:223], v[0:3]
	s_barrier
	s_add_u32 s4, s4, 0x100
	s_addc_u32 s5, s5, 0
	s_add_u32 s9, s9, 0x100
	s_addc_u32 s27, s27, 0
	s_cmp_ge_i32 s28, s33
	s_mov_b32 s6, s28
	s_cbranch_scc0 .LBB0_597
	s_branch .Lpeel_x2
.LBB0_597:
	ds_read_b128 v[128:131], v177
	ds_read_b128 v[154:157], v177 offset:1024
	ds_read_b128 v[158:161], v177 offset:2048
	ds_read_b128 v[162:165], v177 offset:3072
	ds_read_b128 v[166:169], v179
	ds_read_b128 v[170:173], v179 offset:1024
	ds_read_b128 v[184:187], v179 offset:2048
	ds_read_b128 v[188:191], v179 offset:3072
	s_add_i32 s28, s6, 2
	s_add_u32 s29, s4, 0x80
	s_addc_u32 s7, s5, 0
	s_cmp_eq_u32 s86, s6
	s_cselect_b32 s6, s0, s29
	s_cselect_b32 s7, s1, s7
	s_cselect_b32 s39, s37, s27
	s_cselect_b32 s38, s36, s9
	v_lshl_add_u64 v[224:225], s[4:5], 0, v[146:147]
	s_add_i32 m0, s67, 0xc000
	ds_read_b128 v[192:195], v180
	ds_read_b128 v[196:199], v180 offset:1024
	ds_read_b128 v[200:203], v180 offset:2048
	ds_read_b128 v[204:207], v180 offset:3072
	ds_read_b128 v[208:211], v180 offset:4096
	ds_read_b128 v[212:215], v180 offset:5120
	ds_read_b128 v[216:219], v180 offset:6144
	ds_read_b128 v[220:223], v180 offset:7168
	global_load_lds_dwordx4 v[224:225], off
	v_lshl_add_u64 v[224:225], s[4:5], 0, v[148:149]
	s_add_i32 m0, s67, 0xe000
	s_nop 0
	global_load_lds_dwordx4 v[224:225], off
	s_waitcnt vmcnt(8)
	s_waitcnt lgkmcnt(0)
	s_barrier
; #define PG8_STAGE(bufoff, gbase, voff) do { _Pragma("unroll") for (int _i = 0; _i < 2; ++_i) \
;         __builtin_amdgcn_global_load_lds((const unsigned*)((const char*)(gbase) + (voff)[_i]), (PG8_LAS unsigned*)(lds + (bufoff) + ldsw + _i * 8192), 16, 0, 0); } while (0)
; #define PG8_LDA(dst, b, h) do { _Pragma("unroll") for (int m = 0; m < 4; ++m) _Pragma("unroll") for (int k = 0; k < 2; ++k) dst[m][k] = *(const PG8_LAS bf16x8*)(lds + PG8_SA(b, h) + aoff + m * 2048 + k * 1024); } while (0)
; #define PG8_MMA(ai, bj, At, Bt) do { __builtin_amdgcn_s_setprio(1); _Pragma("unroll") for (int m = 0; m < 4; ++m) _Pragma("unroll") for (int n = 0; n < 2; ++n) _Pragma("unroll") for (int k = 0; k < 2; ++k) \
;         acc[ai][bj][m][n] = __builtin_amdgcn_mfma_f32_16x16x32_bf16(Bt[n][k], At[m][k], acc[ai][bj][m][n], 0, 0, 0); __builtin_amdgcn_s_setprio(0); } while (0)
; #define PG8_WAIT_V(n) asm volatile("s_waitcnt vmcnt(" #n ")" ::: "memory")
; #define PG8_WAIT_L(n) asm volatile("s_waitcnt lgkmcnt(" #n ")" ::: "memory")
; #define PG8_BAR __builtin_amdgcn_s_barrier()
; #define PG8_SCHED __builtin_amdgcn_sched_barrier(0)
; template <class Epi, class Sched, bool ALIGN_EPI = false, bool SP2 = false>
; __device__ __forceinline__ void gemm_phase(PG8_LAS unsigned char* lds, const Gemm g, const Sched& S, const Epi& E) {
;     ...
;             PG8_WAIT_V(8); PG8_WAIT_L(0); PG8_BAR; PG8_MMA(0, 0, At, B0); PG8_MMA(0, 1, At, B1); PG8_BAR; PG8_SCHED;
;             PG8_LDA(At, 0, 1); PG8_STAGE(PG8_SB(0, 0), b2, voffB); PG8_STAGE(PG8_SB(0, 1), b2 + hstep, voffB); PG8_STAGE(PG8_SA(0, 0), a2, voffA);
;             PG8_WAIT_V(8); PG8_WAIT_L(0); PG8_BAR; PG8_MMA(1, 0, At, B0); PG8_MMA(1, 1, At, B1); PG8_BAR; PG8_SCHED;
	s_waitcnt lgkmcnt(0)
	v_mfma_f32_16x16x32_bf16 v[120:123], v[128:131], v[192:195], v[120:123]
	v_mfma_f32_16x16x32_bf16 v[124:127], v[158:161], v[192:195], v[124:127]
	v_mfma_f32_16x16x32_bf16 v[108:111], v[128:131], v[200:203], v[108:111]
	v_mfma_f32_16x16x32_bf16 v[104:107], v[158:161], v[200:203], v[104:107]
	v_mfma_f32_16x16x32_bf16 v[92:95], v[128:131], v[208:211], v[92:95]
	v_mfma_f32_16x16x32_bf16 v[88:91], v[158:161], v[208:211], v[88:91]
	v_mfma_f32_16x16x32_bf16 v[76:79], v[128:131], v[216:219], v[76:79]
	v_mfma_f32_16x16x32_bf16 v[72:75], v[158:161], v[216:219], v[72:75]
	v_mfma_f32_16x16x32_bf16 v[120:123], v[154:157], v[196:199], v[120:123]
	v_mfma_f32_16x16x32_bf16 v[124:127], v[162:165], v[196:199], v[124:127]
	v_mfma_f32_16x16x32_bf16 v[108:111], v[154:157], v[204:207], v[108:111]
	v_mfma_f32_16x16x32_bf16 v[104:107], v[162:165], v[204:207], v[104:107]
	v_mfma_f32_16x16x32_bf16 v[92:95], v[154:157], v[212:215], v[92:95]
	v_mfma_f32_16x16x32_bf16 v[88:91], v[162:165], v[212:215], v[88:91]
	v_mfma_f32_16x16x32_bf16 v[76:79], v[154:157], v[220:223], v[76:79]
	v_mfma_f32_16x16x32_bf16 v[72:75], v[162:165], v[220:223], v[72:75]
	v_mfma_f32_16x16x32_bf16 v[116:119], v[166:169], v[192:195], v[116:119]
	v_mfma_f32_16x16x32_bf16 v[112:115], v[184:187], v[192:195], v[112:115]
	v_mfma_f32_16x16x32_bf16 v[100:103], v[166:169], v[200:203], v[100:103]
	v_mfma_f32_16x16x32_bf16 v[96:99], v[184:187], v[200:203], v[96:99]
	v_mfma_f32_16x16x32_bf16 v[84:87], v[166:169], v[208:211], v[84:87]
	v_mfma_f32_16x16x32_bf16 v[80:83], v[184:187], v[208:211], v[80:83]
	v_mfma_f32_16x16x32_bf16 v[68:71], v[166:169], v[216:219], v[68:71]
	v_mfma_f32_16x16x32_bf16 v[64:67], v[184:187], v[216:219], v[64:67]
	v_mfma_f32_16x16x32_bf16 v[116:119], v[170:173], v[196:199], v[116:119]
	v_mfma_f32_16x16x32_bf16 v[112:115], v[188:191], v[196:199], v[112:115]
	v_mfma_f32_16x16x32_bf16 v[100:103], v[170:173], v[204:207], v[100:103]
	v_mfma_f32_16x16x32_bf16 v[96:99], v[188:191], v[204:207], v[96:99]
	v_mfma_f32_16x16x32_bf16 v[84:87], v[170:173], v[212:215], v[84:87]
	v_mfma_f32_16x16x32_bf16 v[80:83], v[188:191], v[212:215], v[80:83]
	v_mfma_f32_16x16x32_bf16 v[68:71], v[170:173], v[220:223], v[68:71]
	v_mfma_f32_16x16x32_bf16 v[64:67], v[188:191], v[220:223], v[64:67]
	s_barrier
	s_add_i32 s29, s11, s66
	v_lshl_add_u64 v[224:225], s[38:39], 0, v[134:135]
	s_mov_b32 m0, s29
	ds_read_b128 v[192:195], v180 offset:16384
	ds_read_b128 v[196:199], v180 offset:17408
	ds_read_b128 v[200:203], v180 offset:18432
	ds_read_b128 v[204:207], v180 offset:19456
	ds_read_b128 v[208:211], v180 offset:20480
	ds_read_b128 v[212:215], v180 offset:21504
	ds_read_b128 v[216:219], v180 offset:22528
	ds_read_b128 v[220:223], v180 offset:23552
	global_load_lds_dwordx4 v[224:225], off
	s_add_i32 m0, s29, 0x2000
	v_lshl_add_u64 v[226:227], s[38:39], 0, v[138:139]
	s_add_u32 s38, s38, s14
	s_addc_u32 s39, s39, s15
	s_add_i32 s29, s19, s66
	global_load_lds_dwordx4 v[226:227], off
	v_lshl_add_u64 v[228:229], s[38:39], 0, v[134:135]
	s_mov_b32 m0, s29
	v_lshl_add_u64 v[230:231], s[38:39], 0, v[138:139]
	global_load_lds_dwordx4 v[228:229], off
	s_add_i32 m0, s29, 0x2000
	v_lshl_add_u64 v[232:233], s[6:7], 0, v[132:133]
	global_load_lds_dwordx4 v[230:231], off
	s_mov_b32 m0, s67
	v_lshl_add_u64 v[234:235], s[6:7], 0, v[136:137]
	global_load_lds_dwordx4 v[232:233], off
	s_mov_b32 m0, s68
	s_nop 0
	global_load_lds_dwordx4 v[234:235], off
	s_waitcnt vmcnt(8)
	s_waitcnt lgkmcnt(0)
	s_barrier
	s_waitcnt lgkmcnt(0)
	v_mfma_f32_16x16x32_bf16 v[60:63], v[128:131], v[192:195], v[60:63]
	v_mfma_f32_16x16x32_bf16 v[56:59], v[158:161], v[192:195], v[56:59]
	v_mfma_f32_16x16x32_bf16 v[44:47], v[128:131], v[200:203], v[44:47]
	v_mfma_f32_16x16x32_bf16 v[40:43], v[158:161], v[200:203], v[40:43]
	v_mfma_f32_16x16x32_bf16 v[28:31], v[128:131], v[208:211], v[28:31]
	v_mfma_f32_16x16x32_bf16 v[24:27], v[158:161], v[208:211], v[24:27]
	v_mfma_f32_16x16x32_bf16 v[12:15], v[128:131], v[216:219], v[12:15]
	v_mfma_f32_16x16x32_bf16 v[8:11], v[158:161], v[216:219], v[8:11]
	v_mfma_f32_16x16x32_bf16 v[60:63], v[154:157], v[196:199], v[60:63]
	v_mfma_f32_16x16x32_bf16 v[56:59], v[162:165], v[196:199], v[56:59]
	v_mfma_f32_16x16x32_bf16 v[44:47], v[154:157], v[204:207], v[44:47]
	v_mfma_f32_16x16x32_bf16 v[40:43], v[162:165], v[204:207], v[40:43]
	v_mfma_f32_16x16x32_bf16 v[28:31], v[154:157], v[212:215], v[28:31]
	v_mfma_f32_16x16x32_bf16 v[24:27], v[162:165], v[212:215], v[24:27]
	v_mfma_f32_16x16x32_bf16 v[12:15], v[154:157], v[220:223], v[12:15]
	v_mfma_f32_16x16x32_bf16 v[8:11], v[162:165], v[220:223], v[8:11]
	v_mfma_f32_16x16x32_bf16 v[52:55], v[166:169], v[192:195], v[52:55]
	v_mfma_f32_16x16x32_bf16 v[48:51], v[184:187], v[192:195], v[48:51]
	v_mfma_f32_16x16x32_bf16 v[36:39], v[166:169], v[200:203], v[36:39]
	v_mfma_f32_16x16x32_bf16 v[32:35], v[184:187], v[200:203], v[32:35]
	v_mfma_f32_16x16x32_bf16 v[20:23], v[166:169], v[208:211], v[20:23]
	v_mfma_f32_16x16x32_bf16 v[16:19], v[184:187], v[208:211], v[16:19]
	v_mfma_f32_16x16x32_bf16 v[4:7], v[166:169], v[216:219], v[4:7]
	v_mfma_f32_16x16x32_bf16 v[0:3], v[184:187], v[216:219], v[0:3]
	v_mfma_f32_16x16x32_bf16 v[52:55], v[170:173], v[196:199], v[52:55]
	v_mfma_f32_16x16x32_bf16 v[48:51], v[188:191], v[196:199], v[48:51]
	v_mfma_f32_16x16x32_bf16 v[36:39], v[170:173], v[204:207], v[36:39]
	v_mfma_f32_16x16x32_bf16 v[32:35], v[188:191], v[204:207], v[32:35]
	v_mfma_f32_16x16x32_bf16 v[20:23], v[170:173], v[212:215], v[20:23]
	v_mfma_f32_16x16x32_bf16 v[16:19], v[188:191], v[212:215], v[16:19]
	v_mfma_f32_16x16x32_bf16 v[4:7], v[170:173], v[220:223], v[4:7]
	v_mfma_f32_16x16x32_bf16 v[0:3], v[188:191], v[220:223], v[0:3]
	s_barrier
; #define PG8_STAGE(bufoff, gbase, voff) do { _Pragma("unroll") for (int _i = 0; _i < 2; ++_i) \
;         __builtin_amdgcn_global_load_lds((const unsigned*)((const char*)(gbase) + (voff)[_i]), (PG8_LAS unsigned*)(lds + (bufoff) + ldsw + _i * 8192), 16, 0, 0); } while (0)
; #define PG8_LDA(dst, b, h) do { _Pragma("unroll") for (int m = 0; m < 4; ++m) _Pragma("unroll") for (int k = 0; k < 2; ++k) dst[m][k] = *(const PG8_LAS bf16x8*)(lds + PG8_SA(b, h) + aoff + m * 2048 + k * 1024); } while (0)
; #define PG8_LDB(dst, b, h) do { _Pragma("unroll") for (int n = 0; n < 2; ++n) _Pragma("unroll") for (int k = 0; k < 2; ++k) dst[n][k] = *(const PG8_LAS bf16x8*)(lds + PG8_SB(b, h) + boff + n * 2048 + k * 1024); } while (0)
; #define PG8_MMA(ai, bj, At, Bt) do { __builtin_amdgcn_s_setprio(1); _Pragma("unroll") for (int m = 0; m < 4; ++m) _Pragma("unroll") for (int n = 0; n < 2; ++n) _Pragma("unroll") for (int k = 0; k < 2; ++k) \
;         acc[ai][bj][m][n] = __builtin_amdgcn_mfma_f32_16x16x32_bf16(Bt[n][k], At[m][k], acc[ai][bj][m][n], 0, 0, 0); __builtin_amdgcn_s_setprio(0); } while (0)
; #define PG8_WAIT_V(n) asm volatile("s_waitcnt vmcnt(" #n ")" ::: "memory")
; #define PG8_WAIT_L(n) asm volatile("s_waitcnt lgkmcnt(" #n ")" ::: "memory")
; #define PG8_BAR __builtin_amdgcn_s_barrier()
; #define PG8_SCHED __builtin_amdgcn_sched_barrier(0)
; template <class Epi, class Sched, bool ALIGN_EPI = false, bool SP2 = false>
; __device__ __forceinline__ void gemm_phase(PG8_LAS unsigned char* lds, const Gemm g, const Sched& S, const Epi& E) {
;     ...
;             PG8_LDB(B0, 1, 0); PG8_LDB(B1, 1, 1); PG8_SCHED; PG8_LDA(At, 1, 0); PG8_STAGE(PG8_SA(0, 1), a2 + hstep, voffA);
;             PG8_WAIT_V(8); PG8_WAIT_L(0); PG8_BAR; PG8_MMA(0, 0, At, B0); PG8_MMA(0, 1, At, B1); PG8_BAR; PG8_SCHED;
;             PG8_LDA(At, 1, 1); PG8_STAGE(PG8_SB(1, 0), b3, voffB); PG8_STAGE(PG8_SB(1, 1), b3 + hstep, voffB); PG8_STAGE(PG8_SA(1, 0), a3, voffA);
;             PG8_WAIT_V(8); PG8_WAIT_L(0); PG8_BAR; PG8_MMA(1, 0, At, B0); PG8_MMA(1, 1, At, B1); PG8_BAR; PG8_SCHED;
	s_add_i32 s29, 0, 0x18000
	v_add_u32_e32 v140, s29, v175
	s_add_i32 s38, 0, 0x1c000
	ds_read_b128 v[128:131], v140
	ds_read_b128 v[154:157], v140 offset:1024
	ds_read_b128 v[158:161], v140 offset:2048
	ds_read_b128 v[162:165], v140 offset:3072
	v_add_u32_e32 v140, s38, v175
	ds_read_b128 v[166:169], v140
	ds_read_b128 v[170:173], v140 offset:1024
	ds_read_b128 v[184:187], v140 offset:2048
	ds_read_b128 v[188:191], v140 offset:3072
	s_add_u32 s6, s6, s14
	s_addc_u32 s7, s7, s15
	s_mov_b32 m0, s69
	v_lshl_add_u64 v[236:237], s[6:7], 0, v[132:133]
	ds_read_b128 v[192:195], v180 offset:32768
	ds_read_b128 v[196:199], v180 offset:33792
	ds_read_b128 v[200:203], v180 offset:34816
	ds_read_b128 v[204:207], v180 offset:35840
	ds_read_b128 v[208:211], v180 offset:36864
	ds_read_b128 v[212:215], v180 offset:37888
	ds_read_b128 v[216:219], v180 offset:38912
	ds_read_b128 v[220:223], v180 offset:39936
	global_load_lds_dwordx4 v[236:237], off
	v_lshl_add_u64 v[236:237], s[6:7], 0, v[136:137]
	s_mov_b32 m0, s70
	s_nop 0
	global_load_lds_dwordx4 v[236:237], off
	s_waitcnt vmcnt(8)
	s_waitcnt lgkmcnt(0)
	s_barrier
	s_waitcnt lgkmcnt(0)
	v_mfma_f32_16x16x32_bf16 v[120:123], v[128:131], v[192:195], v[120:123]
	v_mfma_f32_16x16x32_bf16 v[124:127], v[158:161], v[192:195], v[124:127]
	v_mfma_f32_16x16x32_bf16 v[108:111], v[128:131], v[200:203], v[108:111]
	v_mfma_f32_16x16x32_bf16 v[104:107], v[158:161], v[200:203], v[104:107]
	v_mfma_f32_16x16x32_bf16 v[92:95], v[128:131], v[208:211], v[92:95]
	v_mfma_f32_16x16x32_bf16 v[88:91], v[158:161], v[208:211], v[88:91]
	v_mfma_f32_16x16x32_bf16 v[76:79], v[128:131], v[216:219], v[76:79]
	v_mfma_f32_16x16x32_bf16 v[72:75], v[158:161], v[216:219], v[72:75]
	v_mfma_f32_16x16x32_bf16 v[120:123], v[154:157], v[196:199], v[120:123]
	v_mfma_f32_16x16x32_bf16 v[124:127], v[162:165], v[196:199], v[124:127]
	v_mfma_f32_16x16x32_bf16 v[108:111], v[154:157], v[204:207], v[108:111]
	v_mfma_f32_16x16x32_bf16 v[104:107], v[162:165], v[204:207], v[104:107]
	v_mfma_f32_16x16x32_bf16 v[92:95], v[154:157], v[212:215], v[92:95]
	v_mfma_f32_16x16x32_bf16 v[88:91], v[162:165], v[212:215], v[88:91]
	v_mfma_f32_16x16x32_bf16 v[76:79], v[154:157], v[220:223], v[76:79]
	v_mfma_f32_16x16x32_bf16 v[72:75], v[162:165], v[220:223], v[72:75]
	v_mfma_f32_16x16x32_bf16 v[116:119], v[166:169], v[192:195], v[116:119]
	v_mfma_f32_16x16x32_bf16 v[112:115], v[184:187], v[192:195], v[112:115]
	v_mfma_f32_16x16x32_bf16 v[100:103], v[166:169], v[200:203], v[100:103]
	v_mfma_f32_16x16x32_bf16 v[96:99], v[184:187], v[200:203], v[96:99]
	v_mfma_f32_16x16x32_bf16 v[84:87], v[166:169], v[208:211], v[84:87]
	v_mfma_f32_16x16x32_bf16 v[80:83], v[184:187], v[208:211], v[80:83]
	v_mfma_f32_16x16x32_bf16 v[68:71], v[166:169], v[216:219], v[68:71]
	v_mfma_f32_16x16x32_bf16 v[64:67], v[184:187], v[216:219], v[64:67]
	v_mfma_f32_16x16x32_bf16 v[116:119], v[170:173], v[196:199], v[116:119]
	v_mfma_f32_16x16x32_bf16 v[112:115], v[188:191], v[196:199], v[112:115]
	v_mfma_f32_16x16x32_bf16 v[100:103], v[170:173], v[204:207], v[100:103]
	v_mfma_f32_16x16x32_bf16 v[96:99], v[188:191], v[204:207], v[96:99]
	v_mfma_f32_16x16x32_bf16 v[84:87], v[170:173], v[212:215], v[84:87]
	v_mfma_f32_16x16x32_bf16 v[80:83], v[188:191], v[212:215], v[80:83]
	v_mfma_f32_16x16x32_bf16 v[68:71], v[170:173], v[220:223], v[68:71]
	v_mfma_f32_16x16x32_bf16 v[64:67], v[188:191], v[220:223], v[64:67]
	s_barrier
	s_add_i32 s6, s29, s66
	v_lshl_add_u64 v[224:225], v[224:225], 0, s[24:25]
	s_mov_b32 m0, s6
	ds_read_b128 v[192:195], v180 offset:49152
	ds_read_b128 v[196:199], v180 offset:50176
	ds_read_b128 v[200:203], v180 offset:51200
	ds_read_b128 v[204:207], v180 offset:52224
	ds_read_b128 v[208:211], v180 offset:53248
	ds_read_b128 v[212:215], v180 offset:54272
	ds_read_b128 v[216:219], v180 offset:55296
	ds_read_b128 v[220:223], v180 offset:56320
	global_load_lds_dwordx4 v[224:225], off
	v_lshl_add_u64 v[224:225], v[226:227], 0, s[24:25]
	s_add_i32 m0, s6, 0x2000
	s_add_i32 s6, s38, s66
	global_load_lds_dwordx4 v[224:225], off
	v_lshl_add_u64 v[224:225], v[228:229], 0, s[24:25]
	s_mov_b32 m0, s6
	s_nop 0
	global_load_lds_dwordx4 v[224:225], off
	v_lshl_add_u64 v[224:225], v[230:231], 0, s[24:25]
	s_add_i32 m0, s6, 0x2000
	s_nop 0
	global_load_lds_dwordx4 v[224:225], off
	v_lshl_add_u64 v[224:225], v[232:233], 0, s[24:25]
	s_mov_b32 m0, s72
	s_nop 0
	global_load_lds_dwordx4 v[224:225], off
	v_lshl_add_u64 v[224:225], v[234:235], 0, s[24:25]
	s_mov_b32 m0, s73
	s_nop 0
	global_load_lds_dwordx4 v[224:225], off
	s_waitcnt vmcnt(8)
	s_waitcnt lgkmcnt(0)
	s_barrier
	s_waitcnt lgkmcnt(0)
	v_mfma_f32_16x16x32_bf16 v[60:63], v[128:131], v[192:195], v[60:63]
	v_mfma_f32_16x16x32_bf16 v[56:59], v[158:161], v[192:195], v[56:59]
	v_mfma_f32_16x16x32_bf16 v[44:47], v[128:131], v[200:203], v[44:47]
	v_mfma_f32_16x16x32_bf16 v[40:43], v[158:161], v[200:203], v[40:43]
	v_mfma_f32_16x16x32_bf16 v[28:31], v[128:131], v[208:211], v[28:31]
	v_mfma_f32_16x16x32_bf16 v[24:27], v[158:161], v[208:211], v[24:27]
	v_mfma_f32_16x16x32_bf16 v[12:15], v[128:131], v[216:219], v[12:15]
	v_mfma_f32_16x16x32_bf16 v[8:11], v[158:161], v[216:219], v[8:11]
	v_mfma_f32_16x16x32_bf16 v[60:63], v[154:157], v[196:199], v[60:63]
	v_mfma_f32_16x16x32_bf16 v[56:59], v[162:165], v[196:199], v[56:59]
	v_mfma_f32_16x16x32_bf16 v[44:47], v[154:157], v[204:207], v[44:47]
	v_mfma_f32_16x16x32_bf16 v[40:43], v[162:165], v[204:207], v[40:43]
	v_mfma_f32_16x16x32_bf16 v[28:31], v[154:157], v[212:215], v[28:31]
	v_mfma_f32_16x16x32_bf16 v[24:27], v[162:165], v[212:215], v[24:27]
	v_mfma_f32_16x16x32_bf16 v[12:15], v[154:157], v[220:223], v[12:15]
	v_mfma_f32_16x16x32_bf16 v[8:11], v[162:165], v[220:223], v[8:11]
	v_mfma_f32_16x16x32_bf16 v[52:55], v[166:169], v[192:195], v[52:55]
	v_mfma_f32_16x16x32_bf16 v[48:51], v[184:187], v[192:195], v[48:51]
	v_mfma_f32_16x16x32_bf16 v[36:39], v[166:169], v[200:203], v[36:39]
	v_mfma_f32_16x16x32_bf16 v[32:35], v[184:187], v[200:203], v[32:35]
	v_mfma_f32_16x16x32_bf16 v[20:23], v[166:169], v[208:211], v[20:23]
	v_mfma_f32_16x16x32_bf16 v[16:19], v[184:187], v[208:211], v[16:19]
	v_mfma_f32_16x16x32_bf16 v[4:7], v[166:169], v[216:219], v[4:7]
	v_mfma_f32_16x16x32_bf16 v[0:3], v[184:187], v[216:219], v[0:3]
	v_mfma_f32_16x16x32_bf16 v[52:55], v[170:173], v[196:199], v[52:55]
	v_mfma_f32_16x16x32_bf16 v[48:51], v[188:191], v[196:199], v[48:51]
	v_mfma_f32_16x16x32_bf16 v[36:39], v[170:173], v[204:207], v[36:39]
	v_mfma_f32_16x16x32_bf16 v[32:35], v[188:191], v[204:207], v[32:35]
	v_mfma_f32_16x16x32_bf16 v[20:23], v[170:173], v[212:215], v[20:23]
	v_mfma_f32_16x16x32_bf16 v[16:19], v[188:191], v[212:215], v[16:19]
	v_mfma_f32_16x16x32_bf16 v[4:7], v[170:173], v[220:223], v[4:7]
	v_mfma_f32_16x16x32_bf16 v[0:3], v[188:191], v[220:223], v[0:3]
	s_barrier
	s_add_u32 s4, s4, 0x100
	s_addc_u32 s5, s5, 0
	s_add_u32 s9, s9, 0x100
	s_addc_u32 s27, s27, 0
	s_cmp_ge_i32 s28, s33
	s_mov_b32 s6, s28
	s_cbranch_scc0 .LBB0_597

; #define PG8_STAGE(bufoff, gbase, voff) do { _Pragma("unroll") for (int _i = 0; _i < 2; ++_i) \
;         __builtin_amdgcn_global_load_lds((const unsigned*)((const char*)(gbase) + (voff)[_i]), (PG8_LAS unsigned*)(lds + (bufoff) + ldsw + _i * 8192), 16, 0, 0); } while (0)
; #define PG8_LDA(dst, b, h) do { _Pragma("unroll") for (int m = 0; m < 4; ++m) _Pragma("unroll") for (int k = 0; k < 2; ++k) dst[m][k] = *(const PG8_LAS bf16x8*)(lds + PG8_SA(b, h) + aoff + m * 2048 + k * 1024); } while (0)
; #define PG8_LDB(dst, b, h) do { _Pragma("unroll") for (int n = 0; n < 2; ++n) _Pragma("unroll") for (int k = 0; k < 2; ++k) dst[n][k] = *(const PG8_LAS bf16x8*)(lds + PG8_SB(b, h) + boff + n * 2048 + k * 1024); } while (0)
; #define PG8_MMA(ai, bj, At, Bt) do { __builtin_amdgcn_s_setprio(1); _Pragma("unroll") for (int m = 0; m < 4; ++m) _Pragma("unroll") for (int n = 0; n < 2; ++n) _Pragma("unroll") for (int k = 0; k < 2; ++k) \
;         acc[ai][bj][m][n] = __builtin_amdgcn_mfma_f32_16x16x32_bf16(Bt[n][k], At[m][k], acc[ai][bj][m][n], 0, 0, 0); __builtin_amdgcn_s_setprio(0); } while (0)
; #define PG8_WAIT_V(n) asm volatile("s_waitcnt vmcnt(" #n ")" ::: "memory")
; #define PG8_WAIT_L(n) asm volatile("s_waitcnt lgkmcnt(" #n ")" ::: "memory")
; #define PG8_BAR __builtin_amdgcn_s_barrier()
; #define PG8_SCHED __builtin_amdgcn_sched_barrier(0)
; template <class Epi, class Sched, bool ALIGN_EPI = false, bool SP2 = false>
; __device__ __forceinline__ void gemm_phase(PG8_LAS unsigned char* lds, const Gemm g, const Sched& S, const Epi& E) {
;     ...
;         for (int t = 0; t < nt; t += 2) {
;             const bool last = (t == nt - 2);
;             const char* a1 = cA + (size_t)(t + 1) * kstep;
;             const char* a2 = last ? nA : cA + (size_t)(t + 2) * kstep; const char* b2 = last ? nB : cB + (size_t)(t + 2) * kstep;
;             const char* a3 = a2 + kstep; const char* b3 = b2 + kstep;
;             if (last && has_next) S.a_ready(nxt);
;             if constexpr (SP2) {
;             PG8_LDB(B0, 0, 0); PG8_LDB(B1, 0, 1); PG8_SCHED; PG8_LDA(At, 0, 0); PG8_STAGE(PG8_SA(1, 1), a1 + hstep, voffA);
;             PG8_WAIT_V(8); PG8_WAIT_L(0); PG8_BAR; PG8_MMA(0, 0, At, B0); PG8_MMA(0, 1, At, B1); PG8_BAR; PG8_SCHED;
;             PG8_LDA(At, 0, 1); PG8_STAGE(PG8_SB(0, 0), b2, voffB); PG8_STAGE(PG8_SB(0, 1), b2 + hstep, voffB); PG8_STAGE(PG8_SA(0, 0), a2, voffA);
.LBB0_1220:
	s_andn2_b64 vcc, exec, s[24:25]
	s_waitcnt vmcnt(0)
	s_waitcnt lgkmcnt(0)
	s_cbranch_vccnz .LBB0_1223
	s_add_u32 s30, s30, 0x80
	s_addc_u32 s31, s31, 0
	s_add_u32 s63, s34, 0x100
	s_addc_u32 s64, s35, 0
	s_mov_b32 s34, 0
	ds_read_b128 v[144:147], v151
	ds_read_b128 v[156:159], v151 offset:1024
	ds_read_b128 v[160:163], v151 offset:2048
	ds_read_b128 v[164:167], v151 offset:3072
	ds_read_b128 v[168:171], v152
	ds_read_b128 v[172:175], v152 offset:1024
	ds_read_b128 v[180:183], v152 offset:2048
	ds_read_b128 v[184:187], v152 offset:3072
	s_add_i32 s65, s34, 2
	s_add_u32 s66, s30, 0x80
	s_addc_u32 s35, s31, 0
	s_cmp_eq_u32 s41, s34
	s_cselect_b32 s34, s0, s66
	s_cselect_b32 s35, s1, s35
	s_cselect_b32 s67, s29, s64
	s_cselect_b32 s66, s28, s63
	v_lshl_add_u64 v[176:177], s[30:31], 0, v[136:137]
	s_add_i32 m0, s17, 0xc000
	ds_read_b128 v[188:191], v153
	ds_read_b128 v[192:195], v153 offset:1024
	ds_read_b128 v[196:199], v153 offset:2048
	ds_read_b128 v[200:203], v153 offset:3072
	ds_read_b128 v[204:207], v153 offset:4096
	ds_read_b128 v[208:211], v153 offset:5120
	ds_read_b128 v[212:215], v153 offset:6144
	ds_read_b128 v[216:219], v153 offset:7168
	global_load_lds_dwordx4 v[176:177], off
	v_lshl_add_u64 v[176:177], s[30:31], 0, v[138:139]
	s_add_i32 m0, s17, 0xe000
	s_nop 0
	global_load_lds_dwordx4 v[176:177], off
	s_waitcnt vmcnt(8)
	s_waitcnt lgkmcnt(0)
	s_barrier
	s_waitcnt lgkmcnt(0)
	v_mfma_f32_16x16x32_bf16 v[124:127], v[144:147], v[188:191], 0
	v_mfma_f32_16x16x32_bf16 v[120:123], v[160:163], v[188:191], 0
	v_mfma_f32_16x16x32_bf16 v[108:111], v[144:147], v[196:199], 0
	v_mfma_f32_16x16x32_bf16 v[104:107], v[160:163], v[196:199], 0
	v_mfma_f32_16x16x32_bf16 v[92:95], v[144:147], v[204:207], 0
	v_mfma_f32_16x16x32_bf16 v[88:91], v[160:163], v[204:207], 0
	v_mfma_f32_16x16x32_bf16 v[76:79], v[144:147], v[212:215], 0
	v_mfma_f32_16x16x32_bf16 v[72:75], v[160:163], v[212:215], 0
	v_mfma_f32_16x16x32_bf16 v[124:127], v[156:159], v[192:195], v[124:127]
	v_mfma_f32_16x16x32_bf16 v[120:123], v[164:167], v[192:195], v[120:123]
	v_mfma_f32_16x16x32_bf16 v[108:111], v[156:159], v[200:203], v[108:111]
	v_mfma_f32_16x16x32_bf16 v[104:107], v[164:167], v[200:203], v[104:107]
	v_mfma_f32_16x16x32_bf16 v[92:95], v[156:159], v[208:211], v[92:95]
	v_mfma_f32_16x16x32_bf16 v[88:91], v[164:167], v[208:211], v[88:91]
	v_mfma_f32_16x16x32_bf16 v[76:79], v[156:159], v[216:219], v[76:79]
	v_mfma_f32_16x16x32_bf16 v[72:75], v[164:167], v[216:219], v[72:75]
	v_mfma_f32_16x16x32_bf16 v[116:119], v[168:171], v[188:191], 0
	v_mfma_f32_16x16x32_bf16 v[112:115], v[180:183], v[188:191], 0
	v_mfma_f32_16x16x32_bf16 v[100:103], v[168:171], v[196:199], 0
	v_mfma_f32_16x16x32_bf16 v[96:99], v[180:183], v[196:199], 0
	v_mfma_f32_16x16x32_bf16 v[84:87], v[168:171], v[204:207], 0
	v_mfma_f32_16x16x32_bf16 v[80:83], v[180:183], v[204:207], 0
	v_mfma_f32_16x16x32_bf16 v[68:71], v[168:171], v[212:215], 0
	v_mfma_f32_16x16x32_bf16 v[64:67], v[180:183], v[212:215], 0
	v_mfma_f32_16x16x32_bf16 v[116:119], v[172:175], v[192:195], v[116:119]
	v_mfma_f32_16x16x32_bf16 v[112:115], v[184:187], v[192:195], v[112:115]
	v_mfma_f32_16x16x32_bf16 v[100:103], v[172:175], v[200:203], v[100:103]
	v_mfma_f32_16x16x32_bf16 v[96:99], v[184:187], v[200:203], v[96:99]
	v_mfma_f32_16x16x32_bf16 v[84:87], v[172:175], v[208:211], v[84:87]
	v_mfma_f32_16x16x32_bf16 v[80:83], v[184:187], v[208:211], v[80:83]
	v_mfma_f32_16x16x32_bf16 v[68:71], v[172:175], v[216:219], v[68:71]
	v_mfma_f32_16x16x32_bf16 v[64:67], v[184:187], v[216:219], v[64:67]
	s_barrier
	s_add_i32 s68, s57, s16
	v_lshl_add_u64 v[176:177], s[66:67], 0, v[130:131]
	s_mov_b32 m0, s68
	ds_read_b128 v[188:191], v153 offset:16384
	ds_read_b128 v[192:195], v153 offset:17408
	ds_read_b128 v[196:199], v153 offset:18432
	ds_read_b128 v[200:203], v153 offset:19456
	ds_read_b128 v[204:207], v153 offset:20480
	ds_read_b128 v[208:211], v153 offset:21504
	ds_read_b128 v[212:215], v153 offset:22528
	ds_read_b128 v[216:219], v153 offset:23552
	global_load_lds_dwordx4 v[176:177], off
	s_add_i32 m0, s68, 0x2000
	v_lshl_add_u64 v[178:179], s[66:67], 0, v[134:135]
	s_add_u32 s66, s66, s6
	s_addc_u32 s67, s67, s7
	s_add_i32 s68, s58, s16
	global_load_lds_dwordx4 v[178:179], off
	v_lshl_add_u64 v[220:221], s[66:67], 0, v[130:131]
	s_mov_b32 m0, s68
	v_lshl_add_u64 v[222:223], s[66:67], 0, v[134:135]
	global_load_lds_dwordx4 v[220:221], off
	s_add_i32 m0, s68, 0x2000
	v_lshl_add_u64 v[224:225], s[34:35], 0, v[128:129]
	global_load_lds_dwordx4 v[222:223], off
	s_mov_b32 m0, s17
	v_lshl_add_u64 v[226:227], s[34:35], 0, v[132:133]
	global_load_lds_dwordx4 v[224:225], off
	s_mov_b32 m0, s19
	s_nop 0
	global_load_lds_dwordx4 v[226:227], off
	s_waitcnt vmcnt(8)
	s_waitcnt lgkmcnt(0)
	s_barrier
; #define PG8_STAGE(bufoff, gbase, voff) do { _Pragma("unroll") for (int _i = 0; _i < 2; ++_i) \
;         __builtin_amdgcn_global_load_lds((const unsigned*)((const char*)(gbase) + (voff)[_i]), (PG8_LAS unsigned*)(lds + (bufoff) + ldsw + _i * 8192), 16, 0, 0); } while (0)
; #define PG8_LDA(dst, b, h) do { _Pragma("unroll") for (int m = 0; m < 4; ++m) _Pragma("unroll") for (int k = 0; k < 2; ++k) dst[m][k] = *(const PG8_LAS bf16x8*)(lds + PG8_SA(b, h) + aoff + m * 2048 + k * 1024); } while (0)
; #define PG8_LDB(dst, b, h) do { _Pragma("unroll") for (int n = 0; n < 2; ++n) _Pragma("unroll") for (int k = 0; k < 2; ++k) dst[n][k] = *(const PG8_LAS bf16x8*)(lds + PG8_SB(b, h) + boff + n * 2048 + k * 1024); } while (0)
; #define PG8_MMA(ai, bj, At, Bt) do { __builtin_amdgcn_s_setprio(1); _Pragma("unroll") for (int m = 0; m < 4; ++m) _Pragma("unroll") for (int n = 0; n < 2; ++n) _Pragma("unroll") for (int k = 0; k < 2; ++k) \
;         acc[ai][bj][m][n] = __builtin_amdgcn_mfma_f32_16x16x32_bf16(Bt[n][k], At[m][k], acc[ai][bj][m][n], 0, 0, 0); __builtin_amdgcn_s_setprio(0); } while (0)
; #define PG8_WAIT_V(n) asm volatile("s_waitcnt vmcnt(" #n ")" ::: "memory")
; #define PG8_WAIT_L(n) asm volatile("s_waitcnt lgkmcnt(" #n ")" ::: "memory")
; #define PG8_BAR __builtin_amdgcn_s_barrier()
; #define PG8_SCHED __builtin_amdgcn_sched_barrier(0)
; template <class Epi, class Sched, bool ALIGN_EPI = false, bool SP2 = false>
; __device__ __forceinline__ void gemm_phase(PG8_LAS unsigned char* lds, const Gemm g, const Sched& S, const Epi& E) {
;     ...
;             PG8_LDA(At, 0, 1); PG8_STAGE(PG8_SB(0, 0), b2, voffB); PG8_STAGE(PG8_SB(0, 1), b2 + hstep, voffB); PG8_STAGE(PG8_SA(0, 0), a2, voffA);
;             PG8_WAIT_V(8); PG8_WAIT_L(0); PG8_BAR; PG8_MMA(1, 0, At, B0); PG8_MMA(1, 1, At, B1); PG8_BAR; PG8_SCHED;
;             PG8_LDB(B0, 1, 0); PG8_LDB(B1, 1, 1); PG8_SCHED; PG8_LDA(At, 1, 0); PG8_STAGE(PG8_SA(0, 1), a2 + hstep, voffA);
;             PG8_WAIT_V(8); PG8_WAIT_L(0); PG8_BAR; PG8_MMA(0, 0, At, B0); PG8_MMA(0, 1, At, B1); PG8_BAR; PG8_SCHED;
	s_waitcnt lgkmcnt(0)
	v_mfma_f32_16x16x32_bf16 v[60:63], v[144:147], v[188:191], 0
	v_mfma_f32_16x16x32_bf16 v[56:59], v[160:163], v[188:191], 0
	v_mfma_f32_16x16x32_bf16 v[44:47], v[144:147], v[196:199], 0
	v_mfma_f32_16x16x32_bf16 v[40:43], v[160:163], v[196:199], 0
	v_mfma_f32_16x16x32_bf16 v[28:31], v[144:147], v[204:207], 0
	v_mfma_f32_16x16x32_bf16 v[24:27], v[160:163], v[204:207], 0
	v_mfma_f32_16x16x32_bf16 v[12:15], v[144:147], v[212:215], 0
	v_mfma_f32_16x16x32_bf16 v[8:11], v[160:163], v[212:215], 0
	v_mfma_f32_16x16x32_bf16 v[60:63], v[156:159], v[192:195], v[60:63]
	v_mfma_f32_16x16x32_bf16 v[56:59], v[164:167], v[192:195], v[56:59]
	v_mfma_f32_16x16x32_bf16 v[44:47], v[156:159], v[200:203], v[44:47]
	v_mfma_f32_16x16x32_bf16 v[40:43], v[164:167], v[200:203], v[40:43]
	v_mfma_f32_16x16x32_bf16 v[28:31], v[156:159], v[208:211], v[28:31]
	v_mfma_f32_16x16x32_bf16 v[24:27], v[164:167], v[208:211], v[24:27]
	v_mfma_f32_16x16x32_bf16 v[12:15], v[156:159], v[216:219], v[12:15]
	v_mfma_f32_16x16x32_bf16 v[8:11], v[164:167], v[216:219], v[8:11]
	v_mfma_f32_16x16x32_bf16 v[52:55], v[168:171], v[188:191], 0
	v_mfma_f32_16x16x32_bf16 v[48:51], v[180:183], v[188:191], 0
	v_mfma_f32_16x16x32_bf16 v[36:39], v[168:171], v[196:199], 0
	v_mfma_f32_16x16x32_bf16 v[32:35], v[180:183], v[196:199], 0
	v_mfma_f32_16x16x32_bf16 v[20:23], v[168:171], v[204:207], 0
	v_mfma_f32_16x16x32_bf16 v[16:19], v[180:183], v[204:207], 0
	v_mfma_f32_16x16x32_bf16 v[4:7], v[168:171], v[212:215], 0
	v_mfma_f32_16x16x32_bf16 v[0:3], v[180:183], v[212:215], 0
	v_mfma_f32_16x16x32_bf16 v[52:55], v[172:175], v[192:195], v[52:55]
	v_mfma_f32_16x16x32_bf16 v[48:51], v[184:187], v[192:195], v[48:51]
	v_mfma_f32_16x16x32_bf16 v[36:39], v[172:175], v[200:203], v[36:39]
	v_mfma_f32_16x16x32_bf16 v[32:35], v[184:187], v[200:203], v[32:35]
	v_mfma_f32_16x16x32_bf16 v[20:23], v[172:175], v[208:211], v[20:23]
	v_mfma_f32_16x16x32_bf16 v[16:19], v[184:187], v[208:211], v[16:19]
	v_mfma_f32_16x16x32_bf16 v[4:7], v[172:175], v[216:219], v[4:7]
	v_mfma_f32_16x16x32_bf16 v[0:3], v[184:187], v[216:219], v[0:3]
	s_barrier
	s_add_i32 s66, 0, 0x18000
	v_add_u32_e32 v155, s66, v149
	s_add_i32 s67, 0, 0x1c000
	ds_read_b128 v[144:147], v155
	ds_read_b128 v[156:159], v155 offset:1024
	ds_read_b128 v[160:163], v155 offset:2048
	ds_read_b128 v[164:167], v155 offset:3072
	v_add_u32_e32 v155, s67, v149
	ds_read_b128 v[168:171], v155
	ds_read_b128 v[172:175], v155 offset:1024
	ds_read_b128 v[180:183], v155 offset:2048
	ds_read_b128 v[184:187], v155 offset:3072
	s_add_u32 s34, s34, s6
	s_addc_u32 s35, s35, s7
	s_mov_b32 m0, s33
	v_lshl_add_u64 v[228:229], s[34:35], 0, v[128:129]
	ds_read_b128 v[188:191], v153 offset:32768
	ds_read_b128 v[192:195], v153 offset:33792
	ds_read_b128 v[196:199], v153 offset:34816
	ds_read_b128 v[200:203], v153 offset:35840
	ds_read_b128 v[204:207], v153 offset:36864
	ds_read_b128 v[208:211], v153 offset:37888
	ds_read_b128 v[212:215], v153 offset:38912
	ds_read_b128 v[216:219], v153 offset:39936
	global_load_lds_dwordx4 v[228:229], off
	v_lshl_add_u64 v[228:229], s[34:35], 0, v[132:133]
	s_mov_b32 m0, s36
	s_nop 0
	global_load_lds_dwordx4 v[228:229], off
	s_waitcnt vmcnt(8)
	s_waitcnt lgkmcnt(0)
	s_barrier
	s_waitcnt lgkmcnt(0)
	v_mfma_f32_16x16x32_bf16 v[124:127], v[144:147], v[188:191], v[124:127]
	v_mfma_f32_16x16x32_bf16 v[120:123], v[160:163], v[188:191], v[120:123]
	v_mfma_f32_16x16x32_bf16 v[108:111], v[144:147], v[196:199], v[108:111]
	v_mfma_f32_16x16x32_bf16 v[104:107], v[160:163], v[196:199], v[104:107]
	v_mfma_f32_16x16x32_bf16 v[92:95], v[144:147], v[204:207], v[92:95]
	v_mfma_f32_16x16x32_bf16 v[88:91], v[160:163], v[204:207], v[88:91]
	v_mfma_f32_16x16x32_bf16 v[76:79], v[144:147], v[212:215], v[76:79]
	v_mfma_f32_16x16x32_bf16 v[72:75], v[160:163], v[212:215], v[72:75]
	v_mfma_f32_16x16x32_bf16 v[124:127], v[156:159], v[192:195], v[124:127]
	v_mfma_f32_16x16x32_bf16 v[120:123], v[164:167], v[192:195], v[120:123]
	v_mfma_f32_16x16x32_bf16 v[108:111], v[156:159], v[200:203], v[108:111]
	v_mfma_f32_16x16x32_bf16 v[104:107], v[164:167], v[200:203], v[104:107]
	v_mfma_f32_16x16x32_bf16 v[92:95], v[156:159], v[208:211], v[92:95]
	v_mfma_f32_16x16x32_bf16 v[88:91], v[164:167], v[208:211], v[88:91]
	v_mfma_f32_16x16x32_bf16 v[76:79], v[156:159], v[216:219], v[76:79]
	v_mfma_f32_16x16x32_bf16 v[72:75], v[164:167], v[216:219], v[72:75]
	v_mfma_f32_16x16x32_bf16 v[116:119], v[168:171], v[188:191], v[116:119]
	v_mfma_f32_16x16x32_bf16 v[112:115], v[180:183], v[188:191], v[112:115]
	v_mfma_f32_16x16x32_bf16 v[100:103], v[168:171], v[196:199], v[100:103]
	v_mfma_f32_16x16x32_bf16 v[96:99], v[180:183], v[196:199], v[96:99]
	v_mfma_f32_16x16x32_bf16 v[84:87], v[168:171], v[204:207], v[84:87]
	v_mfma_f32_16x16x32_bf16 v[80:83], v[180:183], v[204:207], v[80:83]
	v_mfma_f32_16x16x32_bf16 v[68:71], v[168:171], v[212:215], v[68:71]
	v_mfma_f32_16x16x32_bf16 v[64:67], v[180:183], v[212:215], v[64:67]
	v_mfma_f32_16x16x32_bf16 v[116:119], v[172:175], v[192:195], v[116:119]
	v_mfma_f32_16x16x32_bf16 v[112:115], v[184:187], v[192:195], v[112:115]
	v_mfma_f32_16x16x32_bf16 v[100:103], v[172:175], v[200:203], v[100:103]
	v_mfma_f32_16x16x32_bf16 v[96:99], v[184:187], v[200:203], v[96:99]
	v_mfma_f32_16x16x32_bf16 v[84:87], v[172:175], v[208:211], v[84:87]
	v_mfma_f32_16x16x32_bf16 v[80:83], v[184:187], v[208:211], v[80:83]
	v_mfma_f32_16x16x32_bf16 v[68:71], v[172:175], v[216:219], v[68:71]
	v_mfma_f32_16x16x32_bf16 v[64:67], v[184:187], v[216:219], v[64:67]
	s_barrier
; #define PG8_STAGE(bufoff, gbase, voff) do { _Pragma("unroll") for (int _i = 0; _i < 2; ++_i) \
;         __builtin_amdgcn_global_load_lds((const unsigned*)((const char*)(gbase) + (voff)[_i]), (PG8_LAS unsigned*)(lds + (bufoff) + ldsw + _i * 8192), 16, 0, 0); } while (0)
; #define PG8_LDA(dst, b, h) do { _Pragma("unroll") for (int m = 0; m < 4; ++m) _Pragma("unroll") for (int k = 0; k < 2; ++k) dst[m][k] = *(const PG8_LAS bf16x8*)(lds + PG8_SA(b, h) + aoff + m * 2048 + k * 1024); } while (0)
; #define PG8_LDB(dst, b, h) do { _Pragma("unroll") for (int n = 0; n < 2; ++n) _Pragma("unroll") for (int k = 0; k < 2; ++k) dst[n][k] = *(const PG8_LAS bf16x8*)(lds + PG8_SB(b, h) + boff + n * 2048 + k * 1024); } while (0)
; #define PG8_MMA(ai, bj, At, Bt) do { __builtin_amdgcn_s_setprio(1); _Pragma("unroll") for (int m = 0; m < 4; ++m) _Pragma("unroll") for (int n = 0; n < 2; ++n) _Pragma("unroll") for (int k = 0; k < 2; ++k) \
;         acc[ai][bj][m][n] = __builtin_amdgcn_mfma_f32_16x16x32_bf16(Bt[n][k], At[m][k], acc[ai][bj][m][n], 0, 0, 0); __builtin_amdgcn_s_setprio(0); } while (0)
; #define PG8_WAIT_V(n) asm volatile("s_waitcnt vmcnt(" #n ")" ::: "memory")
; #define PG8_WAIT_L(n) asm volatile("s_waitcnt lgkmcnt(" #n ")" ::: "memory")
; #define PG8_BAR __builtin_amdgcn_s_barrier()
; #define PG8_SCHED __builtin_amdgcn_sched_barrier(0)
; template <class Epi, class Sched, bool ALIGN_EPI = false, bool SP2 = false>
; __device__ __forceinline__ void gemm_phase(PG8_LAS unsigned char* lds, const Gemm g, const Sched& S, const Epi& E) {
;     ...
;         for (int t = 0; t < nt; t += 2) {
;             const bool last = (t == nt - 2);
;             const char* a1 = cA + (size_t)(t + 1) * kstep;
;             const char* a2 = last ? nA : cA + (size_t)(t + 2) * kstep; const char* b2 = last ? nB : cB + (size_t)(t + 2) * kstep;
;             const char* a3 = a2 + kstep; const char* b3 = b2 + kstep;
;             if (last && has_next) S.a_ready(nxt);
;             if constexpr (SP2) {
;             PG8_LDB(B0, 0, 0); PG8_LDB(B1, 0, 1); PG8_SCHED; PG8_LDA(At, 0, 0); PG8_STAGE(PG8_SA(1, 1), a1 + hstep, voffA);
;     ...
;             PG8_LDA(At, 1, 1); PG8_STAGE(PG8_SB(1, 0), b3, voffB); PG8_STAGE(PG8_SB(1, 1), b3 + hstep, voffB); PG8_STAGE(PG8_SA(1, 0), a3, voffA);
;             PG8_WAIT_V(8); PG8_WAIT_L(0); PG8_BAR; PG8_MMA(1, 0, At, B0); PG8_MMA(1, 1, At, B1); PG8_BAR; PG8_SCHED;
	s_add_i32 s34, s66, s16
	v_lshl_add_u64 v[176:177], v[176:177], 0, s[22:23]
	s_mov_b32 m0, s34
	ds_read_b128 v[188:191], v153 offset:49152
	ds_read_b128 v[192:195], v153 offset:50176
	ds_read_b128 v[196:199], v153 offset:51200
	ds_read_b128 v[200:203], v153 offset:52224
	ds_read_b128 v[204:207], v153 offset:53248
	ds_read_b128 v[208:211], v153 offset:54272
	ds_read_b128 v[212:215], v153 offset:55296
	ds_read_b128 v[216:219], v153 offset:56320
	global_load_lds_dwordx4 v[176:177], off
	v_lshl_add_u64 v[176:177], v[178:179], 0, s[22:23]
	s_add_i32 m0, s34, 0x2000
	s_add_i32 s34, s67, s16
	global_load_lds_dwordx4 v[176:177], off
	v_lshl_add_u64 v[176:177], v[220:221], 0, s[22:23]
	s_mov_b32 m0, s34
	s_nop 0
	global_load_lds_dwordx4 v[176:177], off
	v_lshl_add_u64 v[176:177], v[222:223], 0, s[22:23]
	s_add_i32 m0, s34, 0x2000
	s_nop 0
	global_load_lds_dwordx4 v[176:177], off
	v_lshl_add_u64 v[176:177], v[224:225], 0, s[22:23]
	s_mov_b32 m0, s37
	s_nop 0
	global_load_lds_dwordx4 v[176:177], off
	v_lshl_add_u64 v[176:177], v[226:227], 0, s[22:23]
	s_mov_b32 m0, s38
	s_nop 0
	global_load_lds_dwordx4 v[176:177], off
	s_waitcnt vmcnt(8)
	s_waitcnt lgkmcnt(0)
	s_barrier
	s_waitcnt lgkmcnt(0)
	v_mfma_f32_16x16x32_bf16 v[60:63], v[144:147], v[188:191], v[60:63]
	v_mfma_f32_16x16x32_bf16 v[56:59], v[160:163], v[188:191], v[56:59]
	v_mfma_f32_16x16x32_bf16 v[44:47], v[144:147], v[196:199], v[44:47]
	v_mfma_f32_16x16x32_bf16 v[40:43], v[160:163], v[196:199], v[40:43]
	v_mfma_f32_16x16x32_bf16 v[28:31], v[144:147], v[204:207], v[28:31]
	v_mfma_f32_16x16x32_bf16 v[24:27], v[160:163], v[204:207], v[24:27]
	v_mfma_f32_16x16x32_bf16 v[12:15], v[144:147], v[212:215], v[12:15]
	v_mfma_f32_16x16x32_bf16 v[8:11], v[160:163], v[212:215], v[8:11]
	v_mfma_f32_16x16x32_bf16 v[60:63], v[156:159], v[192:195], v[60:63]
	v_mfma_f32_16x16x32_bf16 v[56:59], v[164:167], v[192:195], v[56:59]
	v_mfma_f32_16x16x32_bf16 v[44:47], v[156:159], v[200:203], v[44:47]
	v_mfma_f32_16x16x32_bf16 v[40:43], v[164:167], v[200:203], v[40:43]
	v_mfma_f32_16x16x32_bf16 v[28:31], v[156:159], v[208:211], v[28:31]
	v_mfma_f32_16x16x32_bf16 v[24:27], v[164:167], v[208:211], v[24:27]
	v_mfma_f32_16x16x32_bf16 v[12:15], v[156:159], v[216:219], v[12:15]
	v_mfma_f32_16x16x32_bf16 v[8:11], v[164:167], v[216:219], v[8:11]
	v_mfma_f32_16x16x32_bf16 v[52:55], v[168:171], v[188:191], v[52:55]
	v_mfma_f32_16x16x32_bf16 v[48:51], v[180:183], v[188:191], v[48:51]
	v_mfma_f32_16x16x32_bf16 v[36:39], v[168:171], v[196:199], v[36:39]
	v_mfma_f32_16x16x32_bf16 v[32:35], v[180:183], v[196:199], v[32:35]
	v_mfma_f32_16x16x32_bf16 v[20:23], v[168:171], v[204:207], v[20:23]
	v_mfma_f32_16x16x32_bf16 v[16:19], v[180:183], v[204:207], v[16:19]
	v_mfma_f32_16x16x32_bf16 v[4:7], v[168:171], v[212:215], v[4:7]
	v_mfma_f32_16x16x32_bf16 v[0:3], v[180:183], v[212:215], v[0:3]
	v_mfma_f32_16x16x32_bf16 v[52:55], v[172:175], v[192:195], v[52:55]
	v_mfma_f32_16x16x32_bf16 v[48:51], v[184:187], v[192:195], v[48:51]
	v_mfma_f32_16x16x32_bf16 v[36:39], v[172:175], v[200:203], v[36:39]
	v_mfma_f32_16x16x32_bf16 v[32:35], v[184:187], v[200:203], v[32:35]
	v_mfma_f32_16x16x32_bf16 v[20:23], v[172:175], v[208:211], v[20:23]
	v_mfma_f32_16x16x32_bf16 v[16:19], v[184:187], v[208:211], v[16:19]
	v_mfma_f32_16x16x32_bf16 v[4:7], v[172:175], v[216:219], v[4:7]
	v_mfma_f32_16x16x32_bf16 v[0:3], v[184:187], v[216:219], v[0:3]
	s_barrier
	s_add_u32 s30, s30, 0x100
	s_addc_u32 s31, s31, 0
	s_add_u32 s63, s63, 0x100
	s_addc_u32 s64, s64, 0
	s_cmp_ge_i32 s65, s40
	s_mov_b32 s34, s65
	s_cbranch_scc0 .LBB0_1222
	s_branch .Lpeel_x3
.LBB0_1222:
	ds_read_b128 v[144:147], v151
	ds_read_b128 v[156:159], v151 offset:1024
	ds_read_b128 v[160:163], v151 offset:2048
	ds_read_b128 v[164:167], v151 offset:3072
	ds_read_b128 v[168:171], v152
	ds_read_b128 v[172:175], v152 offset:1024
	ds_read_b128 v[180:183], v152 offset:2048
	ds_read_b128 v[184:187], v152 offset:3072
	s_add_i32 s65, s34, 2
	s_add_u32 s66, s30, 0x80
	s_addc_u32 s35, s31, 0
	s_cmp_eq_u32 s41, s34
	s_cselect_b32 s34, s0, s66
	s_cselect_b32 s35, s1, s35
	s_cselect_b32 s67, s29, s64
	s_cselect_b32 s66, s28, s63
	v_lshl_add_u64 v[176:177], s[30:31], 0, v[136:137]
	s_add_i32 m0, s17, 0xc000
	ds_read_b128 v[188:191], v153
	ds_read_b128 v[192:195], v153 offset:1024
	ds_read_b128 v[196:199], v153 offset:2048
	ds_read_b128 v[200:203], v153 offset:3072
	ds_read_b128 v[204:207], v153 offset:4096
	ds_read_b128 v[208:211], v153 offset:5120
	ds_read_b128 v[212:215], v153 offset:6144
	ds_read_b128 v[216:219], v153 offset:7168
	global_load_lds_dwordx4 v[176:177], off
	v_lshl_add_u64 v[176:177], s[30:31], 0, v[138:139]
	s_add_i32 m0, s17, 0xe000
	s_nop 0
	global_load_lds_dwordx4 v[176:177], off
	s_waitcnt vmcnt(8)
	s_waitcnt lgkmcnt(0)
	s_barrier
; #define PG8_STAGE(bufoff, gbase, voff) do { _Pragma("unroll") for (int _i = 0; _i < 2; ++_i) \
;         __builtin_amdgcn_global_load_lds((const unsigned*)((const char*)(gbase) + (voff)[_i]), (PG8_LAS unsigned*)(lds + (bufoff) + ldsw + _i * 8192), 16, 0, 0); } while (0)
; #define PG8_LDA(dst, b, h) do { _Pragma("unroll") for (int m = 0; m < 4; ++m) _Pragma("unroll") for (int k = 0; k < 2; ++k) dst[m][k] = *(const PG8_LAS bf16x8*)(lds + PG8_SA(b, h) + aoff + m * 2048 + k * 1024); } while (0)
; #define PG8_MMA(ai, bj, At, Bt) do { __builtin_amdgcn_s_setprio(1); _Pragma("unroll") for (int m = 0; m < 4; ++m) _Pragma("unroll") for (int n = 0; n < 2; ++n) _Pragma("unroll") for (int k = 0; k < 2; ++k) \
;         acc[ai][bj][m][n] = __builtin_amdgcn_mfma_f32_16x16x32_bf16(Bt[n][k], At[m][k], acc[ai][bj][m][n], 0, 0, 0); __builtin_amdgcn_s_setprio(0); } while (0)
; #define PG8_WAIT_V(n) asm volatile("s_waitcnt vmcnt(" #n ")" ::: "memory")
; #define PG8_WAIT_L(n) asm volatile("s_waitcnt lgkmcnt(" #n ")" ::: "memory")
; #define PG8_BAR __builtin_amdgcn_s_barrier()
; #define PG8_SCHED __builtin_amdgcn_sched_barrier(0)
; template <class Epi, class Sched, bool ALIGN_EPI = false, bool SP2 = false>
; __device__ __forceinline__ void gemm_phase(PG8_LAS unsigned char* lds, const Gemm g, const Sched& S, const Epi& E) {
;     ...
;             PG8_WAIT_V(8); PG8_WAIT_L(0); PG8_BAR; PG8_MMA(0, 0, At, B0); PG8_MMA(0, 1, At, B1); PG8_BAR; PG8_SCHED;
;             PG8_LDA(At, 0, 1); PG8_STAGE(PG8_SB(0, 0), b2, voffB); PG8_STAGE(PG8_SB(0, 1), b2 + hstep, voffB); PG8_STAGE(PG8_SA(0, 0), a2, voffA);
;             PG8_WAIT_V(8); PG8_WAIT_L(0); PG8_BAR; PG8_MMA(1, 0, At, B0); PG8_MMA(1, 1, At, B1); PG8_BAR; PG8_SCHED;
	s_waitcnt lgkmcnt(0)
	v_mfma_f32_16x16x32_bf16 v[124:127], v[144:147], v[188:191], v[124:127]
	v_mfma_f32_16x16x32_bf16 v[120:123], v[160:163], v[188:191], v[120:123]
	v_mfma_f32_16x16x32_bf16 v[108:111], v[144:147], v[196:199], v[108:111]
	v_mfma_f32_16x16x32_bf16 v[104:107], v[160:163], v[196:199], v[104:107]
	v_mfma_f32_16x16x32_bf16 v[92:95], v[144:147], v[204:207], v[92:95]
	v_mfma_f32_16x16x32_bf16 v[88:91], v[160:163], v[204:207], v[88:91]
	v_mfma_f32_16x16x32_bf16 v[76:79], v[144:147], v[212:215], v[76:79]
	v_mfma_f32_16x16x32_bf16 v[72:75], v[160:163], v[212:215], v[72:75]
	v_mfma_f32_16x16x32_bf16 v[124:127], v[156:159], v[192:195], v[124:127]
	v_mfma_f32_16x16x32_bf16 v[120:123], v[164:167], v[192:195], v[120:123]
	v_mfma_f32_16x16x32_bf16 v[108:111], v[156:159], v[200:203], v[108:111]
	v_mfma_f32_16x16x32_bf16 v[104:107], v[164:167], v[200:203], v[104:107]
	v_mfma_f32_16x16x32_bf16 v[92:95], v[156:159], v[208:211], v[92:95]
	v_mfma_f32_16x16x32_bf16 v[88:91], v[164:167], v[208:211], v[88:91]
	v_mfma_f32_16x16x32_bf16 v[76:79], v[156:159], v[216:219], v[76:79]
	v_mfma_f32_16x16x32_bf16 v[72:75], v[164:167], v[216:219], v[72:75]
	v_mfma_f32_16x16x32_bf16 v[116:119], v[168:171], v[188:191], v[116:119]
	v_mfma_f32_16x16x32_bf16 v[112:115], v[180:183], v[188:191], v[112:115]
	v_mfma_f32_16x16x32_bf16 v[100:103], v[168:171], v[196:199], v[100:103]
	v_mfma_f32_16x16x32_bf16 v[96:99], v[180:183], v[196:199], v[96:99]
	v_mfma_f32_16x16x32_bf16 v[84:87], v[168:171], v[204:207], v[84:87]
	v_mfma_f32_16x16x32_bf16 v[80:83], v[180:183], v[204:207], v[80:83]
	v_mfma_f32_16x16x32_bf16 v[68:71], v[168:171], v[212:215], v[68:71]
	v_mfma_f32_16x16x32_bf16 v[64:67], v[180:183], v[212:215], v[64:67]
	v_mfma_f32_16x16x32_bf16 v[116:119], v[172:175], v[192:195], v[116:119]
	v_mfma_f32_16x16x32_bf16 v[112:115], v[184:187], v[192:195], v[112:115]
	v_mfma_f32_16x16x32_bf16 v[100:103], v[172:175], v[200:203], v[100:103]
	v_mfma_f32_16x16x32_bf16 v[96:99], v[184:187], v[200:203], v[96:99]
	v_mfma_f32_16x16x32_bf16 v[84:87], v[172:175], v[208:211], v[84:87]
	v_mfma_f32_16x16x32_bf16 v[80:83], v[184:187], v[208:211], v[80:83]
	v_mfma_f32_16x16x32_bf16 v[68:71], v[172:175], v[216:219], v[68:71]
	v_mfma_f32_16x16x32_bf16 v[64:67], v[184:187], v[216:219], v[64:67]
	s_barrier
	s_add_i32 s68, s57, s16
	v_lshl_add_u64 v[176:177], s[66:67], 0, v[130:131]
	s_mov_b32 m0, s68
	ds_read_b128 v[188:191], v153 offset:16384
	ds_read_b128 v[192:195], v153 offset:17408
	ds_read_b128 v[196:199], v153 offset:18432
	ds_read_b128 v[200:203], v153 offset:19456
	ds_read_b128 v[204:207], v153 offset:20480
	ds_read_b128 v[208:211], v153 offset:21504
	ds_read_b128 v[212:215], v153 offset:22528
	ds_read_b128 v[216:219], v153 offset:23552
	global_load_lds_dwordx4 v[176:177], off
	s_add_i32 m0, s68, 0x2000
	v_lshl_add_u64 v[178:179], s[66:67], 0, v[134:135]
	s_add_u32 s66, s66, s6
	s_addc_u32 s67, s67, s7
	s_add_i32 s68, s58, s16
	global_load_lds_dwordx4 v[178:179], off
	v_lshl_add_u64 v[220:221], s[66:67], 0, v[130:131]
	s_mov_b32 m0, s68
	v_lshl_add_u64 v[222:223], s[66:67], 0, v[134:135]
	global_load_lds_dwordx4 v[220:221], off
	s_add_i32 m0, s68, 0x2000
	v_lshl_add_u64 v[224:225], s[34:35], 0, v[128:129]
	global_load_lds_dwordx4 v[222:223], off
	s_mov_b32 m0, s17
	v_lshl_add_u64 v[226:227], s[34:35], 0, v[132:133]
	global_load_lds_dwordx4 v[224:225], off
	s_mov_b32 m0, s19
	s_nop 0
	global_load_lds_dwordx4 v[226:227], off
	s_waitcnt vmcnt(8)
	s_waitcnt lgkmcnt(0)
	s_barrier
	s_waitcnt lgkmcnt(0)
	v_mfma_f32_16x16x32_bf16 v[60:63], v[144:147], v[188:191], v[60:63]
	v_mfma_f32_16x16x32_bf16 v[56:59], v[160:163], v[188:191], v[56:59]
	v_mfma_f32_16x16x32_bf16 v[44:47], v[144:147], v[196:199], v[44:47]
	v_mfma_f32_16x16x32_bf16 v[40:43], v[160:163], v[196:199], v[40:43]
	v_mfma_f32_16x16x32_bf16 v[28:31], v[144:147], v[204:207], v[28:31]
	v_mfma_f32_16x16x32_bf16 v[24:27], v[160:163], v[204:207], v[24:27]
	v_mfma_f32_16x16x32_bf16 v[12:15], v[144:147], v[212:215], v[12:15]
	v_mfma_f32_16x16x32_bf16 v[8:11], v[160:163], v[212:215], v[8:11]
	v_mfma_f32_16x16x32_bf16 v[60:63], v[156:159], v[192:195], v[60:63]
	v_mfma_f32_16x16x32_bf16 v[56:59], v[164:167], v[192:195], v[56:59]
	v_mfma_f32_16x16x32_bf16 v[44:47], v[156:159], v[200:203], v[44:47]
	v_mfma_f32_16x16x32_bf16 v[40:43], v[164:167], v[200:203], v[40:43]
	v_mfma_f32_16x16x32_bf16 v[28:31], v[156:159], v[208:211], v[28:31]
	v_mfma_f32_16x16x32_bf16 v[24:27], v[164:167], v[208:211], v[24:27]
	v_mfma_f32_16x16x32_bf16 v[12:15], v[156:159], v[216:219], v[12:15]
	v_mfma_f32_16x16x32_bf16 v[8:11], v[164:167], v[216:219], v[8:11]
	v_mfma_f32_16x16x32_bf16 v[52:55], v[168:171], v[188:191], v[52:55]
	v_mfma_f32_16x16x32_bf16 v[48:51], v[180:183], v[188:191], v[48:51]
	v_mfma_f32_16x16x32_bf16 v[36:39], v[168:171], v[196:199], v[36:39]
	v_mfma_f32_16x16x32_bf16 v[32:35], v[180:183], v[196:199], v[32:35]
	v_mfma_f32_16x16x32_bf16 v[20:23], v[168:171], v[204:207], v[20:23]
	v_mfma_f32_16x16x32_bf16 v[16:19], v[180:183], v[204:207], v[16:19]
	v_mfma_f32_16x16x32_bf16 v[4:7], v[168:171], v[212:215], v[4:7]
	v_mfma_f32_16x16x32_bf16 v[0:3], v[180:183], v[212:215], v[0:3]
	v_mfma_f32_16x16x32_bf16 v[52:55], v[172:175], v[192:195], v[52:55]
	v_mfma_f32_16x16x32_bf16 v[48:51], v[184:187], v[192:195], v[48:51]
	v_mfma_f32_16x16x32_bf16 v[36:39], v[172:175], v[200:203], v[36:39]
	v_mfma_f32_16x16x32_bf16 v[32:35], v[184:187], v[200:203], v[32:35]
	v_mfma_f32_16x16x32_bf16 v[20:23], v[172:175], v[208:211], v[20:23]
	v_mfma_f32_16x16x32_bf16 v[16:19], v[184:187], v[208:211], v[16:19]
	v_mfma_f32_16x16x32_bf16 v[4:7], v[172:175], v[216:219], v[4:7]
	v_mfma_f32_16x16x32_bf16 v[0:3], v[184:187], v[216:219], v[0:3]
	s_barrier
; #define PG8_STAGE(bufoff, gbase, voff) do { _Pragma("unroll") for (int _i = 0; _i < 2; ++_i) \
;         __builtin_amdgcn_global_load_lds((const unsigned*)((const char*)(gbase) + (voff)[_i]), (PG8_LAS unsigned*)(lds + (bufoff) + ldsw + _i * 8192), 16, 0, 0); } while (0)
; #define PG8_LDA(dst, b, h) do { _Pragma("unroll") for (int m = 0; m < 4; ++m) _Pragma("unroll") for (int k = 0; k < 2; ++k) dst[m][k] = *(const PG8_LAS bf16x8*)(lds + PG8_SA(b, h) + aoff + m * 2048 + k * 1024); } while (0)
; #define PG8_LDB(dst, b, h) do { _Pragma("unroll") for (int n = 0; n < 2; ++n) _Pragma("unroll") for (int k = 0; k < 2; ++k) dst[n][k] = *(const PG8_LAS bf16x8*)(lds + PG8_SB(b, h) + boff + n * 2048 + k * 1024); } while (0)
; #define PG8_MMA(ai, bj, At, Bt) do { __builtin_amdgcn_s_setprio(1); _Pragma("unroll") for (int m = 0; m < 4; ++m) _Pragma("unroll") for (int n = 0; n < 2; ++n) _Pragma("unroll") for (int k = 0; k < 2; ++k) \
;         acc[ai][bj][m][n] = __builtin_amdgcn_mfma_f32_16x16x32_bf16(Bt[n][k], At[m][k], acc[ai][bj][m][n], 0, 0, 0); __builtin_amdgcn_s_setprio(0); } while (0)
; #define PG8_WAIT_V(n) asm volatile("s_waitcnt vmcnt(" #n ")" ::: "memory")
; #define PG8_WAIT_L(n) asm volatile("s_waitcnt lgkmcnt(" #n ")" ::: "memory")
; #define PG8_BAR __builtin_amdgcn_s_barrier()
; #define PG8_SCHED __builtin_amdgcn_sched_barrier(0)
; template <class Epi, class Sched, bool ALIGN_EPI = false, bool SP2 = false>
; __device__ __forceinline__ void gemm_phase(PG8_LAS unsigned char* lds, const Gemm g, const Sched& S, const Epi& E) {
;     ...
;             PG8_LDB(B0, 1, 0); PG8_LDB(B1, 1, 1); PG8_SCHED; PG8_LDA(At, 1, 0); PG8_STAGE(PG8_SA(0, 1), a2 + hstep, voffA);
;             PG8_WAIT_V(8); PG8_WAIT_L(0); PG8_BAR; PG8_MMA(0, 0, At, B0); PG8_MMA(0, 1, At, B1); PG8_BAR; PG8_SCHED;
;             PG8_LDA(At, 1, 1); PG8_STAGE(PG8_SB(1, 0), b3, voffB); PG8_STAGE(PG8_SB(1, 1), b3 + hstep, voffB); PG8_STAGE(PG8_SA(1, 0), a3, voffA);
;             PG8_WAIT_V(8); PG8_WAIT_L(0); PG8_BAR; PG8_MMA(1, 0, At, B0); PG8_MMA(1, 1, At, B1); PG8_BAR; PG8_SCHED;
	s_add_i32 s66, 0, 0x18000
	v_add_u32_e32 v155, s66, v149
	s_add_i32 s67, 0, 0x1c000
	ds_read_b128 v[144:147], v155
	ds_read_b128 v[156:159], v155 offset:1024
	ds_read_b128 v[160:163], v155 offset:2048
	ds_read_b128 v[164:167], v155 offset:3072
	v_add_u32_e32 v155, s67, v149
	ds_read_b128 v[168:171], v155
	ds_read_b128 v[172:175], v155 offset:1024
	ds_read_b128 v[180:183], v155 offset:2048
	ds_read_b128 v[184:187], v155 offset:3072
	s_add_u32 s34, s34, s6
	s_addc_u32 s35, s35, s7
	s_mov_b32 m0, s33
	v_lshl_add_u64 v[228:229], s[34:35], 0, v[128:129]
	ds_read_b128 v[188:191], v153 offset:32768
	ds_read_b128 v[192:195], v153 offset:33792
	ds_read_b128 v[196:199], v153 offset:34816
	ds_read_b128 v[200:203], v153 offset:35840
	ds_read_b128 v[204:207], v153 offset:36864
	ds_read_b128 v[208:211], v153 offset:37888
	ds_read_b128 v[212:215], v153 offset:38912
	ds_read_b128 v[216:219], v153 offset:39936
	global_load_lds_dwordx4 v[228:229], off
	v_lshl_add_u64 v[228:229], s[34:35], 0, v[132:133]
	s_mov_b32 m0, s36
	s_nop 0
	global_load_lds_dwordx4 v[228:229], off
	s_waitcnt vmcnt(8)
	s_waitcnt lgkmcnt(0)
	s_barrier
	s_waitcnt lgkmcnt(0)
	v_mfma_f32_16x16x32_bf16 v[124:127], v[144:147], v[188:191], v[124:127]
	v_mfma_f32_16x16x32_bf16 v[120:123], v[160:163], v[188:191], v[120:123]
	v_mfma_f32_16x16x32_bf16 v[108:111], v[144:147], v[196:199], v[108:111]
	v_mfma_f32_16x16x32_bf16 v[104:107], v[160:163], v[196:199], v[104:107]
	v_mfma_f32_16x16x32_bf16 v[92:95], v[144:147], v[204:207], v[92:95]
	v_mfma_f32_16x16x32_bf16 v[88:91], v[160:163], v[204:207], v[88:91]
	v_mfma_f32_16x16x32_bf16 v[76:79], v[144:147], v[212:215], v[76:79]
	v_mfma_f32_16x16x32_bf16 v[72:75], v[160:163], v[212:215], v[72:75]
	v_mfma_f32_16x16x32_bf16 v[124:127], v[156:159], v[192:195], v[124:127]
	v_mfma_f32_16x16x32_bf16 v[120:123], v[164:167], v[192:195], v[120:123]
	v_mfma_f32_16x16x32_bf16 v[108:111], v[156:159], v[200:203], v[108:111]
	v_mfma_f32_16x16x32_bf16 v[104:107], v[164:167], v[200:203], v[104:107]
	v_mfma_f32_16x16x32_bf16 v[92:95], v[156:159], v[208:211], v[92:95]
	v_mfma_f32_16x16x32_bf16 v[88:91], v[164:167], v[208:211], v[88:91]
	v_mfma_f32_16x16x32_bf16 v[76:79], v[156:159], v[216:219], v[76:79]
	v_mfma_f32_16x16x32_bf16 v[72:75], v[164:167], v[216:219], v[72:75]
	v_mfma_f32_16x16x32_bf16 v[116:119], v[168:171], v[188:191], v[116:119]
	v_mfma_f32_16x16x32_bf16 v[112:115], v[180:183], v[188:191], v[112:115]
	v_mfma_f32_16x16x32_bf16 v[100:103], v[168:171], v[196:199], v[100:103]
	v_mfma_f32_16x16x32_bf16 v[96:99], v[180:183], v[196:199], v[96:99]
	v_mfma_f32_16x16x32_bf16 v[84:87], v[168:171], v[204:207], v[84:87]
	v_mfma_f32_16x16x32_bf16 v[80:83], v[180:183], v[204:207], v[80:83]
	v_mfma_f32_16x16x32_bf16 v[68:71], v[168:171], v[212:215], v[68:71]
	v_mfma_f32_16x16x32_bf16 v[64:67], v[180:183], v[212:215], v[64:67]
	v_mfma_f32_16x16x32_bf16 v[116:119], v[172:175], v[192:195], v[116:119]
	v_mfma_f32_16x16x32_bf16 v[112:115], v[184:187], v[192:195], v[112:115]
	v_mfma_f32_16x16x32_bf16 v[100:103], v[172:175], v[200:203], v[100:103]
	v_mfma_f32_16x16x32_bf16 v[96:99], v[184:187], v[200:203], v[96:99]
	v_mfma_f32_16x16x32_bf16 v[84:87], v[172:175], v[208:211], v[84:87]
	v_mfma_f32_16x16x32_bf16 v[80:83], v[184:187], v[208:211], v[80:83]
	v_mfma_f32_16x16x32_bf16 v[68:71], v[172:175], v[216:219], v[68:71]
	v_mfma_f32_16x16x32_bf16 v[64:67], v[184:187], v[216:219], v[64:67]
	s_barrier
	s_add_i32 s34, s66, s16
	v_lshl_add_u64 v[176:177], v[176:177], 0, s[22:23]
	s_mov_b32 m0, s34
	ds_read_b128 v[188:191], v153 offset:49152
	ds_read_b128 v[192:195], v153 offset:50176
	ds_read_b128 v[196:199], v153 offset:51200
	ds_read_b128 v[200:203], v153 offset:52224
	ds_read_b128 v[204:207], v153 offset:53248
	ds_read_b128 v[208:211], v153 offset:54272
	ds_read_b128 v[212:215], v153 offset:55296
	ds_read_b128 v[216:219], v153 offset:56320
	global_load_lds_dwordx4 v[176:177], off
	v_lshl_add_u64 v[176:177], v[178:179], 0, s[22:23]
	s_add_i32 m0, s34, 0x2000
	s_add_i32 s34, s67, s16
	global_load_lds_dwordx4 v[176:177], off
	v_lshl_add_u64 v[176:177], v[220:221], 0, s[22:23]
	s_mov_b32 m0, s34
	s_nop 0
	global_load_lds_dwordx4 v[176:177], off
	v_lshl_add_u64 v[176:177], v[222:223], 0, s[22:23]
	s_add_i32 m0, s34, 0x2000
	s_nop 0
	global_load_lds_dwordx4 v[176:177], off
	v_lshl_add_u64 v[176:177], v[224:225], 0, s[22:23]
	s_mov_b32 m0, s37
	s_nop 0
	global_load_lds_dwordx4 v[176:177], off
	v_lshl_add_u64 v[176:177], v[226:227], 0, s[22:23]
	s_mov_b32 m0, s38
	s_nop 0
	global_load_lds_dwordx4 v[176:177], off
	s_waitcnt vmcnt(8)
	s_waitcnt lgkmcnt(0)
	s_barrier
	s_waitcnt lgkmcnt(0)
	v_mfma_f32_16x16x32_bf16 v[60:63], v[144:147], v[188:191], v[60:63]
	v_mfma_f32_16x16x32_bf16 v[56:59], v[160:163], v[188:191], v[56:59]
	v_mfma_f32_16x16x32_bf16 v[44:47], v[144:147], v[196:199], v[44:47]
	v_mfma_f32_16x16x32_bf16 v[40:43], v[160:163], v[196:199], v[40:43]
	v_mfma_f32_16x16x32_bf16 v[28:31], v[144:147], v[204:207], v[28:31]
	v_mfma_f32_16x16x32_bf16 v[24:27], v[160:163], v[204:207], v[24:27]
	v_mfma_f32_16x16x32_bf16 v[12:15], v[144:147], v[212:215], v[12:15]
	v_mfma_f32_16x16x32_bf16 v[8:11], v[160:163], v[212:215], v[8:11]
	v_mfma_f32_16x16x32_bf16 v[60:63], v[156:159], v[192:195], v[60:63]
	v_mfma_f32_16x16x32_bf16 v[56:59], v[164:167], v[192:195], v[56:59]
	v_mfma_f32_16x16x32_bf16 v[44:47], v[156:159], v[200:203], v[44:47]
	v_mfma_f32_16x16x32_bf16 v[40:43], v[164:167], v[200:203], v[40:43]
	v_mfma_f32_16x16x32_bf16 v[28:31], v[156:159], v[208:211], v[28:31]
	v_mfma_f32_16x16x32_bf16 v[24:27], v[164:167], v[208:211], v[24:27]
	v_mfma_f32_16x16x32_bf16 v[12:15], v[156:159], v[216:219], v[12:15]
	v_mfma_f32_16x16x32_bf16 v[8:11], v[164:167], v[216:219], v[8:11]
	v_mfma_f32_16x16x32_bf16 v[52:55], v[168:171], v[188:191], v[52:55]
	v_mfma_f32_16x16x32_bf16 v[48:51], v[180:183], v[188:191], v[48:51]
	v_mfma_f32_16x16x32_bf16 v[36:39], v[168:171], v[196:199], v[36:39]
	v_mfma_f32_16x16x32_bf16 v[32:35], v[180:183], v[196:199], v[32:35]
	v_mfma_f32_16x16x32_bf16 v[20:23], v[168:171], v[204:207], v[20:23]
	v_mfma_f32_16x16x32_bf16 v[16:19], v[180:183], v[204:207], v[16:19]
	v_mfma_f32_16x16x32_bf16 v[4:7], v[168:171], v[212:215], v[4:7]
	v_mfma_f32_16x16x32_bf16 v[0:3], v[180:183], v[212:215], v[0:3]
	v_mfma_f32_16x16x32_bf16 v[52:55], v[172:175], v[192:195], v[52:55]
	v_mfma_f32_16x16x32_bf16 v[48:51], v[184:187], v[192:195], v[48:51]
	v_mfma_f32_16x16x32_bf16 v[36:39], v[172:175], v[200:203], v[36:39]
	v_mfma_f32_16x16x32_bf16 v[32:35], v[184:187], v[200:203], v[32:35]
	v_mfma_f32_16x16x32_bf16 v[20:23], v[172:175], v[208:211], v[20:23]
	v_mfma_f32_16x16x32_bf16 v[16:19], v[184:187], v[208:211], v[16:19]
	v_mfma_f32_16x16x32_bf16 v[4:7], v[172:175], v[216:219], v[4:7]
	v_mfma_f32_16x16x32_bf16 v[0:3], v[184:187], v[216:219], v[0:3]
	s_barrier
	s_add_u32 s30, s30, 0x100
	s_addc_u32 s31, s31, 0
	s_add_u32 s63, s63, 0x100
	s_addc_u32 s64, s64, 0
	s_cmp_ge_i32 s65, s40
	s_mov_b32 s34, s65
	s_cbranch_scc0 .LBB0_1222

; #define PG8_STAGE(bufoff, gbase, voff) do { _Pragma("unroll") for (int _i = 0; _i < 2; ++_i) \
;         __builtin_amdgcn_global_load_lds((const unsigned*)((const char*)(gbase) + (voff)[_i]), (PG8_LAS unsigned*)(lds + (bufoff) + ldsw + _i * 8192), 16, 0, 0); } while (0)
; #define PG8_LDA(dst, b, h) do { _Pragma("unroll") for (int m = 0; m < 4; ++m) _Pragma("unroll") for (int k = 0; k < 2; ++k) dst[m][k] = *(const PG8_LAS bf16x8*)(lds + PG8_SA(b, h) + aoff + m * 2048 + k * 1024); } while (0)
; #define PG8_LDB(dst, b, h) do { _Pragma("unroll") for (int n = 0; n < 2; ++n) _Pragma("unroll") for (int k = 0; k < 2; ++k) dst[n][k] = *(const PG8_LAS bf16x8*)(lds + PG8_SB(b, h) + boff + n * 2048 + k * 1024); } while (0)
; #define PG8_MMA(ai, bj, At, Bt) do { __builtin_amdgcn_s_setprio(1); _Pragma("unroll") for (int m = 0; m < 4; ++m) _Pragma("unroll") for (int n = 0; n < 2; ++n) _Pragma("unroll") for (int k = 0; k < 2; ++k) \
;         acc[ai][bj][m][n] = __builtin_amdgcn_mfma_f32_16x16x32_bf16(Bt[n][k], At[m][k], acc[ai][bj][m][n], 0, 0, 0); __builtin_amdgcn_s_setprio(0); } while (0)
; #define PG8_WAIT_V(n) asm volatile("s_waitcnt vmcnt(" #n ")" ::: "memory")
; #define PG8_WAIT_L(n) asm volatile("s_waitcnt lgkmcnt(" #n ")" ::: "memory")
; #define PG8_BAR __builtin_amdgcn_s_barrier()
; #define PG8_SCHED __builtin_amdgcn_sched_barrier(0)
; template <class Epi, class Sched, bool ALIGN_EPI = false, bool SP2 = false>
; __device__ __forceinline__ void gemm_phase(PG8_LAS unsigned char* lds, const Gemm g, const Sched& S, const Epi& E) {
;     ...
;         for (int t = 0; t < nt; t += 2) {
;             const bool last = (t == nt - 2);
;             const char* a1 = cA + (size_t)(t + 1) * kstep;
;             const char* a2 = last ? nA : cA + (size_t)(t + 2) * kstep; const char* b2 = last ? nB : cB + (size_t)(t + 2) * kstep;
;             const char* a3 = a2 + kstep; const char* b3 = b2 + kstep;
;             if (last && has_next) S.a_ready(nxt);
;             if constexpr (SP2) {
;             PG8_LDB(B0, 0, 0); PG8_LDB(B1, 0, 1); PG8_SCHED; PG8_LDA(At, 0, 0); PG8_STAGE(PG8_SA(1, 1), a1 + hstep, voffA);
;             PG8_WAIT_V(8); PG8_WAIT_L(0); PG8_BAR; PG8_MMA(0, 0, At, B0); PG8_MMA(0, 1, At, B1); PG8_BAR; PG8_SCHED;
;             PG8_LDA(At, 0, 1); PG8_STAGE(PG8_SB(0, 0), b2, voffB); PG8_STAGE(PG8_SB(0, 1), b2 + hstep, voffB); PG8_STAGE(PG8_SA(0, 0), a2, voffA);
.LBB0_1315:
	s_andn2_b64 vcc, exec, s[20:21]
	s_waitcnt vmcnt(0)
	s_cbranch_vccnz .LBB0_1318
	s_add_u32 s26, s26, 0x80
	s_addc_u32 s27, s27, 0
	s_add_u32 s62, s28, 0x100
	s_addc_u32 s63, s29, 0
	s_mov_b32 s28, 0
	ds_read_b128 v[154:157], v149
	ds_read_b128 v[158:161], v149 offset:1024
	ds_read_b128 v[162:165], v149 offset:2048
	ds_read_b128 v[166:169], v149 offset:3072
	ds_read_b128 v[170:173], v150
	ds_read_b128 v[174:177], v150 offset:1024
	ds_read_b128 v[180:183], v150 offset:2048
	ds_read_b128 v[184:187], v150 offset:3072
	s_add_i32 s64, s28, 2
	s_add_u32 s65, s26, 0x80
	s_addc_u32 s29, s27, 0
	s_cmp_eq_u32 s39, s28
	s_cselect_b32 s28, s0, s65
	s_cselect_b32 s29, s1, s29
	s_cselect_b32 s67, s25, s63
	s_cselect_b32 s66, s24, s62
	v_lshl_add_u64 v[144:145], s[26:27], 0, v[136:137]
	s_add_i32 m0, s30, 0xc000
	ds_read_b128 v[188:191], v151
	ds_read_b128 v[192:195], v151 offset:1024
	ds_read_b128 v[196:199], v151 offset:2048
	ds_read_b128 v[200:203], v151 offset:3072
	ds_read_b128 v[204:207], v151 offset:4096
	ds_read_b128 v[208:211], v151 offset:5120
	ds_read_b128 v[212:215], v151 offset:6144
	ds_read_b128 v[216:219], v151 offset:7168
	global_load_lds_dwordx4 v[144:145], off
	v_lshl_add_u64 v[144:145], s[26:27], 0, v[138:139]
	s_add_i32 m0, s30, 0xe000
	s_nop 0
	global_load_lds_dwordx4 v[144:145], off
	s_waitcnt vmcnt(8)
	s_waitcnt lgkmcnt(0)
	s_barrier
	s_waitcnt lgkmcnt(0)
	v_mfma_f32_16x16x32_bf16 v[116:119], v[154:157], v[188:191], 0
	v_mfma_f32_16x16x32_bf16 v[112:115], v[162:165], v[188:191], 0
	v_mfma_f32_16x16x32_bf16 v[100:103], v[154:157], v[196:199], 0
	v_mfma_f32_16x16x32_bf16 v[96:99], v[162:165], v[196:199], 0
	v_mfma_f32_16x16x32_bf16 v[84:87], v[154:157], v[204:207], 0
	v_mfma_f32_16x16x32_bf16 v[80:83], v[162:165], v[204:207], 0
	v_mfma_f32_16x16x32_bf16 v[68:71], v[154:157], v[212:215], 0
	v_mfma_f32_16x16x32_bf16 v[64:67], v[162:165], v[212:215], 0
	v_mfma_f32_16x16x32_bf16 v[116:119], v[158:161], v[192:195], v[116:119]
	v_mfma_f32_16x16x32_bf16 v[112:115], v[166:169], v[192:195], v[112:115]
	v_mfma_f32_16x16x32_bf16 v[100:103], v[158:161], v[200:203], v[100:103]
	v_mfma_f32_16x16x32_bf16 v[96:99], v[166:169], v[200:203], v[96:99]
	v_mfma_f32_16x16x32_bf16 v[84:87], v[158:161], v[208:211], v[84:87]
	v_mfma_f32_16x16x32_bf16 v[80:83], v[166:169], v[208:211], v[80:83]
	v_mfma_f32_16x16x32_bf16 v[68:71], v[158:161], v[216:219], v[68:71]
	v_mfma_f32_16x16x32_bf16 v[64:67], v[166:169], v[216:219], v[64:67]
	v_mfma_f32_16x16x32_bf16 v[124:127], v[170:173], v[188:191], 0
	v_mfma_f32_16x16x32_bf16 v[120:123], v[180:183], v[188:191], 0
	v_mfma_f32_16x16x32_bf16 v[108:111], v[170:173], v[196:199], 0
	v_mfma_f32_16x16x32_bf16 v[104:107], v[180:183], v[196:199], 0
	v_mfma_f32_16x16x32_bf16 v[92:95], v[170:173], v[204:207], 0
	v_mfma_f32_16x16x32_bf16 v[88:91], v[180:183], v[204:207], 0
	v_mfma_f32_16x16x32_bf16 v[76:79], v[170:173], v[212:215], 0
	v_mfma_f32_16x16x32_bf16 v[72:75], v[180:183], v[212:215], 0
	v_mfma_f32_16x16x32_bf16 v[124:127], v[174:177], v[192:195], v[124:127]
	v_mfma_f32_16x16x32_bf16 v[120:123], v[184:187], v[192:195], v[120:123]
	v_mfma_f32_16x16x32_bf16 v[108:111], v[174:177], v[200:203], v[108:111]
	v_mfma_f32_16x16x32_bf16 v[104:107], v[184:187], v[200:203], v[104:107]
	v_mfma_f32_16x16x32_bf16 v[92:95], v[174:177], v[208:211], v[92:95]
	v_mfma_f32_16x16x32_bf16 v[88:91], v[184:187], v[208:211], v[88:91]
	v_mfma_f32_16x16x32_bf16 v[76:79], v[174:177], v[216:219], v[76:79]
	v_mfma_f32_16x16x32_bf16 v[72:75], v[184:187], v[216:219], v[72:75]
	s_barrier
	s_add_i32 s65, s50, s16
	v_lshl_add_u64 v[144:145], s[66:67], 0, v[132:133]
	s_mov_b32 m0, s65
	ds_read_b128 v[188:191], v151 offset:16384
	ds_read_b128 v[192:195], v151 offset:17408
	ds_read_b128 v[196:199], v151 offset:18432
	ds_read_b128 v[200:203], v151 offset:19456
	ds_read_b128 v[204:207], v151 offset:20480
	ds_read_b128 v[208:211], v151 offset:21504
	ds_read_b128 v[212:215], v151 offset:22528
	ds_read_b128 v[216:219], v151 offset:23552
	global_load_lds_dwordx4 v[144:145], off
	s_add_i32 m0, s65, 0x2000
	v_lshl_add_u64 v[178:179], s[66:67], 0, v[128:129]
	s_add_u32 s66, s66, s8
	s_addc_u32 s67, s67, s9
	s_add_i32 s65, s51, s16
	global_load_lds_dwordx4 v[178:179], off
	v_lshl_add_u64 v[220:221], s[66:67], 0, v[132:133]
	s_mov_b32 m0, s65
	v_lshl_add_u64 v[222:223], s[66:67], 0, v[128:129]
	global_load_lds_dwordx4 v[220:221], off
	s_add_i32 m0, s65, 0x2000
	v_lshl_add_u64 v[224:225], s[28:29], 0, v[134:135]
	global_load_lds_dwordx4 v[222:223], off
	s_mov_b32 m0, s30
	v_lshl_add_u64 v[226:227], s[28:29], 0, v[130:131]
	global_load_lds_dwordx4 v[224:225], off
	s_mov_b32 m0, s31
	s_nop 0
	global_load_lds_dwordx4 v[226:227], off
	s_waitcnt vmcnt(8)
	s_waitcnt lgkmcnt(0)
	s_barrier
; #define PG8_STAGE(bufoff, gbase, voff) do { _Pragma("unroll") for (int _i = 0; _i < 2; ++_i) \
;         __builtin_amdgcn_global_load_lds((const unsigned*)((const char*)(gbase) + (voff)[_i]), (PG8_LAS unsigned*)(lds + (bufoff) + ldsw + _i * 8192), 16, 0, 0); } while (0)
; #define PG8_LDA(dst, b, h) do { _Pragma("unroll") for (int m = 0; m < 4; ++m) _Pragma("unroll") for (int k = 0; k < 2; ++k) dst[m][k] = *(const PG8_LAS bf16x8*)(lds + PG8_SA(b, h) + aoff + m * 2048 + k * 1024); } while (0)
; #define PG8_LDB(dst, b, h) do { _Pragma("unroll") for (int n = 0; n < 2; ++n) _Pragma("unroll") for (int k = 0; k < 2; ++k) dst[n][k] = *(const PG8_LAS bf16x8*)(lds + PG8_SB(b, h) + boff + n * 2048 + k * 1024); } while (0)
; #define PG8_MMA(ai, bj, At, Bt) do { __builtin_amdgcn_s_setprio(1); _Pragma("unroll") for (int m = 0; m < 4; ++m) _Pragma("unroll") for (int n = 0; n < 2; ++n) _Pragma("unroll") for (int k = 0; k < 2; ++k) \
;         acc[ai][bj][m][n] = __builtin_amdgcn_mfma_f32_16x16x32_bf16(Bt[n][k], At[m][k], acc[ai][bj][m][n], 0, 0, 0); __builtin_amdgcn_s_setprio(0); } while (0)
; #define PG8_WAIT_V(n) asm volatile("s_waitcnt vmcnt(" #n ")" ::: "memory")
; #define PG8_WAIT_L(n) asm volatile("s_waitcnt lgkmcnt(" #n ")" ::: "memory")
; #define PG8_BAR __builtin_amdgcn_s_barrier()
; #define PG8_SCHED __builtin_amdgcn_sched_barrier(0)
; template <class Epi, class Sched, bool ALIGN_EPI = false, bool SP2 = false>
; __device__ __forceinline__ void gemm_phase(PG8_LAS unsigned char* lds, const Gemm g, const Sched& S, const Epi& E) {
;     ...
;             PG8_LDA(At, 0, 1); PG8_STAGE(PG8_SB(0, 0), b2, voffB); PG8_STAGE(PG8_SB(0, 1), b2 + hstep, voffB); PG8_STAGE(PG8_SA(0, 0), a2, voffA);
;             PG8_WAIT_V(8); PG8_WAIT_L(0); PG8_BAR; PG8_MMA(1, 0, At, B0); PG8_MMA(1, 1, At, B1); PG8_BAR; PG8_SCHED;
;             PG8_LDB(B0, 1, 0); PG8_LDB(B1, 1, 1); PG8_SCHED; PG8_LDA(At, 1, 0); PG8_STAGE(PG8_SA(0, 1), a2 + hstep, voffA);
;             PG8_WAIT_V(8); PG8_WAIT_L(0); PG8_BAR; PG8_MMA(0, 0, At, B0); PG8_MMA(0, 1, At, B1); PG8_BAR; PG8_SCHED;
	s_waitcnt lgkmcnt(0)
	v_mfma_f32_16x16x32_bf16 v[52:55], v[154:157], v[188:191], 0
	v_mfma_f32_16x16x32_bf16 v[48:51], v[162:165], v[188:191], 0
	v_mfma_f32_16x16x32_bf16 v[36:39], v[154:157], v[196:199], 0
	v_mfma_f32_16x16x32_bf16 v[32:35], v[162:165], v[196:199], 0
	v_mfma_f32_16x16x32_bf16 v[20:23], v[154:157], v[204:207], 0
	v_mfma_f32_16x16x32_bf16 v[16:19], v[162:165], v[204:207], 0
	v_mfma_f32_16x16x32_bf16 v[4:7], v[154:157], v[212:215], 0
	v_mfma_f32_16x16x32_bf16 v[0:3], v[162:165], v[212:215], 0
	v_mfma_f32_16x16x32_bf16 v[52:55], v[158:161], v[192:195], v[52:55]
	v_mfma_f32_16x16x32_bf16 v[48:51], v[166:169], v[192:195], v[48:51]
	v_mfma_f32_16x16x32_bf16 v[36:39], v[158:161], v[200:203], v[36:39]
	v_mfma_f32_16x16x32_bf16 v[32:35], v[166:169], v[200:203], v[32:35]
	v_mfma_f32_16x16x32_bf16 v[20:23], v[158:161], v[208:211], v[20:23]
	v_mfma_f32_16x16x32_bf16 v[16:19], v[166:169], v[208:211], v[16:19]
	v_mfma_f32_16x16x32_bf16 v[4:7], v[158:161], v[216:219], v[4:7]
	v_mfma_f32_16x16x32_bf16 v[0:3], v[166:169], v[216:219], v[0:3]
	v_mfma_f32_16x16x32_bf16 v[60:63], v[170:173], v[188:191], 0
	v_mfma_f32_16x16x32_bf16 v[56:59], v[180:183], v[188:191], 0
	v_mfma_f32_16x16x32_bf16 v[44:47], v[170:173], v[196:199], 0
	v_mfma_f32_16x16x32_bf16 v[40:43], v[180:183], v[196:199], 0
	v_mfma_f32_16x16x32_bf16 v[28:31], v[170:173], v[204:207], 0
	v_mfma_f32_16x16x32_bf16 v[24:27], v[180:183], v[204:207], 0
	v_mfma_f32_16x16x32_bf16 v[12:15], v[170:173], v[212:215], 0
	v_mfma_f32_16x16x32_bf16 v[8:11], v[180:183], v[212:215], 0
	v_mfma_f32_16x16x32_bf16 v[60:63], v[174:177], v[192:195], v[60:63]
	v_mfma_f32_16x16x32_bf16 v[56:59], v[184:187], v[192:195], v[56:59]
	v_mfma_f32_16x16x32_bf16 v[44:47], v[174:177], v[200:203], v[44:47]
	v_mfma_f32_16x16x32_bf16 v[40:43], v[184:187], v[200:203], v[40:43]
	v_mfma_f32_16x16x32_bf16 v[28:31], v[174:177], v[208:211], v[28:31]
	v_mfma_f32_16x16x32_bf16 v[24:27], v[184:187], v[208:211], v[24:27]
	v_mfma_f32_16x16x32_bf16 v[12:15], v[174:177], v[216:219], v[12:15]
	v_mfma_f32_16x16x32_bf16 v[8:11], v[184:187], v[216:219], v[8:11]
	s_barrier
	s_add_i32 s65, 0, 0x18000
	v_add_u32_e32 v153, s65, v147
	s_add_i32 s66, 0, 0x1c000
	ds_read_b128 v[154:157], v153
	ds_read_b128 v[158:161], v153 offset:1024
	ds_read_b128 v[162:165], v153 offset:2048
	ds_read_b128 v[166:169], v153 offset:3072
	v_add_u32_e32 v153, s66, v147
	ds_read_b128 v[170:173], v153
	ds_read_b128 v[174:177], v153 offset:1024
	ds_read_b128 v[180:183], v153 offset:2048
	ds_read_b128 v[184:187], v153 offset:3072
	s_add_u32 s28, s28, s8
	s_addc_u32 s29, s29, s9
	s_mov_b32 m0, s33
	v_lshl_add_u64 v[228:229], s[28:29], 0, v[134:135]
	ds_read_b128 v[188:191], v151 offset:32768
	ds_read_b128 v[192:195], v151 offset:33792
	ds_read_b128 v[196:199], v151 offset:34816
	ds_read_b128 v[200:203], v151 offset:35840
	ds_read_b128 v[204:207], v151 offset:36864
	ds_read_b128 v[208:211], v151 offset:37888
	ds_read_b128 v[212:215], v151 offset:38912
	ds_read_b128 v[216:219], v151 offset:39936
	global_load_lds_dwordx4 v[228:229], off
	v_lshl_add_u64 v[228:229], s[28:29], 0, v[130:131]
	s_mov_b32 m0, s34
	s_nop 0
	global_load_lds_dwordx4 v[228:229], off
	s_waitcnt vmcnt(8)
	s_waitcnt lgkmcnt(0)
	s_barrier
	s_waitcnt lgkmcnt(0)
	v_mfma_f32_16x16x32_bf16 v[116:119], v[154:157], v[188:191], v[116:119]
	v_mfma_f32_16x16x32_bf16 v[112:115], v[162:165], v[188:191], v[112:115]
	v_mfma_f32_16x16x32_bf16 v[100:103], v[154:157], v[196:199], v[100:103]
	v_mfma_f32_16x16x32_bf16 v[96:99], v[162:165], v[196:199], v[96:99]
	v_mfma_f32_16x16x32_bf16 v[84:87], v[154:157], v[204:207], v[84:87]
	v_mfma_f32_16x16x32_bf16 v[80:83], v[162:165], v[204:207], v[80:83]
	v_mfma_f32_16x16x32_bf16 v[68:71], v[154:157], v[212:215], v[68:71]
	v_mfma_f32_16x16x32_bf16 v[64:67], v[162:165], v[212:215], v[64:67]
	v_mfma_f32_16x16x32_bf16 v[116:119], v[158:161], v[192:195], v[116:119]
	v_mfma_f32_16x16x32_bf16 v[112:115], v[166:169], v[192:195], v[112:115]
	v_mfma_f32_16x16x32_bf16 v[100:103], v[158:161], v[200:203], v[100:103]
	v_mfma_f32_16x16x32_bf16 v[96:99], v[166:169], v[200:203], v[96:99]
	v_mfma_f32_16x16x32_bf16 v[84:87], v[158:161], v[208:211], v[84:87]
	v_mfma_f32_16x16x32_bf16 v[80:83], v[166:169], v[208:211], v[80:83]
	v_mfma_f32_16x16x32_bf16 v[68:71], v[158:161], v[216:219], v[68:71]
	v_mfma_f32_16x16x32_bf16 v[64:67], v[166:169], v[216:219], v[64:67]
	v_mfma_f32_16x16x32_bf16 v[124:127], v[170:173], v[188:191], v[124:127]
	v_mfma_f32_16x16x32_bf16 v[120:123], v[180:183], v[188:191], v[120:123]
	v_mfma_f32_16x16x32_bf16 v[108:111], v[170:173], v[196:199], v[108:111]
	v_mfma_f32_16x16x32_bf16 v[104:107], v[180:183], v[196:199], v[104:107]
	v_mfma_f32_16x16x32_bf16 v[92:95], v[170:173], v[204:207], v[92:95]
	v_mfma_f32_16x16x32_bf16 v[88:91], v[180:183], v[204:207], v[88:91]
	v_mfma_f32_16x16x32_bf16 v[76:79], v[170:173], v[212:215], v[76:79]
	v_mfma_f32_16x16x32_bf16 v[72:75], v[180:183], v[212:215], v[72:75]
	v_mfma_f32_16x16x32_bf16 v[124:127], v[174:177], v[192:195], v[124:127]
	v_mfma_f32_16x16x32_bf16 v[120:123], v[184:187], v[192:195], v[120:123]
	v_mfma_f32_16x16x32_bf16 v[108:111], v[174:177], v[200:203], v[108:111]
	v_mfma_f32_16x16x32_bf16 v[104:107], v[184:187], v[200:203], v[104:107]
	v_mfma_f32_16x16x32_bf16 v[92:95], v[174:177], v[208:211], v[92:95]
	v_mfma_f32_16x16x32_bf16 v[88:91], v[184:187], v[208:211], v[88:91]
	v_mfma_f32_16x16x32_bf16 v[76:79], v[174:177], v[216:219], v[76:79]
	v_mfma_f32_16x16x32_bf16 v[72:75], v[184:187], v[216:219], v[72:75]
	s_barrier
; #define PG8_STAGE(bufoff, gbase, voff) do { _Pragma("unroll") for (int _i = 0; _i < 2; ++_i) \
;         __builtin_amdgcn_global_load_lds((const unsigned*)((const char*)(gbase) + (voff)[_i]), (PG8_LAS unsigned*)(lds + (bufoff) + ldsw + _i * 8192), 16, 0, 0); } while (0)
; #define PG8_LDA(dst, b, h) do { _Pragma("unroll") for (int m = 0; m < 4; ++m) _Pragma("unroll") for (int k = 0; k < 2; ++k) dst[m][k] = *(const PG8_LAS bf16x8*)(lds + PG8_SA(b, h) + aoff + m * 2048 + k * 1024); } while (0)
; #define PG8_LDB(dst, b, h) do { _Pragma("unroll") for (int n = 0; n < 2; ++n) _Pragma("unroll") for (int k = 0; k < 2; ++k) dst[n][k] = *(const PG8_LAS bf16x8*)(lds + PG8_SB(b, h) + boff + n * 2048 + k * 1024); } while (0)
; #define PG8_MMA(ai, bj, At, Bt) do { __builtin_amdgcn_s_setprio(1); _Pragma("unroll") for (int m = 0; m < 4; ++m) _Pragma("unroll") for (int n = 0; n < 2; ++n) _Pragma("unroll") for (int k = 0; k < 2; ++k) \
;         acc[ai][bj][m][n] = __builtin_amdgcn_mfma_f32_16x16x32_bf16(Bt[n][k], At[m][k], acc[ai][bj][m][n], 0, 0, 0); __builtin_amdgcn_s_setprio(0); } while (0)
; #define PG8_WAIT_V(n) asm volatile("s_waitcnt vmcnt(" #n ")" ::: "memory")
; #define PG8_WAIT_L(n) asm volatile("s_waitcnt lgkmcnt(" #n ")" ::: "memory")
; #define PG8_BAR __builtin_amdgcn_s_barrier()
; #define PG8_SCHED __builtin_amdgcn_sched_barrier(0)
; template <class Epi, class Sched, bool ALIGN_EPI = false, bool SP2 = false>
; __device__ __forceinline__ void gemm_phase(PG8_LAS unsigned char* lds, const Gemm g, const Sched& S, const Epi& E) {
;     ...
;         for (int t = 0; t < nt; t += 2) {
;             const bool last = (t == nt - 2);
;             const char* a1 = cA + (size_t)(t + 1) * kstep;
;             const char* a2 = last ? nA : cA + (size_t)(t + 2) * kstep; const char* b2 = last ? nB : cB + (size_t)(t + 2) * kstep;
;             const char* a3 = a2 + kstep; const char* b3 = b2 + kstep;
;             if (last && has_next) S.a_ready(nxt);
;             if constexpr (SP2) {
;             PG8_LDB(B0, 0, 0); PG8_LDB(B1, 0, 1); PG8_SCHED; PG8_LDA(At, 0, 0); PG8_STAGE(PG8_SA(1, 1), a1 + hstep, voffA);
;     ...
;             PG8_LDA(At, 1, 1); PG8_STAGE(PG8_SB(1, 0), b3, voffB); PG8_STAGE(PG8_SB(1, 1), b3 + hstep, voffB); PG8_STAGE(PG8_SA(1, 0), a3, voffA);
;             PG8_WAIT_V(8); PG8_WAIT_L(0); PG8_BAR; PG8_MMA(1, 0, At, B0); PG8_MMA(1, 1, At, B1); PG8_BAR; PG8_SCHED;
	s_add_i32 s28, s65, s16
	v_lshl_add_u64 v[144:145], v[144:145], 0, s[14:15]
	s_mov_b32 m0, s28
	ds_read_b128 v[188:191], v151 offset:49152
	ds_read_b128 v[192:195], v151 offset:50176
	ds_read_b128 v[196:199], v151 offset:51200
	ds_read_b128 v[200:203], v151 offset:52224
	ds_read_b128 v[204:207], v151 offset:53248
	ds_read_b128 v[208:211], v151 offset:54272
	ds_read_b128 v[212:215], v151 offset:55296
	ds_read_b128 v[216:219], v151 offset:56320
	global_load_lds_dwordx4 v[144:145], off
	v_lshl_add_u64 v[144:145], v[178:179], 0, s[14:15]
	s_add_i32 m0, s28, 0x2000
	s_add_i32 s28, s66, s16
	global_load_lds_dwordx4 v[144:145], off
	v_lshl_add_u64 v[144:145], v[220:221], 0, s[14:15]
	s_mov_b32 m0, s28
	s_nop 0
	global_load_lds_dwordx4 v[144:145], off
	v_lshl_add_u64 v[144:145], v[222:223], 0, s[14:15]
	s_add_i32 m0, s28, 0x2000
	s_nop 0
	global_load_lds_dwordx4 v[144:145], off
	v_lshl_add_u64 v[144:145], v[224:225], 0, s[14:15]
	s_mov_b32 m0, s36
	s_nop 0
	global_load_lds_dwordx4 v[144:145], off
	v_lshl_add_u64 v[144:145], v[226:227], 0, s[14:15]
	s_mov_b32 m0, s37
	s_nop 0
	global_load_lds_dwordx4 v[144:145], off
	s_waitcnt vmcnt(8)
	s_waitcnt lgkmcnt(0)
	s_barrier
	s_waitcnt lgkmcnt(0)
	v_mfma_f32_16x16x32_bf16 v[52:55], v[154:157], v[188:191], v[52:55]
	v_mfma_f32_16x16x32_bf16 v[48:51], v[162:165], v[188:191], v[48:51]
	v_mfma_f32_16x16x32_bf16 v[36:39], v[154:157], v[196:199], v[36:39]
	v_mfma_f32_16x16x32_bf16 v[32:35], v[162:165], v[196:199], v[32:35]
	v_mfma_f32_16x16x32_bf16 v[20:23], v[154:157], v[204:207], v[20:23]
	v_mfma_f32_16x16x32_bf16 v[16:19], v[162:165], v[204:207], v[16:19]
	v_mfma_f32_16x16x32_bf16 v[4:7], v[154:157], v[212:215], v[4:7]
	v_mfma_f32_16x16x32_bf16 v[0:3], v[162:165], v[212:215], v[0:3]
	v_mfma_f32_16x16x32_bf16 v[52:55], v[158:161], v[192:195], v[52:55]
	v_mfma_f32_16x16x32_bf16 v[48:51], v[166:169], v[192:195], v[48:51]
	v_mfma_f32_16x16x32_bf16 v[36:39], v[158:161], v[200:203], v[36:39]
	v_mfma_f32_16x16x32_bf16 v[32:35], v[166:169], v[200:203], v[32:35]
	v_mfma_f32_16x16x32_bf16 v[20:23], v[158:161], v[208:211], v[20:23]
	v_mfma_f32_16x16x32_bf16 v[16:19], v[166:169], v[208:211], v[16:19]
	v_mfma_f32_16x16x32_bf16 v[4:7], v[158:161], v[216:219], v[4:7]
	v_mfma_f32_16x16x32_bf16 v[0:3], v[166:169], v[216:219], v[0:3]
	v_mfma_f32_16x16x32_bf16 v[60:63], v[170:173], v[188:191], v[60:63]
	v_mfma_f32_16x16x32_bf16 v[56:59], v[180:183], v[188:191], v[56:59]
	v_mfma_f32_16x16x32_bf16 v[44:47], v[170:173], v[196:199], v[44:47]
	v_mfma_f32_16x16x32_bf16 v[40:43], v[180:183], v[196:199], v[40:43]
	v_mfma_f32_16x16x32_bf16 v[28:31], v[170:173], v[204:207], v[28:31]
	v_mfma_f32_16x16x32_bf16 v[24:27], v[180:183], v[204:207], v[24:27]
	v_mfma_f32_16x16x32_bf16 v[12:15], v[170:173], v[212:215], v[12:15]
	v_mfma_f32_16x16x32_bf16 v[8:11], v[180:183], v[212:215], v[8:11]
	v_mfma_f32_16x16x32_bf16 v[60:63], v[174:177], v[192:195], v[60:63]
	v_mfma_f32_16x16x32_bf16 v[56:59], v[184:187], v[192:195], v[56:59]
	v_mfma_f32_16x16x32_bf16 v[44:47], v[174:177], v[200:203], v[44:47]
	v_mfma_f32_16x16x32_bf16 v[40:43], v[184:187], v[200:203], v[40:43]
	v_mfma_f32_16x16x32_bf16 v[28:31], v[174:177], v[208:211], v[28:31]
	v_mfma_f32_16x16x32_bf16 v[24:27], v[184:187], v[208:211], v[24:27]
	v_mfma_f32_16x16x32_bf16 v[12:15], v[174:177], v[216:219], v[12:15]
	v_mfma_f32_16x16x32_bf16 v[8:11], v[184:187], v[216:219], v[8:11]
	s_barrier
	s_add_u32 s26, s26, 0x100
	s_addc_u32 s27, s27, 0
	s_add_u32 s62, s62, 0x100
	s_addc_u32 s63, s63, 0
	s_cmp_ge_i32 s64, s38
	s_mov_b32 s28, s64
	s_cbranch_scc0 .LBB0_1317
	s_branch .Lpeel_x4
.LBB0_1317:
	ds_read_b128 v[154:157], v149
	ds_read_b128 v[158:161], v149 offset:1024
	ds_read_b128 v[162:165], v149 offset:2048
	ds_read_b128 v[166:169], v149 offset:3072
	ds_read_b128 v[170:173], v150
	ds_read_b128 v[174:177], v150 offset:1024
	ds_read_b128 v[180:183], v150 offset:2048
	ds_read_b128 v[184:187], v150 offset:3072
	s_add_i32 s64, s28, 2
	s_add_u32 s65, s26, 0x80
	s_addc_u32 s29, s27, 0
	s_cmp_eq_u32 s39, s28
	s_cselect_b32 s28, s0, s65
	s_cselect_b32 s29, s1, s29
	s_cselect_b32 s67, s25, s63
	s_cselect_b32 s66, s24, s62
	v_lshl_add_u64 v[144:145], s[26:27], 0, v[136:137]
	s_add_i32 m0, s30, 0xc000
	ds_read_b128 v[188:191], v151
	ds_read_b128 v[192:195], v151 offset:1024
	ds_read_b128 v[196:199], v151 offset:2048
	ds_read_b128 v[200:203], v151 offset:3072
	ds_read_b128 v[204:207], v151 offset:4096
	ds_read_b128 v[208:211], v151 offset:5120
	ds_read_b128 v[212:215], v151 offset:6144
	ds_read_b128 v[216:219], v151 offset:7168
	global_load_lds_dwordx4 v[144:145], off
	v_lshl_add_u64 v[144:145], s[26:27], 0, v[138:139]
	s_add_i32 m0, s30, 0xe000
	s_nop 0
	global_load_lds_dwordx4 v[144:145], off
	s_waitcnt vmcnt(8)
	s_waitcnt lgkmcnt(0)
	s_barrier
; #define PG8_STAGE(bufoff, gbase, voff) do { _Pragma("unroll") for (int _i = 0; _i < 2; ++_i) \
;         __builtin_amdgcn_global_load_lds((const unsigned*)((const char*)(gbase) + (voff)[_i]), (PG8_LAS unsigned*)(lds + (bufoff) + ldsw + _i * 8192), 16, 0, 0); } while (0)
; #define PG8_LDA(dst, b, h) do { _Pragma("unroll") for (int m = 0; m < 4; ++m) _Pragma("unroll") for (int k = 0; k < 2; ++k) dst[m][k] = *(const PG8_LAS bf16x8*)(lds + PG8_SA(b, h) + aoff + m * 2048 + k * 1024); } while (0)
; #define PG8_MMA(ai, bj, At, Bt) do { __builtin_amdgcn_s_setprio(1); _Pragma("unroll") for (int m = 0; m < 4; ++m) _Pragma("unroll") for (int n = 0; n < 2; ++n) _Pragma("unroll") for (int k = 0; k < 2; ++k) \
;         acc[ai][bj][m][n] = __builtin_amdgcn_mfma_f32_16x16x32_bf16(Bt[n][k], At[m][k], acc[ai][bj][m][n], 0, 0, 0); __builtin_amdgcn_s_setprio(0); } while (0)
; #define PG8_WAIT_V(n) asm volatile("s_waitcnt vmcnt(" #n ")" ::: "memory")
; #define PG8_WAIT_L(n) asm volatile("s_waitcnt lgkmcnt(" #n ")" ::: "memory")
; #define PG8_BAR __builtin_amdgcn_s_barrier()
; #define PG8_SCHED __builtin_amdgcn_sched_barrier(0)
; template <class Epi, class Sched, bool ALIGN_EPI = false, bool SP2 = false>
; __device__ __forceinline__ void gemm_phase(PG8_LAS unsigned char* lds, const Gemm g, const Sched& S, const Epi& E) {
;     ...
;             PG8_WAIT_V(8); PG8_WAIT_L(0); PG8_BAR; PG8_MMA(0, 0, At, B0); PG8_MMA(0, 1, At, B1); PG8_BAR; PG8_SCHED;
;             PG8_LDA(At, 0, 1); PG8_STAGE(PG8_SB(0, 0), b2, voffB); PG8_STAGE(PG8_SB(0, 1), b2 + hstep, voffB); PG8_STAGE(PG8_SA(0, 0), a2, voffA);
;             PG8_WAIT_V(8); PG8_WAIT_L(0); PG8_BAR; PG8_MMA(1, 0, At, B0); PG8_MMA(1, 1, At, B1); PG8_BAR; PG8_SCHED;
	s_waitcnt lgkmcnt(0)
	v_mfma_f32_16x16x32_bf16 v[116:119], v[154:157], v[188:191], v[116:119]
	v_mfma_f32_16x16x32_bf16 v[112:115], v[162:165], v[188:191], v[112:115]
	v_mfma_f32_16x16x32_bf16 v[100:103], v[154:157], v[196:199], v[100:103]
	v_mfma_f32_16x16x32_bf16 v[96:99], v[162:165], v[196:199], v[96:99]
	v_mfma_f32_16x16x32_bf16 v[84:87], v[154:157], v[204:207], v[84:87]
	v_mfma_f32_16x16x32_bf16 v[80:83], v[162:165], v[204:207], v[80:83]
	v_mfma_f32_16x16x32_bf16 v[68:71], v[154:157], v[212:215], v[68:71]
	v_mfma_f32_16x16x32_bf16 v[64:67], v[162:165], v[212:215], v[64:67]
	v_mfma_f32_16x16x32_bf16 v[116:119], v[158:161], v[192:195], v[116:119]
	v_mfma_f32_16x16x32_bf16 v[112:115], v[166:169], v[192:195], v[112:115]
	v_mfma_f32_16x16x32_bf16 v[100:103], v[158:161], v[200:203], v[100:103]
	v_mfma_f32_16x16x32_bf16 v[96:99], v[166:169], v[200:203], v[96:99]
	v_mfma_f32_16x16x32_bf16 v[84:87], v[158:161], v[208:211], v[84:87]
	v_mfma_f32_16x16x32_bf16 v[80:83], v[166:169], v[208:211], v[80:83]
	v_mfma_f32_16x16x32_bf16 v[68:71], v[158:161], v[216:219], v[68:71]
	v_mfma_f32_16x16x32_bf16 v[64:67], v[166:169], v[216:219], v[64:67]
	v_mfma_f32_16x16x32_bf16 v[124:127], v[170:173], v[188:191], v[124:127]
	v_mfma_f32_16x16x32_bf16 v[120:123], v[180:183], v[188:191], v[120:123]
	v_mfma_f32_16x16x32_bf16 v[108:111], v[170:173], v[196:199], v[108:111]
	v_mfma_f32_16x16x32_bf16 v[104:107], v[180:183], v[196:199], v[104:107]
	v_mfma_f32_16x16x32_bf16 v[92:95], v[170:173], v[204:207], v[92:95]
	v_mfma_f32_16x16x32_bf16 v[88:91], v[180:183], v[204:207], v[88:91]
	v_mfma_f32_16x16x32_bf16 v[76:79], v[170:173], v[212:215], v[76:79]
	v_mfma_f32_16x16x32_bf16 v[72:75], v[180:183], v[212:215], v[72:75]
	v_mfma_f32_16x16x32_bf16 v[124:127], v[174:177], v[192:195], v[124:127]
	v_mfma_f32_16x16x32_bf16 v[120:123], v[184:187], v[192:195], v[120:123]
	v_mfma_f32_16x16x32_bf16 v[108:111], v[174:177], v[200:203], v[108:111]
	v_mfma_f32_16x16x32_bf16 v[104:107], v[184:187], v[200:203], v[104:107]
	v_mfma_f32_16x16x32_bf16 v[92:95], v[174:177], v[208:211], v[92:95]
	v_mfma_f32_16x16x32_bf16 v[88:91], v[184:187], v[208:211], v[88:91]
	v_mfma_f32_16x16x32_bf16 v[76:79], v[174:177], v[216:219], v[76:79]
	v_mfma_f32_16x16x32_bf16 v[72:75], v[184:187], v[216:219], v[72:75]
	s_barrier
	s_add_i32 s65, s50, s16
	v_lshl_add_u64 v[144:145], s[66:67], 0, v[132:133]
	s_mov_b32 m0, s65
	ds_read_b128 v[188:191], v151 offset:16384
	ds_read_b128 v[192:195], v151 offset:17408
	ds_read_b128 v[196:199], v151 offset:18432
	ds_read_b128 v[200:203], v151 offset:19456
	ds_read_b128 v[204:207], v151 offset:20480
	ds_read_b128 v[208:211], v151 offset:21504
	ds_read_b128 v[212:215], v151 offset:22528
	ds_read_b128 v[216:219], v151 offset:23552
	global_load_lds_dwordx4 v[144:145], off
	s_add_i32 m0, s65, 0x2000
	v_lshl_add_u64 v[178:179], s[66:67], 0, v[128:129]
	s_add_u32 s66, s66, s8
	s_addc_u32 s67, s67, s9
	s_add_i32 s65, s51, s16
	global_load_lds_dwordx4 v[178:179], off
	v_lshl_add_u64 v[220:221], s[66:67], 0, v[132:133]
	s_mov_b32 m0, s65
	v_lshl_add_u64 v[222:223], s[66:67], 0, v[128:129]
	global_load_lds_dwordx4 v[220:221], off
	s_add_i32 m0, s65, 0x2000
	v_lshl_add_u64 v[224:225], s[28:29], 0, v[134:135]
	global_load_lds_dwordx4 v[222:223], off
	s_mov_b32 m0, s30
	v_lshl_add_u64 v[226:227], s[28:29], 0, v[130:131]
	global_load_lds_dwordx4 v[224:225], off
	s_mov_b32 m0, s31
	s_nop 0
	global_load_lds_dwordx4 v[226:227], off
	s_waitcnt vmcnt(8)
	s_waitcnt lgkmcnt(0)
	s_barrier
	s_waitcnt lgkmcnt(0)
	v_mfma_f32_16x16x32_bf16 v[52:55], v[154:157], v[188:191], v[52:55]
	v_mfma_f32_16x16x32_bf16 v[48:51], v[162:165], v[188:191], v[48:51]
	v_mfma_f32_16x16x32_bf16 v[36:39], v[154:157], v[196:199], v[36:39]
	v_mfma_f32_16x16x32_bf16 v[32:35], v[162:165], v[196:199], v[32:35]
	v_mfma_f32_16x16x32_bf16 v[20:23], v[154:157], v[204:207], v[20:23]
	v_mfma_f32_16x16x32_bf16 v[16:19], v[162:165], v[204:207], v[16:19]
	v_mfma_f32_16x16x32_bf16 v[4:7], v[154:157], v[212:215], v[4:7]
	v_mfma_f32_16x16x32_bf16 v[0:3], v[162:165], v[212:215], v[0:3]
	v_mfma_f32_16x16x32_bf16 v[52:55], v[158:161], v[192:195], v[52:55]
	v_mfma_f32_16x16x32_bf16 v[48:51], v[166:169], v[192:195], v[48:51]
	v_mfma_f32_16x16x32_bf16 v[36:39], v[158:161], v[200:203], v[36:39]
	v_mfma_f32_16x16x32_bf16 v[32:35], v[166:169], v[200:203], v[32:35]
	v_mfma_f32_16x16x32_bf16 v[20:23], v[158:161], v[208:211], v[20:23]
	v_mfma_f32_16x16x32_bf16 v[16:19], v[166:169], v[208:211], v[16:19]
	v_mfma_f32_16x16x32_bf16 v[4:7], v[158:161], v[216:219], v[4:7]
	v_mfma_f32_16x16x32_bf16 v[0:3], v[166:169], v[216:219], v[0:3]
	v_mfma_f32_16x16x32_bf16 v[60:63], v[170:173], v[188:191], v[60:63]
	v_mfma_f32_16x16x32_bf16 v[56:59], v[180:183], v[188:191], v[56:59]
	v_mfma_f32_16x16x32_bf16 v[44:47], v[170:173], v[196:199], v[44:47]
	v_mfma_f32_16x16x32_bf16 v[40:43], v[180:183], v[196:199], v[40:43]
	v_mfma_f32_16x16x32_bf16 v[28:31], v[170:173], v[204:207], v[28:31]
	v_mfma_f32_16x16x32_bf16 v[24:27], v[180:183], v[204:207], v[24:27]
	v_mfma_f32_16x16x32_bf16 v[12:15], v[170:173], v[212:215], v[12:15]
	v_mfma_f32_16x16x32_bf16 v[8:11], v[180:183], v[212:215], v[8:11]
	v_mfma_f32_16x16x32_bf16 v[60:63], v[174:177], v[192:195], v[60:63]
	v_mfma_f32_16x16x32_bf16 v[56:59], v[184:187], v[192:195], v[56:59]
	v_mfma_f32_16x16x32_bf16 v[44:47], v[174:177], v[200:203], v[44:47]
	v_mfma_f32_16x16x32_bf16 v[40:43], v[184:187], v[200:203], v[40:43]
	v_mfma_f32_16x16x32_bf16 v[28:31], v[174:177], v[208:211], v[28:31]
	v_mfma_f32_16x16x32_bf16 v[24:27], v[184:187], v[208:211], v[24:27]
	v_mfma_f32_16x16x32_bf16 v[12:15], v[174:177], v[216:219], v[12:15]
	v_mfma_f32_16x16x32_bf16 v[8:11], v[184:187], v[216:219], v[8:11]
	s_barrier
; #define PG8_STAGE(bufoff, gbase, voff) do { _Pragma("unroll") for (int _i = 0; _i < 2; ++_i) \
;         __builtin_amdgcn_global_load_lds((const unsigned*)((const char*)(gbase) + (voff)[_i]), (PG8_LAS unsigned*)(lds + (bufoff) + ldsw + _i * 8192), 16, 0, 0); } while (0)
; #define PG8_LDA(dst, b, h) do { _Pragma("unroll") for (int m = 0; m < 4; ++m) _Pragma("unroll") for (int k = 0; k < 2; ++k) dst[m][k] = *(const PG8_LAS bf16x8*)(lds + PG8_SA(b, h) + aoff + m * 2048 + k * 1024); } while (0)
; #define PG8_LDB(dst, b, h) do { _Pragma("unroll") for (int n = 0; n < 2; ++n) _Pragma("unroll") for (int k = 0; k < 2; ++k) dst[n][k] = *(const PG8_LAS bf16x8*)(lds + PG8_SB(b, h) + boff + n * 2048 + k * 1024); } while (0)
; #define PG8_MMA(ai, bj, At, Bt) do { __builtin_amdgcn_s_setprio(1); _Pragma("unroll") for (int m = 0; m < 4; ++m) _Pragma("unroll") for (int n = 0; n < 2; ++n) _Pragma("unroll") for (int k = 0; k < 2; ++k) \
;         acc[ai][bj][m][n] = __builtin_amdgcn_mfma_f32_16x16x32_bf16(Bt[n][k], At[m][k], acc[ai][bj][m][n], 0, 0, 0); __builtin_amdgcn_s_setprio(0); } while (0)
; #define PG8_WAIT_V(n) asm volatile("s_waitcnt vmcnt(" #n ")" ::: "memory")
; #define PG8_WAIT_L(n) asm volatile("s_waitcnt lgkmcnt(" #n ")" ::: "memory")
; #define PG8_BAR __builtin_amdgcn_s_barrier()
; #define PG8_SCHED __builtin_amdgcn_sched_barrier(0)
; template <class Epi, class Sched, bool ALIGN_EPI = false, bool SP2 = false>
; __device__ __forceinline__ void gemm_phase(PG8_LAS unsigned char* lds, const Gemm g, const Sched& S, const Epi& E) {
;     ...
;             PG8_LDB(B0, 1, 0); PG8_LDB(B1, 1, 1); PG8_SCHED; PG8_LDA(At, 1, 0); PG8_STAGE(PG8_SA(0, 1), a2 + hstep, voffA);
;             PG8_WAIT_V(8); PG8_WAIT_L(0); PG8_BAR; PG8_MMA(0, 0, At, B0); PG8_MMA(0, 1, At, B1); PG8_BAR; PG8_SCHED;
;             PG8_LDA(At, 1, 1); PG8_STAGE(PG8_SB(1, 0), b3, voffB); PG8_STAGE(PG8_SB(1, 1), b3 + hstep, voffB); PG8_STAGE(PG8_SA(1, 0), a3, voffA);
;             PG8_WAIT_V(8); PG8_WAIT_L(0); PG8_BAR; PG8_MMA(1, 0, At, B0); PG8_MMA(1, 1, At, B1); PG8_BAR; PG8_SCHED;
	s_add_i32 s65, 0, 0x18000
	v_add_u32_e32 v153, s65, v147
	s_add_i32 s66, 0, 0x1c000
	ds_read_b128 v[154:157], v153
	ds_read_b128 v[158:161], v153 offset:1024
	ds_read_b128 v[162:165], v153 offset:2048
	ds_read_b128 v[166:169], v153 offset:3072
	v_add_u32_e32 v153, s66, v147
	ds_read_b128 v[170:173], v153
	ds_read_b128 v[174:177], v153 offset:1024
	ds_read_b128 v[180:183], v153 offset:2048
	ds_read_b128 v[184:187], v153 offset:3072
	s_add_u32 s28, s28, s8
	s_addc_u32 s29, s29, s9
	s_mov_b32 m0, s33
	v_lshl_add_u64 v[228:229], s[28:29], 0, v[134:135]
	ds_read_b128 v[188:191], v151 offset:32768
	ds_read_b128 v[192:195], v151 offset:33792
	ds_read_b128 v[196:199], v151 offset:34816
	ds_read_b128 v[200:203], v151 offset:35840
	ds_read_b128 v[204:207], v151 offset:36864
	ds_read_b128 v[208:211], v151 offset:37888
	ds_read_b128 v[212:215], v151 offset:38912
	ds_read_b128 v[216:219], v151 offset:39936
	global_load_lds_dwordx4 v[228:229], off
	v_lshl_add_u64 v[228:229], s[28:29], 0, v[130:131]
	s_mov_b32 m0, s34
	s_nop 0
	global_load_lds_dwordx4 v[228:229], off
	s_waitcnt vmcnt(8)
	s_waitcnt lgkmcnt(0)
	s_barrier
	s_waitcnt lgkmcnt(0)
	v_mfma_f32_16x16x32_bf16 v[116:119], v[154:157], v[188:191], v[116:119]
	v_mfma_f32_16x16x32_bf16 v[112:115], v[162:165], v[188:191], v[112:115]
	v_mfma_f32_16x16x32_bf16 v[100:103], v[154:157], v[196:199], v[100:103]
	v_mfma_f32_16x16x32_bf16 v[96:99], v[162:165], v[196:199], v[96:99]
	v_mfma_f32_16x16x32_bf16 v[84:87], v[154:157], v[204:207], v[84:87]
	v_mfma_f32_16x16x32_bf16 v[80:83], v[162:165], v[204:207], v[80:83]
	v_mfma_f32_16x16x32_bf16 v[68:71], v[154:157], v[212:215], v[68:71]
	v_mfma_f32_16x16x32_bf16 v[64:67], v[162:165], v[212:215], v[64:67]
	v_mfma_f32_16x16x32_bf16 v[116:119], v[158:161], v[192:195], v[116:119]
	v_mfma_f32_16x16x32_bf16 v[112:115], v[166:169], v[192:195], v[112:115]
	v_mfma_f32_16x16x32_bf16 v[100:103], v[158:161], v[200:203], v[100:103]
	v_mfma_f32_16x16x32_bf16 v[96:99], v[166:169], v[200:203], v[96:99]
	v_mfma_f32_16x16x32_bf16 v[84:87], v[158:161], v[208:211], v[84:87]
	v_mfma_f32_16x16x32_bf16 v[80:83], v[166:169], v[208:211], v[80:83]
	v_mfma_f32_16x16x32_bf16 v[68:71], v[158:161], v[216:219], v[68:71]
	v_mfma_f32_16x16x32_bf16 v[64:67], v[166:169], v[216:219], v[64:67]
	v_mfma_f32_16x16x32_bf16 v[124:127], v[170:173], v[188:191], v[124:127]
	v_mfma_f32_16x16x32_bf16 v[120:123], v[180:183], v[188:191], v[120:123]
	v_mfma_f32_16x16x32_bf16 v[108:111], v[170:173], v[196:199], v[108:111]
	v_mfma_f32_16x16x32_bf16 v[104:107], v[180:183], v[196:199], v[104:107]
	v_mfma_f32_16x16x32_bf16 v[92:95], v[170:173], v[204:207], v[92:95]
	v_mfma_f32_16x16x32_bf16 v[88:91], v[180:183], v[204:207], v[88:91]
	v_mfma_f32_16x16x32_bf16 v[76:79], v[170:173], v[212:215], v[76:79]
	v_mfma_f32_16x16x32_bf16 v[72:75], v[180:183], v[212:215], v[72:75]
	v_mfma_f32_16x16x32_bf16 v[124:127], v[174:177], v[192:195], v[124:127]
	v_mfma_f32_16x16x32_bf16 v[120:123], v[184:187], v[192:195], v[120:123]
	v_mfma_f32_16x16x32_bf16 v[108:111], v[174:177], v[200:203], v[108:111]
	v_mfma_f32_16x16x32_bf16 v[104:107], v[184:187], v[200:203], v[104:107]
	v_mfma_f32_16x16x32_bf16 v[92:95], v[174:177], v[208:211], v[92:95]
	v_mfma_f32_16x16x32_bf16 v[88:91], v[184:187], v[208:211], v[88:91]
	v_mfma_f32_16x16x32_bf16 v[76:79], v[174:177], v[216:219], v[76:79]
	v_mfma_f32_16x16x32_bf16 v[72:75], v[184:187], v[216:219], v[72:75]
	s_barrier
	s_add_i32 s28, s65, s16
	v_lshl_add_u64 v[144:145], v[144:145], 0, s[14:15]
	s_mov_b32 m0, s28
	ds_read_b128 v[188:191], v151 offset:49152
	ds_read_b128 v[192:195], v151 offset:50176
	ds_read_b128 v[196:199], v151 offset:51200
	ds_read_b128 v[200:203], v151 offset:52224
	ds_read_b128 v[204:207], v151 offset:53248
	ds_read_b128 v[208:211], v151 offset:54272
	ds_read_b128 v[212:215], v151 offset:55296
	ds_read_b128 v[216:219], v151 offset:56320
	global_load_lds_dwordx4 v[144:145], off
	v_lshl_add_u64 v[144:145], v[178:179], 0, s[14:15]
	s_add_i32 m0, s28, 0x2000
	s_add_i32 s28, s66, s16
	global_load_lds_dwordx4 v[144:145], off
	v_lshl_add_u64 v[144:145], v[220:221], 0, s[14:15]
	s_mov_b32 m0, s28
	s_nop 0
	global_load_lds_dwordx4 v[144:145], off
	v_lshl_add_u64 v[144:145], v[222:223], 0, s[14:15]
	s_add_i32 m0, s28, 0x2000
	s_nop 0
	global_load_lds_dwordx4 v[144:145], off
	v_lshl_add_u64 v[144:145], v[224:225], 0, s[14:15]
	s_mov_b32 m0, s36
	s_nop 0
	global_load_lds_dwordx4 v[144:145], off
	v_lshl_add_u64 v[144:145], v[226:227], 0, s[14:15]
	s_mov_b32 m0, s37
	s_nop 0
	global_load_lds_dwordx4 v[144:145], off
	s_waitcnt vmcnt(8)
	s_waitcnt lgkmcnt(0)
	s_barrier
	s_waitcnt lgkmcnt(0)
	v_mfma_f32_16x16x32_bf16 v[52:55], v[154:157], v[188:191], v[52:55]
	v_mfma_f32_16x16x32_bf16 v[48:51], v[162:165], v[188:191], v[48:51]
	v_mfma_f32_16x16x32_bf16 v[36:39], v[154:157], v[196:199], v[36:39]
	v_mfma_f32_16x16x32_bf16 v[32:35], v[162:165], v[196:199], v[32:35]
	v_mfma_f32_16x16x32_bf16 v[20:23], v[154:157], v[204:207], v[20:23]
	v_mfma_f32_16x16x32_bf16 v[16:19], v[162:165], v[204:207], v[16:19]
	v_mfma_f32_16x16x32_bf16 v[4:7], v[154:157], v[212:215], v[4:7]
	v_mfma_f32_16x16x32_bf16 v[0:3], v[162:165], v[212:215], v[0:3]
	v_mfma_f32_16x16x32_bf16 v[52:55], v[158:161], v[192:195], v[52:55]
	v_mfma_f32_16x16x32_bf16 v[48:51], v[166:169], v[192:195], v[48:51]
	v_mfma_f32_16x16x32_bf16 v[36:39], v[158:161], v[200:203], v[36:39]
	v_mfma_f32_16x16x32_bf16 v[32:35], v[166:169], v[200:203], v[32:35]
	v_mfma_f32_16x16x32_bf16 v[20:23], v[158:161], v[208:211], v[20:23]
	v_mfma_f32_16x16x32_bf16 v[16:19], v[166:169], v[208:211], v[16:19]
	v_mfma_f32_16x16x32_bf16 v[4:7], v[158:161], v[216:219], v[4:7]
	v_mfma_f32_16x16x32_bf16 v[0:3], v[166:169], v[216:219], v[0:3]
	v_mfma_f32_16x16x32_bf16 v[60:63], v[170:173], v[188:191], v[60:63]
	v_mfma_f32_16x16x32_bf16 v[56:59], v[180:183], v[188:191], v[56:59]
	v_mfma_f32_16x16x32_bf16 v[44:47], v[170:173], v[196:199], v[44:47]
	v_mfma_f32_16x16x32_bf16 v[40:43], v[180:183], v[196:199], v[40:43]
	v_mfma_f32_16x16x32_bf16 v[28:31], v[170:173], v[204:207], v[28:31]
	v_mfma_f32_16x16x32_bf16 v[24:27], v[180:183], v[204:207], v[24:27]
	v_mfma_f32_16x16x32_bf16 v[12:15], v[170:173], v[212:215], v[12:15]
	v_mfma_f32_16x16x32_bf16 v[8:11], v[180:183], v[212:215], v[8:11]
	v_mfma_f32_16x16x32_bf16 v[60:63], v[174:177], v[192:195], v[60:63]
	v_mfma_f32_16x16x32_bf16 v[56:59], v[184:187], v[192:195], v[56:59]
	v_mfma_f32_16x16x32_bf16 v[44:47], v[174:177], v[200:203], v[44:47]
	v_mfma_f32_16x16x32_bf16 v[40:43], v[184:187], v[200:203], v[40:43]
	v_mfma_f32_16x16x32_bf16 v[28:31], v[174:177], v[208:211], v[28:31]
	v_mfma_f32_16x16x32_bf16 v[24:27], v[184:187], v[208:211], v[24:27]
	v_mfma_f32_16x16x32_bf16 v[12:15], v[174:177], v[216:219], v[12:15]
	v_mfma_f32_16x16x32_bf16 v[8:11], v[184:187], v[216:219], v[8:11]
	s_barrier
	s_add_u32 s26, s26, 0x100
	s_addc_u32 s27, s27, 0
	s_add_u32 s62, s62, 0x100
	s_addc_u32 s63, s63, 0
	s_cmp_ge_i32 s64, s38
	s_mov_b32 s28, s64
	s_cbranch_scc0 .LBB0_1317

; #define PG8_STAGE(bufoff, gbase, voff) do { _Pragma("unroll") for (int _i = 0; _i < 2; ++_i) \
;         __builtin_amdgcn_global_load_lds((const unsigned*)((const char*)(gbase) + (voff)[_i]), (PG8_LAS unsigned*)(lds + (bufoff) + ldsw + _i * 8192), 16, 0, 0); } while (0)
; #define PG8_LDA(dst, b, h) do { _Pragma("unroll") for (int m = 0; m < 4; ++m) _Pragma("unroll") for (int k = 0; k < 2; ++k) dst[m][k] = *(const PG8_LAS bf16x8*)(lds + PG8_SA(b, h) + aoff + m * 2048 + k * 1024); } while (0)
; #define PG8_LDB(dst, b, h) do { _Pragma("unroll") for (int n = 0; n < 2; ++n) _Pragma("unroll") for (int k = 0; k < 2; ++k) dst[n][k] = *(const PG8_LAS bf16x8*)(lds + PG8_SB(b, h) + boff + n * 2048 + k * 1024); } while (0)
; #define PG8_MMA(ai, bj, At, Bt) do { __builtin_amdgcn_s_setprio(1); _Pragma("unroll") for (int m = 0; m < 4; ++m) _Pragma("unroll") for (int n = 0; n < 2; ++n) _Pragma("unroll") for (int k = 0; k < 2; ++k) \
;         acc[ai][bj][m][n] = __builtin_amdgcn_mfma_f32_16x16x32_bf16(Bt[n][k], At[m][k], acc[ai][bj][m][n], 0, 0, 0); __builtin_amdgcn_s_setprio(0); } while (0)
; #define PG8_WAIT_V(n) asm volatile("s_waitcnt vmcnt(" #n ")" ::: "memory")
; #define PG8_WAIT_L(n) asm volatile("s_waitcnt lgkmcnt(" #n ")" ::: "memory")
; #define PG8_BAR __builtin_amdgcn_s_barrier()
; #define PG8_SCHED __builtin_amdgcn_sched_barrier(0)
; template <class Epi, class Sched, bool ALIGN_EPI = false, bool SP2 = false>
; __device__ __forceinline__ void gemm_phase(PG8_LAS unsigned char* lds, const Gemm g, const Sched& S, const Epi& E) {
;     ...
;         for (int t = 0; t < nt; t += 2) {
;             const bool last = (t == nt - 2);
;             const char* a1 = cA + (size_t)(t + 1) * kstep;
;             const char* a2 = last ? nA : cA + (size_t)(t + 2) * kstep; const char* b2 = last ? nB : cB + (size_t)(t + 2) * kstep;
;             const char* a3 = a2 + kstep; const char* b3 = b2 + kstep;
;             if (last && has_next) S.a_ready(nxt);
;             if constexpr (SP2) {
;             PG8_LDB(B0, 0, 0); PG8_LDB(B1, 0, 1); PG8_SCHED; PG8_LDA(At, 0, 0); PG8_STAGE(PG8_SA(1, 1), a1 + hstep, voffA);
;             PG8_WAIT_V(8); PG8_WAIT_L(0); PG8_BAR; PG8_MMA(0, 0, At, B0); PG8_MMA(0, 1, At, B1); PG8_BAR; PG8_SCHED;
;             PG8_LDA(At, 0, 1); PG8_STAGE(PG8_SB(0, 0), b2, voffB); PG8_STAGE(PG8_SB(0, 1), b2 + hstep, voffB); PG8_STAGE(PG8_SA(0, 0), a2, voffA);
.LBB0_1409:
	v_mov_b32_e32 v151, 0
	s_andn2_b64 vcc, exec, s[24:25]
	v_mov_b32_e32 v150, 0
	v_mov_b32_e32 v155, 0
	v_mov_b32_e32 v154, 0
	v_mov_b32_e32 v153, 0
	v_mov_b32_e32 v152, 0
	v_mov_b32_e32 v149, 0
	v_mov_b32_e32 v148, 0
	s_waitcnt vmcnt(0)
	v_mov_b32_e32 v145, 0
	v_mov_b32_e32 v144, 0
	v_mov_b32_e32 v147, 0
	v_mov_b32_e32 v146, 0
	s_waitcnt lgkmcnt(0)
	s_cbranch_vccnz .LBB0_1413
	s_add_u32 s30, s30, 0x80
	s_addc_u32 s31, s31, 0
	s_add_u32 s63, s34, 0x100
	s_addc_u32 s64, s35, 0
	s_mov_b32 s34, 0
	ds_read_b128 v[144:147], v159
	ds_read_b128 v[148:151], v159 offset:1024
	ds_read_b128 v[152:155], v159 offset:2048
	ds_read_b128 v[164:167], v159 offset:3072
	ds_read_b128 v[168:171], v160
	ds_read_b128 v[172:175], v160 offset:1024
	ds_read_b128 v[180:183], v160 offset:2048
	ds_read_b128 v[184:187], v160 offset:3072
	s_add_i32 s65, s34, 2
	s_add_u32 s66, s30, 0x80
	s_addc_u32 s35, s31, 0
	s_cmp_eq_u32 s41, s34
	s_cselect_b32 s34, s0, s66
	s_cselect_b32 s35, s1, s35
	s_cselect_b32 s67, s29, s64
	s_cselect_b32 s66, s28, s63
	v_lshl_add_u64 v[176:177], s[30:31], 0, v[136:137]
	s_add_i32 m0, s17, 0xc000
	ds_read_b128 v[188:191], v161
	ds_read_b128 v[192:195], v161 offset:1024
	ds_read_b128 v[196:199], v161 offset:2048
	ds_read_b128 v[200:203], v161 offset:3072
	ds_read_b128 v[204:207], v161 offset:4096
	ds_read_b128 v[208:211], v161 offset:5120
	ds_read_b128 v[212:215], v161 offset:6144
	ds_read_b128 v[216:219], v161 offset:7168
	global_load_lds_dwordx4 v[176:177], off
	v_lshl_add_u64 v[176:177], s[30:31], 0, v[138:139]
	s_add_i32 m0, s17, 0xe000
	s_nop 0
	global_load_lds_dwordx4 v[176:177], off
	s_waitcnt vmcnt(8)
	s_waitcnt lgkmcnt(0)
	s_barrier
	s_waitcnt lgkmcnt(0)
	v_mfma_f32_16x16x32_bf16 v[124:127], v[144:147], v[188:191], 0
	v_mfma_f32_16x16x32_bf16 v[120:123], v[152:155], v[188:191], 0
	v_mfma_f32_16x16x32_bf16 v[116:119], v[144:147], v[196:199], 0
	v_mfma_f32_16x16x32_bf16 v[112:115], v[152:155], v[196:199], 0
	v_mfma_f32_16x16x32_bf16 v[104:107], v[144:147], v[204:207], 0
	v_mfma_f32_16x16x32_bf16 v[96:99], v[152:155], v[204:207], 0
	v_mfma_f32_16x16x32_bf16 v[88:91], v[144:147], v[212:215], 0
	v_mfma_f32_16x16x32_bf16 v[80:83], v[152:155], v[212:215], 0
	v_mfma_f32_16x16x32_bf16 v[124:127], v[148:151], v[192:195], v[124:127]
	v_mfma_f32_16x16x32_bf16 v[120:123], v[164:167], v[192:195], v[120:123]
	v_mfma_f32_16x16x32_bf16 v[116:119], v[148:151], v[200:203], v[116:119]
	v_mfma_f32_16x16x32_bf16 v[112:115], v[164:167], v[200:203], v[112:115]
	v_mfma_f32_16x16x32_bf16 v[104:107], v[148:151], v[208:211], v[104:107]
	v_mfma_f32_16x16x32_bf16 v[96:99], v[164:167], v[208:211], v[96:99]
	v_mfma_f32_16x16x32_bf16 v[88:91], v[148:151], v[216:219], v[88:91]
	v_mfma_f32_16x16x32_bf16 v[80:83], v[164:167], v[216:219], v[80:83]
	v_mfma_f32_16x16x32_bf16 v[108:111], v[168:171], v[188:191], 0
	v_mfma_f32_16x16x32_bf16 v[100:103], v[180:183], v[188:191], 0
	v_mfma_f32_16x16x32_bf16 v[92:95], v[168:171], v[196:199], 0
	v_mfma_f32_16x16x32_bf16 v[84:87], v[180:183], v[196:199], 0
	v_mfma_f32_16x16x32_bf16 v[76:79], v[168:171], v[204:207], 0
	v_mfma_f32_16x16x32_bf16 v[72:75], v[180:183], v[204:207], 0
	v_mfma_f32_16x16x32_bf16 v[68:71], v[168:171], v[212:215], 0
	v_mfma_f32_16x16x32_bf16 v[64:67], v[180:183], v[212:215], 0
	v_mfma_f32_16x16x32_bf16 v[108:111], v[172:175], v[192:195], v[108:111]
	v_mfma_f32_16x16x32_bf16 v[100:103], v[184:187], v[192:195], v[100:103]
	v_mfma_f32_16x16x32_bf16 v[92:95], v[172:175], v[200:203], v[92:95]
	v_mfma_f32_16x16x32_bf16 v[84:87], v[184:187], v[200:203], v[84:87]
	v_mfma_f32_16x16x32_bf16 v[76:79], v[172:175], v[208:211], v[76:79]
	v_mfma_f32_16x16x32_bf16 v[72:75], v[184:187], v[208:211], v[72:75]
	v_mfma_f32_16x16x32_bf16 v[68:71], v[172:175], v[216:219], v[68:71]
	v_mfma_f32_16x16x32_bf16 v[64:67], v[184:187], v[216:219], v[64:67]
	s_barrier
	s_add_i32 s68, s57, s16
	v_lshl_add_u64 v[176:177], s[66:67], 0, v[130:131]
	s_mov_b32 m0, s68
	ds_read_b128 v[188:191], v161 offset:16384
	ds_read_b128 v[192:195], v161 offset:17408
	ds_read_b128 v[196:199], v161 offset:18432
	ds_read_b128 v[200:203], v161 offset:19456
	ds_read_b128 v[204:207], v161 offset:20480
	ds_read_b128 v[208:211], v161 offset:21504
	ds_read_b128 v[212:215], v161 offset:22528
	ds_read_b128 v[216:219], v161 offset:23552
	global_load_lds_dwordx4 v[176:177], off
	s_add_i32 m0, s68, 0x2000
	v_lshl_add_u64 v[178:179], s[66:67], 0, v[134:135]
	s_add_u32 s66, s66, s6
	s_addc_u32 s67, s67, s7
	s_add_i32 s68, s58, s16
	global_load_lds_dwordx4 v[178:179], off
	v_lshl_add_u64 v[220:221], s[66:67], 0, v[130:131]
	s_mov_b32 m0, s68
	v_lshl_add_u64 v[222:223], s[66:67], 0, v[134:135]
	global_load_lds_dwordx4 v[220:221], off
	s_add_i32 m0, s68, 0x2000
	v_lshl_add_u64 v[224:225], s[34:35], 0, v[128:129]
	global_load_lds_dwordx4 v[222:223], off
	s_mov_b32 m0, s17
	v_lshl_add_u64 v[226:227], s[34:35], 0, v[132:133]
	global_load_lds_dwordx4 v[224:225], off
	s_mov_b32 m0, s19
	s_nop 0
	global_load_lds_dwordx4 v[226:227], off
	s_waitcnt vmcnt(8)
	s_waitcnt lgkmcnt(0)
	s_barrier
; #define PG8_STAGE(bufoff, gbase, voff) do { _Pragma("unroll") for (int _i = 0; _i < 2; ++_i) \
;         __builtin_amdgcn_global_load_lds((const unsigned*)((const char*)(gbase) + (voff)[_i]), (PG8_LAS unsigned*)(lds + (bufoff) + ldsw + _i * 8192), 16, 0, 0); } while (0)
; #define PG8_LDA(dst, b, h) do { _Pragma("unroll") for (int m = 0; m < 4; ++m) _Pragma("unroll") for (int k = 0; k < 2; ++k) dst[m][k] = *(const PG8_LAS bf16x8*)(lds + PG8_SA(b, h) + aoff + m * 2048 + k * 1024); } while (0)
; #define PG8_LDB(dst, b, h) do { _Pragma("unroll") for (int n = 0; n < 2; ++n) _Pragma("unroll") for (int k = 0; k < 2; ++k) dst[n][k] = *(const PG8_LAS bf16x8*)(lds + PG8_SB(b, h) + boff + n * 2048 + k * 1024); } while (0)
; #define PG8_MMA(ai, bj, At, Bt) do { __builtin_amdgcn_s_setprio(1); _Pragma("unroll") for (int m = 0; m < 4; ++m) _Pragma("unroll") for (int n = 0; n < 2; ++n) _Pragma("unroll") for (int k = 0; k < 2; ++k) \
;         acc[ai][bj][m][n] = __builtin_amdgcn_mfma_f32_16x16x32_bf16(Bt[n][k], At[m][k], acc[ai][bj][m][n], 0, 0, 0); __builtin_amdgcn_s_setprio(0); } while (0)
; #define PG8_WAIT_V(n) asm volatile("s_waitcnt vmcnt(" #n ")" ::: "memory")
; #define PG8_WAIT_L(n) asm volatile("s_waitcnt lgkmcnt(" #n ")" ::: "memory")
; #define PG8_BAR __builtin_amdgcn_s_barrier()
; #define PG8_SCHED __builtin_amdgcn_sched_barrier(0)
; template <class Epi, class Sched, bool ALIGN_EPI = false, bool SP2 = false>
; __device__ __forceinline__ void gemm_phase(PG8_LAS unsigned char* lds, const Gemm g, const Sched& S, const Epi& E) {
;     ...
;             PG8_LDA(At, 0, 1); PG8_STAGE(PG8_SB(0, 0), b2, voffB); PG8_STAGE(PG8_SB(0, 1), b2 + hstep, voffB); PG8_STAGE(PG8_SA(0, 0), a2, voffA);
;             PG8_WAIT_V(8); PG8_WAIT_L(0); PG8_BAR; PG8_MMA(1, 0, At, B0); PG8_MMA(1, 1, At, B1); PG8_BAR; PG8_SCHED;
;             PG8_LDB(B0, 1, 0); PG8_LDB(B1, 1, 1); PG8_SCHED; PG8_LDA(At, 1, 0); PG8_STAGE(PG8_SA(0, 1), a2 + hstep, voffA);
;             PG8_WAIT_V(8); PG8_WAIT_L(0); PG8_BAR; PG8_MMA(0, 0, At, B0); PG8_MMA(0, 1, At, B1); PG8_BAR; PG8_SCHED;
	s_waitcnt lgkmcnt(0)
	v_mfma_f32_16x16x32_bf16 v[60:63], v[144:147], v[188:191], 0
	v_mfma_f32_16x16x32_bf16 v[56:59], v[152:155], v[188:191], 0
	v_mfma_f32_16x16x32_bf16 v[52:55], v[144:147], v[196:199], 0
	v_mfma_f32_16x16x32_bf16 v[48:51], v[152:155], v[196:199], 0
	v_mfma_f32_16x16x32_bf16 v[40:43], v[144:147], v[204:207], 0
	v_mfma_f32_16x16x32_bf16 v[32:35], v[152:155], v[204:207], 0
	v_mfma_f32_16x16x32_bf16 v[24:27], v[144:147], v[212:215], 0
	v_mfma_f32_16x16x32_bf16 v[16:19], v[152:155], v[212:215], 0
	v_mfma_f32_16x16x32_bf16 v[60:63], v[148:151], v[192:195], v[60:63]
	v_mfma_f32_16x16x32_bf16 v[56:59], v[164:167], v[192:195], v[56:59]
	v_mfma_f32_16x16x32_bf16 v[52:55], v[148:151], v[200:203], v[52:55]
	v_mfma_f32_16x16x32_bf16 v[48:51], v[164:167], v[200:203], v[48:51]
	v_mfma_f32_16x16x32_bf16 v[40:43], v[148:151], v[208:211], v[40:43]
	v_mfma_f32_16x16x32_bf16 v[32:35], v[164:167], v[208:211], v[32:35]
	v_mfma_f32_16x16x32_bf16 v[24:27], v[148:151], v[216:219], v[24:27]
	v_mfma_f32_16x16x32_bf16 v[16:19], v[164:167], v[216:219], v[16:19]
	v_mfma_f32_16x16x32_bf16 v[44:47], v[168:171], v[188:191], 0
	v_mfma_f32_16x16x32_bf16 v[36:39], v[180:183], v[188:191], 0
	v_mfma_f32_16x16x32_bf16 v[28:31], v[168:171], v[196:199], 0
	v_mfma_f32_16x16x32_bf16 v[20:23], v[180:183], v[196:199], 0
	v_mfma_f32_16x16x32_bf16 v[12:15], v[168:171], v[204:207], 0
	v_mfma_f32_16x16x32_bf16 v[8:11], v[180:183], v[204:207], 0
	v_mfma_f32_16x16x32_bf16 v[4:7], v[168:171], v[212:215], 0
	v_mfma_f32_16x16x32_bf16 v[0:3], v[180:183], v[212:215], 0
	v_mfma_f32_16x16x32_bf16 v[44:47], v[172:175], v[192:195], v[44:47]
	v_mfma_f32_16x16x32_bf16 v[36:39], v[184:187], v[192:195], v[36:39]
	v_mfma_f32_16x16x32_bf16 v[28:31], v[172:175], v[200:203], v[28:31]
	v_mfma_f32_16x16x32_bf16 v[20:23], v[184:187], v[200:203], v[20:23]
	v_mfma_f32_16x16x32_bf16 v[12:15], v[172:175], v[208:211], v[12:15]
	v_mfma_f32_16x16x32_bf16 v[8:11], v[184:187], v[208:211], v[8:11]
	v_mfma_f32_16x16x32_bf16 v[4:7], v[172:175], v[216:219], v[4:7]
	v_mfma_f32_16x16x32_bf16 v[0:3], v[184:187], v[216:219], v[0:3]
	s_barrier
	s_add_i32 s66, 0, 0x18000
	v_add_u32_e32 v163, s66, v157
	s_add_i32 s67, 0, 0x1c000
	ds_read_b128 v[144:147], v163
	ds_read_b128 v[148:151], v163 offset:1024
	ds_read_b128 v[152:155], v163 offset:2048
	ds_read_b128 v[164:167], v163 offset:3072
	v_add_u32_e32 v163, s67, v157
	ds_read_b128 v[168:171], v163
	ds_read_b128 v[172:175], v163 offset:1024
	ds_read_b128 v[180:183], v163 offset:2048
	ds_read_b128 v[184:187], v163 offset:3072
	s_add_u32 s34, s34, s6
	s_addc_u32 s35, s35, s7
	s_mov_b32 m0, s33
	v_lshl_add_u64 v[228:229], s[34:35], 0, v[128:129]
	ds_read_b128 v[188:191], v161 offset:32768
	ds_read_b128 v[192:195], v161 offset:33792
	ds_read_b128 v[196:199], v161 offset:34816
	ds_read_b128 v[200:203], v161 offset:35840
	ds_read_b128 v[204:207], v161 offset:36864
	ds_read_b128 v[208:211], v161 offset:37888
	ds_read_b128 v[212:215], v161 offset:38912
	ds_read_b128 v[216:219], v161 offset:39936
	global_load_lds_dwordx4 v[228:229], off
	v_lshl_add_u64 v[228:229], s[34:35], 0, v[132:133]
	s_mov_b32 m0, s36
	s_nop 0
	global_load_lds_dwordx4 v[228:229], off
	s_waitcnt vmcnt(8)
	s_waitcnt lgkmcnt(0)
	s_barrier
	s_waitcnt lgkmcnt(0)
	v_mfma_f32_16x16x32_bf16 v[124:127], v[144:147], v[188:191], v[124:127]
	v_mfma_f32_16x16x32_bf16 v[120:123], v[152:155], v[188:191], v[120:123]
	v_mfma_f32_16x16x32_bf16 v[116:119], v[144:147], v[196:199], v[116:119]
	v_mfma_f32_16x16x32_bf16 v[112:115], v[152:155], v[196:199], v[112:115]
	v_mfma_f32_16x16x32_bf16 v[104:107], v[144:147], v[204:207], v[104:107]
	v_mfma_f32_16x16x32_bf16 v[96:99], v[152:155], v[204:207], v[96:99]
	v_mfma_f32_16x16x32_bf16 v[88:91], v[144:147], v[212:215], v[88:91]
	v_mfma_f32_16x16x32_bf16 v[80:83], v[152:155], v[212:215], v[80:83]
	v_mfma_f32_16x16x32_bf16 v[124:127], v[148:151], v[192:195], v[124:127]
	v_mfma_f32_16x16x32_bf16 v[120:123], v[164:167], v[192:195], v[120:123]
	v_mfma_f32_16x16x32_bf16 v[116:119], v[148:151], v[200:203], v[116:119]
	v_mfma_f32_16x16x32_bf16 v[112:115], v[164:167], v[200:203], v[112:115]
	v_mfma_f32_16x16x32_bf16 v[104:107], v[148:151], v[208:211], v[104:107]
	v_mfma_f32_16x16x32_bf16 v[96:99], v[164:167], v[208:211], v[96:99]
	v_mfma_f32_16x16x32_bf16 v[88:91], v[148:151], v[216:219], v[88:91]
	v_mfma_f32_16x16x32_bf16 v[80:83], v[164:167], v[216:219], v[80:83]
	v_mfma_f32_16x16x32_bf16 v[108:111], v[168:171], v[188:191], v[108:111]
	v_mfma_f32_16x16x32_bf16 v[100:103], v[180:183], v[188:191], v[100:103]
	v_mfma_f32_16x16x32_bf16 v[92:95], v[168:171], v[196:199], v[92:95]
	v_mfma_f32_16x16x32_bf16 v[84:87], v[180:183], v[196:199], v[84:87]
	v_mfma_f32_16x16x32_bf16 v[76:79], v[168:171], v[204:207], v[76:79]
	v_mfma_f32_16x16x32_bf16 v[72:75], v[180:183], v[204:207], v[72:75]
	v_mfma_f32_16x16x32_bf16 v[68:71], v[168:171], v[212:215], v[68:71]
	v_mfma_f32_16x16x32_bf16 v[64:67], v[180:183], v[212:215], v[64:67]
	v_mfma_f32_16x16x32_bf16 v[108:111], v[172:175], v[192:195], v[108:111]
	v_mfma_f32_16x16x32_bf16 v[100:103], v[184:187], v[192:195], v[100:103]
	v_mfma_f32_16x16x32_bf16 v[92:95], v[172:175], v[200:203], v[92:95]
	v_mfma_f32_16x16x32_bf16 v[84:87], v[184:187], v[200:203], v[84:87]
	v_mfma_f32_16x16x32_bf16 v[76:79], v[172:175], v[208:211], v[76:79]
	v_mfma_f32_16x16x32_bf16 v[72:75], v[184:187], v[208:211], v[72:75]
	v_mfma_f32_16x16x32_bf16 v[68:71], v[172:175], v[216:219], v[68:71]
	v_mfma_f32_16x16x32_bf16 v[64:67], v[184:187], v[216:219], v[64:67]
	s_barrier
; #define PG8_STAGE(bufoff, gbase, voff) do { _Pragma("unroll") for (int _i = 0; _i < 2; ++_i) \
;         __builtin_amdgcn_global_load_lds((const unsigned*)((const char*)(gbase) + (voff)[_i]), (PG8_LAS unsigned*)(lds + (bufoff) + ldsw + _i * 8192), 16, 0, 0); } while (0)
; #define PG8_LDA(dst, b, h) do { _Pragma("unroll") for (int m = 0; m < 4; ++m) _Pragma("unroll") for (int k = 0; k < 2; ++k) dst[m][k] = *(const PG8_LAS bf16x8*)(lds + PG8_SA(b, h) + aoff + m * 2048 + k * 1024); } while (0)
; #define PG8_LDB(dst, b, h) do { _Pragma("unroll") for (int n = 0; n < 2; ++n) _Pragma("unroll") for (int k = 0; k < 2; ++k) dst[n][k] = *(const PG8_LAS bf16x8*)(lds + PG8_SB(b, h) + boff + n * 2048 + k * 1024); } while (0)
; #define PG8_MMA(ai, bj, At, Bt) do { __builtin_amdgcn_s_setprio(1); _Pragma("unroll") for (int m = 0; m < 4; ++m) _Pragma("unroll") for (int n = 0; n < 2; ++n) _Pragma("unroll") for (int k = 0; k < 2; ++k) \
;         acc[ai][bj][m][n] = __builtin_amdgcn_mfma_f32_16x16x32_bf16(Bt[n][k], At[m][k], acc[ai][bj][m][n], 0, 0, 0); __builtin_amdgcn_s_setprio(0); } while (0)
; #define PG8_WAIT_V(n) asm volatile("s_waitcnt vmcnt(" #n ")" ::: "memory")
; #define PG8_WAIT_L(n) asm volatile("s_waitcnt lgkmcnt(" #n ")" ::: "memory")
; #define PG8_BAR __builtin_amdgcn_s_barrier()
; #define PG8_SCHED __builtin_amdgcn_sched_barrier(0)
; template <class Epi, class Sched, bool ALIGN_EPI = false, bool SP2 = false>
; __device__ __forceinline__ void gemm_phase(PG8_LAS unsigned char* lds, const Gemm g, const Sched& S, const Epi& E) {
;     ...
;         for (int t = 0; t < nt; t += 2) {
;             const bool last = (t == nt - 2);
;             const char* a1 = cA + (size_t)(t + 1) * kstep;
;             const char* a2 = last ? nA : cA + (size_t)(t + 2) * kstep; const char* b2 = last ? nB : cB + (size_t)(t + 2) * kstep;
;             const char* a3 = a2 + kstep; const char* b3 = b2 + kstep;
;             if (last && has_next) S.a_ready(nxt);
;             if constexpr (SP2) {
;             PG8_LDB(B0, 0, 0); PG8_LDB(B1, 0, 1); PG8_SCHED; PG8_LDA(At, 0, 0); PG8_STAGE(PG8_SA(1, 1), a1 + hstep, voffA);
;     ...
;             PG8_LDA(At, 1, 1); PG8_STAGE(PG8_SB(1, 0), b3, voffB); PG8_STAGE(PG8_SB(1, 1), b3 + hstep, voffB); PG8_STAGE(PG8_SA(1, 0), a3, voffA);
;             PG8_WAIT_V(8); PG8_WAIT_L(0); PG8_BAR; PG8_MMA(1, 0, At, B0); PG8_MMA(1, 1, At, B1); PG8_BAR; PG8_SCHED;
	s_add_i32 s34, s66, s16
	v_lshl_add_u64 v[176:177], v[176:177], 0, s[22:23]
	s_mov_b32 m0, s34
	ds_read_b128 v[188:191], v161 offset:49152
	ds_read_b128 v[192:195], v161 offset:50176
	ds_read_b128 v[196:199], v161 offset:51200
	ds_read_b128 v[200:203], v161 offset:52224
	ds_read_b128 v[204:207], v161 offset:53248
	ds_read_b128 v[208:211], v161 offset:54272
	ds_read_b128 v[212:215], v161 offset:55296
	ds_read_b128 v[216:219], v161 offset:56320
	global_load_lds_dwordx4 v[176:177], off
	v_lshl_add_u64 v[176:177], v[178:179], 0, s[22:23]
	s_add_i32 m0, s34, 0x2000
	s_add_i32 s34, s67, s16
	global_load_lds_dwordx4 v[176:177], off
	v_lshl_add_u64 v[176:177], v[220:221], 0, s[22:23]
	s_mov_b32 m0, s34
	s_nop 0
	global_load_lds_dwordx4 v[176:177], off
	v_lshl_add_u64 v[176:177], v[222:223], 0, s[22:23]
	s_add_i32 m0, s34, 0x2000
	s_nop 0
	global_load_lds_dwordx4 v[176:177], off
	v_lshl_add_u64 v[176:177], v[224:225], 0, s[22:23]
	s_mov_b32 m0, s37
	s_nop 0
	global_load_lds_dwordx4 v[176:177], off
	v_lshl_add_u64 v[176:177], v[226:227], 0, s[22:23]
	s_mov_b32 m0, s38
	s_nop 0
	global_load_lds_dwordx4 v[176:177], off
	s_waitcnt vmcnt(8)
	s_waitcnt lgkmcnt(0)
	s_barrier
	s_waitcnt lgkmcnt(0)
	v_mfma_f32_16x16x32_bf16 v[60:63], v[144:147], v[188:191], v[60:63]
	v_mfma_f32_16x16x32_bf16 v[56:59], v[152:155], v[188:191], v[56:59]
	v_mfma_f32_16x16x32_bf16 v[52:55], v[144:147], v[196:199], v[52:55]
	v_mfma_f32_16x16x32_bf16 v[48:51], v[152:155], v[196:199], v[48:51]
	v_mfma_f32_16x16x32_bf16 v[40:43], v[144:147], v[204:207], v[40:43]
	v_mfma_f32_16x16x32_bf16 v[32:35], v[152:155], v[204:207], v[32:35]
	v_mfma_f32_16x16x32_bf16 v[24:27], v[144:147], v[212:215], v[24:27]
	v_mfma_f32_16x16x32_bf16 v[16:19], v[152:155], v[212:215], v[16:19]
	v_mfma_f32_16x16x32_bf16 v[60:63], v[148:151], v[192:195], v[60:63]
	v_mfma_f32_16x16x32_bf16 v[56:59], v[164:167], v[192:195], v[56:59]
	v_mfma_f32_16x16x32_bf16 v[52:55], v[148:151], v[200:203], v[52:55]
	v_mfma_f32_16x16x32_bf16 v[48:51], v[164:167], v[200:203], v[48:51]
	v_mfma_f32_16x16x32_bf16 v[40:43], v[148:151], v[208:211], v[40:43]
	v_mfma_f32_16x16x32_bf16 v[32:35], v[164:167], v[208:211], v[32:35]
	v_mfma_f32_16x16x32_bf16 v[24:27], v[148:151], v[216:219], v[24:27]
	v_mfma_f32_16x16x32_bf16 v[16:19], v[164:167], v[216:219], v[16:19]
	v_mfma_f32_16x16x32_bf16 v[44:47], v[168:171], v[188:191], v[44:47]
	v_mfma_f32_16x16x32_bf16 v[36:39], v[180:183], v[188:191], v[36:39]
	v_mfma_f32_16x16x32_bf16 v[28:31], v[168:171], v[196:199], v[28:31]
	v_mfma_f32_16x16x32_bf16 v[20:23], v[180:183], v[196:199], v[20:23]
	v_mfma_f32_16x16x32_bf16 v[12:15], v[168:171], v[204:207], v[12:15]
	v_mfma_f32_16x16x32_bf16 v[8:11], v[180:183], v[204:207], v[8:11]
	v_mfma_f32_16x16x32_bf16 v[4:7], v[168:171], v[212:215], v[4:7]
	v_mfma_f32_16x16x32_bf16 v[0:3], v[180:183], v[212:215], v[0:3]
	v_mfma_f32_16x16x32_bf16 v[44:47], v[172:175], v[192:195], v[44:47]
	v_mfma_f32_16x16x32_bf16 v[36:39], v[184:187], v[192:195], v[36:39]
	v_mfma_f32_16x16x32_bf16 v[28:31], v[172:175], v[200:203], v[28:31]
	v_mfma_f32_16x16x32_bf16 v[20:23], v[184:187], v[200:203], v[20:23]
	v_mfma_f32_16x16x32_bf16 v[12:15], v[172:175], v[208:211], v[12:15]
	v_mfma_f32_16x16x32_bf16 v[8:11], v[184:187], v[208:211], v[8:11]
	v_mfma_f32_16x16x32_bf16 v[4:7], v[172:175], v[216:219], v[4:7]
	v_mfma_f32_16x16x32_bf16 v[0:3], v[184:187], v[216:219], v[0:3]
	s_barrier
	s_add_u32 s30, s30, 0x100
	s_addc_u32 s31, s31, 0
	s_add_u32 s63, s63, 0x100
	s_addc_u32 s64, s64, 0
	s_cmp_ge_i32 s65, s40
	s_mov_b32 s34, s65
	s_cbranch_scc0 .LBB0_1411
	s_branch .Lpeel_x5
.LBB0_1411:
	ds_read_b128 v[144:147], v159
	ds_read_b128 v[148:151], v159 offset:1024
	ds_read_b128 v[152:155], v159 offset:2048
	ds_read_b128 v[164:167], v159 offset:3072
	ds_read_b128 v[168:171], v160
	ds_read_b128 v[172:175], v160 offset:1024
	ds_read_b128 v[180:183], v160 offset:2048
	ds_read_b128 v[184:187], v160 offset:3072
	s_add_i32 s65, s34, 2
	s_add_u32 s66, s30, 0x80
	s_addc_u32 s35, s31, 0
	s_cmp_eq_u32 s41, s34
	s_cselect_b32 s34, s0, s66
	s_cselect_b32 s35, s1, s35
	s_cselect_b32 s67, s29, s64
	s_cselect_b32 s66, s28, s63
	v_lshl_add_u64 v[176:177], s[30:31], 0, v[136:137]
	s_add_i32 m0, s17, 0xc000
	ds_read_b128 v[188:191], v161
	ds_read_b128 v[192:195], v161 offset:1024
	ds_read_b128 v[196:199], v161 offset:2048
	ds_read_b128 v[200:203], v161 offset:3072
	ds_read_b128 v[204:207], v161 offset:4096
	ds_read_b128 v[208:211], v161 offset:5120
	ds_read_b128 v[212:215], v161 offset:6144
	ds_read_b128 v[216:219], v161 offset:7168
	global_load_lds_dwordx4 v[176:177], off
	v_lshl_add_u64 v[176:177], s[30:31], 0, v[138:139]
	s_add_i32 m0, s17, 0xe000
	s_nop 0
	global_load_lds_dwordx4 v[176:177], off
	s_waitcnt vmcnt(8)
	s_waitcnt lgkmcnt(0)
	s_barrier
; #define PG8_STAGE(bufoff, gbase, voff) do { _Pragma("unroll") for (int _i = 0; _i < 2; ++_i) \
;         __builtin_amdgcn_global_load_lds((const unsigned*)((const char*)(gbase) + (voff)[_i]), (PG8_LAS unsigned*)(lds + (bufoff) + ldsw + _i * 8192), 16, 0, 0); } while (0)
; #define PG8_LDA(dst, b, h) do { _Pragma("unroll") for (int m = 0; m < 4; ++m) _Pragma("unroll") for (int k = 0; k < 2; ++k) dst[m][k] = *(const PG8_LAS bf16x8*)(lds + PG8_SA(b, h) + aoff + m * 2048 + k * 1024); } while (0)
; #define PG8_MMA(ai, bj, At, Bt) do { __builtin_amdgcn_s_setprio(1); _Pragma("unroll") for (int m = 0; m < 4; ++m) _Pragma("unroll") for (int n = 0; n < 2; ++n) _Pragma("unroll") for (int k = 0; k < 2; ++k) \
;         acc[ai][bj][m][n] = __builtin_amdgcn_mfma_f32_16x16x32_bf16(Bt[n][k], At[m][k], acc[ai][bj][m][n], 0, 0, 0); __builtin_amdgcn_s_setprio(0); } while (0)
; #define PG8_WAIT_V(n) asm volatile("s_waitcnt vmcnt(" #n ")" ::: "memory")
; #define PG8_WAIT_L(n) asm volatile("s_waitcnt lgkmcnt(" #n ")" ::: "memory")
; #define PG8_BAR __builtin_amdgcn_s_barrier()
; #define PG8_SCHED __builtin_amdgcn_sched_barrier(0)
; template <class Epi, class Sched, bool ALIGN_EPI = false, bool SP2 = false>
; __device__ __forceinline__ void gemm_phase(PG8_LAS unsigned char* lds, const Gemm g, const Sched& S, const Epi& E) {
;     ...
;             PG8_WAIT_V(8); PG8_WAIT_L(0); PG8_BAR; PG8_MMA(0, 0, At, B0); PG8_MMA(0, 1, At, B1); PG8_BAR; PG8_SCHED;
;             PG8_LDA(At, 0, 1); PG8_STAGE(PG8_SB(0, 0), b2, voffB); PG8_STAGE(PG8_SB(0, 1), b2 + hstep, voffB); PG8_STAGE(PG8_SA(0, 0), a2, voffA);
;             PG8_WAIT_V(8); PG8_WAIT_L(0); PG8_BAR; PG8_MMA(1, 0, At, B0); PG8_MMA(1, 1, At, B1); PG8_BAR; PG8_SCHED;
	s_waitcnt lgkmcnt(0)
	v_mfma_f32_16x16x32_bf16 v[124:127], v[144:147], v[188:191], v[124:127]
	v_mfma_f32_16x16x32_bf16 v[120:123], v[152:155], v[188:191], v[120:123]
	v_mfma_f32_16x16x32_bf16 v[116:119], v[144:147], v[196:199], v[116:119]
	v_mfma_f32_16x16x32_bf16 v[112:115], v[152:155], v[196:199], v[112:115]
	v_mfma_f32_16x16x32_bf16 v[104:107], v[144:147], v[204:207], v[104:107]
	v_mfma_f32_16x16x32_bf16 v[96:99], v[152:155], v[204:207], v[96:99]
	v_mfma_f32_16x16x32_bf16 v[88:91], v[144:147], v[212:215], v[88:91]
	v_mfma_f32_16x16x32_bf16 v[80:83], v[152:155], v[212:215], v[80:83]
	v_mfma_f32_16x16x32_bf16 v[124:127], v[148:151], v[192:195], v[124:127]
	v_mfma_f32_16x16x32_bf16 v[120:123], v[164:167], v[192:195], v[120:123]
	v_mfma_f32_16x16x32_bf16 v[116:119], v[148:151], v[200:203], v[116:119]
	v_mfma_f32_16x16x32_bf16 v[112:115], v[164:167], v[200:203], v[112:115]
	v_mfma_f32_16x16x32_bf16 v[104:107], v[148:151], v[208:211], v[104:107]
	v_mfma_f32_16x16x32_bf16 v[96:99], v[164:167], v[208:211], v[96:99]
	v_mfma_f32_16x16x32_bf16 v[88:91], v[148:151], v[216:219], v[88:91]
	v_mfma_f32_16x16x32_bf16 v[80:83], v[164:167], v[216:219], v[80:83]
	v_mfma_f32_16x16x32_bf16 v[108:111], v[168:171], v[188:191], v[108:111]
	v_mfma_f32_16x16x32_bf16 v[100:103], v[180:183], v[188:191], v[100:103]
	v_mfma_f32_16x16x32_bf16 v[92:95], v[168:171], v[196:199], v[92:95]
	v_mfma_f32_16x16x32_bf16 v[84:87], v[180:183], v[196:199], v[84:87]
	v_mfma_f32_16x16x32_bf16 v[76:79], v[168:171], v[204:207], v[76:79]
	v_mfma_f32_16x16x32_bf16 v[72:75], v[180:183], v[204:207], v[72:75]
	v_mfma_f32_16x16x32_bf16 v[68:71], v[168:171], v[212:215], v[68:71]
	v_mfma_f32_16x16x32_bf16 v[64:67], v[180:183], v[212:215], v[64:67]
	v_mfma_f32_16x16x32_bf16 v[108:111], v[172:175], v[192:195], v[108:111]
	v_mfma_f32_16x16x32_bf16 v[100:103], v[184:187], v[192:195], v[100:103]
	v_mfma_f32_16x16x32_bf16 v[92:95], v[172:175], v[200:203], v[92:95]
	v_mfma_f32_16x16x32_bf16 v[84:87], v[184:187], v[200:203], v[84:87]
	v_mfma_f32_16x16x32_bf16 v[76:79], v[172:175], v[208:211], v[76:79]
	v_mfma_f32_16x16x32_bf16 v[72:75], v[184:187], v[208:211], v[72:75]
	v_mfma_f32_16x16x32_bf16 v[68:71], v[172:175], v[216:219], v[68:71]
	v_mfma_f32_16x16x32_bf16 v[64:67], v[184:187], v[216:219], v[64:67]
	s_barrier
	s_add_i32 s68, s57, s16
	v_lshl_add_u64 v[176:177], s[66:67], 0, v[130:131]
	s_mov_b32 m0, s68
	ds_read_b128 v[188:191], v161 offset:16384
	ds_read_b128 v[192:195], v161 offset:17408
	ds_read_b128 v[196:199], v161 offset:18432
	ds_read_b128 v[200:203], v161 offset:19456
	ds_read_b128 v[204:207], v161 offset:20480
	ds_read_b128 v[208:211], v161 offset:21504
	ds_read_b128 v[212:215], v161 offset:22528
	ds_read_b128 v[216:219], v161 offset:23552
	global_load_lds_dwordx4 v[176:177], off
	s_add_i32 m0, s68, 0x2000
	v_lshl_add_u64 v[178:179], s[66:67], 0, v[134:135]
	s_add_u32 s66, s66, s6
	s_addc_u32 s67, s67, s7
	s_add_i32 s68, s58, s16
	global_load_lds_dwordx4 v[178:179], off
	v_lshl_add_u64 v[220:221], s[66:67], 0, v[130:131]
	s_mov_b32 m0, s68
	v_lshl_add_u64 v[222:223], s[66:67], 0, v[134:135]
	global_load_lds_dwordx4 v[220:221], off
	s_add_i32 m0, s68, 0x2000
	v_lshl_add_u64 v[224:225], s[34:35], 0, v[128:129]
	global_load_lds_dwordx4 v[222:223], off
	s_mov_b32 m0, s17
	v_lshl_add_u64 v[226:227], s[34:35], 0, v[132:133]
	global_load_lds_dwordx4 v[224:225], off
	s_mov_b32 m0, s19
	s_nop 0
	global_load_lds_dwordx4 v[226:227], off
	s_waitcnt vmcnt(8)
	s_waitcnt lgkmcnt(0)
	s_barrier
	s_waitcnt lgkmcnt(0)
	v_mfma_f32_16x16x32_bf16 v[60:63], v[144:147], v[188:191], v[60:63]
	v_mfma_f32_16x16x32_bf16 v[56:59], v[152:155], v[188:191], v[56:59]
	v_mfma_f32_16x16x32_bf16 v[52:55], v[144:147], v[196:199], v[52:55]
	v_mfma_f32_16x16x32_bf16 v[48:51], v[152:155], v[196:199], v[48:51]
	v_mfma_f32_16x16x32_bf16 v[40:43], v[144:147], v[204:207], v[40:43]
	v_mfma_f32_16x16x32_bf16 v[32:35], v[152:155], v[204:207], v[32:35]
	v_mfma_f32_16x16x32_bf16 v[24:27], v[144:147], v[212:215], v[24:27]
	v_mfma_f32_16x16x32_bf16 v[16:19], v[152:155], v[212:215], v[16:19]
	v_mfma_f32_16x16x32_bf16 v[60:63], v[148:151], v[192:195], v[60:63]
	v_mfma_f32_16x16x32_bf16 v[56:59], v[164:167], v[192:195], v[56:59]
	v_mfma_f32_16x16x32_bf16 v[52:55], v[148:151], v[200:203], v[52:55]
	v_mfma_f32_16x16x32_bf16 v[48:51], v[164:167], v[200:203], v[48:51]
	v_mfma_f32_16x16x32_bf16 v[40:43], v[148:151], v[208:211], v[40:43]
	v_mfma_f32_16x16x32_bf16 v[32:35], v[164:167], v[208:211], v[32:35]
	v_mfma_f32_16x16x32_bf16 v[24:27], v[148:151], v[216:219], v[24:27]
	v_mfma_f32_16x16x32_bf16 v[16:19], v[164:167], v[216:219], v[16:19]
	v_mfma_f32_16x16x32_bf16 v[44:47], v[168:171], v[188:191], v[44:47]
	v_mfma_f32_16x16x32_bf16 v[36:39], v[180:183], v[188:191], v[36:39]
	v_mfma_f32_16x16x32_bf16 v[28:31], v[168:171], v[196:199], v[28:31]
	v_mfma_f32_16x16x32_bf16 v[20:23], v[180:183], v[196:199], v[20:23]
	v_mfma_f32_16x16x32_bf16 v[12:15], v[168:171], v[204:207], v[12:15]
	v_mfma_f32_16x16x32_bf16 v[8:11], v[180:183], v[204:207], v[8:11]
	v_mfma_f32_16x16x32_bf16 v[4:7], v[168:171], v[212:215], v[4:7]
	v_mfma_f32_16x16x32_bf16 v[0:3], v[180:183], v[212:215], v[0:3]
	v_mfma_f32_16x16x32_bf16 v[44:47], v[172:175], v[192:195], v[44:47]
	v_mfma_f32_16x16x32_bf16 v[36:39], v[184:187], v[192:195], v[36:39]
	v_mfma_f32_16x16x32_bf16 v[28:31], v[172:175], v[200:203], v[28:31]
	v_mfma_f32_16x16x32_bf16 v[20:23], v[184:187], v[200:203], v[20:23]
	v_mfma_f32_16x16x32_bf16 v[12:15], v[172:175], v[208:211], v[12:15]
	v_mfma_f32_16x16x32_bf16 v[8:11], v[184:187], v[208:211], v[8:11]
	v_mfma_f32_16x16x32_bf16 v[4:7], v[172:175], v[216:219], v[4:7]
	v_mfma_f32_16x16x32_bf16 v[0:3], v[184:187], v[216:219], v[0:3]
	s_barrier
; #define PG8_STAGE(bufoff, gbase, voff) do { _Pragma("unroll") for (int _i = 0; _i < 2; ++_i) \
;         __builtin_amdgcn_global_load_lds((const unsigned*)((const char*)(gbase) + (voff)[_i]), (PG8_LAS unsigned*)(lds + (bufoff) + ldsw + _i * 8192), 16, 0, 0); } while (0)
; #define PG8_LDA(dst, b, h) do { _Pragma("unroll") for (int m = 0; m < 4; ++m) _Pragma("unroll") for (int k = 0; k < 2; ++k) dst[m][k] = *(const PG8_LAS bf16x8*)(lds + PG8_SA(b, h) + aoff + m * 2048 + k * 1024); } while (0)
; #define PG8_LDB(dst, b, h) do { _Pragma("unroll") for (int n = 0; n < 2; ++n) _Pragma("unroll") for (int k = 0; k < 2; ++k) dst[n][k] = *(const PG8_LAS bf16x8*)(lds + PG8_SB(b, h) + boff + n * 2048 + k * 1024); } while (0)
; #define PG8_MMA(ai, bj, At, Bt) do { __builtin_amdgcn_s_setprio(1); _Pragma("unroll") for (int m = 0; m < 4; ++m) _Pragma("unroll") for (int n = 0; n < 2; ++n) _Pragma("unroll") for (int k = 0; k < 2; ++k) \
;         acc[ai][bj][m][n] = __builtin_amdgcn_mfma_f32_16x16x32_bf16(Bt[n][k], At[m][k], acc[ai][bj][m][n], 0, 0, 0); __builtin_amdgcn_s_setprio(0); } while (0)
; #define PG8_WAIT_V(n) asm volatile("s_waitcnt vmcnt(" #n ")" ::: "memory")
; #define PG8_WAIT_L(n) asm volatile("s_waitcnt lgkmcnt(" #n ")" ::: "memory")
; #define PG8_BAR __builtin_amdgcn_s_barrier()
; #define PG8_SCHED __builtin_amdgcn_sched_barrier(0)
; template <class Epi, class Sched, bool ALIGN_EPI = false, bool SP2 = false>
; __device__ __forceinline__ void gemm_phase(PG8_LAS unsigned char* lds, const Gemm g, const Sched& S, const Epi& E) {
;     ...
;             PG8_LDB(B0, 1, 0); PG8_LDB(B1, 1, 1); PG8_SCHED; PG8_LDA(At, 1, 0); PG8_STAGE(PG8_SA(0, 1), a2 + hstep, voffA);
;             PG8_WAIT_V(8); PG8_WAIT_L(0); PG8_BAR; PG8_MMA(0, 0, At, B0); PG8_MMA(0, 1, At, B1); PG8_BAR; PG8_SCHED;
;             PG8_LDA(At, 1, 1); PG8_STAGE(PG8_SB(1, 0), b3, voffB); PG8_STAGE(PG8_SB(1, 1), b3 + hstep, voffB); PG8_STAGE(PG8_SA(1, 0), a3, voffA);
;             PG8_WAIT_V(8); PG8_WAIT_L(0); PG8_BAR; PG8_MMA(1, 0, At, B0); PG8_MMA(1, 1, At, B1); PG8_BAR; PG8_SCHED;
	s_add_i32 s66, 0, 0x18000
	v_add_u32_e32 v163, s66, v157
	s_add_i32 s67, 0, 0x1c000
	ds_read_b128 v[144:147], v163
	ds_read_b128 v[148:151], v163 offset:1024
	ds_read_b128 v[152:155], v163 offset:2048
	ds_read_b128 v[164:167], v163 offset:3072
	v_add_u32_e32 v163, s67, v157
	ds_read_b128 v[168:171], v163
	ds_read_b128 v[172:175], v163 offset:1024
	ds_read_b128 v[180:183], v163 offset:2048
	ds_read_b128 v[184:187], v163 offset:3072
	s_add_u32 s34, s34, s6
	s_addc_u32 s35, s35, s7
	s_mov_b32 m0, s33
	v_lshl_add_u64 v[228:229], s[34:35], 0, v[128:129]
	ds_read_b128 v[188:191], v161 offset:32768
	ds_read_b128 v[192:195], v161 offset:33792
	ds_read_b128 v[196:199], v161 offset:34816
	ds_read_b128 v[200:203], v161 offset:35840
	ds_read_b128 v[204:207], v161 offset:36864
	ds_read_b128 v[208:211], v161 offset:37888
	ds_read_b128 v[212:215], v161 offset:38912
	ds_read_b128 v[216:219], v161 offset:39936
	global_load_lds_dwordx4 v[228:229], off
	v_lshl_add_u64 v[228:229], s[34:35], 0, v[132:133]
	s_mov_b32 m0, s36
	s_nop 0
	global_load_lds_dwordx4 v[228:229], off
	s_waitcnt vmcnt(8)
	s_waitcnt lgkmcnt(0)
	s_barrier
	s_waitcnt lgkmcnt(0)
	v_mfma_f32_16x16x32_bf16 v[124:127], v[144:147], v[188:191], v[124:127]
	v_mfma_f32_16x16x32_bf16 v[120:123], v[152:155], v[188:191], v[120:123]
	v_mfma_f32_16x16x32_bf16 v[116:119], v[144:147], v[196:199], v[116:119]
	v_mfma_f32_16x16x32_bf16 v[112:115], v[152:155], v[196:199], v[112:115]
	v_mfma_f32_16x16x32_bf16 v[104:107], v[144:147], v[204:207], v[104:107]
	v_mfma_f32_16x16x32_bf16 v[96:99], v[152:155], v[204:207], v[96:99]
	v_mfma_f32_16x16x32_bf16 v[88:91], v[144:147], v[212:215], v[88:91]
	v_mfma_f32_16x16x32_bf16 v[80:83], v[152:155], v[212:215], v[80:83]
	v_mfma_f32_16x16x32_bf16 v[124:127], v[148:151], v[192:195], v[124:127]
	v_mfma_f32_16x16x32_bf16 v[120:123], v[164:167], v[192:195], v[120:123]
	v_mfma_f32_16x16x32_bf16 v[116:119], v[148:151], v[200:203], v[116:119]
	v_mfma_f32_16x16x32_bf16 v[112:115], v[164:167], v[200:203], v[112:115]
	v_mfma_f32_16x16x32_bf16 v[104:107], v[148:151], v[208:211], v[104:107]
	v_mfma_f32_16x16x32_bf16 v[96:99], v[164:167], v[208:211], v[96:99]
	v_mfma_f32_16x16x32_bf16 v[88:91], v[148:151], v[216:219], v[88:91]
	v_mfma_f32_16x16x32_bf16 v[80:83], v[164:167], v[216:219], v[80:83]
	v_mfma_f32_16x16x32_bf16 v[108:111], v[168:171], v[188:191], v[108:111]
	v_mfma_f32_16x16x32_bf16 v[100:103], v[180:183], v[188:191], v[100:103]
	v_mfma_f32_16x16x32_bf16 v[92:95], v[168:171], v[196:199], v[92:95]
	v_mfma_f32_16x16x32_bf16 v[84:87], v[180:183], v[196:199], v[84:87]
	v_mfma_f32_16x16x32_bf16 v[76:79], v[168:171], v[204:207], v[76:79]
	v_mfma_f32_16x16x32_bf16 v[72:75], v[180:183], v[204:207], v[72:75]
	v_mfma_f32_16x16x32_bf16 v[68:71], v[168:171], v[212:215], v[68:71]
	v_mfma_f32_16x16x32_bf16 v[64:67], v[180:183], v[212:215], v[64:67]
	v_mfma_f32_16x16x32_bf16 v[108:111], v[172:175], v[192:195], v[108:111]
	v_mfma_f32_16x16x32_bf16 v[100:103], v[184:187], v[192:195], v[100:103]
	v_mfma_f32_16x16x32_bf16 v[92:95], v[172:175], v[200:203], v[92:95]
	v_mfma_f32_16x16x32_bf16 v[84:87], v[184:187], v[200:203], v[84:87]
	v_mfma_f32_16x16x32_bf16 v[76:79], v[172:175], v[208:211], v[76:79]
	v_mfma_f32_16x16x32_bf16 v[72:75], v[184:187], v[208:211], v[72:75]
	v_mfma_f32_16x16x32_bf16 v[68:71], v[172:175], v[216:219], v[68:71]
	v_mfma_f32_16x16x32_bf16 v[64:67], v[184:187], v[216:219], v[64:67]
	s_barrier
	s_add_i32 s34, s66, s16
	v_lshl_add_u64 v[176:177], v[176:177], 0, s[22:23]
	s_mov_b32 m0, s34
	ds_read_b128 v[188:191], v161 offset:49152
	ds_read_b128 v[192:195], v161 offset:50176
	ds_read_b128 v[196:199], v161 offset:51200
	ds_read_b128 v[200:203], v161 offset:52224
	ds_read_b128 v[204:207], v161 offset:53248
	ds_read_b128 v[208:211], v161 offset:54272
	ds_read_b128 v[212:215], v161 offset:55296
	ds_read_b128 v[216:219], v161 offset:56320
	global_load_lds_dwordx4 v[176:177], off
	v_lshl_add_u64 v[176:177], v[178:179], 0, s[22:23]
	s_add_i32 m0, s34, 0x2000
	s_add_i32 s34, s67, s16
	global_load_lds_dwordx4 v[176:177], off
	v_lshl_add_u64 v[176:177], v[220:221], 0, s[22:23]
	s_mov_b32 m0, s34
	s_nop 0
	global_load_lds_dwordx4 v[176:177], off
	v_lshl_add_u64 v[176:177], v[222:223], 0, s[22:23]
	s_add_i32 m0, s34, 0x2000
	s_nop 0
	global_load_lds_dwordx4 v[176:177], off
	v_lshl_add_u64 v[176:177], v[224:225], 0, s[22:23]
	s_mov_b32 m0, s37
	s_nop 0
	global_load_lds_dwordx4 v[176:177], off
	v_lshl_add_u64 v[176:177], v[226:227], 0, s[22:23]
	s_mov_b32 m0, s38
	s_nop 0
	global_load_lds_dwordx4 v[176:177], off
	s_waitcnt vmcnt(8)
	s_waitcnt lgkmcnt(0)
	s_barrier
	s_waitcnt lgkmcnt(0)
	v_mfma_f32_16x16x32_bf16 v[60:63], v[144:147], v[188:191], v[60:63]
	v_mfma_f32_16x16x32_bf16 v[56:59], v[152:155], v[188:191], v[56:59]
	v_mfma_f32_16x16x32_bf16 v[52:55], v[144:147], v[196:199], v[52:55]
	v_mfma_f32_16x16x32_bf16 v[48:51], v[152:155], v[196:199], v[48:51]
	v_mfma_f32_16x16x32_bf16 v[40:43], v[144:147], v[204:207], v[40:43]
	v_mfma_f32_16x16x32_bf16 v[32:35], v[152:155], v[204:207], v[32:35]
	v_mfma_f32_16x16x32_bf16 v[24:27], v[144:147], v[212:215], v[24:27]
	v_mfma_f32_16x16x32_bf16 v[16:19], v[152:155], v[212:215], v[16:19]
	v_mfma_f32_16x16x32_bf16 v[60:63], v[148:151], v[192:195], v[60:63]
	v_mfma_f32_16x16x32_bf16 v[56:59], v[164:167], v[192:195], v[56:59]
	v_mfma_f32_16x16x32_bf16 v[52:55], v[148:151], v[200:203], v[52:55]
	v_mfma_f32_16x16x32_bf16 v[48:51], v[164:167], v[200:203], v[48:51]
	v_mfma_f32_16x16x32_bf16 v[40:43], v[148:151], v[208:211], v[40:43]
	v_mfma_f32_16x16x32_bf16 v[32:35], v[164:167], v[208:211], v[32:35]
	v_mfma_f32_16x16x32_bf16 v[24:27], v[148:151], v[216:219], v[24:27]
	v_mfma_f32_16x16x32_bf16 v[16:19], v[164:167], v[216:219], v[16:19]
	v_mfma_f32_16x16x32_bf16 v[44:47], v[168:171], v[188:191], v[44:47]
	v_mfma_f32_16x16x32_bf16 v[36:39], v[180:183], v[188:191], v[36:39]
	v_mfma_f32_16x16x32_bf16 v[28:31], v[168:171], v[196:199], v[28:31]
	v_mfma_f32_16x16x32_bf16 v[20:23], v[180:183], v[196:199], v[20:23]
	v_mfma_f32_16x16x32_bf16 v[12:15], v[168:171], v[204:207], v[12:15]
	v_mfma_f32_16x16x32_bf16 v[8:11], v[180:183], v[204:207], v[8:11]
	v_mfma_f32_16x16x32_bf16 v[4:7], v[168:171], v[212:215], v[4:7]
	v_mfma_f32_16x16x32_bf16 v[0:3], v[180:183], v[212:215], v[0:3]
	v_mfma_f32_16x16x32_bf16 v[44:47], v[172:175], v[192:195], v[44:47]
	v_mfma_f32_16x16x32_bf16 v[36:39], v[184:187], v[192:195], v[36:39]
	v_mfma_f32_16x16x32_bf16 v[28:31], v[172:175], v[200:203], v[28:31]
	v_mfma_f32_16x16x32_bf16 v[20:23], v[184:187], v[200:203], v[20:23]
	v_mfma_f32_16x16x32_bf16 v[12:15], v[172:175], v[208:211], v[12:15]
	v_mfma_f32_16x16x32_bf16 v[8:11], v[184:187], v[208:211], v[8:11]
	v_mfma_f32_16x16x32_bf16 v[4:7], v[172:175], v[216:219], v[4:7]
	v_mfma_f32_16x16x32_bf16 v[0:3], v[184:187], v[216:219], v[0:3]
	s_barrier
	s_add_u32 s30, s30, 0x100
	s_addc_u32 s31, s31, 0
	s_add_u32 s63, s63, 0x100
	s_addc_u32 s64, s64, 0
	s_cmp_ge_i32 s65, s40
	s_mov_b32 s34, s65
	s_cbranch_scc0 .LBB0_1411

; #define PG8_STAGE(bufoff, gbase, voff) do { _Pragma("unroll") for (int _i = 0; _i < 2; ++_i) \
;         __builtin_amdgcn_global_load_lds((const unsigned*)((const char*)(gbase) + (voff)[_i]), (PG8_LAS unsigned*)(lds + (bufoff) + ldsw + _i * 8192), 16, 0, 0); } while (0)
; #define PG8_LDA(dst, b, h) do { _Pragma("unroll") for (int m = 0; m < 4; ++m) _Pragma("unroll") for (int k = 0; k < 2; ++k) dst[m][k] = *(const PG8_LAS bf16x8*)(lds + PG8_SA(b, h) + aoff + m * 2048 + k * 1024); } while (0)
; #define PG8_LDB(dst, b, h) do { _Pragma("unroll") for (int n = 0; n < 2; ++n) _Pragma("unroll") for (int k = 0; k < 2; ++k) dst[n][k] = *(const PG8_LAS bf16x8*)(lds + PG8_SB(b, h) + boff + n * 2048 + k * 1024); } while (0)
; #define PG8_MMA(ai, bj, At, Bt) do { __builtin_amdgcn_s_setprio(1); _Pragma("unroll") for (int m = 0; m < 4; ++m) _Pragma("unroll") for (int n = 0; n < 2; ++n) _Pragma("unroll") for (int k = 0; k < 2; ++k) \
;         acc[ai][bj][m][n] = __builtin_amdgcn_mfma_f32_16x16x32_bf16(Bt[n][k], At[m][k], acc[ai][bj][m][n], 0, 0, 0); __builtin_amdgcn_s_setprio(0); } while (0)
; #define PG8_WAIT_V(n) asm volatile("s_waitcnt vmcnt(" #n ")" ::: "memory")
; #define PG8_WAIT_L(n) asm volatile("s_waitcnt lgkmcnt(" #n ")" ::: "memory")
; #define PG8_BAR __builtin_amdgcn_s_barrier()
; #define PG8_SCHED __builtin_amdgcn_sched_barrier(0)
; template <class Epi, class Sched, bool ALIGN_EPI = false, bool SP2 = false>
; __device__ __forceinline__ void gemm_phase(PG8_LAS unsigned char* lds, const Gemm g, const Sched& S, const Epi& E) {
;     ...
;         for (int t = 0; t < nt; t += 2) {
;             const bool last = (t == nt - 2);
;             const char* a1 = cA + (size_t)(t + 1) * kstep;
;             const char* a2 = last ? nA : cA + (size_t)(t + 2) * kstep; const char* b2 = last ? nB : cB + (size_t)(t + 2) * kstep;
;             const char* a3 = a2 + kstep; const char* b3 = b2 + kstep;
;             if (last && has_next) S.a_ready(nxt);
;             if constexpr (SP2) {
;             PG8_LDB(B0, 0, 0); PG8_LDB(B1, 0, 1); PG8_SCHED; PG8_LDA(At, 0, 0); PG8_STAGE(PG8_SA(1, 1), a1 + hstep, voffA);
;             PG8_WAIT_V(8); PG8_WAIT_L(0); PG8_BAR; PG8_MMA(0, 0, At, B0); PG8_MMA(0, 1, At, B1); PG8_BAR; PG8_SCHED;
;             PG8_LDA(At, 0, 1); PG8_STAGE(PG8_SB(0, 0), b2, voffB); PG8_STAGE(PG8_SB(0, 1), b2 + hstep, voffB); PG8_STAGE(PG8_SA(0, 0), a2, voffA);
.LBB0_1729:
	s_andn2_b64 vcc, exec, s[36:37]
	s_waitcnt vmcnt(0)
	s_waitcnt lgkmcnt(0)
	s_waitcnt lgkmcnt(0)
	s_cbranch_vccnz .LBB0_1732
	s_add_u32 s0, s8, 0x80
	s_addc_u32 s1, s9, 0
	s_add_u32 s8, s6, 0x100
	s_addc_u32 s9, s7, 0
	s_mov_b32 s6, 0
	ds_read_b128 v[146:149], v167
	ds_read_b128 v[150:153], v167 offset:1024
	ds_read_b128 v[154:157], v167 offset:2048
	ds_read_b128 v[158:161], v167 offset:3072
	ds_read_b128 v[172:175], v168
	ds_read_b128 v[176:179], v168 offset:1024
	ds_read_b128 v[180:183], v168 offset:2048
	ds_read_b128 v[184:187], v168 offset:3072
	s_add_i32 s10, s6, 2
	s_add_u32 s11, s0, 0x80
	s_addc_u32 s7, s1, 0
	s_cmp_eq_u32 s71, s6
	s_cselect_b32 s6, s56, s11
	s_cselect_b32 s7, s57, s7
	s_cselect_b32 s15, s59, s9
	s_cselect_b32 s14, s58, s8
	v_lshl_add_u64 v[162:163], s[0:1], 0, v[138:139]
	s_add_i32 m0, s19, 0xc000
	ds_read_b128 v[188:191], v169
	ds_read_b128 v[192:195], v169 offset:1024
	ds_read_b128 v[196:199], v169 offset:2048
	ds_read_b128 v[200:203], v169 offset:3072
	ds_read_b128 v[204:207], v169 offset:4096
	ds_read_b128 v[208:211], v169 offset:5120
	ds_read_b128 v[212:215], v169 offset:6144
	ds_read_b128 v[216:219], v169 offset:7168
	global_load_lds_dwordx4 v[162:163], off
	v_lshl_add_u64 v[162:163], s[0:1], 0, v[140:141]
	s_add_i32 m0, s19, 0xe000
	s_nop 0
	global_load_lds_dwordx4 v[162:163], off
	s_waitcnt vmcnt(8)
	s_waitcnt lgkmcnt(0)
	s_barrier
	s_waitcnt lgkmcnt(0)
	v_mfma_f32_16x16x32_bf16 v[124:127], v[146:149], v[188:191], 0
	v_mfma_f32_16x16x32_bf16 v[120:123], v[154:157], v[188:191], 0
	v_mfma_f32_16x16x32_bf16 v[108:111], v[146:149], v[196:199], 0
	v_mfma_f32_16x16x32_bf16 v[104:107], v[154:157], v[196:199], 0
	v_mfma_f32_16x16x32_bf16 v[92:95], v[146:149], v[204:207], 0
	v_mfma_f32_16x16x32_bf16 v[88:91], v[154:157], v[204:207], 0
	v_mfma_f32_16x16x32_bf16 v[76:79], v[146:149], v[212:215], 0
	v_mfma_f32_16x16x32_bf16 v[72:75], v[154:157], v[212:215], 0
	v_mfma_f32_16x16x32_bf16 v[124:127], v[150:153], v[192:195], v[124:127]
	v_mfma_f32_16x16x32_bf16 v[120:123], v[158:161], v[192:195], v[120:123]
	v_mfma_f32_16x16x32_bf16 v[108:111], v[150:153], v[200:203], v[108:111]
	v_mfma_f32_16x16x32_bf16 v[104:107], v[158:161], v[200:203], v[104:107]
	v_mfma_f32_16x16x32_bf16 v[92:95], v[150:153], v[208:211], v[92:95]
	v_mfma_f32_16x16x32_bf16 v[88:91], v[158:161], v[208:211], v[88:91]
	v_mfma_f32_16x16x32_bf16 v[76:79], v[150:153], v[216:219], v[76:79]
	v_mfma_f32_16x16x32_bf16 v[72:75], v[158:161], v[216:219], v[72:75]
	v_mfma_f32_16x16x32_bf16 v[116:119], v[172:175], v[188:191], 0
	v_mfma_f32_16x16x32_bf16 v[112:115], v[180:183], v[188:191], 0
	v_mfma_f32_16x16x32_bf16 v[100:103], v[172:175], v[196:199], 0
	v_mfma_f32_16x16x32_bf16 v[96:99], v[180:183], v[196:199], 0
	v_mfma_f32_16x16x32_bf16 v[84:87], v[172:175], v[204:207], 0
	v_mfma_f32_16x16x32_bf16 v[80:83], v[180:183], v[204:207], 0
	v_mfma_f32_16x16x32_bf16 v[68:71], v[172:175], v[212:215], 0
	v_mfma_f32_16x16x32_bf16 v[64:67], v[180:183], v[212:215], 0
	v_mfma_f32_16x16x32_bf16 v[116:119], v[176:179], v[192:195], v[116:119]
	v_mfma_f32_16x16x32_bf16 v[112:115], v[184:187], v[192:195], v[112:115]
	v_mfma_f32_16x16x32_bf16 v[100:103], v[176:179], v[200:203], v[100:103]
	v_mfma_f32_16x16x32_bf16 v[96:99], v[184:187], v[200:203], v[96:99]
	v_mfma_f32_16x16x32_bf16 v[84:87], v[176:179], v[208:211], v[84:87]
	v_mfma_f32_16x16x32_bf16 v[80:83], v[184:187], v[208:211], v[80:83]
	v_mfma_f32_16x16x32_bf16 v[68:71], v[176:179], v[216:219], v[68:71]
	v_mfma_f32_16x16x32_bf16 v[64:67], v[184:187], v[216:219], v[64:67]
	s_barrier
	s_add_i32 s11, s75, s17
	v_lshl_add_u64 v[162:163], s[14:15], 0, v[130:131]
	s_mov_b32 m0, s11
	ds_read_b128 v[188:191], v169 offset:16384
	ds_read_b128 v[192:195], v169 offset:17408
	ds_read_b128 v[196:199], v169 offset:18432
	ds_read_b128 v[200:203], v169 offset:19456
	ds_read_b128 v[204:207], v169 offset:20480
	ds_read_b128 v[208:211], v169 offset:21504
	ds_read_b128 v[212:215], v169 offset:22528
	ds_read_b128 v[216:219], v169 offset:23552
	global_load_lds_dwordx4 v[162:163], off
	s_add_i32 m0, s11, 0x2000
	v_lshl_add_u64 v[220:221], s[14:15], 0, v[134:135]
	s_add_u32 s14, s14, s24
	s_addc_u32 s15, s15, s25
	s_add_i32 s11, s76, s17
	global_load_lds_dwordx4 v[220:221], off
	v_lshl_add_u64 v[222:223], s[14:15], 0, v[130:131]
	s_mov_b32 m0, s11
	v_lshl_add_u64 v[224:225], s[14:15], 0, v[134:135]
	global_load_lds_dwordx4 v[222:223], off
	s_add_i32 m0, s11, 0x2000
	v_lshl_add_u64 v[226:227], s[6:7], 0, v[128:129]
	global_load_lds_dwordx4 v[224:225], off
	s_mov_b32 m0, s19
	v_lshl_add_u64 v[228:229], s[6:7], 0, v[132:133]
	global_load_lds_dwordx4 v[226:227], off
	s_mov_b32 m0, s33
	s_nop 0
	global_load_lds_dwordx4 v[228:229], off
	s_waitcnt vmcnt(8)
	s_waitcnt lgkmcnt(0)
	s_barrier
; #define PG8_STAGE(bufoff, gbase, voff) do { _Pragma("unroll") for (int _i = 0; _i < 2; ++_i) \
;         __builtin_amdgcn_global_load_lds((const unsigned*)((const char*)(gbase) + (voff)[_i]), (PG8_LAS unsigned*)(lds + (bufoff) + ldsw + _i * 8192), 16, 0, 0); } while (0)
; #define PG8_LDA(dst, b, h) do { _Pragma("unroll") for (int m = 0; m < 4; ++m) _Pragma("unroll") for (int k = 0; k < 2; ++k) dst[m][k] = *(const PG8_LAS bf16x8*)(lds + PG8_SA(b, h) + aoff + m * 2048 + k * 1024); } while (0)
; #define PG8_LDB(dst, b, h) do { _Pragma("unroll") for (int n = 0; n < 2; ++n) _Pragma("unroll") for (int k = 0; k < 2; ++k) dst[n][k] = *(const PG8_LAS bf16x8*)(lds + PG8_SB(b, h) + boff + n * 2048 + k * 1024); } while (0)
; #define PG8_MMA(ai, bj, At, Bt) do { __builtin_amdgcn_s_setprio(1); _Pragma("unroll") for (int m = 0; m < 4; ++m) _Pragma("unroll") for (int n = 0; n < 2; ++n) _Pragma("unroll") for (int k = 0; k < 2; ++k) \
;         acc[ai][bj][m][n] = __builtin_amdgcn_mfma_f32_16x16x32_bf16(Bt[n][k], At[m][k], acc[ai][bj][m][n], 0, 0, 0); __builtin_amdgcn_s_setprio(0); } while (0)
; #define PG8_WAIT_V(n) asm volatile("s_waitcnt vmcnt(" #n ")" ::: "memory")
; #define PG8_WAIT_L(n) asm volatile("s_waitcnt lgkmcnt(" #n ")" ::: "memory")
; #define PG8_BAR __builtin_amdgcn_s_barrier()
; #define PG8_SCHED __builtin_amdgcn_sched_barrier(0)
; template <class Epi, class Sched, bool ALIGN_EPI = false, bool SP2 = false>
; __device__ __forceinline__ void gemm_phase(PG8_LAS unsigned char* lds, const Gemm g, const Sched& S, const Epi& E) {
;     ...
;             PG8_LDA(At, 0, 1); PG8_STAGE(PG8_SB(0, 0), b2, voffB); PG8_STAGE(PG8_SB(0, 1), b2 + hstep, voffB); PG8_STAGE(PG8_SA(0, 0), a2, voffA);
;             PG8_WAIT_V(8); PG8_WAIT_L(0); PG8_BAR; PG8_MMA(1, 0, At, B0); PG8_MMA(1, 1, At, B1); PG8_BAR; PG8_SCHED;
;             PG8_LDB(B0, 1, 0); PG8_LDB(B1, 1, 1); PG8_SCHED; PG8_LDA(At, 1, 0); PG8_STAGE(PG8_SA(0, 1), a2 + hstep, voffA);
;             PG8_WAIT_V(8); PG8_WAIT_L(0); PG8_BAR; PG8_MMA(0, 0, At, B0); PG8_MMA(0, 1, At, B1); PG8_BAR; PG8_SCHED;
	s_waitcnt lgkmcnt(0)
	v_mfma_f32_16x16x32_bf16 v[60:63], v[146:149], v[188:191], 0
	v_mfma_f32_16x16x32_bf16 v[56:59], v[154:157], v[188:191], 0
	v_mfma_f32_16x16x32_bf16 v[44:47], v[146:149], v[196:199], 0
	v_mfma_f32_16x16x32_bf16 v[40:43], v[154:157], v[196:199], 0
	v_mfma_f32_16x16x32_bf16 v[28:31], v[146:149], v[204:207], 0
	v_mfma_f32_16x16x32_bf16 v[24:27], v[154:157], v[204:207], 0
	v_mfma_f32_16x16x32_bf16 v[12:15], v[146:149], v[212:215], 0
	v_mfma_f32_16x16x32_bf16 v[8:11], v[154:157], v[212:215], 0
	v_mfma_f32_16x16x32_bf16 v[60:63], v[150:153], v[192:195], v[60:63]
	v_mfma_f32_16x16x32_bf16 v[56:59], v[158:161], v[192:195], v[56:59]
	v_mfma_f32_16x16x32_bf16 v[44:47], v[150:153], v[200:203], v[44:47]
	v_mfma_f32_16x16x32_bf16 v[40:43], v[158:161], v[200:203], v[40:43]
	v_mfma_f32_16x16x32_bf16 v[28:31], v[150:153], v[208:211], v[28:31]
	v_mfma_f32_16x16x32_bf16 v[24:27], v[158:161], v[208:211], v[24:27]
	v_mfma_f32_16x16x32_bf16 v[12:15], v[150:153], v[216:219], v[12:15]
	v_mfma_f32_16x16x32_bf16 v[8:11], v[158:161], v[216:219], v[8:11]
	v_mfma_f32_16x16x32_bf16 v[52:55], v[172:175], v[188:191], 0
	v_mfma_f32_16x16x32_bf16 v[48:51], v[180:183], v[188:191], 0
	v_mfma_f32_16x16x32_bf16 v[36:39], v[172:175], v[196:199], 0
	v_mfma_f32_16x16x32_bf16 v[32:35], v[180:183], v[196:199], 0
	v_mfma_f32_16x16x32_bf16 v[20:23], v[172:175], v[204:207], 0
	v_mfma_f32_16x16x32_bf16 v[16:19], v[180:183], v[204:207], 0
	v_mfma_f32_16x16x32_bf16 v[4:7], v[172:175], v[212:215], 0
	v_mfma_f32_16x16x32_bf16 v[0:3], v[180:183], v[212:215], 0
	v_mfma_f32_16x16x32_bf16 v[52:55], v[176:179], v[192:195], v[52:55]
	v_mfma_f32_16x16x32_bf16 v[48:51], v[184:187], v[192:195], v[48:51]
	v_mfma_f32_16x16x32_bf16 v[36:39], v[176:179], v[200:203], v[36:39]
	v_mfma_f32_16x16x32_bf16 v[32:35], v[184:187], v[200:203], v[32:35]
	v_mfma_f32_16x16x32_bf16 v[20:23], v[176:179], v[208:211], v[20:23]
	v_mfma_f32_16x16x32_bf16 v[16:19], v[184:187], v[208:211], v[16:19]
	v_mfma_f32_16x16x32_bf16 v[4:7], v[176:179], v[216:219], v[4:7]
	v_mfma_f32_16x16x32_bf16 v[0:3], v[184:187], v[216:219], v[0:3]
	s_barrier
	s_add_i32 s11, 0, 0x18000
	v_add_u32_e32 v136, s11, v165
	s_add_i32 s13, 0, 0x1c000
	ds_read_b128 v[146:149], v136
	ds_read_b128 v[150:153], v136 offset:1024
	ds_read_b128 v[154:157], v136 offset:2048
	ds_read_b128 v[158:161], v136 offset:3072
	v_add_u32_e32 v136, s13, v165
	ds_read_b128 v[172:175], v136
	ds_read_b128 v[176:179], v136 offset:1024
	ds_read_b128 v[180:183], v136 offset:2048
	ds_read_b128 v[184:187], v136 offset:3072
	s_add_u32 s6, s6, s24
	s_addc_u32 s7, s7, s25
	s_mov_b32 m0, s66
	v_lshl_add_u64 v[230:231], s[6:7], 0, v[128:129]
	ds_read_b128 v[188:191], v169 offset:32768
	ds_read_b128 v[192:195], v169 offset:33792
	ds_read_b128 v[196:199], v169 offset:34816
	ds_read_b128 v[200:203], v169 offset:35840
	ds_read_b128 v[204:207], v169 offset:36864
	ds_read_b128 v[208:211], v169 offset:37888
	ds_read_b128 v[212:215], v169 offset:38912
	ds_read_b128 v[216:219], v169 offset:39936
	global_load_lds_dwordx4 v[230:231], off
	v_lshl_add_u64 v[230:231], s[6:7], 0, v[132:133]
	s_mov_b32 m0, s67
	s_nop 0
	global_load_lds_dwordx4 v[230:231], off
	s_waitcnt vmcnt(8)
	s_waitcnt lgkmcnt(0)
	s_barrier
	s_waitcnt lgkmcnt(0)
	v_mfma_f32_16x16x32_bf16 v[124:127], v[146:149], v[188:191], v[124:127]
	v_mfma_f32_16x16x32_bf16 v[120:123], v[154:157], v[188:191], v[120:123]
	v_mfma_f32_16x16x32_bf16 v[108:111], v[146:149], v[196:199], v[108:111]
	v_mfma_f32_16x16x32_bf16 v[104:107], v[154:157], v[196:199], v[104:107]
	v_mfma_f32_16x16x32_bf16 v[92:95], v[146:149], v[204:207], v[92:95]
	v_mfma_f32_16x16x32_bf16 v[88:91], v[154:157], v[204:207], v[88:91]
	v_mfma_f32_16x16x32_bf16 v[76:79], v[146:149], v[212:215], v[76:79]
	v_mfma_f32_16x16x32_bf16 v[72:75], v[154:157], v[212:215], v[72:75]
	v_mfma_f32_16x16x32_bf16 v[124:127], v[150:153], v[192:195], v[124:127]
	v_mfma_f32_16x16x32_bf16 v[120:123], v[158:161], v[192:195], v[120:123]
	v_mfma_f32_16x16x32_bf16 v[108:111], v[150:153], v[200:203], v[108:111]
	v_mfma_f32_16x16x32_bf16 v[104:107], v[158:161], v[200:203], v[104:107]
	v_mfma_f32_16x16x32_bf16 v[92:95], v[150:153], v[208:211], v[92:95]
	v_mfma_f32_16x16x32_bf16 v[88:91], v[158:161], v[208:211], v[88:91]
	v_mfma_f32_16x16x32_bf16 v[76:79], v[150:153], v[216:219], v[76:79]
	v_mfma_f32_16x16x32_bf16 v[72:75], v[158:161], v[216:219], v[72:75]
	v_mfma_f32_16x16x32_bf16 v[116:119], v[172:175], v[188:191], v[116:119]
	v_mfma_f32_16x16x32_bf16 v[112:115], v[180:183], v[188:191], v[112:115]
	v_mfma_f32_16x16x32_bf16 v[100:103], v[172:175], v[196:199], v[100:103]
	v_mfma_f32_16x16x32_bf16 v[96:99], v[180:183], v[196:199], v[96:99]
	v_mfma_f32_16x16x32_bf16 v[84:87], v[172:175], v[204:207], v[84:87]
	v_mfma_f32_16x16x32_bf16 v[80:83], v[180:183], v[204:207], v[80:83]
	v_mfma_f32_16x16x32_bf16 v[68:71], v[172:175], v[212:215], v[68:71]
	v_mfma_f32_16x16x32_bf16 v[64:67], v[180:183], v[212:215], v[64:67]
	v_mfma_f32_16x16x32_bf16 v[116:119], v[176:179], v[192:195], v[116:119]
	v_mfma_f32_16x16x32_bf16 v[112:115], v[184:187], v[192:195], v[112:115]
	v_mfma_f32_16x16x32_bf16 v[100:103], v[176:179], v[200:203], v[100:103]
	v_mfma_f32_16x16x32_bf16 v[96:99], v[184:187], v[200:203], v[96:99]
	v_mfma_f32_16x16x32_bf16 v[84:87], v[176:179], v[208:211], v[84:87]
	v_mfma_f32_16x16x32_bf16 v[80:83], v[184:187], v[208:211], v[80:83]
	v_mfma_f32_16x16x32_bf16 v[68:71], v[176:179], v[216:219], v[68:71]
	v_mfma_f32_16x16x32_bf16 v[64:67], v[184:187], v[216:219], v[64:67]
	s_barrier
; #define PG8_STAGE(bufoff, gbase, voff) do { _Pragma("unroll") for (int _i = 0; _i < 2; ++_i) \
;         __builtin_amdgcn_global_load_lds((const unsigned*)((const char*)(gbase) + (voff)[_i]), (PG8_LAS unsigned*)(lds + (bufoff) + ldsw + _i * 8192), 16, 0, 0); } while (0)
; #define PG8_LDA(dst, b, h) do { _Pragma("unroll") for (int m = 0; m < 4; ++m) _Pragma("unroll") for (int k = 0; k < 2; ++k) dst[m][k] = *(const PG8_LAS bf16x8*)(lds + PG8_SA(b, h) + aoff + m * 2048 + k * 1024); } while (0)
; #define PG8_LDB(dst, b, h) do { _Pragma("unroll") for (int n = 0; n < 2; ++n) _Pragma("unroll") for (int k = 0; k < 2; ++k) dst[n][k] = *(const PG8_LAS bf16x8*)(lds + PG8_SB(b, h) + boff + n * 2048 + k * 1024); } while (0)
; #define PG8_MMA(ai, bj, At, Bt) do { __builtin_amdgcn_s_setprio(1); _Pragma("unroll") for (int m = 0; m < 4; ++m) _Pragma("unroll") for (int n = 0; n < 2; ++n) _Pragma("unroll") for (int k = 0; k < 2; ++k) \
;         acc[ai][bj][m][n] = __builtin_amdgcn_mfma_f32_16x16x32_bf16(Bt[n][k], At[m][k], acc[ai][bj][m][n], 0, 0, 0); __builtin_amdgcn_s_setprio(0); } while (0)
; #define PG8_WAIT_V(n) asm volatile("s_waitcnt vmcnt(" #n ")" ::: "memory")
; #define PG8_WAIT_L(n) asm volatile("s_waitcnt lgkmcnt(" #n ")" ::: "memory")
; #define PG8_BAR __builtin_amdgcn_s_barrier()
; #define PG8_SCHED __builtin_amdgcn_sched_barrier(0)
; template <class Epi, class Sched, bool ALIGN_EPI = false, bool SP2 = false>
; __device__ __forceinline__ void gemm_phase(PG8_LAS unsigned char* lds, const Gemm g, const Sched& S, const Epi& E) {
;     ...
;         for (int t = 0; t < nt; t += 2) {
;             const bool last = (t == nt - 2);
;             const char* a1 = cA + (size_t)(t + 1) * kstep;
;             const char* a2 = last ? nA : cA + (size_t)(t + 2) * kstep; const char* b2 = last ? nB : cB + (size_t)(t + 2) * kstep;
;             const char* a3 = a2 + kstep; const char* b3 = b2 + kstep;
;             if (last && has_next) S.a_ready(nxt);
;             if constexpr (SP2) {
;             PG8_LDB(B0, 0, 0); PG8_LDB(B1, 0, 1); PG8_SCHED; PG8_LDA(At, 0, 0); PG8_STAGE(PG8_SA(1, 1), a1 + hstep, voffA);
;     ...
;             PG8_LDA(At, 1, 1); PG8_STAGE(PG8_SB(1, 0), b3, voffB); PG8_STAGE(PG8_SB(1, 1), b3 + hstep, voffB); PG8_STAGE(PG8_SA(1, 0), a3, voffA);
;             PG8_WAIT_V(8); PG8_WAIT_L(0); PG8_BAR; PG8_MMA(1, 0, At, B0); PG8_MMA(1, 1, At, B1); PG8_BAR; PG8_SCHED;
	s_add_i32 s6, s11, s17
	v_lshl_add_u64 v[162:163], v[162:163], 0, s[34:35]
	s_mov_b32 m0, s6
	ds_read_b128 v[188:191], v169 offset:49152
	ds_read_b128 v[192:195], v169 offset:50176
	ds_read_b128 v[196:199], v169 offset:51200
	ds_read_b128 v[200:203], v169 offset:52224
	ds_read_b128 v[204:207], v169 offset:53248
	ds_read_b128 v[208:211], v169 offset:54272
	ds_read_b128 v[212:215], v169 offset:55296
	ds_read_b128 v[216:219], v169 offset:56320
	global_load_lds_dwordx4 v[162:163], off
	v_lshl_add_u64 v[162:163], v[220:221], 0, s[34:35]
	s_add_i32 m0, s6, 0x2000
	s_add_i32 s6, s13, s17
	global_load_lds_dwordx4 v[162:163], off
	v_lshl_add_u64 v[162:163], v[222:223], 0, s[34:35]
	s_mov_b32 m0, s6
	s_nop 0
	global_load_lds_dwordx4 v[162:163], off
	v_lshl_add_u64 v[162:163], v[224:225], 0, s[34:35]
	s_add_i32 m0, s6, 0x2000
	s_nop 0
	global_load_lds_dwordx4 v[162:163], off
	v_lshl_add_u64 v[162:163], v[226:227], 0, s[34:35]
	s_mov_b32 m0, s68
	s_nop 0
	global_load_lds_dwordx4 v[162:163], off
	v_lshl_add_u64 v[162:163], v[228:229], 0, s[34:35]
	s_mov_b32 m0, s69
	s_nop 0
	global_load_lds_dwordx4 v[162:163], off
	s_waitcnt vmcnt(8)
	s_waitcnt lgkmcnt(0)
	s_barrier
	s_waitcnt lgkmcnt(0)
	v_mfma_f32_16x16x32_bf16 v[60:63], v[146:149], v[188:191], v[60:63]
	v_mfma_f32_16x16x32_bf16 v[56:59], v[154:157], v[188:191], v[56:59]
	v_mfma_f32_16x16x32_bf16 v[44:47], v[146:149], v[196:199], v[44:47]
	v_mfma_f32_16x16x32_bf16 v[40:43], v[154:157], v[196:199], v[40:43]
	v_mfma_f32_16x16x32_bf16 v[28:31], v[146:149], v[204:207], v[28:31]
	v_mfma_f32_16x16x32_bf16 v[24:27], v[154:157], v[204:207], v[24:27]
	v_mfma_f32_16x16x32_bf16 v[12:15], v[146:149], v[212:215], v[12:15]
	v_mfma_f32_16x16x32_bf16 v[8:11], v[154:157], v[212:215], v[8:11]
	v_mfma_f32_16x16x32_bf16 v[60:63], v[150:153], v[192:195], v[60:63]
	v_mfma_f32_16x16x32_bf16 v[56:59], v[158:161], v[192:195], v[56:59]
	v_mfma_f32_16x16x32_bf16 v[44:47], v[150:153], v[200:203], v[44:47]
	v_mfma_f32_16x16x32_bf16 v[40:43], v[158:161], v[200:203], v[40:43]
	v_mfma_f32_16x16x32_bf16 v[28:31], v[150:153], v[208:211], v[28:31]
	v_mfma_f32_16x16x32_bf16 v[24:27], v[158:161], v[208:211], v[24:27]
	v_mfma_f32_16x16x32_bf16 v[12:15], v[150:153], v[216:219], v[12:15]
	v_mfma_f32_16x16x32_bf16 v[8:11], v[158:161], v[216:219], v[8:11]
	v_mfma_f32_16x16x32_bf16 v[52:55], v[172:175], v[188:191], v[52:55]
	v_mfma_f32_16x16x32_bf16 v[48:51], v[180:183], v[188:191], v[48:51]
	v_mfma_f32_16x16x32_bf16 v[36:39], v[172:175], v[196:199], v[36:39]
	v_mfma_f32_16x16x32_bf16 v[32:35], v[180:183], v[196:199], v[32:35]
	v_mfma_f32_16x16x32_bf16 v[20:23], v[172:175], v[204:207], v[20:23]
	v_mfma_f32_16x16x32_bf16 v[16:19], v[180:183], v[204:207], v[16:19]
	v_mfma_f32_16x16x32_bf16 v[4:7], v[172:175], v[212:215], v[4:7]
	v_mfma_f32_16x16x32_bf16 v[0:3], v[180:183], v[212:215], v[0:3]
	v_mfma_f32_16x16x32_bf16 v[52:55], v[176:179], v[192:195], v[52:55]
	v_mfma_f32_16x16x32_bf16 v[48:51], v[184:187], v[192:195], v[48:51]
	v_mfma_f32_16x16x32_bf16 v[36:39], v[176:179], v[200:203], v[36:39]
	v_mfma_f32_16x16x32_bf16 v[32:35], v[184:187], v[200:203], v[32:35]
	v_mfma_f32_16x16x32_bf16 v[20:23], v[176:179], v[208:211], v[20:23]
	v_mfma_f32_16x16x32_bf16 v[16:19], v[184:187], v[208:211], v[16:19]
	v_mfma_f32_16x16x32_bf16 v[4:7], v[176:179], v[216:219], v[4:7]
	v_mfma_f32_16x16x32_bf16 v[0:3], v[184:187], v[216:219], v[0:3]
	s_barrier
	s_add_u32 s0, s0, 0x100
	s_addc_u32 s1, s1, 0
	s_add_u32 s8, s8, 0x100
	s_addc_u32 s9, s9, 0
	s_cmp_ge_i32 s10, s70
	s_mov_b32 s6, s10
	s_cbranch_scc0 .LBB0_1731
	s_branch .Lpeel_x8
.LBB0_1731:
	ds_read_b128 v[146:149], v167
	ds_read_b128 v[150:153], v167 offset:1024
	ds_read_b128 v[154:157], v167 offset:2048
	ds_read_b128 v[158:161], v167 offset:3072
	ds_read_b128 v[172:175], v168
	ds_read_b128 v[176:179], v168 offset:1024
	ds_read_b128 v[180:183], v168 offset:2048
	ds_read_b128 v[184:187], v168 offset:3072
	s_add_i32 s10, s6, 2
	s_add_u32 s11, s0, 0x80
	s_addc_u32 s7, s1, 0
	s_cmp_eq_u32 s71, s6
	s_cselect_b32 s6, s56, s11
	s_cselect_b32 s7, s57, s7
	s_cselect_b32 s15, s59, s9
	s_cselect_b32 s14, s58, s8
	v_lshl_add_u64 v[162:163], s[0:1], 0, v[138:139]
	s_add_i32 m0, s19, 0xc000
	ds_read_b128 v[188:191], v169
	ds_read_b128 v[192:195], v169 offset:1024
	ds_read_b128 v[196:199], v169 offset:2048
	ds_read_b128 v[200:203], v169 offset:3072
	ds_read_b128 v[204:207], v169 offset:4096
	ds_read_b128 v[208:211], v169 offset:5120
	ds_read_b128 v[212:215], v169 offset:6144
	ds_read_b128 v[216:219], v169 offset:7168
	global_load_lds_dwordx4 v[162:163], off
	v_lshl_add_u64 v[162:163], s[0:1], 0, v[140:141]
	s_add_i32 m0, s19, 0xe000
	s_nop 0
	global_load_lds_dwordx4 v[162:163], off
	s_waitcnt vmcnt(8)
	s_waitcnt lgkmcnt(0)
	s_barrier
; #define PG8_STAGE(bufoff, gbase, voff) do { _Pragma("unroll") for (int _i = 0; _i < 2; ++_i) \
;         __builtin_amdgcn_global_load_lds((const unsigned*)((const char*)(gbase) + (voff)[_i]), (PG8_LAS unsigned*)(lds + (bufoff) + ldsw + _i * 8192), 16, 0, 0); } while (0)
; #define PG8_LDA(dst, b, h) do { _Pragma("unroll") for (int m = 0; m < 4; ++m) _Pragma("unroll") for (int k = 0; k < 2; ++k) dst[m][k] = *(const PG8_LAS bf16x8*)(lds + PG8_SA(b, h) + aoff + m * 2048 + k * 1024); } while (0)
; #define PG8_MMA(ai, bj, At, Bt) do { __builtin_amdgcn_s_setprio(1); _Pragma("unroll") for (int m = 0; m < 4; ++m) _Pragma("unroll") for (int n = 0; n < 2; ++n) _Pragma("unroll") for (int k = 0; k < 2; ++k) \
;         acc[ai][bj][m][n] = __builtin_amdgcn_mfma_f32_16x16x32_bf16(Bt[n][k], At[m][k], acc[ai][bj][m][n], 0, 0, 0); __builtin_amdgcn_s_setprio(0); } while (0)
; #define PG8_WAIT_V(n) asm volatile("s_waitcnt vmcnt(" #n ")" ::: "memory")
; #define PG8_WAIT_L(n) asm volatile("s_waitcnt lgkmcnt(" #n ")" ::: "memory")
; #define PG8_BAR __builtin_amdgcn_s_barrier()
; #define PG8_SCHED __builtin_amdgcn_sched_barrier(0)
; template <class Epi, class Sched, bool ALIGN_EPI = false, bool SP2 = false>
; __device__ __forceinline__ void gemm_phase(PG8_LAS unsigned char* lds, const Gemm g, const Sched& S, const Epi& E) {
;     ...
;             PG8_WAIT_V(8); PG8_WAIT_L(0); PG8_BAR; PG8_MMA(0, 0, At, B0); PG8_MMA(0, 1, At, B1); PG8_BAR; PG8_SCHED;
;             PG8_LDA(At, 0, 1); PG8_STAGE(PG8_SB(0, 0), b2, voffB); PG8_STAGE(PG8_SB(0, 1), b2 + hstep, voffB); PG8_STAGE(PG8_SA(0, 0), a2, voffA);
;             PG8_WAIT_V(8); PG8_WAIT_L(0); PG8_BAR; PG8_MMA(1, 0, At, B0); PG8_MMA(1, 1, At, B1); PG8_BAR; PG8_SCHED;
	s_waitcnt lgkmcnt(0)
	v_mfma_f32_16x16x32_bf16 v[124:127], v[146:149], v[188:191], v[124:127]
	v_mfma_f32_16x16x32_bf16 v[120:123], v[154:157], v[188:191], v[120:123]
	v_mfma_f32_16x16x32_bf16 v[108:111], v[146:149], v[196:199], v[108:111]
	v_mfma_f32_16x16x32_bf16 v[104:107], v[154:157], v[196:199], v[104:107]
	v_mfma_f32_16x16x32_bf16 v[92:95], v[146:149], v[204:207], v[92:95]
	v_mfma_f32_16x16x32_bf16 v[88:91], v[154:157], v[204:207], v[88:91]
	v_mfma_f32_16x16x32_bf16 v[76:79], v[146:149], v[212:215], v[76:79]
	v_mfma_f32_16x16x32_bf16 v[72:75], v[154:157], v[212:215], v[72:75]
	v_mfma_f32_16x16x32_bf16 v[124:127], v[150:153], v[192:195], v[124:127]
	v_mfma_f32_16x16x32_bf16 v[120:123], v[158:161], v[192:195], v[120:123]
	v_mfma_f32_16x16x32_bf16 v[108:111], v[150:153], v[200:203], v[108:111]
	v_mfma_f32_16x16x32_bf16 v[104:107], v[158:161], v[200:203], v[104:107]
	v_mfma_f32_16x16x32_bf16 v[92:95], v[150:153], v[208:211], v[92:95]
	v_mfma_f32_16x16x32_bf16 v[88:91], v[158:161], v[208:211], v[88:91]
	v_mfma_f32_16x16x32_bf16 v[76:79], v[150:153], v[216:219], v[76:79]
	v_mfma_f32_16x16x32_bf16 v[72:75], v[158:161], v[216:219], v[72:75]
	v_mfma_f32_16x16x32_bf16 v[116:119], v[172:175], v[188:191], v[116:119]
	v_mfma_f32_16x16x32_bf16 v[112:115], v[180:183], v[188:191], v[112:115]
	v_mfma_f32_16x16x32_bf16 v[100:103], v[172:175], v[196:199], v[100:103]
	v_mfma_f32_16x16x32_bf16 v[96:99], v[180:183], v[196:199], v[96:99]
	v_mfma_f32_16x16x32_bf16 v[84:87], v[172:175], v[204:207], v[84:87]
	v_mfma_f32_16x16x32_bf16 v[80:83], v[180:183], v[204:207], v[80:83]
	v_mfma_f32_16x16x32_bf16 v[68:71], v[172:175], v[212:215], v[68:71]
	v_mfma_f32_16x16x32_bf16 v[64:67], v[180:183], v[212:215], v[64:67]
	v_mfma_f32_16x16x32_bf16 v[116:119], v[176:179], v[192:195], v[116:119]
	v_mfma_f32_16x16x32_bf16 v[112:115], v[184:187], v[192:195], v[112:115]
	v_mfma_f32_16x16x32_bf16 v[100:103], v[176:179], v[200:203], v[100:103]
	v_mfma_f32_16x16x32_bf16 v[96:99], v[184:187], v[200:203], v[96:99]
	v_mfma_f32_16x16x32_bf16 v[84:87], v[176:179], v[208:211], v[84:87]
	v_mfma_f32_16x16x32_bf16 v[80:83], v[184:187], v[208:211], v[80:83]
	v_mfma_f32_16x16x32_bf16 v[68:71], v[176:179], v[216:219], v[68:71]
	v_mfma_f32_16x16x32_bf16 v[64:67], v[184:187], v[216:219], v[64:67]
	s_barrier
	s_add_i32 s11, s75, s17
	v_lshl_add_u64 v[162:163], s[14:15], 0, v[130:131]
	s_mov_b32 m0, s11
	ds_read_b128 v[188:191], v169 offset:16384
	ds_read_b128 v[192:195], v169 offset:17408
	ds_read_b128 v[196:199], v169 offset:18432
	ds_read_b128 v[200:203], v169 offset:19456
	ds_read_b128 v[204:207], v169 offset:20480
	ds_read_b128 v[208:211], v169 offset:21504
	ds_read_b128 v[212:215], v169 offset:22528
	ds_read_b128 v[216:219], v169 offset:23552
	global_load_lds_dwordx4 v[162:163], off
	s_add_i32 m0, s11, 0x2000
	v_lshl_add_u64 v[220:221], s[14:15], 0, v[134:135]
	s_add_u32 s14, s14, s24
	s_addc_u32 s15, s15, s25
	s_add_i32 s11, s76, s17
	global_load_lds_dwordx4 v[220:221], off
	v_lshl_add_u64 v[222:223], s[14:15], 0, v[130:131]
	s_mov_b32 m0, s11
	v_lshl_add_u64 v[224:225], s[14:15], 0, v[134:135]
	global_load_lds_dwordx4 v[222:223], off
	s_add_i32 m0, s11, 0x2000
	v_lshl_add_u64 v[226:227], s[6:7], 0, v[128:129]
	global_load_lds_dwordx4 v[224:225], off
	s_mov_b32 m0, s19
	v_lshl_add_u64 v[228:229], s[6:7], 0, v[132:133]
	global_load_lds_dwordx4 v[226:227], off
	s_mov_b32 m0, s33
	s_nop 0
	global_load_lds_dwordx4 v[228:229], off
	s_waitcnt vmcnt(8)
	s_waitcnt lgkmcnt(0)
	s_barrier
	s_waitcnt lgkmcnt(0)
	v_mfma_f32_16x16x32_bf16 v[60:63], v[146:149], v[188:191], v[60:63]
	v_mfma_f32_16x16x32_bf16 v[56:59], v[154:157], v[188:191], v[56:59]
	v_mfma_f32_16x16x32_bf16 v[44:47], v[146:149], v[196:199], v[44:47]
	v_mfma_f32_16x16x32_bf16 v[40:43], v[154:157], v[196:199], v[40:43]
	v_mfma_f32_16x16x32_bf16 v[28:31], v[146:149], v[204:207], v[28:31]
	v_mfma_f32_16x16x32_bf16 v[24:27], v[154:157], v[204:207], v[24:27]
	v_mfma_f32_16x16x32_bf16 v[12:15], v[146:149], v[212:215], v[12:15]
	v_mfma_f32_16x16x32_bf16 v[8:11], v[154:157], v[212:215], v[8:11]
	v_mfma_f32_16x16x32_bf16 v[60:63], v[150:153], v[192:195], v[60:63]
	v_mfma_f32_16x16x32_bf16 v[56:59], v[158:161], v[192:195], v[56:59]
	v_mfma_f32_16x16x32_bf16 v[44:47], v[150:153], v[200:203], v[44:47]
	v_mfma_f32_16x16x32_bf16 v[40:43], v[158:161], v[200:203], v[40:43]
	v_mfma_f32_16x16x32_bf16 v[28:31], v[150:153], v[208:211], v[28:31]
	v_mfma_f32_16x16x32_bf16 v[24:27], v[158:161], v[208:211], v[24:27]
	v_mfma_f32_16x16x32_bf16 v[12:15], v[150:153], v[216:219], v[12:15]
	v_mfma_f32_16x16x32_bf16 v[8:11], v[158:161], v[216:219], v[8:11]
	v_mfma_f32_16x16x32_bf16 v[52:55], v[172:175], v[188:191], v[52:55]
	v_mfma_f32_16x16x32_bf16 v[48:51], v[180:183], v[188:191], v[48:51]
	v_mfma_f32_16x16x32_bf16 v[36:39], v[172:175], v[196:199], v[36:39]
	v_mfma_f32_16x16x32_bf16 v[32:35], v[180:183], v[196:199], v[32:35]
	v_mfma_f32_16x16x32_bf16 v[20:23], v[172:175], v[204:207], v[20:23]
	v_mfma_f32_16x16x32_bf16 v[16:19], v[180:183], v[204:207], v[16:19]
	v_mfma_f32_16x16x32_bf16 v[4:7], v[172:175], v[212:215], v[4:7]
	v_mfma_f32_16x16x32_bf16 v[0:3], v[180:183], v[212:215], v[0:3]
	v_mfma_f32_16x16x32_bf16 v[52:55], v[176:179], v[192:195], v[52:55]
	v_mfma_f32_16x16x32_bf16 v[48:51], v[184:187], v[192:195], v[48:51]
	v_mfma_f32_16x16x32_bf16 v[36:39], v[176:179], v[200:203], v[36:39]
	v_mfma_f32_16x16x32_bf16 v[32:35], v[184:187], v[200:203], v[32:35]
	v_mfma_f32_16x16x32_bf16 v[20:23], v[176:179], v[208:211], v[20:23]
	v_mfma_f32_16x16x32_bf16 v[16:19], v[184:187], v[208:211], v[16:19]
	v_mfma_f32_16x16x32_bf16 v[4:7], v[176:179], v[216:219], v[4:7]
	v_mfma_f32_16x16x32_bf16 v[0:3], v[184:187], v[216:219], v[0:3]
	s_barrier
; #define PG8_STAGE(bufoff, gbase, voff) do { _Pragma("unroll") for (int _i = 0; _i < 2; ++_i) \
;         __builtin_amdgcn_global_load_lds((const unsigned*)((const char*)(gbase) + (voff)[_i]), (PG8_LAS unsigned*)(lds + (bufoff) + ldsw + _i * 8192), 16, 0, 0); } while (0)
; #define PG8_LDA(dst, b, h) do { _Pragma("unroll") for (int m = 0; m < 4; ++m) _Pragma("unroll") for (int k = 0; k < 2; ++k) dst[m][k] = *(const PG8_LAS bf16x8*)(lds + PG8_SA(b, h) + aoff + m * 2048 + k * 1024); } while (0)
; #define PG8_LDB(dst, b, h) do { _Pragma("unroll") for (int n = 0; n < 2; ++n) _Pragma("unroll") for (int k = 0; k < 2; ++k) dst[n][k] = *(const PG8_LAS bf16x8*)(lds + PG8_SB(b, h) + boff + n * 2048 + k * 1024); } while (0)
; #define PG8_MMA(ai, bj, At, Bt) do { __builtin_amdgcn_s_setprio(1); _Pragma("unroll") for (int m = 0; m < 4; ++m) _Pragma("unroll") for (int n = 0; n < 2; ++n) _Pragma("unroll") for (int k = 0; k < 2; ++k) \
;         acc[ai][bj][m][n] = __builtin_amdgcn_mfma_f32_16x16x32_bf16(Bt[n][k], At[m][k], acc[ai][bj][m][n], 0, 0, 0); __builtin_amdgcn_s_setprio(0); } while (0)
; #define PG8_WAIT_V(n) asm volatile("s_waitcnt vmcnt(" #n ")" ::: "memory")
; #define PG8_WAIT_L(n) asm volatile("s_waitcnt lgkmcnt(" #n ")" ::: "memory")
; #define PG8_BAR __builtin_amdgcn_s_barrier()
; #define PG8_SCHED __builtin_amdgcn_sched_barrier(0)
; template <class Epi, class Sched, bool ALIGN_EPI = false, bool SP2 = false>
; __device__ __forceinline__ void gemm_phase(PG8_LAS unsigned char* lds, const Gemm g, const Sched& S, const Epi& E) {
;     ...
;             PG8_LDB(B0, 1, 0); PG8_LDB(B1, 1, 1); PG8_SCHED; PG8_LDA(At, 1, 0); PG8_STAGE(PG8_SA(0, 1), a2 + hstep, voffA);
;             PG8_WAIT_V(8); PG8_WAIT_L(0); PG8_BAR; PG8_MMA(0, 0, At, B0); PG8_MMA(0, 1, At, B1); PG8_BAR; PG8_SCHED;
;             PG8_LDA(At, 1, 1); PG8_STAGE(PG8_SB(1, 0), b3, voffB); PG8_STAGE(PG8_SB(1, 1), b3 + hstep, voffB); PG8_STAGE(PG8_SA(1, 0), a3, voffA);
;             PG8_WAIT_V(8); PG8_WAIT_L(0); PG8_BAR; PG8_MMA(1, 0, At, B0); PG8_MMA(1, 1, At, B1); PG8_BAR; PG8_SCHED;
	s_add_i32 s11, 0, 0x18000
	v_add_u32_e32 v136, s11, v165
	s_add_i32 s13, 0, 0x1c000
	ds_read_b128 v[146:149], v136
	ds_read_b128 v[150:153], v136 offset:1024
	ds_read_b128 v[154:157], v136 offset:2048
	ds_read_b128 v[158:161], v136 offset:3072
	v_add_u32_e32 v136, s13, v165
	ds_read_b128 v[172:175], v136
	ds_read_b128 v[176:179], v136 offset:1024
	ds_read_b128 v[180:183], v136 offset:2048
	ds_read_b128 v[184:187], v136 offset:3072
	s_add_u32 s6, s6, s24
	s_addc_u32 s7, s7, s25
	s_mov_b32 m0, s66
	v_lshl_add_u64 v[230:231], s[6:7], 0, v[128:129]
	ds_read_b128 v[188:191], v169 offset:32768
	ds_read_b128 v[192:195], v169 offset:33792
	ds_read_b128 v[196:199], v169 offset:34816
	ds_read_b128 v[200:203], v169 offset:35840
	ds_read_b128 v[204:207], v169 offset:36864
	ds_read_b128 v[208:211], v169 offset:37888
	ds_read_b128 v[212:215], v169 offset:38912
	ds_read_b128 v[216:219], v169 offset:39936
	global_load_lds_dwordx4 v[230:231], off
	v_lshl_add_u64 v[230:231], s[6:7], 0, v[132:133]
	s_mov_b32 m0, s67
	s_nop 0
	global_load_lds_dwordx4 v[230:231], off
	s_waitcnt vmcnt(8)
	s_waitcnt lgkmcnt(0)
	s_barrier
	s_waitcnt lgkmcnt(0)
	v_mfma_f32_16x16x32_bf16 v[124:127], v[146:149], v[188:191], v[124:127]
	v_mfma_f32_16x16x32_bf16 v[120:123], v[154:157], v[188:191], v[120:123]
	v_mfma_f32_16x16x32_bf16 v[108:111], v[146:149], v[196:199], v[108:111]
	v_mfma_f32_16x16x32_bf16 v[104:107], v[154:157], v[196:199], v[104:107]
	v_mfma_f32_16x16x32_bf16 v[92:95], v[146:149], v[204:207], v[92:95]
	v_mfma_f32_16x16x32_bf16 v[88:91], v[154:157], v[204:207], v[88:91]
	v_mfma_f32_16x16x32_bf16 v[76:79], v[146:149], v[212:215], v[76:79]
	v_mfma_f32_16x16x32_bf16 v[72:75], v[154:157], v[212:215], v[72:75]
	v_mfma_f32_16x16x32_bf16 v[124:127], v[150:153], v[192:195], v[124:127]
	v_mfma_f32_16x16x32_bf16 v[120:123], v[158:161], v[192:195], v[120:123]
	v_mfma_f32_16x16x32_bf16 v[108:111], v[150:153], v[200:203], v[108:111]
	v_mfma_f32_16x16x32_bf16 v[104:107], v[158:161], v[200:203], v[104:107]
	v_mfma_f32_16x16x32_bf16 v[92:95], v[150:153], v[208:211], v[92:95]
	v_mfma_f32_16x16x32_bf16 v[88:91], v[158:161], v[208:211], v[88:91]
	v_mfma_f32_16x16x32_bf16 v[76:79], v[150:153], v[216:219], v[76:79]
	v_mfma_f32_16x16x32_bf16 v[72:75], v[158:161], v[216:219], v[72:75]
	v_mfma_f32_16x16x32_bf16 v[116:119], v[172:175], v[188:191], v[116:119]
	v_mfma_f32_16x16x32_bf16 v[112:115], v[180:183], v[188:191], v[112:115]
	v_mfma_f32_16x16x32_bf16 v[100:103], v[172:175], v[196:199], v[100:103]
	v_mfma_f32_16x16x32_bf16 v[96:99], v[180:183], v[196:199], v[96:99]
	v_mfma_f32_16x16x32_bf16 v[84:87], v[172:175], v[204:207], v[84:87]
	v_mfma_f32_16x16x32_bf16 v[80:83], v[180:183], v[204:207], v[80:83]
	v_mfma_f32_16x16x32_bf16 v[68:71], v[172:175], v[212:215], v[68:71]
	v_mfma_f32_16x16x32_bf16 v[64:67], v[180:183], v[212:215], v[64:67]
	v_mfma_f32_16x16x32_bf16 v[116:119], v[176:179], v[192:195], v[116:119]
	v_mfma_f32_16x16x32_bf16 v[112:115], v[184:187], v[192:195], v[112:115]
	v_mfma_f32_16x16x32_bf16 v[100:103], v[176:179], v[200:203], v[100:103]
	v_mfma_f32_16x16x32_bf16 v[96:99], v[184:187], v[200:203], v[96:99]
	v_mfma_f32_16x16x32_bf16 v[84:87], v[176:179], v[208:211], v[84:87]
	v_mfma_f32_16x16x32_bf16 v[80:83], v[184:187], v[208:211], v[80:83]
	v_mfma_f32_16x16x32_bf16 v[68:71], v[176:179], v[216:219], v[68:71]
	v_mfma_f32_16x16x32_bf16 v[64:67], v[184:187], v[216:219], v[64:67]
	s_barrier
	s_add_i32 s6, s11, s17
	v_lshl_add_u64 v[162:163], v[162:163], 0, s[34:35]
	s_mov_b32 m0, s6
	ds_read_b128 v[188:191], v169 offset:49152
	ds_read_b128 v[192:195], v169 offset:50176
	ds_read_b128 v[196:199], v169 offset:51200
	ds_read_b128 v[200:203], v169 offset:52224
	ds_read_b128 v[204:207], v169 offset:53248
	ds_read_b128 v[208:211], v169 offset:54272
	ds_read_b128 v[212:215], v169 offset:55296
	ds_read_b128 v[216:219], v169 offset:56320
	global_load_lds_dwordx4 v[162:163], off
	v_lshl_add_u64 v[162:163], v[220:221], 0, s[34:35]
	s_add_i32 m0, s6, 0x2000
	s_add_i32 s6, s13, s17
	global_load_lds_dwordx4 v[162:163], off
	v_lshl_add_u64 v[162:163], v[222:223], 0, s[34:35]
	s_mov_b32 m0, s6
	s_nop 0
	global_load_lds_dwordx4 v[162:163], off
	v_lshl_add_u64 v[162:163], v[224:225], 0, s[34:35]
	s_add_i32 m0, s6, 0x2000
	s_nop 0
	global_load_lds_dwordx4 v[162:163], off
	v_lshl_add_u64 v[162:163], v[226:227], 0, s[34:35]
	s_mov_b32 m0, s68
	s_nop 0
	global_load_lds_dwordx4 v[162:163], off
	v_lshl_add_u64 v[162:163], v[228:229], 0, s[34:35]
	s_mov_b32 m0, s69
	s_nop 0
	global_load_lds_dwordx4 v[162:163], off
	s_waitcnt vmcnt(8)
	s_waitcnt lgkmcnt(0)
	s_barrier
	s_waitcnt lgkmcnt(0)
	v_mfma_f32_16x16x32_bf16 v[60:63], v[146:149], v[188:191], v[60:63]
	v_mfma_f32_16x16x32_bf16 v[56:59], v[154:157], v[188:191], v[56:59]
	v_mfma_f32_16x16x32_bf16 v[44:47], v[146:149], v[196:199], v[44:47]
	v_mfma_f32_16x16x32_bf16 v[40:43], v[154:157], v[196:199], v[40:43]
	v_mfma_f32_16x16x32_bf16 v[28:31], v[146:149], v[204:207], v[28:31]
	v_mfma_f32_16x16x32_bf16 v[24:27], v[154:157], v[204:207], v[24:27]
	v_mfma_f32_16x16x32_bf16 v[12:15], v[146:149], v[212:215], v[12:15]
	v_mfma_f32_16x16x32_bf16 v[8:11], v[154:157], v[212:215], v[8:11]
	v_mfma_f32_16x16x32_bf16 v[60:63], v[150:153], v[192:195], v[60:63]
	v_mfma_f32_16x16x32_bf16 v[56:59], v[158:161], v[192:195], v[56:59]
	v_mfma_f32_16x16x32_bf16 v[44:47], v[150:153], v[200:203], v[44:47]
	v_mfma_f32_16x16x32_bf16 v[40:43], v[158:161], v[200:203], v[40:43]
	v_mfma_f32_16x16x32_bf16 v[28:31], v[150:153], v[208:211], v[28:31]
	v_mfma_f32_16x16x32_bf16 v[24:27], v[158:161], v[208:211], v[24:27]
	v_mfma_f32_16x16x32_bf16 v[12:15], v[150:153], v[216:219], v[12:15]
	v_mfma_f32_16x16x32_bf16 v[8:11], v[158:161], v[216:219], v[8:11]
	v_mfma_f32_16x16x32_bf16 v[52:55], v[172:175], v[188:191], v[52:55]
	v_mfma_f32_16x16x32_bf16 v[48:51], v[180:183], v[188:191], v[48:51]
	v_mfma_f32_16x16x32_bf16 v[36:39], v[172:175], v[196:199], v[36:39]
	v_mfma_f32_16x16x32_bf16 v[32:35], v[180:183], v[196:199], v[32:35]
	v_mfma_f32_16x16x32_bf16 v[20:23], v[172:175], v[204:207], v[20:23]
	v_mfma_f32_16x16x32_bf16 v[16:19], v[180:183], v[204:207], v[16:19]
	v_mfma_f32_16x16x32_bf16 v[4:7], v[172:175], v[212:215], v[4:7]
	v_mfma_f32_16x16x32_bf16 v[0:3], v[180:183], v[212:215], v[0:3]
	v_mfma_f32_16x16x32_bf16 v[52:55], v[176:179], v[192:195], v[52:55]
	v_mfma_f32_16x16x32_bf16 v[48:51], v[184:187], v[192:195], v[48:51]
	v_mfma_f32_16x16x32_bf16 v[36:39], v[176:179], v[200:203], v[36:39]
	v_mfma_f32_16x16x32_bf16 v[32:35], v[184:187], v[200:203], v[32:35]
	v_mfma_f32_16x16x32_bf16 v[20:23], v[176:179], v[208:211], v[20:23]
	v_mfma_f32_16x16x32_bf16 v[16:19], v[184:187], v[208:211], v[16:19]
	v_mfma_f32_16x16x32_bf16 v[4:7], v[176:179], v[216:219], v[4:7]
	v_mfma_f32_16x16x32_bf16 v[0:3], v[184:187], v[216:219], v[0:3]
	s_barrier
	s_add_u32 s0, s0, 0x100
	s_addc_u32 s1, s1, 0
	s_add_u32 s8, s8, 0x100
	s_addc_u32 s9, s9, 0
	s_cmp_ge_i32 s10, s70
	s_mov_b32 s6, s10
	s_cbranch_scc0 .LBB0_1731

; #define PG8_STAGE(bufoff, gbase, voff) do { _Pragma("unroll") for (int _i = 0; _i < 2; ++_i) \
;         __builtin_amdgcn_global_load_lds((const unsigned*)((const char*)(gbase) + (voff)[_i]), (PG8_LAS unsigned*)(lds + (bufoff) + ldsw + _i * 8192), 16, 0, 0); } while (0)
; #define PG8_LDA(dst, b, h) do { _Pragma("unroll") for (int m = 0; m < 4; ++m) _Pragma("unroll") for (int k = 0; k < 2; ++k) dst[m][k] = *(const PG8_LAS bf16x8*)(lds + PG8_SA(b, h) + aoff + m * 2048 + k * 1024); } while (0)
; #define PG8_LDB(dst, b, h) do { _Pragma("unroll") for (int n = 0; n < 2; ++n) _Pragma("unroll") for (int k = 0; k < 2; ++k) dst[n][k] = *(const PG8_LAS bf16x8*)(lds + PG8_SB(b, h) + boff + n * 2048 + k * 1024); } while (0)
; #define PG8_MMA(ai, bj, At, Bt) do { __builtin_amdgcn_s_setprio(1); _Pragma("unroll") for (int m = 0; m < 4; ++m) _Pragma("unroll") for (int n = 0; n < 2; ++n) _Pragma("unroll") for (int k = 0; k < 2; ++k) \
;         acc[ai][bj][m][n] = __builtin_amdgcn_mfma_f32_16x16x32_bf16(Bt[n][k], At[m][k], acc[ai][bj][m][n], 0, 0, 0); __builtin_amdgcn_s_setprio(0); } while (0)
; #define PG8_WAIT_V(n) asm volatile("s_waitcnt vmcnt(" #n ")" ::: "memory")
; #define PG8_WAIT_L(n) asm volatile("s_waitcnt lgkmcnt(" #n ")" ::: "memory")
; #define PG8_BAR __builtin_amdgcn_s_barrier()
; #define PG8_SCHED __builtin_amdgcn_sched_barrier(0)
; template <class Epi, class Sched, bool ALIGN_EPI = false, bool SP2 = false>
; __device__ __forceinline__ void gemm_phase(PG8_LAS unsigned char* lds, const Gemm g, const Sched& S, const Epi& E) {
;     ...
;         for (int t = 0; t < nt; t += 2) {
;             const bool last = (t == nt - 2);
;             const char* a1 = cA + (size_t)(t + 1) * kstep;
;             const char* a2 = last ? nA : cA + (size_t)(t + 2) * kstep; const char* b2 = last ? nB : cB + (size_t)(t + 2) * kstep;
;             const char* a3 = a2 + kstep; const char* b3 = b2 + kstep;
;             if (last && has_next) S.a_ready(nxt);
;             if constexpr (SP2) {
;             PG8_LDB(B0, 0, 0); PG8_LDB(B1, 0, 1); PG8_SCHED; PG8_LDA(At, 0, 0); PG8_STAGE(PG8_SA(1, 1), a1 + hstep, voffA);
;             PG8_WAIT_V(8); PG8_WAIT_L(0); PG8_BAR; PG8_MMA(0, 0, At, B0); PG8_MMA(0, 1, At, B1); PG8_BAR; PG8_SCHED;
;             PG8_LDA(At, 0, 1); PG8_STAGE(PG8_SB(0, 0), b2, voffB); PG8_STAGE(PG8_SB(0, 1), b2 + hstep, voffB); PG8_STAGE(PG8_SA(0, 0), a2, voffA);
.LBB0_2050:
	s_andn2_b64 vcc, exec, s[24:25]
	s_waitcnt vmcnt(0)
	s_cbranch_vccnz .LBB0_2053
	s_add_u32 s0, s6, 0x80
	s_addc_u32 s1, s7, 0
	s_add_u32 s6, s4, 0x100
	s_addc_u32 s7, s5, 0
	s_mov_b32 s4, 0
	ds_read_b128 v[146:149], v156
	ds_read_b128 v[160:163], v156 offset:1024
	ds_read_b128 v[164:167], v156 offset:2048
	ds_read_b128 v[168:171], v156 offset:3072
	ds_read_b128 v[172:175], v157
	ds_read_b128 v[176:179], v157 offset:1024
	ds_read_b128 v[180:183], v157 offset:2048
	ds_read_b128 v[184:187], v157 offset:3072
	s_add_i32 s78, s4, 2
	s_add_u32 s79, s0, 0x80
	s_addc_u32 s5, s1, 0
	s_cmp_eq_u32 s57, s4
	s_cselect_b32 s4, s36, s79
	s_cselect_b32 s5, s37, s5
	s_cselect_b32 s81, s39, s7
	s_cselect_b32 s80, s38, s6
	v_lshl_add_u64 v[150:151], s[0:1], 0, v[138:139]
	s_add_i32 m0, s19, 0xc000
	ds_read_b128 v[188:191], v158
	ds_read_b128 v[192:195], v158 offset:1024
	ds_read_b128 v[196:199], v158 offset:2048
	ds_read_b128 v[200:203], v158 offset:3072
	ds_read_b128 v[204:207], v158 offset:4096
	ds_read_b128 v[208:211], v158 offset:5120
	ds_read_b128 v[212:215], v158 offset:6144
	ds_read_b128 v[216:219], v158 offset:7168
	global_load_lds_dwordx4 v[150:151], off
	v_lshl_add_u64 v[150:151], s[0:1], 0, v[140:141]
	s_add_i32 m0, s19, 0xe000
	s_nop 0
	global_load_lds_dwordx4 v[150:151], off
	s_waitcnt vmcnt(8)
	s_waitcnt lgkmcnt(0)
	s_barrier
	s_waitcnt lgkmcnt(0)
	v_mfma_f32_16x16x32_bf16 v[120:123], v[146:149], v[188:191], 0
	v_mfma_f32_16x16x32_bf16 v[124:127], v[164:167], v[188:191], 0
	v_mfma_f32_16x16x32_bf16 v[108:111], v[146:149], v[196:199], 0
	v_mfma_f32_16x16x32_bf16 v[104:107], v[164:167], v[196:199], 0
	v_mfma_f32_16x16x32_bf16 v[92:95], v[146:149], v[204:207], 0
	v_mfma_f32_16x16x32_bf16 v[88:91], v[164:167], v[204:207], 0
	v_mfma_f32_16x16x32_bf16 v[76:79], v[146:149], v[212:215], 0
	v_mfma_f32_16x16x32_bf16 v[72:75], v[164:167], v[212:215], 0
	v_mfma_f32_16x16x32_bf16 v[120:123], v[160:163], v[192:195], v[120:123]
	v_mfma_f32_16x16x32_bf16 v[124:127], v[168:171], v[192:195], v[124:127]
	v_mfma_f32_16x16x32_bf16 v[108:111], v[160:163], v[200:203], v[108:111]
	v_mfma_f32_16x16x32_bf16 v[104:107], v[168:171], v[200:203], v[104:107]
	v_mfma_f32_16x16x32_bf16 v[92:95], v[160:163], v[208:211], v[92:95]
	v_mfma_f32_16x16x32_bf16 v[88:91], v[168:171], v[208:211], v[88:91]
	v_mfma_f32_16x16x32_bf16 v[76:79], v[160:163], v[216:219], v[76:79]
	v_mfma_f32_16x16x32_bf16 v[72:75], v[168:171], v[216:219], v[72:75]
	v_mfma_f32_16x16x32_bf16 v[116:119], v[172:175], v[188:191], 0
	v_mfma_f32_16x16x32_bf16 v[112:115], v[180:183], v[188:191], 0
	v_mfma_f32_16x16x32_bf16 v[100:103], v[172:175], v[196:199], 0
	v_mfma_f32_16x16x32_bf16 v[96:99], v[180:183], v[196:199], 0
	v_mfma_f32_16x16x32_bf16 v[84:87], v[172:175], v[204:207], 0
	v_mfma_f32_16x16x32_bf16 v[80:83], v[180:183], v[204:207], 0
	v_mfma_f32_16x16x32_bf16 v[68:71], v[172:175], v[212:215], 0
	v_mfma_f32_16x16x32_bf16 v[64:67], v[180:183], v[212:215], 0
	v_mfma_f32_16x16x32_bf16 v[116:119], v[176:179], v[192:195], v[116:119]
	v_mfma_f32_16x16x32_bf16 v[112:115], v[184:187], v[192:195], v[112:115]
	v_mfma_f32_16x16x32_bf16 v[100:103], v[176:179], v[200:203], v[100:103]
	v_mfma_f32_16x16x32_bf16 v[96:99], v[184:187], v[200:203], v[96:99]
	v_mfma_f32_16x16x32_bf16 v[84:87], v[176:179], v[208:211], v[84:87]
	v_mfma_f32_16x16x32_bf16 v[80:83], v[184:187], v[208:211], v[80:83]
	v_mfma_f32_16x16x32_bf16 v[68:71], v[176:179], v[216:219], v[68:71]
	v_mfma_f32_16x16x32_bf16 v[64:67], v[184:187], v[216:219], v[64:67]
	s_barrier
	s_add_i32 s79, s63, s17
	v_lshl_add_u64 v[150:151], s[80:81], 0, v[130:131]
	s_mov_b32 m0, s79
	ds_read_b128 v[188:191], v158 offset:16384
	ds_read_b128 v[192:195], v158 offset:17408
	ds_read_b128 v[196:199], v158 offset:18432
	ds_read_b128 v[200:203], v158 offset:19456
	ds_read_b128 v[204:207], v158 offset:20480
	ds_read_b128 v[208:211], v158 offset:21504
	ds_read_b128 v[212:215], v158 offset:22528
	ds_read_b128 v[216:219], v158 offset:23552
	global_load_lds_dwordx4 v[150:151], off
	s_add_i32 m0, s79, 0x2000
	v_lshl_add_u64 v[220:221], s[80:81], 0, v[134:135]
	s_add_u32 s80, s80, s12
	s_addc_u32 s81, s81, s13
	s_add_i32 s79, s64, s17
	global_load_lds_dwordx4 v[220:221], off
	v_lshl_add_u64 v[222:223], s[80:81], 0, v[130:131]
	s_mov_b32 m0, s79
	v_lshl_add_u64 v[224:225], s[80:81], 0, v[134:135]
	global_load_lds_dwordx4 v[222:223], off
	s_add_i32 m0, s79, 0x2000
	v_lshl_add_u64 v[226:227], s[4:5], 0, v[128:129]
	global_load_lds_dwordx4 v[224:225], off
	s_mov_b32 m0, s19
	v_lshl_add_u64 v[228:229], s[4:5], 0, v[132:133]
	global_load_lds_dwordx4 v[226:227], off
	s_mov_b32 m0, s33
	s_nop 0
	global_load_lds_dwordx4 v[228:229], off
	s_waitcnt vmcnt(8)
	s_waitcnt lgkmcnt(0)
	s_barrier
; #define PG8_STAGE(bufoff, gbase, voff) do { _Pragma("unroll") for (int _i = 0; _i < 2; ++_i) \
;         __builtin_amdgcn_global_load_lds((const unsigned*)((const char*)(gbase) + (voff)[_i]), (PG8_LAS unsigned*)(lds + (bufoff) + ldsw + _i * 8192), 16, 0, 0); } while (0)
; #define PG8_LDA(dst, b, h) do { _Pragma("unroll") for (int m = 0; m < 4; ++m) _Pragma("unroll") for (int k = 0; k < 2; ++k) dst[m][k] = *(const PG8_LAS bf16x8*)(lds + PG8_SA(b, h) + aoff + m * 2048 + k * 1024); } while (0)
; #define PG8_LDB(dst, b, h) do { _Pragma("unroll") for (int n = 0; n < 2; ++n) _Pragma("unroll") for (int k = 0; k < 2; ++k) dst[n][k] = *(const PG8_LAS bf16x8*)(lds + PG8_SB(b, h) + boff + n * 2048 + k * 1024); } while (0)
; #define PG8_MMA(ai, bj, At, Bt) do { __builtin_amdgcn_s_setprio(1); _Pragma("unroll") for (int m = 0; m < 4; ++m) _Pragma("unroll") for (int n = 0; n < 2; ++n) _Pragma("unroll") for (int k = 0; k < 2; ++k) \
;         acc[ai][bj][m][n] = __builtin_amdgcn_mfma_f32_16x16x32_bf16(Bt[n][k], At[m][k], acc[ai][bj][m][n], 0, 0, 0); __builtin_amdgcn_s_setprio(0); } while (0)
; #define PG8_WAIT_V(n) asm volatile("s_waitcnt vmcnt(" #n ")" ::: "memory")
; #define PG8_WAIT_L(n) asm volatile("s_waitcnt lgkmcnt(" #n ")" ::: "memory")
; #define PG8_BAR __builtin_amdgcn_s_barrier()
; #define PG8_SCHED __builtin_amdgcn_sched_barrier(0)
; template <class Epi, class Sched, bool ALIGN_EPI = false, bool SP2 = false>
; __device__ __forceinline__ void gemm_phase(PG8_LAS unsigned char* lds, const Gemm g, const Sched& S, const Epi& E) {
;     ...
;             PG8_LDA(At, 0, 1); PG8_STAGE(PG8_SB(0, 0), b2, voffB); PG8_STAGE(PG8_SB(0, 1), b2 + hstep, voffB); PG8_STAGE(PG8_SA(0, 0), a2, voffA);
;             PG8_WAIT_V(8); PG8_WAIT_L(0); PG8_BAR; PG8_MMA(1, 0, At, B0); PG8_MMA(1, 1, At, B1); PG8_BAR; PG8_SCHED;
;             PG8_LDB(B0, 1, 0); PG8_LDB(B1, 1, 1); PG8_SCHED; PG8_LDA(At, 1, 0); PG8_STAGE(PG8_SA(0, 1), a2 + hstep, voffA);
;             PG8_WAIT_V(8); PG8_WAIT_L(0); PG8_BAR; PG8_MMA(0, 0, At, B0); PG8_MMA(0, 1, At, B1); PG8_BAR; PG8_SCHED;
	s_waitcnt lgkmcnt(0)
	v_mfma_f32_16x16x32_bf16 v[60:63], v[146:149], v[188:191], 0
	v_mfma_f32_16x16x32_bf16 v[56:59], v[164:167], v[188:191], 0
	v_mfma_f32_16x16x32_bf16 v[44:47], v[146:149], v[196:199], 0
	v_mfma_f32_16x16x32_bf16 v[40:43], v[164:167], v[196:199], 0
	v_mfma_f32_16x16x32_bf16 v[28:31], v[146:149], v[204:207], 0
	v_mfma_f32_16x16x32_bf16 v[24:27], v[164:167], v[204:207], 0
	v_mfma_f32_16x16x32_bf16 v[12:15], v[146:149], v[212:215], 0
	v_mfma_f32_16x16x32_bf16 v[8:11], v[164:167], v[212:215], 0
	v_mfma_f32_16x16x32_bf16 v[60:63], v[160:163], v[192:195], v[60:63]
	v_mfma_f32_16x16x32_bf16 v[56:59], v[168:171], v[192:195], v[56:59]
	v_mfma_f32_16x16x32_bf16 v[44:47], v[160:163], v[200:203], v[44:47]
	v_mfma_f32_16x16x32_bf16 v[40:43], v[168:171], v[200:203], v[40:43]
	v_mfma_f32_16x16x32_bf16 v[28:31], v[160:163], v[208:211], v[28:31]
	v_mfma_f32_16x16x32_bf16 v[24:27], v[168:171], v[208:211], v[24:27]
	v_mfma_f32_16x16x32_bf16 v[12:15], v[160:163], v[216:219], v[12:15]
	v_mfma_f32_16x16x32_bf16 v[8:11], v[168:171], v[216:219], v[8:11]
	v_mfma_f32_16x16x32_bf16 v[52:55], v[172:175], v[188:191], 0
	v_mfma_f32_16x16x32_bf16 v[48:51], v[180:183], v[188:191], 0
	v_mfma_f32_16x16x32_bf16 v[36:39], v[172:175], v[196:199], 0
	v_mfma_f32_16x16x32_bf16 v[32:35], v[180:183], v[196:199], 0
	v_mfma_f32_16x16x32_bf16 v[20:23], v[172:175], v[204:207], 0
	v_mfma_f32_16x16x32_bf16 v[16:19], v[180:183], v[204:207], 0
	v_mfma_f32_16x16x32_bf16 v[4:7], v[172:175], v[212:215], 0
	v_mfma_f32_16x16x32_bf16 v[0:3], v[180:183], v[212:215], 0
	v_mfma_f32_16x16x32_bf16 v[52:55], v[176:179], v[192:195], v[52:55]
	v_mfma_f32_16x16x32_bf16 v[48:51], v[184:187], v[192:195], v[48:51]
	v_mfma_f32_16x16x32_bf16 v[36:39], v[176:179], v[200:203], v[36:39]
	v_mfma_f32_16x16x32_bf16 v[32:35], v[184:187], v[200:203], v[32:35]
	v_mfma_f32_16x16x32_bf16 v[20:23], v[176:179], v[208:211], v[20:23]
	v_mfma_f32_16x16x32_bf16 v[16:19], v[184:187], v[208:211], v[16:19]
	v_mfma_f32_16x16x32_bf16 v[4:7], v[176:179], v[216:219], v[4:7]
	v_mfma_f32_16x16x32_bf16 v[0:3], v[184:187], v[216:219], v[0:3]
	s_barrier
	s_add_i32 s79, 0, 0x18000
	v_add_u32_e32 v137, s79, v153
	s_add_i32 s80, 0, 0x1c000
	ds_read_b128 v[146:149], v137
	ds_read_b128 v[160:163], v137 offset:1024
	ds_read_b128 v[164:167], v137 offset:2048
	ds_read_b128 v[168:171], v137 offset:3072
	v_add_u32_e32 v137, s80, v153
	ds_read_b128 v[172:175], v137
	ds_read_b128 v[176:179], v137 offset:1024
	ds_read_b128 v[180:183], v137 offset:2048
	ds_read_b128 v[184:187], v137 offset:3072
	s_add_u32 s4, s4, s12
	s_addc_u32 s5, s5, s13
	s_mov_b32 m0, s40
	v_lshl_add_u64 v[230:231], s[4:5], 0, v[128:129]
	ds_read_b128 v[188:191], v158 offset:32768
	ds_read_b128 v[192:195], v158 offset:33792
	ds_read_b128 v[196:199], v158 offset:34816
	ds_read_b128 v[200:203], v158 offset:35840
	ds_read_b128 v[204:207], v158 offset:36864
	ds_read_b128 v[208:211], v158 offset:37888
	ds_read_b128 v[212:215], v158 offset:38912
	ds_read_b128 v[216:219], v158 offset:39936
	global_load_lds_dwordx4 v[230:231], off
	v_lshl_add_u64 v[230:231], s[4:5], 0, v[132:133]
	s_mov_b32 m0, s41
	s_nop 0
	global_load_lds_dwordx4 v[230:231], off
	s_waitcnt vmcnt(8)
	s_waitcnt lgkmcnt(0)
	s_barrier
	s_waitcnt lgkmcnt(0)
	v_mfma_f32_16x16x32_bf16 v[120:123], v[146:149], v[188:191], v[120:123]
	v_mfma_f32_16x16x32_bf16 v[124:127], v[164:167], v[188:191], v[124:127]
	v_mfma_f32_16x16x32_bf16 v[108:111], v[146:149], v[196:199], v[108:111]
	v_mfma_f32_16x16x32_bf16 v[104:107], v[164:167], v[196:199], v[104:107]
	v_mfma_f32_16x16x32_bf16 v[92:95], v[146:149], v[204:207], v[92:95]
	v_mfma_f32_16x16x32_bf16 v[88:91], v[164:167], v[204:207], v[88:91]
	v_mfma_f32_16x16x32_bf16 v[76:79], v[146:149], v[212:215], v[76:79]
	v_mfma_f32_16x16x32_bf16 v[72:75], v[164:167], v[212:215], v[72:75]
	v_mfma_f32_16x16x32_bf16 v[120:123], v[160:163], v[192:195], v[120:123]
	v_mfma_f32_16x16x32_bf16 v[124:127], v[168:171], v[192:195], v[124:127]
	v_mfma_f32_16x16x32_bf16 v[108:111], v[160:163], v[200:203], v[108:111]
	v_mfma_f32_16x16x32_bf16 v[104:107], v[168:171], v[200:203], v[104:107]
	v_mfma_f32_16x16x32_bf16 v[92:95], v[160:163], v[208:211], v[92:95]
	v_mfma_f32_16x16x32_bf16 v[88:91], v[168:171], v[208:211], v[88:91]
	v_mfma_f32_16x16x32_bf16 v[76:79], v[160:163], v[216:219], v[76:79]
	v_mfma_f32_16x16x32_bf16 v[72:75], v[168:171], v[216:219], v[72:75]
	v_mfma_f32_16x16x32_bf16 v[116:119], v[172:175], v[188:191], v[116:119]
	v_mfma_f32_16x16x32_bf16 v[112:115], v[180:183], v[188:191], v[112:115]
	v_mfma_f32_16x16x32_bf16 v[100:103], v[172:175], v[196:199], v[100:103]
	v_mfma_f32_16x16x32_bf16 v[96:99], v[180:183], v[196:199], v[96:99]
	v_mfma_f32_16x16x32_bf16 v[84:87], v[172:175], v[204:207], v[84:87]
	v_mfma_f32_16x16x32_bf16 v[80:83], v[180:183], v[204:207], v[80:83]
	v_mfma_f32_16x16x32_bf16 v[68:71], v[172:175], v[212:215], v[68:71]
	v_mfma_f32_16x16x32_bf16 v[64:67], v[180:183], v[212:215], v[64:67]
	v_mfma_f32_16x16x32_bf16 v[116:119], v[176:179], v[192:195], v[116:119]
	v_mfma_f32_16x16x32_bf16 v[112:115], v[184:187], v[192:195], v[112:115]
	v_mfma_f32_16x16x32_bf16 v[100:103], v[176:179], v[200:203], v[100:103]
	v_mfma_f32_16x16x32_bf16 v[96:99], v[184:187], v[200:203], v[96:99]
	v_mfma_f32_16x16x32_bf16 v[84:87], v[176:179], v[208:211], v[84:87]
	v_mfma_f32_16x16x32_bf16 v[80:83], v[184:187], v[208:211], v[80:83]
	v_mfma_f32_16x16x32_bf16 v[68:71], v[176:179], v[216:219], v[68:71]
	v_mfma_f32_16x16x32_bf16 v[64:67], v[184:187], v[216:219], v[64:67]
	s_barrier
; #define PG8_STAGE(bufoff, gbase, voff) do { _Pragma("unroll") for (int _i = 0; _i < 2; ++_i) \
;         __builtin_amdgcn_global_load_lds((const unsigned*)((const char*)(gbase) + (voff)[_i]), (PG8_LAS unsigned*)(lds + (bufoff) + ldsw + _i * 8192), 16, 0, 0); } while (0)
; #define PG8_LDA(dst, b, h) do { _Pragma("unroll") for (int m = 0; m < 4; ++m) _Pragma("unroll") for (int k = 0; k < 2; ++k) dst[m][k] = *(const PG8_LAS bf16x8*)(lds + PG8_SA(b, h) + aoff + m * 2048 + k * 1024); } while (0)
; #define PG8_LDB(dst, b, h) do { _Pragma("unroll") for (int n = 0; n < 2; ++n) _Pragma("unroll") for (int k = 0; k < 2; ++k) dst[n][k] = *(const PG8_LAS bf16x8*)(lds + PG8_SB(b, h) + boff + n * 2048 + k * 1024); } while (0)
; #define PG8_MMA(ai, bj, At, Bt) do { __builtin_amdgcn_s_setprio(1); _Pragma("unroll") for (int m = 0; m < 4; ++m) _Pragma("unroll") for (int n = 0; n < 2; ++n) _Pragma("unroll") for (int k = 0; k < 2; ++k) \
;         acc[ai][bj][m][n] = __builtin_amdgcn_mfma_f32_16x16x32_bf16(Bt[n][k], At[m][k], acc[ai][bj][m][n], 0, 0, 0); __builtin_amdgcn_s_setprio(0); } while (0)
; #define PG8_WAIT_V(n) asm volatile("s_waitcnt vmcnt(" #n ")" ::: "memory")
; template <class Epi, class Sched, bool ALIGN_EPI = false, bool SP2 = false>
; __device__ __forceinline__ void gemm_phase(PG8_LAS unsigned char* lds, const Gemm g, const Sched& S, const Epi& E) {
;     ...
;             PG8_LDB(B0, 0, 0); PG8_LDB(B1, 0, 1); PG8_SCHED; PG8_LDA(At, 0, 0); PG8_STAGE(PG8_SA(1, 1), a1 + hstep, voffA);
;             PG8_WAIT_V(8); PG8_WAIT_L(0); PG8_BAR; PG8_MMA(0, 0, At, B0); PG8_MMA(0, 1, At, B1); PG8_BAR; PG8_SCHED;
;             PG8_LDA(At, 0, 1); PG8_STAGE(PG8_SB(0, 0), b2, voffB); PG8_STAGE(PG8_SB(0, 1), b2 + hstep, voffB); PG8_STAGE(PG8_SA(0, 0), a2, voffA);
;             PG8_WAIT_V(8); PG8_WAIT_L(0); PG8_BAR; PG8_MMA(1, 0, At, B0); PG8_MMA(1, 1, At, B1); PG8_BAR; PG8_SCHED;
;             PG8_LDB(B0, 1, 0); PG8_LDB(B1, 1, 1); PG8_SCHED; PG8_LDA(At, 1, 0); PG8_STAGE(PG8_SA(0, 1), a2 + hstep, voffA);
;             PG8_WAIT_V(8); PG8_WAIT_L(0); PG8_BAR; PG8_MMA(0, 0, At, B0); PG8_MMA(0, 1, At, B1); PG8_BAR; PG8_SCHED;
;             PG8_LDA(At, 1, 1); PG8_STAGE(PG8_SB(1, 0), b3, voffB); PG8_STAGE(PG8_SB(1, 1), b3 + hstep, voffB); PG8_STAGE(PG8_SA(1, 0), a3, voffA);
;             PG8_WAIT_V(8); PG8_WAIT_L(0); PG8_BAR; PG8_MMA(1, 0, At, B0); PG8_MMA(1, 1, At, B1); PG8_BAR; PG8_SCHED;
	s_add_i32 s4, s79, s17
	v_lshl_add_u64 v[150:151], v[150:151], 0, s[22:23]
	s_mov_b32 m0, s4
	ds_read_b128 v[188:191], v158 offset:49152
	ds_read_b128 v[192:195], v158 offset:50176
	ds_read_b128 v[196:199], v158 offset:51200
	ds_read_b128 v[200:203], v158 offset:52224
	ds_read_b128 v[204:207], v158 offset:53248
	ds_read_b128 v[208:211], v158 offset:54272
	ds_read_b128 v[212:215], v158 offset:55296
	ds_read_b128 v[216:219], v158 offset:56320
	global_load_lds_dwordx4 v[150:151], off
	v_lshl_add_u64 v[150:151], v[220:221], 0, s[22:23]
	s_add_i32 m0, s4, 0x2000
	s_add_i32 s4, s80, s17
	global_load_lds_dwordx4 v[150:151], off
	v_lshl_add_u64 v[150:151], v[222:223], 0, s[22:23]
	s_mov_b32 m0, s4
	s_nop 0
	global_load_lds_dwordx4 v[150:151], off
	v_lshl_add_u64 v[150:151], v[224:225], 0, s[22:23]
	s_add_i32 m0, s4, 0x2000
	s_nop 0
	global_load_lds_dwordx4 v[150:151], off
	v_lshl_add_u64 v[150:151], v[226:227], 0, s[22:23]
	s_mov_b32 m0, s45
	s_nop 0
	global_load_lds_dwordx4 v[150:151], off
	v_lshl_add_u64 v[150:151], v[228:229], 0, s[22:23]
	s_mov_b32 m0, s50
	s_nop 0
	global_load_lds_dwordx4 v[150:151], off
	s_waitcnt vmcnt(8)
	s_waitcnt lgkmcnt(0)
	s_barrier
	s_waitcnt lgkmcnt(0)
	v_mfma_f32_16x16x32_bf16 v[60:63], v[146:149], v[188:191], v[60:63]
	v_mfma_f32_16x16x32_bf16 v[56:59], v[164:167], v[188:191], v[56:59]
	v_mfma_f32_16x16x32_bf16 v[44:47], v[146:149], v[196:199], v[44:47]
	v_mfma_f32_16x16x32_bf16 v[40:43], v[164:167], v[196:199], v[40:43]
	v_mfma_f32_16x16x32_bf16 v[28:31], v[146:149], v[204:207], v[28:31]
	v_mfma_f32_16x16x32_bf16 v[24:27], v[164:167], v[204:207], v[24:27]
	v_mfma_f32_16x16x32_bf16 v[12:15], v[146:149], v[212:215], v[12:15]
	v_mfma_f32_16x16x32_bf16 v[8:11], v[164:167], v[212:215], v[8:11]
	v_mfma_f32_16x16x32_bf16 v[60:63], v[160:163], v[192:195], v[60:63]
	v_mfma_f32_16x16x32_bf16 v[56:59], v[168:171], v[192:195], v[56:59]
	v_mfma_f32_16x16x32_bf16 v[44:47], v[160:163], v[200:203], v[44:47]
	v_mfma_f32_16x16x32_bf16 v[40:43], v[168:171], v[200:203], v[40:43]
	v_mfma_f32_16x16x32_bf16 v[28:31], v[160:163], v[208:211], v[28:31]
	v_mfma_f32_16x16x32_bf16 v[24:27], v[168:171], v[208:211], v[24:27]
	v_mfma_f32_16x16x32_bf16 v[12:15], v[160:163], v[216:219], v[12:15]
	v_mfma_f32_16x16x32_bf16 v[8:11], v[168:171], v[216:219], v[8:11]
	v_mfma_f32_16x16x32_bf16 v[52:55], v[172:175], v[188:191], v[52:55]
	v_mfma_f32_16x16x32_bf16 v[48:51], v[180:183], v[188:191], v[48:51]
	v_mfma_f32_16x16x32_bf16 v[36:39], v[172:175], v[196:199], v[36:39]
	v_mfma_f32_16x16x32_bf16 v[32:35], v[180:183], v[196:199], v[32:35]
	v_mfma_f32_16x16x32_bf16 v[20:23], v[172:175], v[204:207], v[20:23]
	v_mfma_f32_16x16x32_bf16 v[16:19], v[180:183], v[204:207], v[16:19]
	v_mfma_f32_16x16x32_bf16 v[4:7], v[172:175], v[212:215], v[4:7]
	v_mfma_f32_16x16x32_bf16 v[0:3], v[180:183], v[212:215], v[0:3]
	v_mfma_f32_16x16x32_bf16 v[52:55], v[176:179], v[192:195], v[52:55]
	v_mfma_f32_16x16x32_bf16 v[48:51], v[184:187], v[192:195], v[48:51]
	v_mfma_f32_16x16x32_bf16 v[36:39], v[176:179], v[200:203], v[36:39]
	v_mfma_f32_16x16x32_bf16 v[32:35], v[184:187], v[200:203], v[32:35]
	v_mfma_f32_16x16x32_bf16 v[20:23], v[176:179], v[208:211], v[20:23]
	v_mfma_f32_16x16x32_bf16 v[16:19], v[184:187], v[208:211], v[16:19]
	v_mfma_f32_16x16x32_bf16 v[4:7], v[176:179], v[216:219], v[4:7]
	v_mfma_f32_16x16x32_bf16 v[0:3], v[184:187], v[216:219], v[0:3]
	s_barrier
	s_add_u32 s0, s0, 0x100
	s_addc_u32 s1, s1, 0
	s_add_u32 s6, s6, 0x100
	s_addc_u32 s7, s7, 0
	s_cmp_ge_i32 s78, s51
	s_mov_b32 s4, s78
	s_cbranch_scc0 .LBB0_2052
	s_branch .Lpeel_x9
.LBB0_2052:
	ds_read_b128 v[146:149], v156
	ds_read_b128 v[160:163], v156 offset:1024
	ds_read_b128 v[164:167], v156 offset:2048
	ds_read_b128 v[168:171], v156 offset:3072
	ds_read_b128 v[172:175], v157
	ds_read_b128 v[176:179], v157 offset:1024
	ds_read_b128 v[180:183], v157 offset:2048
	ds_read_b128 v[184:187], v157 offset:3072
	s_add_i32 s78, s4, 2
	s_add_u32 s79, s0, 0x80
	s_addc_u32 s5, s1, 0
	s_cmp_eq_u32 s57, s4
	s_cselect_b32 s4, s36, s79
	s_cselect_b32 s5, s37, s5
	s_cselect_b32 s81, s39, s7
	s_cselect_b32 s80, s38, s6
	v_lshl_add_u64 v[150:151], s[0:1], 0, v[138:139]
	s_add_i32 m0, s19, 0xc000
	ds_read_b128 v[188:191], v158
	ds_read_b128 v[192:195], v158 offset:1024
	ds_read_b128 v[196:199], v158 offset:2048
	ds_read_b128 v[200:203], v158 offset:3072
	ds_read_b128 v[204:207], v158 offset:4096
	ds_read_b128 v[208:211], v158 offset:5120
	ds_read_b128 v[212:215], v158 offset:6144
	ds_read_b128 v[216:219], v158 offset:7168
	global_load_lds_dwordx4 v[150:151], off
	v_lshl_add_u64 v[150:151], s[0:1], 0, v[140:141]
	s_add_i32 m0, s19, 0xe000
	s_nop 0
	global_load_lds_dwordx4 v[150:151], off
	s_waitcnt vmcnt(8)
	s_waitcnt lgkmcnt(0)
	s_barrier
; #define PG8_STAGE(bufoff, gbase, voff) do { _Pragma("unroll") for (int _i = 0; _i < 2; ++_i) \
;         __builtin_amdgcn_global_load_lds((const unsigned*)((const char*)(gbase) + (voff)[_i]), (PG8_LAS unsigned*)(lds + (bufoff) + ldsw + _i * 8192), 16, 0, 0); } while (0)
; #define PG8_LDA(dst, b, h) do { _Pragma("unroll") for (int m = 0; m < 4; ++m) _Pragma("unroll") for (int k = 0; k < 2; ++k) dst[m][k] = *(const PG8_LAS bf16x8*)(lds + PG8_SA(b, h) + aoff + m * 2048 + k * 1024); } while (0)
; #define PG8_MMA(ai, bj, At, Bt) do { __builtin_amdgcn_s_setprio(1); _Pragma("unroll") for (int m = 0; m < 4; ++m) _Pragma("unroll") for (int n = 0; n < 2; ++n) _Pragma("unroll") for (int k = 0; k < 2; ++k) \
;         acc[ai][bj][m][n] = __builtin_amdgcn_mfma_f32_16x16x32_bf16(Bt[n][k], At[m][k], acc[ai][bj][m][n], 0, 0, 0); __builtin_amdgcn_s_setprio(0); } while (0)
; #define PG8_WAIT_V(n) asm volatile("s_waitcnt vmcnt(" #n ")" ::: "memory")
; #define PG8_WAIT_L(n) asm volatile("s_waitcnt lgkmcnt(" #n ")" ::: "memory")
; #define PG8_BAR __builtin_amdgcn_s_barrier()
; #define PG8_SCHED __builtin_amdgcn_sched_barrier(0)
; template <class Epi, class Sched, bool ALIGN_EPI = false, bool SP2 = false>
; __device__ __forceinline__ void gemm_phase(PG8_LAS unsigned char* lds, const Gemm g, const Sched& S, const Epi& E) {
;     ...
;             PG8_WAIT_V(8); PG8_WAIT_L(0); PG8_BAR; PG8_MMA(0, 0, At, B0); PG8_MMA(0, 1, At, B1); PG8_BAR; PG8_SCHED;
;             PG8_LDA(At, 0, 1); PG8_STAGE(PG8_SB(0, 0), b2, voffB); PG8_STAGE(PG8_SB(0, 1), b2 + hstep, voffB); PG8_STAGE(PG8_SA(0, 0), a2, voffA);
;             PG8_WAIT_V(8); PG8_WAIT_L(0); PG8_BAR; PG8_MMA(1, 0, At, B0); PG8_MMA(1, 1, At, B1); PG8_BAR; PG8_SCHED;
	s_waitcnt lgkmcnt(0)
	v_mfma_f32_16x16x32_bf16 v[120:123], v[146:149], v[188:191], v[120:123]
	v_mfma_f32_16x16x32_bf16 v[124:127], v[164:167], v[188:191], v[124:127]
	v_mfma_f32_16x16x32_bf16 v[108:111], v[146:149], v[196:199], v[108:111]
	v_mfma_f32_16x16x32_bf16 v[104:107], v[164:167], v[196:199], v[104:107]
	v_mfma_f32_16x16x32_bf16 v[92:95], v[146:149], v[204:207], v[92:95]
	v_mfma_f32_16x16x32_bf16 v[88:91], v[164:167], v[204:207], v[88:91]
	v_mfma_f32_16x16x32_bf16 v[76:79], v[146:149], v[212:215], v[76:79]
	v_mfma_f32_16x16x32_bf16 v[72:75], v[164:167], v[212:215], v[72:75]
	v_mfma_f32_16x16x32_bf16 v[120:123], v[160:163], v[192:195], v[120:123]
	v_mfma_f32_16x16x32_bf16 v[124:127], v[168:171], v[192:195], v[124:127]
	v_mfma_f32_16x16x32_bf16 v[108:111], v[160:163], v[200:203], v[108:111]
	v_mfma_f32_16x16x32_bf16 v[104:107], v[168:171], v[200:203], v[104:107]
	v_mfma_f32_16x16x32_bf16 v[92:95], v[160:163], v[208:211], v[92:95]
	v_mfma_f32_16x16x32_bf16 v[88:91], v[168:171], v[208:211], v[88:91]
	v_mfma_f32_16x16x32_bf16 v[76:79], v[160:163], v[216:219], v[76:79]
	v_mfma_f32_16x16x32_bf16 v[72:75], v[168:171], v[216:219], v[72:75]
	v_mfma_f32_16x16x32_bf16 v[116:119], v[172:175], v[188:191], v[116:119]
	v_mfma_f32_16x16x32_bf16 v[112:115], v[180:183], v[188:191], v[112:115]
	v_mfma_f32_16x16x32_bf16 v[100:103], v[172:175], v[196:199], v[100:103]
	v_mfma_f32_16x16x32_bf16 v[96:99], v[180:183], v[196:199], v[96:99]
	v_mfma_f32_16x16x32_bf16 v[84:87], v[172:175], v[204:207], v[84:87]
	v_mfma_f32_16x16x32_bf16 v[80:83], v[180:183], v[204:207], v[80:83]
	v_mfma_f32_16x16x32_bf16 v[68:71], v[172:175], v[212:215], v[68:71]
	v_mfma_f32_16x16x32_bf16 v[64:67], v[180:183], v[212:215], v[64:67]
	v_mfma_f32_16x16x32_bf16 v[116:119], v[176:179], v[192:195], v[116:119]
	v_mfma_f32_16x16x32_bf16 v[112:115], v[184:187], v[192:195], v[112:115]
	v_mfma_f32_16x16x32_bf16 v[100:103], v[176:179], v[200:203], v[100:103]
	v_mfma_f32_16x16x32_bf16 v[96:99], v[184:187], v[200:203], v[96:99]
	v_mfma_f32_16x16x32_bf16 v[84:87], v[176:179], v[208:211], v[84:87]
	v_mfma_f32_16x16x32_bf16 v[80:83], v[184:187], v[208:211], v[80:83]
	v_mfma_f32_16x16x32_bf16 v[68:71], v[176:179], v[216:219], v[68:71]
	v_mfma_f32_16x16x32_bf16 v[64:67], v[184:187], v[216:219], v[64:67]
	s_barrier
	s_add_i32 s79, s63, s17
	v_lshl_add_u64 v[150:151], s[80:81], 0, v[130:131]
	s_mov_b32 m0, s79
	ds_read_b128 v[188:191], v158 offset:16384
	ds_read_b128 v[192:195], v158 offset:17408
	ds_read_b128 v[196:199], v158 offset:18432
	ds_read_b128 v[200:203], v158 offset:19456
	ds_read_b128 v[204:207], v158 offset:20480
	ds_read_b128 v[208:211], v158 offset:21504
	ds_read_b128 v[212:215], v158 offset:22528
	ds_read_b128 v[216:219], v158 offset:23552
	global_load_lds_dwordx4 v[150:151], off
	s_add_i32 m0, s79, 0x2000
	v_lshl_add_u64 v[220:221], s[80:81], 0, v[134:135]
	s_add_u32 s80, s80, s12
	s_addc_u32 s81, s81, s13
	s_add_i32 s79, s64, s17
	global_load_lds_dwordx4 v[220:221], off
	v_lshl_add_u64 v[222:223], s[80:81], 0, v[130:131]
	s_mov_b32 m0, s79
	v_lshl_add_u64 v[224:225], s[80:81], 0, v[134:135]
	global_load_lds_dwordx4 v[222:223], off
	s_add_i32 m0, s79, 0x2000
	v_lshl_add_u64 v[226:227], s[4:5], 0, v[128:129]
	global_load_lds_dwordx4 v[224:225], off
	s_mov_b32 m0, s19
	v_lshl_add_u64 v[228:229], s[4:5], 0, v[132:133]
	global_load_lds_dwordx4 v[226:227], off
	s_mov_b32 m0, s33
	s_nop 0
	global_load_lds_dwordx4 v[228:229], off
	s_waitcnt vmcnt(8)
	s_waitcnt lgkmcnt(0)
	s_barrier
	s_waitcnt lgkmcnt(0)
	v_mfma_f32_16x16x32_bf16 v[60:63], v[146:149], v[188:191], v[60:63]
	v_mfma_f32_16x16x32_bf16 v[56:59], v[164:167], v[188:191], v[56:59]
	v_mfma_f32_16x16x32_bf16 v[44:47], v[146:149], v[196:199], v[44:47]
	v_mfma_f32_16x16x32_bf16 v[40:43], v[164:167], v[196:199], v[40:43]
	v_mfma_f32_16x16x32_bf16 v[28:31], v[146:149], v[204:207], v[28:31]
	v_mfma_f32_16x16x32_bf16 v[24:27], v[164:167], v[204:207], v[24:27]
	v_mfma_f32_16x16x32_bf16 v[12:15], v[146:149], v[212:215], v[12:15]
	v_mfma_f32_16x16x32_bf16 v[8:11], v[164:167], v[212:215], v[8:11]
	v_mfma_f32_16x16x32_bf16 v[60:63], v[160:163], v[192:195], v[60:63]
	v_mfma_f32_16x16x32_bf16 v[56:59], v[168:171], v[192:195], v[56:59]
	v_mfma_f32_16x16x32_bf16 v[44:47], v[160:163], v[200:203], v[44:47]
	v_mfma_f32_16x16x32_bf16 v[40:43], v[168:171], v[200:203], v[40:43]
	v_mfma_f32_16x16x32_bf16 v[28:31], v[160:163], v[208:211], v[28:31]
	v_mfma_f32_16x16x32_bf16 v[24:27], v[168:171], v[208:211], v[24:27]
	v_mfma_f32_16x16x32_bf16 v[12:15], v[160:163], v[216:219], v[12:15]
	v_mfma_f32_16x16x32_bf16 v[8:11], v[168:171], v[216:219], v[8:11]
	v_mfma_f32_16x16x32_bf16 v[52:55], v[172:175], v[188:191], v[52:55]
	v_mfma_f32_16x16x32_bf16 v[48:51], v[180:183], v[188:191], v[48:51]
	v_mfma_f32_16x16x32_bf16 v[36:39], v[172:175], v[196:199], v[36:39]
	v_mfma_f32_16x16x32_bf16 v[32:35], v[180:183], v[196:199], v[32:35]
	v_mfma_f32_16x16x32_bf16 v[20:23], v[172:175], v[204:207], v[20:23]
	v_mfma_f32_16x16x32_bf16 v[16:19], v[180:183], v[204:207], v[16:19]
	v_mfma_f32_16x16x32_bf16 v[4:7], v[172:175], v[212:215], v[4:7]
	v_mfma_f32_16x16x32_bf16 v[0:3], v[180:183], v[212:215], v[0:3]
	v_mfma_f32_16x16x32_bf16 v[52:55], v[176:179], v[192:195], v[52:55]
	v_mfma_f32_16x16x32_bf16 v[48:51], v[184:187], v[192:195], v[48:51]
	v_mfma_f32_16x16x32_bf16 v[36:39], v[176:179], v[200:203], v[36:39]
	v_mfma_f32_16x16x32_bf16 v[32:35], v[184:187], v[200:203], v[32:35]
	v_mfma_f32_16x16x32_bf16 v[20:23], v[176:179], v[208:211], v[20:23]
	v_mfma_f32_16x16x32_bf16 v[16:19], v[184:187], v[208:211], v[16:19]
	v_mfma_f32_16x16x32_bf16 v[4:7], v[176:179], v[216:219], v[4:7]
	v_mfma_f32_16x16x32_bf16 v[0:3], v[184:187], v[216:219], v[0:3]
	s_barrier
; #define PG8_STAGE(bufoff, gbase, voff) do { _Pragma("unroll") for (int _i = 0; _i < 2; ++_i) \
;         __builtin_amdgcn_global_load_lds((const unsigned*)((const char*)(gbase) + (voff)[_i]), (PG8_LAS unsigned*)(lds + (bufoff) + ldsw + _i * 8192), 16, 0, 0); } while (0)
; #define PG8_LDA(dst, b, h) do { _Pragma("unroll") for (int m = 0; m < 4; ++m) _Pragma("unroll") for (int k = 0; k < 2; ++k) dst[m][k] = *(const PG8_LAS bf16x8*)(lds + PG8_SA(b, h) + aoff + m * 2048 + k * 1024); } while (0)
; #define PG8_LDB(dst, b, h) do { _Pragma("unroll") for (int n = 0; n < 2; ++n) _Pragma("unroll") for (int k = 0; k < 2; ++k) dst[n][k] = *(const PG8_LAS bf16x8*)(lds + PG8_SB(b, h) + boff + n * 2048 + k * 1024); } while (0)
; #define PG8_MMA(ai, bj, At, Bt) do { __builtin_amdgcn_s_setprio(1); _Pragma("unroll") for (int m = 0; m < 4; ++m) _Pragma("unroll") for (int n = 0; n < 2; ++n) _Pragma("unroll") for (int k = 0; k < 2; ++k) \
;         acc[ai][bj][m][n] = __builtin_amdgcn_mfma_f32_16x16x32_bf16(Bt[n][k], At[m][k], acc[ai][bj][m][n], 0, 0, 0); __builtin_amdgcn_s_setprio(0); } while (0)
; #define PG8_WAIT_V(n) asm volatile("s_waitcnt vmcnt(" #n ")" ::: "memory")
; #define PG8_WAIT_L(n) asm volatile("s_waitcnt lgkmcnt(" #n ")" ::: "memory")
; #define PG8_BAR __builtin_amdgcn_s_barrier()
; #define PG8_SCHED __builtin_amdgcn_sched_barrier(0)
; template <class Epi, class Sched, bool ALIGN_EPI = false, bool SP2 = false>
; __device__ __forceinline__ void gemm_phase(PG8_LAS unsigned char* lds, const Gemm g, const Sched& S, const Epi& E) {
;     ...
;             PG8_LDB(B0, 1, 0); PG8_LDB(B1, 1, 1); PG8_SCHED; PG8_LDA(At, 1, 0); PG8_STAGE(PG8_SA(0, 1), a2 + hstep, voffA);
;             PG8_WAIT_V(8); PG8_WAIT_L(0); PG8_BAR; PG8_MMA(0, 0, At, B0); PG8_MMA(0, 1, At, B1); PG8_BAR; PG8_SCHED;
;             PG8_LDA(At, 1, 1); PG8_STAGE(PG8_SB(1, 0), b3, voffB); PG8_STAGE(PG8_SB(1, 1), b3 + hstep, voffB); PG8_STAGE(PG8_SA(1, 0), a3, voffA);
;             PG8_WAIT_V(8); PG8_WAIT_L(0); PG8_BAR; PG8_MMA(1, 0, At, B0); PG8_MMA(1, 1, At, B1); PG8_BAR; PG8_SCHED;
	s_add_i32 s79, 0, 0x18000
	v_add_u32_e32 v137, s79, v153
	s_add_i32 s80, 0, 0x1c000
	ds_read_b128 v[146:149], v137
	ds_read_b128 v[160:163], v137 offset:1024
	ds_read_b128 v[164:167], v137 offset:2048
	ds_read_b128 v[168:171], v137 offset:3072
	v_add_u32_e32 v137, s80, v153
	ds_read_b128 v[172:175], v137
	ds_read_b128 v[176:179], v137 offset:1024
	ds_read_b128 v[180:183], v137 offset:2048
	ds_read_b128 v[184:187], v137 offset:3072
	s_add_u32 s4, s4, s12
	s_addc_u32 s5, s5, s13
	s_mov_b32 m0, s40
	v_lshl_add_u64 v[230:231], s[4:5], 0, v[128:129]
	ds_read_b128 v[188:191], v158 offset:32768
	ds_read_b128 v[192:195], v158 offset:33792
	ds_read_b128 v[196:199], v158 offset:34816
	ds_read_b128 v[200:203], v158 offset:35840
	ds_read_b128 v[204:207], v158 offset:36864
	ds_read_b128 v[208:211], v158 offset:37888
	ds_read_b128 v[212:215], v158 offset:38912
	ds_read_b128 v[216:219], v158 offset:39936
	global_load_lds_dwordx4 v[230:231], off
	v_lshl_add_u64 v[230:231], s[4:5], 0, v[132:133]
	s_mov_b32 m0, s41
	s_nop 0
	global_load_lds_dwordx4 v[230:231], off
	s_waitcnt vmcnt(8)
	s_waitcnt lgkmcnt(0)
	s_barrier
	s_waitcnt lgkmcnt(0)
	v_mfma_f32_16x16x32_bf16 v[120:123], v[146:149], v[188:191], v[120:123]
	v_mfma_f32_16x16x32_bf16 v[124:127], v[164:167], v[188:191], v[124:127]
	v_mfma_f32_16x16x32_bf16 v[108:111], v[146:149], v[196:199], v[108:111]
	v_mfma_f32_16x16x32_bf16 v[104:107], v[164:167], v[196:199], v[104:107]
	v_mfma_f32_16x16x32_bf16 v[92:95], v[146:149], v[204:207], v[92:95]
	v_mfma_f32_16x16x32_bf16 v[88:91], v[164:167], v[204:207], v[88:91]
	v_mfma_f32_16x16x32_bf16 v[76:79], v[146:149], v[212:215], v[76:79]
	v_mfma_f32_16x16x32_bf16 v[72:75], v[164:167], v[212:215], v[72:75]
	v_mfma_f32_16x16x32_bf16 v[120:123], v[160:163], v[192:195], v[120:123]
	v_mfma_f32_16x16x32_bf16 v[124:127], v[168:171], v[192:195], v[124:127]
	v_mfma_f32_16x16x32_bf16 v[108:111], v[160:163], v[200:203], v[108:111]
	v_mfma_f32_16x16x32_bf16 v[104:107], v[168:171], v[200:203], v[104:107]
	v_mfma_f32_16x16x32_bf16 v[92:95], v[160:163], v[208:211], v[92:95]
	v_mfma_f32_16x16x32_bf16 v[88:91], v[168:171], v[208:211], v[88:91]
	v_mfma_f32_16x16x32_bf16 v[76:79], v[160:163], v[216:219], v[76:79]
	v_mfma_f32_16x16x32_bf16 v[72:75], v[168:171], v[216:219], v[72:75]
	v_mfma_f32_16x16x32_bf16 v[116:119], v[172:175], v[188:191], v[116:119]
	v_mfma_f32_16x16x32_bf16 v[112:115], v[180:183], v[188:191], v[112:115]
	v_mfma_f32_16x16x32_bf16 v[100:103], v[172:175], v[196:199], v[100:103]
	v_mfma_f32_16x16x32_bf16 v[96:99], v[180:183], v[196:199], v[96:99]
	v_mfma_f32_16x16x32_bf16 v[84:87], v[172:175], v[204:207], v[84:87]
	v_mfma_f32_16x16x32_bf16 v[80:83], v[180:183], v[204:207], v[80:83]
	v_mfma_f32_16x16x32_bf16 v[68:71], v[172:175], v[212:215], v[68:71]
	v_mfma_f32_16x16x32_bf16 v[64:67], v[180:183], v[212:215], v[64:67]
	v_mfma_f32_16x16x32_bf16 v[116:119], v[176:179], v[192:195], v[116:119]
	v_mfma_f32_16x16x32_bf16 v[112:115], v[184:187], v[192:195], v[112:115]
	v_mfma_f32_16x16x32_bf16 v[100:103], v[176:179], v[200:203], v[100:103]
	v_mfma_f32_16x16x32_bf16 v[96:99], v[184:187], v[200:203], v[96:99]
	v_mfma_f32_16x16x32_bf16 v[84:87], v[176:179], v[208:211], v[84:87]
	v_mfma_f32_16x16x32_bf16 v[80:83], v[184:187], v[208:211], v[80:83]
	v_mfma_f32_16x16x32_bf16 v[68:71], v[176:179], v[216:219], v[68:71]
	v_mfma_f32_16x16x32_bf16 v[64:67], v[184:187], v[216:219], v[64:67]
	s_barrier
	s_add_i32 s4, s79, s17
	v_lshl_add_u64 v[150:151], v[150:151], 0, s[22:23]
	s_mov_b32 m0, s4
	ds_read_b128 v[188:191], v158 offset:49152
	ds_read_b128 v[192:195], v158 offset:50176
	ds_read_b128 v[196:199], v158 offset:51200
	ds_read_b128 v[200:203], v158 offset:52224
	ds_read_b128 v[204:207], v158 offset:53248
	ds_read_b128 v[208:211], v158 offset:54272
	ds_read_b128 v[212:215], v158 offset:55296
	ds_read_b128 v[216:219], v158 offset:56320
	global_load_lds_dwordx4 v[150:151], off
	v_lshl_add_u64 v[150:151], v[220:221], 0, s[22:23]
	s_add_i32 m0, s4, 0x2000
	s_add_i32 s4, s80, s17
	global_load_lds_dwordx4 v[150:151], off
	v_lshl_add_u64 v[150:151], v[222:223], 0, s[22:23]
	s_mov_b32 m0, s4
	s_nop 0
	global_load_lds_dwordx4 v[150:151], off
	v_lshl_add_u64 v[150:151], v[224:225], 0, s[22:23]
	s_add_i32 m0, s4, 0x2000
	s_nop 0
	global_load_lds_dwordx4 v[150:151], off
	v_lshl_add_u64 v[150:151], v[226:227], 0, s[22:23]
	s_mov_b32 m0, s45
	s_nop 0
	global_load_lds_dwordx4 v[150:151], off
	v_lshl_add_u64 v[150:151], v[228:229], 0, s[22:23]
	s_mov_b32 m0, s50
	s_nop 0
	global_load_lds_dwordx4 v[150:151], off
	s_waitcnt vmcnt(8)
	s_waitcnt lgkmcnt(0)
	s_barrier
	s_waitcnt lgkmcnt(0)
	v_mfma_f32_16x16x32_bf16 v[60:63], v[146:149], v[188:191], v[60:63]
	v_mfma_f32_16x16x32_bf16 v[56:59], v[164:167], v[188:191], v[56:59]
	v_mfma_f32_16x16x32_bf16 v[44:47], v[146:149], v[196:199], v[44:47]
	v_mfma_f32_16x16x32_bf16 v[40:43], v[164:167], v[196:199], v[40:43]
	v_mfma_f32_16x16x32_bf16 v[28:31], v[146:149], v[204:207], v[28:31]
	v_mfma_f32_16x16x32_bf16 v[24:27], v[164:167], v[204:207], v[24:27]
	v_mfma_f32_16x16x32_bf16 v[12:15], v[146:149], v[212:215], v[12:15]
	v_mfma_f32_16x16x32_bf16 v[8:11], v[164:167], v[212:215], v[8:11]
	v_mfma_f32_16x16x32_bf16 v[60:63], v[160:163], v[192:195], v[60:63]
	v_mfma_f32_16x16x32_bf16 v[56:59], v[168:171], v[192:195], v[56:59]
	v_mfma_f32_16x16x32_bf16 v[44:47], v[160:163], v[200:203], v[44:47]
	v_mfma_f32_16x16x32_bf16 v[40:43], v[168:171], v[200:203], v[40:43]
	v_mfma_f32_16x16x32_bf16 v[28:31], v[160:163], v[208:211], v[28:31]
	v_mfma_f32_16x16x32_bf16 v[24:27], v[168:171], v[208:211], v[24:27]
	v_mfma_f32_16x16x32_bf16 v[12:15], v[160:163], v[216:219], v[12:15]
	v_mfma_f32_16x16x32_bf16 v[8:11], v[168:171], v[216:219], v[8:11]
	v_mfma_f32_16x16x32_bf16 v[52:55], v[172:175], v[188:191], v[52:55]
	v_mfma_f32_16x16x32_bf16 v[48:51], v[180:183], v[188:191], v[48:51]
	v_mfma_f32_16x16x32_bf16 v[36:39], v[172:175], v[196:199], v[36:39]
	v_mfma_f32_16x16x32_bf16 v[32:35], v[180:183], v[196:199], v[32:35]
	v_mfma_f32_16x16x32_bf16 v[20:23], v[172:175], v[204:207], v[20:23]
	v_mfma_f32_16x16x32_bf16 v[16:19], v[180:183], v[204:207], v[16:19]
	v_mfma_f32_16x16x32_bf16 v[4:7], v[172:175], v[212:215], v[4:7]
	v_mfma_f32_16x16x32_bf16 v[0:3], v[180:183], v[212:215], v[0:3]
	v_mfma_f32_16x16x32_bf16 v[52:55], v[176:179], v[192:195], v[52:55]
	v_mfma_f32_16x16x32_bf16 v[48:51], v[184:187], v[192:195], v[48:51]
	v_mfma_f32_16x16x32_bf16 v[36:39], v[176:179], v[200:203], v[36:39]
	v_mfma_f32_16x16x32_bf16 v[32:35], v[184:187], v[200:203], v[32:35]
	v_mfma_f32_16x16x32_bf16 v[20:23], v[176:179], v[208:211], v[20:23]
	v_mfma_f32_16x16x32_bf16 v[16:19], v[184:187], v[208:211], v[16:19]
	v_mfma_f32_16x16x32_bf16 v[4:7], v[176:179], v[216:219], v[4:7]
	v_mfma_f32_16x16x32_bf16 v[0:3], v[184:187], v[216:219], v[0:3]
	s_barrier
	s_add_u32 s0, s0, 0x100
	s_addc_u32 s1, s1, 0
	s_add_u32 s6, s6, 0x100
	s_addc_u32 s7, s7, 0
	s_cmp_ge_i32 s78, s51
	s_mov_b32 s4, s78
	s_cbranch_scc0 .LBB0_2052

; #define PG8_STAGE(bufoff, gbase, voff) do { _Pragma("unroll") for (int _i = 0; _i < 2; ++_i) \
;         __builtin_amdgcn_global_load_lds((const unsigned*)((const char*)(gbase) + (voff)[_i]), (PG8_LAS unsigned*)(lds + (bufoff) + ldsw + _i * 8192), 16, 0, 0); } while (0)
; #define PG8_LDA(dst, b, h) do { _Pragma("unroll") for (int m = 0; m < 4; ++m) _Pragma("unroll") for (int k = 0; k < 2; ++k) dst[m][k] = *(const PG8_LAS bf16x8*)(lds + PG8_SA(b, h) + aoff + m * 2048 + k * 1024); } while (0)
; #define PG8_LDB(dst, b, h) do { _Pragma("unroll") for (int n = 0; n < 2; ++n) _Pragma("unroll") for (int k = 0; k < 2; ++k) dst[n][k] = *(const PG8_LAS bf16x8*)(lds + PG8_SB(b, h) + boff + n * 2048 + k * 1024); } while (0)
; #define PG8_WAIT_V(n) asm volatile("s_waitcnt vmcnt(" #n ")" ::: "memory")
; #define PG8_WAIT_L(n) asm volatile("s_waitcnt lgkmcnt(" #n ")" ::: "memory")
; template <class Epi, class Sched, bool ALIGN_EPI = false, bool SP2 = false>
; __device__ __forceinline__ void gemm_phase(PG8_LAS unsigned char* lds, const Gemm g, const Sched& S, const Epi& E) {
;     ...
;         for (int t = 0; t < nt; t += 2) {
;             const bool last = (t == nt - 2);
;             const char* a1 = cA + (size_t)(t + 1) * kstep;
;             const char* a2 = last ? nA : cA + (size_t)(t + 2) * kstep; const char* b2 = last ? nB : cB + (size_t)(t + 2) * kstep;
;             const char* a3 = a2 + kstep; const char* b3 = b2 + kstep;
;             if (last && has_next) S.a_ready(nxt);
;             if constexpr (SP2) {
;             PG8_LDB(B0, 0, 0); PG8_LDB(B1, 0, 1); PG8_SCHED; PG8_LDA(At, 0, 0); PG8_STAGE(PG8_SA(1, 1), a1 + hstep, voffA);
;             PG8_WAIT_V(8); PG8_WAIT_L(0); PG8_BAR; PG8_MMA(0, 0, At, B0); PG8_MMA(0, 1, At, B1); PG8_BAR; PG8_SCHED;
;             PG8_LDA(At, 0, 1); PG8_STAGE(PG8_SB(0, 0), b2, voffB); PG8_STAGE(PG8_SB(0, 1), b2 + hstep, voffB); PG8_STAGE(PG8_SA(0, 0), a2, voffA);
;             PG8_WAIT_V(8); PG8_WAIT_L(0); PG8_BAR; PG8_MMA(1, 0, At, B0); PG8_MMA(1, 1, At, B1); PG8_BAR; PG8_SCHED;
;     ...
; #pragma unroll
;         for (int a = 0; a < 2; ++a)
; #pragma unroll
;             for (int b = 0; b < 2; ++b)
; #pragma unroll
;                 for (int m = 0; m < 4; ++m)
; #pragma unroll
;                     for (int n = 0; n < 2; ++n) acc[a][b][m][n] = (f32x4){0.f, 0.f, 0.f, 0.f};
;         cur = nxt; cA = nA; cB = nB; ++ui;
.LBB0_2163:
	s_andn2_b64 vcc, exec, s[22:23]
	s_cbranch_vccnz .LBB0_2166
	s_add_u32 s30, s30, 0x80
	s_addc_u32 s31, s31, 0
	s_add_u32 s77, s34, 0x100
	s_addc_u32 s78, s35, 0
	s_mov_b32 s34, 0
	ds_read_b128 v[146:149], v152
	ds_read_b128 v[158:161], v152 offset:1024
	ds_read_b128 v[162:165], v152 offset:2048
	ds_read_b128 v[166:169], v152 offset:3072
	ds_read_b128 v[170:173], v153
	ds_read_b128 v[174:177], v153 offset:1024
	ds_read_b128 v[178:181], v153 offset:2048
	ds_read_b128 v[182:185], v153 offset:3072
	s_add_i32 s79, s34, 2
	s_add_u32 s80, s30, 0x80
	s_addc_u32 s35, s31, 0
	s_cmp_eq_u32 s50, s34
	s_cselect_b32 s34, s0, s80
	s_cselect_b32 s35, s1, s35
	s_cselect_b32 s81, s29, s78
	s_cselect_b32 s80, s28, s77
	v_lshl_add_u64 v[218:219], s[30:31], 0, v[138:139]
	s_add_i32 m0, s33, 0xc000
	ds_read_b128 v[186:189], v154
	ds_read_b128 v[190:193], v154 offset:1024
	ds_read_b128 v[194:197], v154 offset:2048
	ds_read_b128 v[198:201], v154 offset:3072
	ds_read_b128 v[202:205], v154 offset:4096
	ds_read_b128 v[206:209], v154 offset:5120
	ds_read_b128 v[210:213], v154 offset:6144
	ds_read_b128 v[214:217], v154 offset:7168
	global_load_lds_dwordx4 v[218:219], off
	v_lshl_add_u64 v[218:219], s[30:31], 0, v[140:141]
	s_add_i32 m0, s33, 0xe000
	s_nop 0
	global_load_lds_dwordx4 v[218:219], off
	s_waitcnt vmcnt(8)
	s_waitcnt lgkmcnt(0)
	s_barrier
	s_waitcnt lgkmcnt(0)
	v_mfma_f32_16x16x32_bf16 v[120:123], v[146:149], v[186:189], 0
	v_mfma_f32_16x16x32_bf16 v[124:127], v[162:165], v[186:189], 0
	v_mfma_f32_16x16x32_bf16 v[108:111], v[146:149], v[194:197], 0
	v_mfma_f32_16x16x32_bf16 v[104:107], v[162:165], v[194:197], 0
	v_mfma_f32_16x16x32_bf16 v[92:95], v[146:149], v[202:205], 0
	v_mfma_f32_16x16x32_bf16 v[88:91], v[162:165], v[202:205], 0
	v_mfma_f32_16x16x32_bf16 v[76:79], v[146:149], v[210:213], 0
	v_mfma_f32_16x16x32_bf16 v[72:75], v[162:165], v[210:213], 0
	v_mfma_f32_16x16x32_bf16 v[120:123], v[158:161], v[190:193], v[120:123]
	v_mfma_f32_16x16x32_bf16 v[124:127], v[166:169], v[190:193], v[124:127]
	v_mfma_f32_16x16x32_bf16 v[108:111], v[158:161], v[198:201], v[108:111]
	v_mfma_f32_16x16x32_bf16 v[104:107], v[166:169], v[198:201], v[104:107]
	v_mfma_f32_16x16x32_bf16 v[92:95], v[158:161], v[206:209], v[92:95]
	v_mfma_f32_16x16x32_bf16 v[88:91], v[166:169], v[206:209], v[88:91]
	v_mfma_f32_16x16x32_bf16 v[76:79], v[158:161], v[214:217], v[76:79]
	v_mfma_f32_16x16x32_bf16 v[72:75], v[166:169], v[214:217], v[72:75]
	v_mfma_f32_16x16x32_bf16 v[116:119], v[170:173], v[186:189], 0
	v_mfma_f32_16x16x32_bf16 v[112:115], v[178:181], v[186:189], 0
	v_mfma_f32_16x16x32_bf16 v[100:103], v[170:173], v[194:197], 0
	v_mfma_f32_16x16x32_bf16 v[96:99], v[178:181], v[194:197], 0
	v_mfma_f32_16x16x32_bf16 v[84:87], v[170:173], v[202:205], 0
	v_mfma_f32_16x16x32_bf16 v[80:83], v[178:181], v[202:205], 0
	v_mfma_f32_16x16x32_bf16 v[68:71], v[170:173], v[210:213], 0
	v_mfma_f32_16x16x32_bf16 v[64:67], v[178:181], v[210:213], 0
	v_mfma_f32_16x16x32_bf16 v[116:119], v[174:177], v[190:193], v[116:119]
	v_mfma_f32_16x16x32_bf16 v[112:115], v[182:185], v[190:193], v[112:115]
	v_mfma_f32_16x16x32_bf16 v[100:103], v[174:177], v[198:201], v[100:103]
	v_mfma_f32_16x16x32_bf16 v[96:99], v[182:185], v[198:201], v[96:99]
	v_mfma_f32_16x16x32_bf16 v[84:87], v[174:177], v[206:209], v[84:87]
	v_mfma_f32_16x16x32_bf16 v[80:83], v[182:185], v[206:209], v[80:83]
	v_mfma_f32_16x16x32_bf16 v[68:71], v[174:177], v[214:217], v[68:71]
	v_mfma_f32_16x16x32_bf16 v[64:67], v[182:185], v[214:217], v[64:67]
	s_barrier
	s_add_i32 s82, s59, s16
	v_lshl_add_u64 v[218:219], s[80:81], 0, v[130:131]
	s_mov_b32 m0, s82
	ds_read_b128 v[186:189], v154 offset:16384
	ds_read_b128 v[190:193], v154 offset:17408
	ds_read_b128 v[194:197], v154 offset:18432
	ds_read_b128 v[198:201], v154 offset:19456
	ds_read_b128 v[202:205], v154 offset:20480
	ds_read_b128 v[206:209], v154 offset:21504
	ds_read_b128 v[210:213], v154 offset:22528
	ds_read_b128 v[214:217], v154 offset:23552
	global_load_lds_dwordx4 v[218:219], off
	s_add_i32 m0, s82, 0x2000
	v_lshl_add_u64 v[220:221], s[80:81], 0, v[134:135]
	s_add_u32 s80, s80, s8
	s_addc_u32 s81, s81, s9
	s_add_i32 s82, s60, s16
	global_load_lds_dwordx4 v[220:221], off
	v_lshl_add_u64 v[222:223], s[80:81], 0, v[130:131]
	s_mov_b32 m0, s82
	v_lshl_add_u64 v[224:225], s[80:81], 0, v[134:135]
	global_load_lds_dwordx4 v[222:223], off
	s_add_i32 m0, s82, 0x2000
	v_lshl_add_u64 v[226:227], s[34:35], 0, v[128:129]
	global_load_lds_dwordx4 v[224:225], off
	s_mov_b32 m0, s33
	v_lshl_add_u64 v[228:229], s[34:35], 0, v[132:133]
	global_load_lds_dwordx4 v[226:227], off
	s_mov_b32 m0, s36
	s_nop 0
	global_load_lds_dwordx4 v[228:229], off
	s_waitcnt vmcnt(8)
	s_waitcnt lgkmcnt(0)
	s_barrier
; #define PG8_STAGE(bufoff, gbase, voff) do { _Pragma("unroll") for (int _i = 0; _i < 2; ++_i) \
;         __builtin_amdgcn_global_load_lds((const unsigned*)((const char*)(gbase) + (voff)[_i]), (PG8_LAS unsigned*)(lds + (bufoff) + ldsw + _i * 8192), 16, 0, 0); } while (0)
; #define PG8_LDA(dst, b, h) do { _Pragma("unroll") for (int m = 0; m < 4; ++m) _Pragma("unroll") for (int k = 0; k < 2; ++k) dst[m][k] = *(const PG8_LAS bf16x8*)(lds + PG8_SA(b, h) + aoff + m * 2048 + k * 1024); } while (0)
; #define PG8_LDB(dst, b, h) do { _Pragma("unroll") for (int n = 0; n < 2; ++n) _Pragma("unroll") for (int k = 0; k < 2; ++k) dst[n][k] = *(const PG8_LAS bf16x8*)(lds + PG8_SB(b, h) + boff + n * 2048 + k * 1024); } while (0)
; #define PG8_MMA(ai, bj, At, Bt) do { __builtin_amdgcn_s_setprio(1); _Pragma("unroll") for (int m = 0; m < 4; ++m) _Pragma("unroll") for (int n = 0; n < 2; ++n) _Pragma("unroll") for (int k = 0; k < 2; ++k) \
;         acc[ai][bj][m][n] = __builtin_amdgcn_mfma_f32_16x16x32_bf16(Bt[n][k], At[m][k], acc[ai][bj][m][n], 0, 0, 0); __builtin_amdgcn_s_setprio(0); } while (0)
; #define PG8_WAIT_V(n) asm volatile("s_waitcnt vmcnt(" #n ")" ::: "memory")
; #define PG8_WAIT_L(n) asm volatile("s_waitcnt lgkmcnt(" #n ")" ::: "memory")
; #define PG8_BAR __builtin_amdgcn_s_barrier()
; #define PG8_SCHED __builtin_amdgcn_sched_barrier(0)
; template <class Epi, class Sched, bool ALIGN_EPI = false, bool SP2 = false>
; __device__ __forceinline__ void gemm_phase(PG8_LAS unsigned char* lds, const Gemm g, const Sched& S, const Epi& E) {
;     ...
;             PG8_WAIT_V(8); PG8_WAIT_L(0); PG8_BAR; PG8_MMA(1, 0, At, B0); PG8_MMA(1, 1, At, B1); PG8_BAR; PG8_SCHED;
;             PG8_LDB(B0, 1, 0); PG8_LDB(B1, 1, 1); PG8_SCHED; PG8_LDA(At, 1, 0); PG8_STAGE(PG8_SA(0, 1), a2 + hstep, voffA);
;             PG8_WAIT_V(8); PG8_WAIT_L(0); PG8_BAR; PG8_MMA(0, 0, At, B0); PG8_MMA(0, 1, At, B1); PG8_BAR; PG8_SCHED;
	s_waitcnt lgkmcnt(0)
	v_mfma_f32_16x16x32_bf16 v[60:63], v[146:149], v[186:189], 0
	v_mfma_f32_16x16x32_bf16 v[56:59], v[162:165], v[186:189], 0
	v_mfma_f32_16x16x32_bf16 v[44:47], v[146:149], v[194:197], 0
	v_mfma_f32_16x16x32_bf16 v[40:43], v[162:165], v[194:197], 0
	v_mfma_f32_16x16x32_bf16 v[28:31], v[146:149], v[202:205], 0
	v_mfma_f32_16x16x32_bf16 v[24:27], v[162:165], v[202:205], 0
	v_mfma_f32_16x16x32_bf16 v[12:15], v[146:149], v[210:213], 0
	v_mfma_f32_16x16x32_bf16 v[8:11], v[162:165], v[210:213], 0
	v_mfma_f32_16x16x32_bf16 v[60:63], v[158:161], v[190:193], v[60:63]
	v_mfma_f32_16x16x32_bf16 v[56:59], v[166:169], v[190:193], v[56:59]
	v_mfma_f32_16x16x32_bf16 v[44:47], v[158:161], v[198:201], v[44:47]
	v_mfma_f32_16x16x32_bf16 v[40:43], v[166:169], v[198:201], v[40:43]
	v_mfma_f32_16x16x32_bf16 v[28:31], v[158:161], v[206:209], v[28:31]
	v_mfma_f32_16x16x32_bf16 v[24:27], v[166:169], v[206:209], v[24:27]
	v_mfma_f32_16x16x32_bf16 v[12:15], v[158:161], v[214:217], v[12:15]
	v_mfma_f32_16x16x32_bf16 v[8:11], v[166:169], v[214:217], v[8:11]
	v_mfma_f32_16x16x32_bf16 v[52:55], v[170:173], v[186:189], 0
	v_mfma_f32_16x16x32_bf16 v[48:51], v[178:181], v[186:189], 0
	v_mfma_f32_16x16x32_bf16 v[36:39], v[170:173], v[194:197], 0
	v_mfma_f32_16x16x32_bf16 v[32:35], v[178:181], v[194:197], 0
	v_mfma_f32_16x16x32_bf16 v[20:23], v[170:173], v[202:205], 0
	v_mfma_f32_16x16x32_bf16 v[16:19], v[178:181], v[202:205], 0
	v_mfma_f32_16x16x32_bf16 v[4:7], v[170:173], v[210:213], 0
	v_mfma_f32_16x16x32_bf16 v[0:3], v[178:181], v[210:213], 0
	v_mfma_f32_16x16x32_bf16 v[52:55], v[174:177], v[190:193], v[52:55]
	v_mfma_f32_16x16x32_bf16 v[48:51], v[182:185], v[190:193], v[48:51]
	v_mfma_f32_16x16x32_bf16 v[36:39], v[174:177], v[198:201], v[36:39]
	v_mfma_f32_16x16x32_bf16 v[32:35], v[182:185], v[198:201], v[32:35]
	v_mfma_f32_16x16x32_bf16 v[20:23], v[174:177], v[206:209], v[20:23]
	v_mfma_f32_16x16x32_bf16 v[16:19], v[182:185], v[206:209], v[16:19]
	v_mfma_f32_16x16x32_bf16 v[4:7], v[174:177], v[214:217], v[4:7]
	v_mfma_f32_16x16x32_bf16 v[0:3], v[182:185], v[214:217], v[0:3]
	s_barrier
	s_add_i32 s80, 0, 0x18000
	s_add_i32 s81, 0, 0x1c000
	v_add_u32_e32 v166, s80, v151
	v_add_u32_e32 v182, s81, v151
	ds_read_b128 v[146:149], v166
	ds_read_b128 v[158:161], v166 offset:1024
	ds_read_b128 v[162:165], v166 offset:2048
	ds_read_b128 v[166:169], v166 offset:3072
	ds_read_b128 v[170:173], v182
	ds_read_b128 v[174:177], v182 offset:1024
	ds_read_b128 v[178:181], v182 offset:2048
	ds_read_b128 v[182:185], v182 offset:3072
	s_add_u32 s34, s34, s8
	s_addc_u32 s35, s35, s9
	s_mov_b32 m0, s37
	v_lshl_add_u64 v[230:231], s[34:35], 0, v[128:129]
	ds_read_b128 v[186:189], v154 offset:32768
	ds_read_b128 v[190:193], v154 offset:33792
	ds_read_b128 v[194:197], v154 offset:34816
	ds_read_b128 v[198:201], v154 offset:35840
	ds_read_b128 v[202:205], v154 offset:36864
	ds_read_b128 v[206:209], v154 offset:37888
	ds_read_b128 v[210:213], v154 offset:38912
	ds_read_b128 v[214:217], v154 offset:39936
	global_load_lds_dwordx4 v[230:231], off
	v_lshl_add_u64 v[230:231], s[34:35], 0, v[132:133]
	s_mov_b32 m0, s38
	s_nop 0
	global_load_lds_dwordx4 v[230:231], off
	s_waitcnt vmcnt(8)
	s_waitcnt lgkmcnt(0)
	s_barrier
	s_waitcnt lgkmcnt(0)
	v_mfma_f32_16x16x32_bf16 v[120:123], v[146:149], v[186:189], v[120:123]
	v_mfma_f32_16x16x32_bf16 v[124:127], v[162:165], v[186:189], v[124:127]
	v_mfma_f32_16x16x32_bf16 v[108:111], v[146:149], v[194:197], v[108:111]
	v_mfma_f32_16x16x32_bf16 v[104:107], v[162:165], v[194:197], v[104:107]
	v_mfma_f32_16x16x32_bf16 v[92:95], v[146:149], v[202:205], v[92:95]
	v_mfma_f32_16x16x32_bf16 v[88:91], v[162:165], v[202:205], v[88:91]
	v_mfma_f32_16x16x32_bf16 v[76:79], v[146:149], v[210:213], v[76:79]
	v_mfma_f32_16x16x32_bf16 v[72:75], v[162:165], v[210:213], v[72:75]
	v_mfma_f32_16x16x32_bf16 v[120:123], v[158:161], v[190:193], v[120:123]
	v_mfma_f32_16x16x32_bf16 v[124:127], v[166:169], v[190:193], v[124:127]
	v_mfma_f32_16x16x32_bf16 v[108:111], v[158:161], v[198:201], v[108:111]
	v_mfma_f32_16x16x32_bf16 v[104:107], v[166:169], v[198:201], v[104:107]
	v_mfma_f32_16x16x32_bf16 v[92:95], v[158:161], v[206:209], v[92:95]
	v_mfma_f32_16x16x32_bf16 v[88:91], v[166:169], v[206:209], v[88:91]
	v_mfma_f32_16x16x32_bf16 v[76:79], v[158:161], v[214:217], v[76:79]
	v_mfma_f32_16x16x32_bf16 v[72:75], v[166:169], v[214:217], v[72:75]
	v_mfma_f32_16x16x32_bf16 v[116:119], v[170:173], v[186:189], v[116:119]
	v_mfma_f32_16x16x32_bf16 v[112:115], v[178:181], v[186:189], v[112:115]
	v_mfma_f32_16x16x32_bf16 v[100:103], v[170:173], v[194:197], v[100:103]
	v_mfma_f32_16x16x32_bf16 v[96:99], v[178:181], v[194:197], v[96:99]
	v_mfma_f32_16x16x32_bf16 v[84:87], v[170:173], v[202:205], v[84:87]
	v_mfma_f32_16x16x32_bf16 v[80:83], v[178:181], v[202:205], v[80:83]
	v_mfma_f32_16x16x32_bf16 v[68:71], v[170:173], v[210:213], v[68:71]
	v_mfma_f32_16x16x32_bf16 v[64:67], v[178:181], v[210:213], v[64:67]
	v_mfma_f32_16x16x32_bf16 v[116:119], v[174:177], v[190:193], v[116:119]
	v_mfma_f32_16x16x32_bf16 v[112:115], v[182:185], v[190:193], v[112:115]
	v_mfma_f32_16x16x32_bf16 v[100:103], v[174:177], v[198:201], v[100:103]
	v_mfma_f32_16x16x32_bf16 v[96:99], v[182:185], v[198:201], v[96:99]
	v_mfma_f32_16x16x32_bf16 v[84:87], v[174:177], v[206:209], v[84:87]
	v_mfma_f32_16x16x32_bf16 v[80:83], v[182:185], v[206:209], v[80:83]
	v_mfma_f32_16x16x32_bf16 v[68:71], v[174:177], v[214:217], v[68:71]
	v_mfma_f32_16x16x32_bf16 v[64:67], v[182:185], v[214:217], v[64:67]
	s_barrier
; #define PG8_STAGE(bufoff, gbase, voff) do { _Pragma("unroll") for (int _i = 0; _i < 2; ++_i) \
;         __builtin_amdgcn_global_load_lds((const unsigned*)((const char*)(gbase) + (voff)[_i]), (PG8_LAS unsigned*)(lds + (bufoff) + ldsw + _i * 8192), 16, 0, 0); } while (0)
; #define PG8_LDA(dst, b, h) do { _Pragma("unroll") for (int m = 0; m < 4; ++m) _Pragma("unroll") for (int k = 0; k < 2; ++k) dst[m][k] = *(const PG8_LAS bf16x8*)(lds + PG8_SA(b, h) + aoff + m * 2048 + k * 1024); } while (0)
; #define PG8_LDB(dst, b, h) do { _Pragma("unroll") for (int n = 0; n < 2; ++n) _Pragma("unroll") for (int k = 0; k < 2; ++k) dst[n][k] = *(const PG8_LAS bf16x8*)(lds + PG8_SB(b, h) + boff + n * 2048 + k * 1024); } while (0)
; #define PG8_MMA(ai, bj, At, Bt) do { __builtin_amdgcn_s_setprio(1); _Pragma("unroll") for (int m = 0; m < 4; ++m) _Pragma("unroll") for (int n = 0; n < 2; ++n) _Pragma("unroll") for (int k = 0; k < 2; ++k) \
;         acc[ai][bj][m][n] = __builtin_amdgcn_mfma_f32_16x16x32_bf16(Bt[n][k], At[m][k], acc[ai][bj][m][n], 0, 0, 0); __builtin_amdgcn_s_setprio(0); } while (0)
; #define PG8_WAIT_V(n) asm volatile("s_waitcnt vmcnt(" #n ")" ::: "memory")
; #define PG8_BAR __builtin_amdgcn_s_barrier()
; template <class Epi, class Sched, bool ALIGN_EPI = false, bool SP2 = false>
; __device__ __forceinline__ void gemm_phase(PG8_LAS unsigned char* lds, const Gemm g, const Sched& S, const Epi& E) {
;     ...
;         for (int t = 0; t < nt; t += 2) {
;             const bool last = (t == nt - 2);
;             const char* a1 = cA + (size_t)(t + 1) * kstep;
;             const char* a2 = last ? nA : cA + (size_t)(t + 2) * kstep; const char* b2 = last ? nB : cB + (size_t)(t + 2) * kstep;
;             const char* a3 = a2 + kstep; const char* b3 = b2 + kstep;
;             if (last && has_next) S.a_ready(nxt);
;             if constexpr (SP2) {
;             PG8_LDB(B0, 0, 0); PG8_LDB(B1, 0, 1); PG8_SCHED; PG8_LDA(At, 0, 0); PG8_STAGE(PG8_SA(1, 1), a1 + hstep, voffA);
;             PG8_WAIT_V(8); PG8_WAIT_L(0); PG8_BAR; PG8_MMA(0, 0, At, B0); PG8_MMA(0, 1, At, B1); PG8_BAR; PG8_SCHED;
;     ...
;             PG8_LDA(At, 1, 1); PG8_STAGE(PG8_SB(1, 0), b3, voffB); PG8_STAGE(PG8_SB(1, 1), b3 + hstep, voffB); PG8_STAGE(PG8_SA(1, 0), a3, voffA);
;             PG8_WAIT_V(8); PG8_WAIT_L(0); PG8_BAR; PG8_MMA(1, 0, At, B0); PG8_MMA(1, 1, At, B1); PG8_BAR; PG8_SCHED;
	s_add_i32 s34, s80, s16
	v_lshl_add_u64 v[218:219], v[218:219], 0, s[20:21]
	s_mov_b32 m0, s34
	ds_read_b128 v[186:189], v154 offset:49152
	ds_read_b128 v[190:193], v154 offset:50176
	ds_read_b128 v[194:197], v154 offset:51200
	ds_read_b128 v[198:201], v154 offset:52224
	ds_read_b128 v[202:205], v154 offset:53248
	ds_read_b128 v[206:209], v154 offset:54272
	ds_read_b128 v[210:213], v154 offset:55296
	ds_read_b128 v[214:217], v154 offset:56320
	global_load_lds_dwordx4 v[218:219], off
	v_lshl_add_u64 v[218:219], v[220:221], 0, s[20:21]
	s_add_i32 m0, s34, 0x2000
	s_add_i32 s34, s81, s16
	global_load_lds_dwordx4 v[218:219], off
	v_lshl_add_u64 v[218:219], v[222:223], 0, s[20:21]
	s_mov_b32 m0, s34
	s_nop 0
	global_load_lds_dwordx4 v[218:219], off
	v_lshl_add_u64 v[218:219], v[224:225], 0, s[20:21]
	s_add_i32 m0, s34, 0x2000
	s_nop 0
	global_load_lds_dwordx4 v[218:219], off
	v_lshl_add_u64 v[218:219], v[226:227], 0, s[20:21]
	s_mov_b32 m0, s44
	s_nop 0
	global_load_lds_dwordx4 v[218:219], off
	v_lshl_add_u64 v[218:219], v[228:229], 0, s[20:21]
	s_mov_b32 m0, s45
	s_nop 0
	global_load_lds_dwordx4 v[218:219], off
	s_waitcnt vmcnt(8)
	s_waitcnt lgkmcnt(0)
	s_barrier
	s_waitcnt lgkmcnt(0)
	v_mfma_f32_16x16x32_bf16 v[60:63], v[146:149], v[186:189], v[60:63]
	v_mfma_f32_16x16x32_bf16 v[56:59], v[162:165], v[186:189], v[56:59]
	v_mfma_f32_16x16x32_bf16 v[44:47], v[146:149], v[194:197], v[44:47]
	v_mfma_f32_16x16x32_bf16 v[40:43], v[162:165], v[194:197], v[40:43]
	v_mfma_f32_16x16x32_bf16 v[28:31], v[146:149], v[202:205], v[28:31]
	v_mfma_f32_16x16x32_bf16 v[24:27], v[162:165], v[202:205], v[24:27]
	v_mfma_f32_16x16x32_bf16 v[12:15], v[146:149], v[210:213], v[12:15]
	v_mfma_f32_16x16x32_bf16 v[8:11], v[162:165], v[210:213], v[8:11]
	v_mfma_f32_16x16x32_bf16 v[60:63], v[158:161], v[190:193], v[60:63]
	v_mfma_f32_16x16x32_bf16 v[56:59], v[166:169], v[190:193], v[56:59]
	v_mfma_f32_16x16x32_bf16 v[44:47], v[158:161], v[198:201], v[44:47]
	v_mfma_f32_16x16x32_bf16 v[40:43], v[166:169], v[198:201], v[40:43]
	v_mfma_f32_16x16x32_bf16 v[28:31], v[158:161], v[206:209], v[28:31]
	v_mfma_f32_16x16x32_bf16 v[24:27], v[166:169], v[206:209], v[24:27]
	v_mfma_f32_16x16x32_bf16 v[12:15], v[158:161], v[214:217], v[12:15]
	v_mfma_f32_16x16x32_bf16 v[8:11], v[166:169], v[214:217], v[8:11]
	v_mfma_f32_16x16x32_bf16 v[52:55], v[170:173], v[186:189], v[52:55]
	v_mfma_f32_16x16x32_bf16 v[48:51], v[178:181], v[186:189], v[48:51]
	v_mfma_f32_16x16x32_bf16 v[36:39], v[170:173], v[194:197], v[36:39]
	v_mfma_f32_16x16x32_bf16 v[32:35], v[178:181], v[194:197], v[32:35]
	v_mfma_f32_16x16x32_bf16 v[20:23], v[170:173], v[202:205], v[20:23]
	v_mfma_f32_16x16x32_bf16 v[16:19], v[178:181], v[202:205], v[16:19]
	v_mfma_f32_16x16x32_bf16 v[4:7], v[170:173], v[210:213], v[4:7]
	v_mfma_f32_16x16x32_bf16 v[0:3], v[178:181], v[210:213], v[0:3]
	v_mfma_f32_16x16x32_bf16 v[52:55], v[174:177], v[190:193], v[52:55]
	v_mfma_f32_16x16x32_bf16 v[48:51], v[182:185], v[190:193], v[48:51]
	v_mfma_f32_16x16x32_bf16 v[36:39], v[174:177], v[198:201], v[36:39]
	v_mfma_f32_16x16x32_bf16 v[32:35], v[182:185], v[198:201], v[32:35]
	v_mfma_f32_16x16x32_bf16 v[20:23], v[174:177], v[206:209], v[20:23]
	v_mfma_f32_16x16x32_bf16 v[16:19], v[182:185], v[206:209], v[16:19]
	v_mfma_f32_16x16x32_bf16 v[4:7], v[174:177], v[214:217], v[4:7]
	v_mfma_f32_16x16x32_bf16 v[0:3], v[182:185], v[214:217], v[0:3]
	s_barrier
	s_add_u32 s30, s30, 0x100
	s_addc_u32 s31, s31, 0
	s_add_u32 s77, s77, 0x100
	s_addc_u32 s78, s78, 0
	s_cmp_ge_i32 s79, s40
	s_mov_b32 s34, s79
	s_cbranch_scc0 .LBB0_2165
	s_branch .Lpeel_x10
.LBB0_2165:
	ds_read_b128 v[146:149], v152
	ds_read_b128 v[158:161], v152 offset:1024
	ds_read_b128 v[162:165], v152 offset:2048
	ds_read_b128 v[166:169], v152 offset:3072
	ds_read_b128 v[170:173], v153
	ds_read_b128 v[174:177], v153 offset:1024
	ds_read_b128 v[178:181], v153 offset:2048
	ds_read_b128 v[182:185], v153 offset:3072
	s_add_i32 s79, s34, 2
	s_add_u32 s80, s30, 0x80
	s_addc_u32 s35, s31, 0
	s_cmp_eq_u32 s50, s34
	s_cselect_b32 s34, s0, s80
	s_cselect_b32 s35, s1, s35
	s_cselect_b32 s81, s29, s78
	s_cselect_b32 s80, s28, s77
	v_lshl_add_u64 v[218:219], s[30:31], 0, v[138:139]
	s_add_i32 m0, s33, 0xc000
	ds_read_b128 v[186:189], v154
	ds_read_b128 v[190:193], v154 offset:1024
	ds_read_b128 v[194:197], v154 offset:2048
	ds_read_b128 v[198:201], v154 offset:3072
	ds_read_b128 v[202:205], v154 offset:4096
	ds_read_b128 v[206:209], v154 offset:5120
	ds_read_b128 v[210:213], v154 offset:6144
	ds_read_b128 v[214:217], v154 offset:7168
	global_load_lds_dwordx4 v[218:219], off
	v_lshl_add_u64 v[218:219], s[30:31], 0, v[140:141]
	s_add_i32 m0, s33, 0xe000
	s_nop 0
	global_load_lds_dwordx4 v[218:219], off
	s_waitcnt vmcnt(8)
	s_waitcnt lgkmcnt(0)
	s_barrier
; #define PG8_STAGE(bufoff, gbase, voff) do { _Pragma("unroll") for (int _i = 0; _i < 2; ++_i) \
;         __builtin_amdgcn_global_load_lds((const unsigned*)((const char*)(gbase) + (voff)[_i]), (PG8_LAS unsigned*)(lds + (bufoff) + ldsw + _i * 8192), 16, 0, 0); } while (0)
; #define PG8_LDA(dst, b, h) do { _Pragma("unroll") for (int m = 0; m < 4; ++m) _Pragma("unroll") for (int k = 0; k < 2; ++k) dst[m][k] = *(const PG8_LAS bf16x8*)(lds + PG8_SA(b, h) + aoff + m * 2048 + k * 1024); } while (0)
; #define PG8_MMA(ai, bj, At, Bt) do { __builtin_amdgcn_s_setprio(1); _Pragma("unroll") for (int m = 0; m < 4; ++m) _Pragma("unroll") for (int n = 0; n < 2; ++n) _Pragma("unroll") for (int k = 0; k < 2; ++k) \
;         acc[ai][bj][m][n] = __builtin_amdgcn_mfma_f32_16x16x32_bf16(Bt[n][k], At[m][k], acc[ai][bj][m][n], 0, 0, 0); __builtin_amdgcn_s_setprio(0); } while (0)
; #define PG8_WAIT_V(n) asm volatile("s_waitcnt vmcnt(" #n ")" ::: "memory")
; #define PG8_WAIT_L(n) asm volatile("s_waitcnt lgkmcnt(" #n ")" ::: "memory")
; #define PG8_BAR __builtin_amdgcn_s_barrier()
; #define PG8_SCHED __builtin_amdgcn_sched_barrier(0)
; template <class Epi, class Sched, bool ALIGN_EPI = false, bool SP2 = false>
; __device__ __forceinline__ void gemm_phase(PG8_LAS unsigned char* lds, const Gemm g, const Sched& S, const Epi& E) {
;     ...
;             PG8_WAIT_V(8); PG8_WAIT_L(0); PG8_BAR; PG8_MMA(0, 0, At, B0); PG8_MMA(0, 1, At, B1); PG8_BAR; PG8_SCHED;
;             PG8_LDA(At, 0, 1); PG8_STAGE(PG8_SB(0, 0), b2, voffB); PG8_STAGE(PG8_SB(0, 1), b2 + hstep, voffB); PG8_STAGE(PG8_SA(0, 0), a2, voffA);
;             PG8_WAIT_V(8); PG8_WAIT_L(0); PG8_BAR; PG8_MMA(1, 0, At, B0); PG8_MMA(1, 1, At, B1); PG8_BAR; PG8_SCHED;
	s_waitcnt lgkmcnt(0)
	v_mfma_f32_16x16x32_bf16 v[120:123], v[146:149], v[186:189], v[120:123]
	v_mfma_f32_16x16x32_bf16 v[124:127], v[162:165], v[186:189], v[124:127]
	v_mfma_f32_16x16x32_bf16 v[108:111], v[146:149], v[194:197], v[108:111]
	v_mfma_f32_16x16x32_bf16 v[104:107], v[162:165], v[194:197], v[104:107]
	v_mfma_f32_16x16x32_bf16 v[92:95], v[146:149], v[202:205], v[92:95]
	v_mfma_f32_16x16x32_bf16 v[88:91], v[162:165], v[202:205], v[88:91]
	v_mfma_f32_16x16x32_bf16 v[76:79], v[146:149], v[210:213], v[76:79]
	v_mfma_f32_16x16x32_bf16 v[72:75], v[162:165], v[210:213], v[72:75]
	v_mfma_f32_16x16x32_bf16 v[120:123], v[158:161], v[190:193], v[120:123]
	v_mfma_f32_16x16x32_bf16 v[124:127], v[166:169], v[190:193], v[124:127]
	v_mfma_f32_16x16x32_bf16 v[108:111], v[158:161], v[198:201], v[108:111]
	v_mfma_f32_16x16x32_bf16 v[104:107], v[166:169], v[198:201], v[104:107]
	v_mfma_f32_16x16x32_bf16 v[92:95], v[158:161], v[206:209], v[92:95]
	v_mfma_f32_16x16x32_bf16 v[88:91], v[166:169], v[206:209], v[88:91]
	v_mfma_f32_16x16x32_bf16 v[76:79], v[158:161], v[214:217], v[76:79]
	v_mfma_f32_16x16x32_bf16 v[72:75], v[166:169], v[214:217], v[72:75]
	v_mfma_f32_16x16x32_bf16 v[116:119], v[170:173], v[186:189], v[116:119]
	v_mfma_f32_16x16x32_bf16 v[112:115], v[178:181], v[186:189], v[112:115]
	v_mfma_f32_16x16x32_bf16 v[100:103], v[170:173], v[194:197], v[100:103]
	v_mfma_f32_16x16x32_bf16 v[96:99], v[178:181], v[194:197], v[96:99]
	v_mfma_f32_16x16x32_bf16 v[84:87], v[170:173], v[202:205], v[84:87]
	v_mfma_f32_16x16x32_bf16 v[80:83], v[178:181], v[202:205], v[80:83]
	v_mfma_f32_16x16x32_bf16 v[68:71], v[170:173], v[210:213], v[68:71]
	v_mfma_f32_16x16x32_bf16 v[64:67], v[178:181], v[210:213], v[64:67]
	v_mfma_f32_16x16x32_bf16 v[116:119], v[174:177], v[190:193], v[116:119]
	v_mfma_f32_16x16x32_bf16 v[112:115], v[182:185], v[190:193], v[112:115]
	v_mfma_f32_16x16x32_bf16 v[100:103], v[174:177], v[198:201], v[100:103]
	v_mfma_f32_16x16x32_bf16 v[96:99], v[182:185], v[198:201], v[96:99]
	v_mfma_f32_16x16x32_bf16 v[84:87], v[174:177], v[206:209], v[84:87]
	v_mfma_f32_16x16x32_bf16 v[80:83], v[182:185], v[206:209], v[80:83]
	v_mfma_f32_16x16x32_bf16 v[68:71], v[174:177], v[214:217], v[68:71]
	v_mfma_f32_16x16x32_bf16 v[64:67], v[182:185], v[214:217], v[64:67]
	s_barrier
	s_add_i32 s82, s59, s16
	v_lshl_add_u64 v[218:219], s[80:81], 0, v[130:131]
	s_mov_b32 m0, s82
	ds_read_b128 v[186:189], v154 offset:16384
	ds_read_b128 v[190:193], v154 offset:17408
	ds_read_b128 v[194:197], v154 offset:18432
	ds_read_b128 v[198:201], v154 offset:19456
	ds_read_b128 v[202:205], v154 offset:20480
	ds_read_b128 v[206:209], v154 offset:21504
	ds_read_b128 v[210:213], v154 offset:22528
	ds_read_b128 v[214:217], v154 offset:23552
	global_load_lds_dwordx4 v[218:219], off
	s_add_i32 m0, s82, 0x2000
	v_lshl_add_u64 v[220:221], s[80:81], 0, v[134:135]
	s_add_u32 s80, s80, s8
	s_addc_u32 s81, s81, s9
	s_add_i32 s82, s60, s16
	global_load_lds_dwordx4 v[220:221], off
	v_lshl_add_u64 v[222:223], s[80:81], 0, v[130:131]
	s_mov_b32 m0, s82
	v_lshl_add_u64 v[224:225], s[80:81], 0, v[134:135]
	global_load_lds_dwordx4 v[222:223], off
	s_add_i32 m0, s82, 0x2000
	v_lshl_add_u64 v[226:227], s[34:35], 0, v[128:129]
	global_load_lds_dwordx4 v[224:225], off
	s_mov_b32 m0, s33
	v_lshl_add_u64 v[228:229], s[34:35], 0, v[132:133]
	global_load_lds_dwordx4 v[226:227], off
	s_mov_b32 m0, s36
	s_nop 0
	global_load_lds_dwordx4 v[228:229], off
	s_waitcnt vmcnt(8)
	s_waitcnt lgkmcnt(0)
	s_barrier
	s_waitcnt lgkmcnt(0)
	v_mfma_f32_16x16x32_bf16 v[60:63], v[146:149], v[186:189], v[60:63]
	v_mfma_f32_16x16x32_bf16 v[56:59], v[162:165], v[186:189], v[56:59]
	v_mfma_f32_16x16x32_bf16 v[44:47], v[146:149], v[194:197], v[44:47]
	v_mfma_f32_16x16x32_bf16 v[40:43], v[162:165], v[194:197], v[40:43]
	v_mfma_f32_16x16x32_bf16 v[28:31], v[146:149], v[202:205], v[28:31]
	v_mfma_f32_16x16x32_bf16 v[24:27], v[162:165], v[202:205], v[24:27]
	v_mfma_f32_16x16x32_bf16 v[12:15], v[146:149], v[210:213], v[12:15]
	v_mfma_f32_16x16x32_bf16 v[8:11], v[162:165], v[210:213], v[8:11]
	v_mfma_f32_16x16x32_bf16 v[60:63], v[158:161], v[190:193], v[60:63]
	v_mfma_f32_16x16x32_bf16 v[56:59], v[166:169], v[190:193], v[56:59]
	v_mfma_f32_16x16x32_bf16 v[44:47], v[158:161], v[198:201], v[44:47]
	v_mfma_f32_16x16x32_bf16 v[40:43], v[166:169], v[198:201], v[40:43]
	v_mfma_f32_16x16x32_bf16 v[28:31], v[158:161], v[206:209], v[28:31]
	v_mfma_f32_16x16x32_bf16 v[24:27], v[166:169], v[206:209], v[24:27]
	v_mfma_f32_16x16x32_bf16 v[12:15], v[158:161], v[214:217], v[12:15]
	v_mfma_f32_16x16x32_bf16 v[8:11], v[166:169], v[214:217], v[8:11]
	v_mfma_f32_16x16x32_bf16 v[52:55], v[170:173], v[186:189], v[52:55]
	v_mfma_f32_16x16x32_bf16 v[48:51], v[178:181], v[186:189], v[48:51]
	v_mfma_f32_16x16x32_bf16 v[36:39], v[170:173], v[194:197], v[36:39]
	v_mfma_f32_16x16x32_bf16 v[32:35], v[178:181], v[194:197], v[32:35]
	v_mfma_f32_16x16x32_bf16 v[20:23], v[170:173], v[202:205], v[20:23]
	v_mfma_f32_16x16x32_bf16 v[16:19], v[178:181], v[202:205], v[16:19]
	v_mfma_f32_16x16x32_bf16 v[4:7], v[170:173], v[210:213], v[4:7]
	v_mfma_f32_16x16x32_bf16 v[0:3], v[178:181], v[210:213], v[0:3]
	v_mfma_f32_16x16x32_bf16 v[52:55], v[174:177], v[190:193], v[52:55]
	v_mfma_f32_16x16x32_bf16 v[48:51], v[182:185], v[190:193], v[48:51]
	v_mfma_f32_16x16x32_bf16 v[36:39], v[174:177], v[198:201], v[36:39]
	v_mfma_f32_16x16x32_bf16 v[32:35], v[182:185], v[198:201], v[32:35]
	v_mfma_f32_16x16x32_bf16 v[20:23], v[174:177], v[206:209], v[20:23]
	v_mfma_f32_16x16x32_bf16 v[16:19], v[182:185], v[206:209], v[16:19]
	v_mfma_f32_16x16x32_bf16 v[4:7], v[174:177], v[214:217], v[4:7]
	v_mfma_f32_16x16x32_bf16 v[0:3], v[182:185], v[214:217], v[0:3]
	s_barrier
; #define PG8_STAGE(bufoff, gbase, voff) do { _Pragma("unroll") for (int _i = 0; _i < 2; ++_i) \
;         __builtin_amdgcn_global_load_lds((const unsigned*)((const char*)(gbase) + (voff)[_i]), (PG8_LAS unsigned*)(lds + (bufoff) + ldsw + _i * 8192), 16, 0, 0); } while (0)
; #define PG8_LDA(dst, b, h) do { _Pragma("unroll") for (int m = 0; m < 4; ++m) _Pragma("unroll") for (int k = 0; k < 2; ++k) dst[m][k] = *(const PG8_LAS bf16x8*)(lds + PG8_SA(b, h) + aoff + m * 2048 + k * 1024); } while (0)
; #define PG8_LDB(dst, b, h) do { _Pragma("unroll") for (int n = 0; n < 2; ++n) _Pragma("unroll") for (int k = 0; k < 2; ++k) dst[n][k] = *(const PG8_LAS bf16x8*)(lds + PG8_SB(b, h) + boff + n * 2048 + k * 1024); } while (0)
; #define PG8_MMA(ai, bj, At, Bt) do { __builtin_amdgcn_s_setprio(1); _Pragma("unroll") for (int m = 0; m < 4; ++m) _Pragma("unroll") for (int n = 0; n < 2; ++n) _Pragma("unroll") for (int k = 0; k < 2; ++k) \
;         acc[ai][bj][m][n] = __builtin_amdgcn_mfma_f32_16x16x32_bf16(Bt[n][k], At[m][k], acc[ai][bj][m][n], 0, 0, 0); __builtin_amdgcn_s_setprio(0); } while (0)
; #define PG8_WAIT_V(n) asm volatile("s_waitcnt vmcnt(" #n ")" ::: "memory")
; #define PG8_WAIT_L(n) asm volatile("s_waitcnt lgkmcnt(" #n ")" ::: "memory")
; #define PG8_BAR __builtin_amdgcn_s_barrier()
; #define PG8_SCHED __builtin_amdgcn_sched_barrier(0)
; template <class Epi, class Sched, bool ALIGN_EPI = false, bool SP2 = false>
; __device__ __forceinline__ void gemm_phase(PG8_LAS unsigned char* lds, const Gemm g, const Sched& S, const Epi& E) {
;     ...
;             PG8_LDB(B0, 1, 0); PG8_LDB(B1, 1, 1); PG8_SCHED; PG8_LDA(At, 1, 0); PG8_STAGE(PG8_SA(0, 1), a2 + hstep, voffA);
;             PG8_WAIT_V(8); PG8_WAIT_L(0); PG8_BAR; PG8_MMA(0, 0, At, B0); PG8_MMA(0, 1, At, B1); PG8_BAR; PG8_SCHED;
;             PG8_LDA(At, 1, 1); PG8_STAGE(PG8_SB(1, 0), b3, voffB); PG8_STAGE(PG8_SB(1, 1), b3 + hstep, voffB); PG8_STAGE(PG8_SA(1, 0), a3, voffA);
;             PG8_WAIT_V(8); PG8_WAIT_L(0); PG8_BAR; PG8_MMA(1, 0, At, B0); PG8_MMA(1, 1, At, B1); PG8_BAR; PG8_SCHED;
	s_add_i32 s80, 0, 0x18000
	s_add_i32 s81, 0, 0x1c000
	v_add_u32_e32 v166, s80, v151
	v_add_u32_e32 v182, s81, v151
	ds_read_b128 v[146:149], v166
	ds_read_b128 v[158:161], v166 offset:1024
	ds_read_b128 v[162:165], v166 offset:2048
	ds_read_b128 v[166:169], v166 offset:3072
	ds_read_b128 v[170:173], v182
	ds_read_b128 v[174:177], v182 offset:1024
	ds_read_b128 v[178:181], v182 offset:2048
	ds_read_b128 v[182:185], v182 offset:3072
	s_add_u32 s34, s34, s8
	s_addc_u32 s35, s35, s9
	s_mov_b32 m0, s37
	v_lshl_add_u64 v[230:231], s[34:35], 0, v[128:129]
	ds_read_b128 v[186:189], v154 offset:32768
	ds_read_b128 v[190:193], v154 offset:33792
	ds_read_b128 v[194:197], v154 offset:34816
	ds_read_b128 v[198:201], v154 offset:35840
	ds_read_b128 v[202:205], v154 offset:36864
	ds_read_b128 v[206:209], v154 offset:37888
	ds_read_b128 v[210:213], v154 offset:38912
	ds_read_b128 v[214:217], v154 offset:39936
	global_load_lds_dwordx4 v[230:231], off
	v_lshl_add_u64 v[230:231], s[34:35], 0, v[132:133]
	s_mov_b32 m0, s38
	s_nop 0
	global_load_lds_dwordx4 v[230:231], off
	s_waitcnt vmcnt(8)
	s_waitcnt lgkmcnt(0)
	s_barrier
	s_waitcnt lgkmcnt(0)
	v_mfma_f32_16x16x32_bf16 v[120:123], v[146:149], v[186:189], v[120:123]
	v_mfma_f32_16x16x32_bf16 v[124:127], v[162:165], v[186:189], v[124:127]
	v_mfma_f32_16x16x32_bf16 v[108:111], v[146:149], v[194:197], v[108:111]
	v_mfma_f32_16x16x32_bf16 v[104:107], v[162:165], v[194:197], v[104:107]
	v_mfma_f32_16x16x32_bf16 v[92:95], v[146:149], v[202:205], v[92:95]
	v_mfma_f32_16x16x32_bf16 v[88:91], v[162:165], v[202:205], v[88:91]
	v_mfma_f32_16x16x32_bf16 v[76:79], v[146:149], v[210:213], v[76:79]
	v_mfma_f32_16x16x32_bf16 v[72:75], v[162:165], v[210:213], v[72:75]
	v_mfma_f32_16x16x32_bf16 v[120:123], v[158:161], v[190:193], v[120:123]
	v_mfma_f32_16x16x32_bf16 v[124:127], v[166:169], v[190:193], v[124:127]
	v_mfma_f32_16x16x32_bf16 v[108:111], v[158:161], v[198:201], v[108:111]
	v_mfma_f32_16x16x32_bf16 v[104:107], v[166:169], v[198:201], v[104:107]
	v_mfma_f32_16x16x32_bf16 v[92:95], v[158:161], v[206:209], v[92:95]
	v_mfma_f32_16x16x32_bf16 v[88:91], v[166:169], v[206:209], v[88:91]
	v_mfma_f32_16x16x32_bf16 v[76:79], v[158:161], v[214:217], v[76:79]
	v_mfma_f32_16x16x32_bf16 v[72:75], v[166:169], v[214:217], v[72:75]
	v_mfma_f32_16x16x32_bf16 v[116:119], v[170:173], v[186:189], v[116:119]
	v_mfma_f32_16x16x32_bf16 v[112:115], v[178:181], v[186:189], v[112:115]
	v_mfma_f32_16x16x32_bf16 v[100:103], v[170:173], v[194:197], v[100:103]
	v_mfma_f32_16x16x32_bf16 v[96:99], v[178:181], v[194:197], v[96:99]
	v_mfma_f32_16x16x32_bf16 v[84:87], v[170:173], v[202:205], v[84:87]
	v_mfma_f32_16x16x32_bf16 v[80:83], v[178:181], v[202:205], v[80:83]
	v_mfma_f32_16x16x32_bf16 v[68:71], v[170:173], v[210:213], v[68:71]
	v_mfma_f32_16x16x32_bf16 v[64:67], v[178:181], v[210:213], v[64:67]
	v_mfma_f32_16x16x32_bf16 v[116:119], v[174:177], v[190:193], v[116:119]
	v_mfma_f32_16x16x32_bf16 v[112:115], v[182:185], v[190:193], v[112:115]
	v_mfma_f32_16x16x32_bf16 v[100:103], v[174:177], v[198:201], v[100:103]
	v_mfma_f32_16x16x32_bf16 v[96:99], v[182:185], v[198:201], v[96:99]
	v_mfma_f32_16x16x32_bf16 v[84:87], v[174:177], v[206:209], v[84:87]
	v_mfma_f32_16x16x32_bf16 v[80:83], v[182:185], v[206:209], v[80:83]
	v_mfma_f32_16x16x32_bf16 v[68:71], v[174:177], v[214:217], v[68:71]
	v_mfma_f32_16x16x32_bf16 v[64:67], v[182:185], v[214:217], v[64:67]
	s_barrier
	s_add_i32 s34, s80, s16
	v_lshl_add_u64 v[218:219], v[218:219], 0, s[20:21]
	s_mov_b32 m0, s34
	ds_read_b128 v[186:189], v154 offset:49152
	ds_read_b128 v[190:193], v154 offset:50176
	ds_read_b128 v[194:197], v154 offset:51200
	ds_read_b128 v[198:201], v154 offset:52224
	ds_read_b128 v[202:205], v154 offset:53248
	ds_read_b128 v[206:209], v154 offset:54272
	ds_read_b128 v[210:213], v154 offset:55296
	ds_read_b128 v[214:217], v154 offset:56320
	global_load_lds_dwordx4 v[218:219], off
	v_lshl_add_u64 v[218:219], v[220:221], 0, s[20:21]
	s_add_i32 m0, s34, 0x2000
	s_add_i32 s34, s81, s16
	global_load_lds_dwordx4 v[218:219], off
	v_lshl_add_u64 v[218:219], v[222:223], 0, s[20:21]
	s_mov_b32 m0, s34
	s_nop 0
	global_load_lds_dwordx4 v[218:219], off
	v_lshl_add_u64 v[218:219], v[224:225], 0, s[20:21]
	s_add_i32 m0, s34, 0x2000
	s_nop 0
	global_load_lds_dwordx4 v[218:219], off
	v_lshl_add_u64 v[218:219], v[226:227], 0, s[20:21]
	s_mov_b32 m0, s44
	s_nop 0
	global_load_lds_dwordx4 v[218:219], off
	v_lshl_add_u64 v[218:219], v[228:229], 0, s[20:21]
	s_mov_b32 m0, s45
	s_nop 0
	global_load_lds_dwordx4 v[218:219], off
	s_waitcnt vmcnt(8)
	s_waitcnt lgkmcnt(0)
	s_barrier
	s_waitcnt lgkmcnt(0)
	v_mfma_f32_16x16x32_bf16 v[60:63], v[146:149], v[186:189], v[60:63]
	v_mfma_f32_16x16x32_bf16 v[56:59], v[162:165], v[186:189], v[56:59]
	v_mfma_f32_16x16x32_bf16 v[44:47], v[146:149], v[194:197], v[44:47]
	v_mfma_f32_16x16x32_bf16 v[40:43], v[162:165], v[194:197], v[40:43]
	v_mfma_f32_16x16x32_bf16 v[28:31], v[146:149], v[202:205], v[28:31]
	v_mfma_f32_16x16x32_bf16 v[24:27], v[162:165], v[202:205], v[24:27]
	v_mfma_f32_16x16x32_bf16 v[12:15], v[146:149], v[210:213], v[12:15]
	v_mfma_f32_16x16x32_bf16 v[8:11], v[162:165], v[210:213], v[8:11]
	v_mfma_f32_16x16x32_bf16 v[60:63], v[158:161], v[190:193], v[60:63]
	v_mfma_f32_16x16x32_bf16 v[56:59], v[166:169], v[190:193], v[56:59]
	v_mfma_f32_16x16x32_bf16 v[44:47], v[158:161], v[198:201], v[44:47]
	v_mfma_f32_16x16x32_bf16 v[40:43], v[166:169], v[198:201], v[40:43]
	v_mfma_f32_16x16x32_bf16 v[28:31], v[158:161], v[206:209], v[28:31]
	v_mfma_f32_16x16x32_bf16 v[24:27], v[166:169], v[206:209], v[24:27]
	v_mfma_f32_16x16x32_bf16 v[12:15], v[158:161], v[214:217], v[12:15]
	v_mfma_f32_16x16x32_bf16 v[8:11], v[166:169], v[214:217], v[8:11]
	v_mfma_f32_16x16x32_bf16 v[52:55], v[170:173], v[186:189], v[52:55]
	v_mfma_f32_16x16x32_bf16 v[48:51], v[178:181], v[186:189], v[48:51]
	v_mfma_f32_16x16x32_bf16 v[36:39], v[170:173], v[194:197], v[36:39]
	v_mfma_f32_16x16x32_bf16 v[32:35], v[178:181], v[194:197], v[32:35]
	v_mfma_f32_16x16x32_bf16 v[20:23], v[170:173], v[202:205], v[20:23]
	v_mfma_f32_16x16x32_bf16 v[16:19], v[178:181], v[202:205], v[16:19]
	v_mfma_f32_16x16x32_bf16 v[4:7], v[170:173], v[210:213], v[4:7]
	v_mfma_f32_16x16x32_bf16 v[0:3], v[178:181], v[210:213], v[0:3]
	v_mfma_f32_16x16x32_bf16 v[52:55], v[174:177], v[190:193], v[52:55]
	v_mfma_f32_16x16x32_bf16 v[48:51], v[182:185], v[190:193], v[48:51]
	v_mfma_f32_16x16x32_bf16 v[36:39], v[174:177], v[198:201], v[36:39]
	v_mfma_f32_16x16x32_bf16 v[32:35], v[182:185], v[198:201], v[32:35]
	v_mfma_f32_16x16x32_bf16 v[20:23], v[174:177], v[206:209], v[20:23]
	v_mfma_f32_16x16x32_bf16 v[16:19], v[182:185], v[206:209], v[16:19]
	v_mfma_f32_16x16x32_bf16 v[4:7], v[174:177], v[214:217], v[4:7]
	v_mfma_f32_16x16x32_bf16 v[0:3], v[182:185], v[214:217], v[0:3]
	s_barrier
	s_add_u32 s30, s30, 0x100
	s_addc_u32 s31, s31, 0
	s_add_u32 s77, s77, 0x100
	s_addc_u32 s78, s78, 0
	s_cmp_ge_i32 s79, s40
	s_mov_b32 s34, s79
	s_cbranch_scc0 .LBB0_2165

; #define PG8_STAGE(bufoff, gbase, voff) do { _Pragma("unroll") for (int _i = 0; _i < 2; ++_i) \
;         __builtin_amdgcn_global_load_lds((const unsigned*)((const char*)(gbase) + (voff)[_i]), (PG8_LAS unsigned*)(lds + (bufoff) + ldsw + _i * 8192), 16, 0, 0); } while (0)
; #define PG8_LDA(dst, b, h) do { _Pragma("unroll") for (int m = 0; m < 4; ++m) _Pragma("unroll") for (int k = 0; k < 2; ++k) dst[m][k] = *(const PG8_LAS bf16x8*)(lds + PG8_SA(b, h) + aoff + m * 2048 + k * 1024); } while (0)
; #define PG8_LDB(dst, b, h) do { _Pragma("unroll") for (int n = 0; n < 2; ++n) _Pragma("unroll") for (int k = 0; k < 2; ++k) dst[n][k] = *(const PG8_LAS bf16x8*)(lds + PG8_SB(b, h) + boff + n * 2048 + k * 1024); } while (0)
; #define PG8_WAIT_V(n) asm volatile("s_waitcnt vmcnt(" #n ")" ::: "memory")
; #define PG8_WAIT_L(n) asm volatile("s_waitcnt lgkmcnt(" #n ")" ::: "memory")
; template <class Epi, class Sched, bool ALIGN_EPI = false, bool SP2 = false>
; __device__ __forceinline__ void gemm_phase(PG8_LAS unsigned char* lds, const Gemm g, const Sched& S, const Epi& E) {
;     ...
;         for (int t = 0; t < nt; t += 2) {
;             const bool last = (t == nt - 2);
;             const char* a1 = cA + (size_t)(t + 1) * kstep;
;             const char* a2 = last ? nA : cA + (size_t)(t + 2) * kstep; const char* b2 = last ? nB : cB + (size_t)(t + 2) * kstep;
;             const char* a3 = a2 + kstep; const char* b3 = b2 + kstep;
;             if (last && has_next) S.a_ready(nxt);
;             if constexpr (SP2) {
;             PG8_LDB(B0, 0, 0); PG8_LDB(B1, 0, 1); PG8_SCHED; PG8_LDA(At, 0, 0); PG8_STAGE(PG8_SA(1, 1), a1 + hstep, voffA);
;             PG8_WAIT_V(8); PG8_WAIT_L(0); PG8_BAR; PG8_MMA(0, 0, At, B0); PG8_MMA(0, 1, At, B1); PG8_BAR; PG8_SCHED;
;             PG8_LDA(At, 0, 1); PG8_STAGE(PG8_SB(0, 0), b2, voffB); PG8_STAGE(PG8_SB(0, 1), b2 + hstep, voffB); PG8_STAGE(PG8_SA(0, 0), a2, voffA);
;             PG8_WAIT_V(8); PG8_WAIT_L(0); PG8_BAR; PG8_MMA(1, 0, At, B0); PG8_MMA(1, 1, At, B1); PG8_BAR; PG8_SCHED;
;     ...
; #pragma unroll
;         for (int a = 0; a < 2; ++a)
; #pragma unroll
;             for (int b = 0; b < 2; ++b)
; #pragma unroll
;                 for (int m = 0; m < 4; ++m)
; #pragma unroll
;                     for (int n = 0; n < 2; ++n) acc[a][b][m][n] = (f32x4){0.f, 0.f, 0.f, 0.f};
;         cur = nxt; cA = nA; cB = nB; ++ui;
.LBB0_2384:
	s_andn2_b64 vcc, exec, s[24:25]
	s_waitcnt vmcnt(0)
	s_waitcnt lgkmcnt(0)
	s_cbranch_vccnz .LBB0_2387
	s_add_u32 s30, s30, 0x80
	s_addc_u32 s31, s31, 0
	s_add_u32 s61, s34, 0x100
	s_addc_u32 s62, s35, 0
	s_mov_b32 s34, 0
	ds_read_b128 v[144:147], v151
	ds_read_b128 v[156:159], v151 offset:1024
	ds_read_b128 v[160:163], v151 offset:2048
	ds_read_b128 v[164:167], v151 offset:3072
	ds_read_b128 v[168:171], v152
	ds_read_b128 v[172:175], v152 offset:1024
	ds_read_b128 v[176:179], v152 offset:2048
	ds_read_b128 v[180:183], v152 offset:3072
	s_add_i32 s63, s34, 2
	s_add_u32 s64, s30, 0x80
	s_addc_u32 s35, s31, 0
	s_cmp_eq_u32 s41, s34
	s_cselect_b32 s34, s0, s64
	s_cselect_b32 s35, s1, s35
	s_cselect_b32 s65, s29, s62
	s_cselect_b32 s64, s28, s61
	v_lshl_add_u64 v[216:217], s[30:31], 0, v[136:137]
	s_add_i32 m0, s17, 0xc000
	ds_read_b128 v[184:187], v153
	ds_read_b128 v[188:191], v153 offset:1024
	ds_read_b128 v[192:195], v153 offset:2048
	ds_read_b128 v[196:199], v153 offset:3072
	ds_read_b128 v[200:203], v153 offset:4096
	ds_read_b128 v[204:207], v153 offset:5120
	ds_read_b128 v[208:211], v153 offset:6144
	ds_read_b128 v[212:215], v153 offset:7168
	global_load_lds_dwordx4 v[216:217], off
	v_lshl_add_u64 v[216:217], s[30:31], 0, v[138:139]
	s_add_i32 m0, s17, 0xe000
	s_nop 0
	global_load_lds_dwordx4 v[216:217], off
	s_waitcnt vmcnt(8)
	s_waitcnt lgkmcnt(0)
	s_barrier
	s_waitcnt lgkmcnt(0)
	v_mfma_f32_16x16x32_bf16 v[124:127], v[144:147], v[184:187], 0
	v_mfma_f32_16x16x32_bf16 v[120:123], v[160:163], v[184:187], 0
	v_mfma_f32_16x16x32_bf16 v[108:111], v[144:147], v[192:195], 0
	v_mfma_f32_16x16x32_bf16 v[104:107], v[160:163], v[192:195], 0
	v_mfma_f32_16x16x32_bf16 v[92:95], v[144:147], v[200:203], 0
	v_mfma_f32_16x16x32_bf16 v[88:91], v[160:163], v[200:203], 0
	v_mfma_f32_16x16x32_bf16 v[76:79], v[144:147], v[208:211], 0
	v_mfma_f32_16x16x32_bf16 v[72:75], v[160:163], v[208:211], 0
	v_mfma_f32_16x16x32_bf16 v[124:127], v[156:159], v[188:191], v[124:127]
	v_mfma_f32_16x16x32_bf16 v[120:123], v[164:167], v[188:191], v[120:123]
	v_mfma_f32_16x16x32_bf16 v[108:111], v[156:159], v[196:199], v[108:111]
	v_mfma_f32_16x16x32_bf16 v[104:107], v[164:167], v[196:199], v[104:107]
	v_mfma_f32_16x16x32_bf16 v[92:95], v[156:159], v[204:207], v[92:95]
	v_mfma_f32_16x16x32_bf16 v[88:91], v[164:167], v[204:207], v[88:91]
	v_mfma_f32_16x16x32_bf16 v[76:79], v[156:159], v[212:215], v[76:79]
	v_mfma_f32_16x16x32_bf16 v[72:75], v[164:167], v[212:215], v[72:75]
	v_mfma_f32_16x16x32_bf16 v[116:119], v[168:171], v[184:187], 0
	v_mfma_f32_16x16x32_bf16 v[112:115], v[176:179], v[184:187], 0
	v_mfma_f32_16x16x32_bf16 v[100:103], v[168:171], v[192:195], 0
	v_mfma_f32_16x16x32_bf16 v[96:99], v[176:179], v[192:195], 0
	v_mfma_f32_16x16x32_bf16 v[84:87], v[168:171], v[200:203], 0
	v_mfma_f32_16x16x32_bf16 v[80:83], v[176:179], v[200:203], 0
	v_mfma_f32_16x16x32_bf16 v[68:71], v[168:171], v[208:211], 0
	v_mfma_f32_16x16x32_bf16 v[64:67], v[176:179], v[208:211], 0
	v_mfma_f32_16x16x32_bf16 v[116:119], v[172:175], v[188:191], v[116:119]
	v_mfma_f32_16x16x32_bf16 v[112:115], v[180:183], v[188:191], v[112:115]
	v_mfma_f32_16x16x32_bf16 v[100:103], v[172:175], v[196:199], v[100:103]
	v_mfma_f32_16x16x32_bf16 v[96:99], v[180:183], v[196:199], v[96:99]
	v_mfma_f32_16x16x32_bf16 v[84:87], v[172:175], v[204:207], v[84:87]
	v_mfma_f32_16x16x32_bf16 v[80:83], v[180:183], v[204:207], v[80:83]
	v_mfma_f32_16x16x32_bf16 v[68:71], v[172:175], v[212:215], v[68:71]
	v_mfma_f32_16x16x32_bf16 v[64:67], v[180:183], v[212:215], v[64:67]
	s_barrier
	s_add_i32 s66, s51, s16
	v_lshl_add_u64 v[216:217], s[64:65], 0, v[130:131]
	s_mov_b32 m0, s66
	ds_read_b128 v[184:187], v153 offset:16384
	ds_read_b128 v[188:191], v153 offset:17408
	ds_read_b128 v[192:195], v153 offset:18432
	ds_read_b128 v[196:199], v153 offset:19456
	ds_read_b128 v[200:203], v153 offset:20480
	ds_read_b128 v[204:207], v153 offset:21504
	ds_read_b128 v[208:211], v153 offset:22528
	ds_read_b128 v[212:215], v153 offset:23552
	global_load_lds_dwordx4 v[216:217], off
	s_add_i32 m0, s66, 0x2000
	v_lshl_add_u64 v[218:219], s[64:65], 0, v[134:135]
	s_add_u32 s64, s64, s6
	s_addc_u32 s65, s65, s7
	s_add_i32 s66, s56, s16
	global_load_lds_dwordx4 v[218:219], off
	v_lshl_add_u64 v[220:221], s[64:65], 0, v[130:131]
	s_mov_b32 m0, s66
	v_lshl_add_u64 v[222:223], s[64:65], 0, v[134:135]
	global_load_lds_dwordx4 v[220:221], off
	s_add_i32 m0, s66, 0x2000
	v_lshl_add_u64 v[224:225], s[34:35], 0, v[128:129]
	global_load_lds_dwordx4 v[222:223], off
	s_mov_b32 m0, s17
	v_lshl_add_u64 v[226:227], s[34:35], 0, v[132:133]
	global_load_lds_dwordx4 v[224:225], off
	s_mov_b32 m0, s19
	s_nop 0
	global_load_lds_dwordx4 v[226:227], off
	s_waitcnt vmcnt(8)
	s_waitcnt lgkmcnt(0)
	s_barrier
; #define PG8_STAGE(bufoff, gbase, voff) do { _Pragma("unroll") for (int _i = 0; _i < 2; ++_i) \
;         __builtin_amdgcn_global_load_lds((const unsigned*)((const char*)(gbase) + (voff)[_i]), (PG8_LAS unsigned*)(lds + (bufoff) + ldsw + _i * 8192), 16, 0, 0); } while (0)
; #define PG8_LDA(dst, b, h) do { _Pragma("unroll") for (int m = 0; m < 4; ++m) _Pragma("unroll") for (int k = 0; k < 2; ++k) dst[m][k] = *(const PG8_LAS bf16x8*)(lds + PG8_SA(b, h) + aoff + m * 2048 + k * 1024); } while (0)
; #define PG8_LDB(dst, b, h) do { _Pragma("unroll") for (int n = 0; n < 2; ++n) _Pragma("unroll") for (int k = 0; k < 2; ++k) dst[n][k] = *(const PG8_LAS bf16x8*)(lds + PG8_SB(b, h) + boff + n * 2048 + k * 1024); } while (0)
; #define PG8_MMA(ai, bj, At, Bt) do { __builtin_amdgcn_s_setprio(1); _Pragma("unroll") for (int m = 0; m < 4; ++m) _Pragma("unroll") for (int n = 0; n < 2; ++n) _Pragma("unroll") for (int k = 0; k < 2; ++k) \
;         acc[ai][bj][m][n] = __builtin_amdgcn_mfma_f32_16x16x32_bf16(Bt[n][k], At[m][k], acc[ai][bj][m][n], 0, 0, 0); __builtin_amdgcn_s_setprio(0); } while (0)
; #define PG8_WAIT_V(n) asm volatile("s_waitcnt vmcnt(" #n ")" ::: "memory")
; #define PG8_WAIT_L(n) asm volatile("s_waitcnt lgkmcnt(" #n ")" ::: "memory")
; #define PG8_BAR __builtin_amdgcn_s_barrier()
; #define PG8_SCHED __builtin_amdgcn_sched_barrier(0)
; template <class Epi, class Sched, bool ALIGN_EPI = false, bool SP2 = false>
; __device__ __forceinline__ void gemm_phase(PG8_LAS unsigned char* lds, const Gemm g, const Sched& S, const Epi& E) {
;     ...
;             PG8_WAIT_V(8); PG8_WAIT_L(0); PG8_BAR; PG8_MMA(1, 0, At, B0); PG8_MMA(1, 1, At, B1); PG8_BAR; PG8_SCHED;
;             PG8_LDB(B0, 1, 0); PG8_LDB(B1, 1, 1); PG8_SCHED; PG8_LDA(At, 1, 0); PG8_STAGE(PG8_SA(0, 1), a2 + hstep, voffA);
;             PG8_WAIT_V(8); PG8_WAIT_L(0); PG8_BAR; PG8_MMA(0, 0, At, B0); PG8_MMA(0, 1, At, B1); PG8_BAR; PG8_SCHED;
	s_waitcnt lgkmcnt(0)
	v_mfma_f32_16x16x32_bf16 v[60:63], v[144:147], v[184:187], 0
	v_mfma_f32_16x16x32_bf16 v[56:59], v[160:163], v[184:187], 0
	v_mfma_f32_16x16x32_bf16 v[44:47], v[144:147], v[192:195], 0
	v_mfma_f32_16x16x32_bf16 v[40:43], v[160:163], v[192:195], 0
	v_mfma_f32_16x16x32_bf16 v[28:31], v[144:147], v[200:203], 0
	v_mfma_f32_16x16x32_bf16 v[24:27], v[160:163], v[200:203], 0
	v_mfma_f32_16x16x32_bf16 v[12:15], v[144:147], v[208:211], 0
	v_mfma_f32_16x16x32_bf16 v[8:11], v[160:163], v[208:211], 0
	v_mfma_f32_16x16x32_bf16 v[60:63], v[156:159], v[188:191], v[60:63]
	v_mfma_f32_16x16x32_bf16 v[56:59], v[164:167], v[188:191], v[56:59]
	v_mfma_f32_16x16x32_bf16 v[44:47], v[156:159], v[196:199], v[44:47]
	v_mfma_f32_16x16x32_bf16 v[40:43], v[164:167], v[196:199], v[40:43]
	v_mfma_f32_16x16x32_bf16 v[28:31], v[156:159], v[204:207], v[28:31]
	v_mfma_f32_16x16x32_bf16 v[24:27], v[164:167], v[204:207], v[24:27]
	v_mfma_f32_16x16x32_bf16 v[12:15], v[156:159], v[212:215], v[12:15]
	v_mfma_f32_16x16x32_bf16 v[8:11], v[164:167], v[212:215], v[8:11]
	v_mfma_f32_16x16x32_bf16 v[52:55], v[168:171], v[184:187], 0
	v_mfma_f32_16x16x32_bf16 v[48:51], v[176:179], v[184:187], 0
	v_mfma_f32_16x16x32_bf16 v[36:39], v[168:171], v[192:195], 0
	v_mfma_f32_16x16x32_bf16 v[32:35], v[176:179], v[192:195], 0
	v_mfma_f32_16x16x32_bf16 v[20:23], v[168:171], v[200:203], 0
	v_mfma_f32_16x16x32_bf16 v[16:19], v[176:179], v[200:203], 0
	v_mfma_f32_16x16x32_bf16 v[4:7], v[168:171], v[208:211], 0
	v_mfma_f32_16x16x32_bf16 v[0:3], v[176:179], v[208:211], 0
	v_mfma_f32_16x16x32_bf16 v[52:55], v[172:175], v[188:191], v[52:55]
	v_mfma_f32_16x16x32_bf16 v[48:51], v[180:183], v[188:191], v[48:51]
	v_mfma_f32_16x16x32_bf16 v[36:39], v[172:175], v[196:199], v[36:39]
	v_mfma_f32_16x16x32_bf16 v[32:35], v[180:183], v[196:199], v[32:35]
	v_mfma_f32_16x16x32_bf16 v[20:23], v[172:175], v[204:207], v[20:23]
	v_mfma_f32_16x16x32_bf16 v[16:19], v[180:183], v[204:207], v[16:19]
	v_mfma_f32_16x16x32_bf16 v[4:7], v[172:175], v[212:215], v[4:7]
	v_mfma_f32_16x16x32_bf16 v[0:3], v[180:183], v[212:215], v[0:3]
	s_barrier
	s_add_i32 s64, 0, 0x18000
	v_add_u32_e32 v155, s64, v149
	s_add_i32 s65, 0, 0x1c000
	ds_read_b128 v[144:147], v155
	ds_read_b128 v[156:159], v155 offset:1024
	ds_read_b128 v[160:163], v155 offset:2048
	ds_read_b128 v[164:167], v155 offset:3072
	v_add_u32_e32 v155, s65, v149
	ds_read_b128 v[168:171], v155
	ds_read_b128 v[172:175], v155 offset:1024
	ds_read_b128 v[176:179], v155 offset:2048
	ds_read_b128 v[180:183], v155 offset:3072
	s_add_u32 s34, s34, s6
	s_addc_u32 s35, s35, s7
	s_mov_b32 m0, s33
	v_lshl_add_u64 v[228:229], s[34:35], 0, v[128:129]
	ds_read_b128 v[184:187], v153 offset:32768
	ds_read_b128 v[188:191], v153 offset:33792
	ds_read_b128 v[192:195], v153 offset:34816
	ds_read_b128 v[196:199], v153 offset:35840
	ds_read_b128 v[200:203], v153 offset:36864
	ds_read_b128 v[204:207], v153 offset:37888
	ds_read_b128 v[208:211], v153 offset:38912
	ds_read_b128 v[212:215], v153 offset:39936
	global_load_lds_dwordx4 v[228:229], off
	v_lshl_add_u64 v[228:229], s[34:35], 0, v[132:133]
	s_mov_b32 m0, s36
	s_nop 0
	global_load_lds_dwordx4 v[228:229], off
	s_waitcnt vmcnt(8)
	s_waitcnt lgkmcnt(0)
	s_barrier
	s_waitcnt lgkmcnt(0)
	v_mfma_f32_16x16x32_bf16 v[124:127], v[144:147], v[184:187], v[124:127]
	v_mfma_f32_16x16x32_bf16 v[120:123], v[160:163], v[184:187], v[120:123]
	v_mfma_f32_16x16x32_bf16 v[108:111], v[144:147], v[192:195], v[108:111]
	v_mfma_f32_16x16x32_bf16 v[104:107], v[160:163], v[192:195], v[104:107]
	v_mfma_f32_16x16x32_bf16 v[92:95], v[144:147], v[200:203], v[92:95]
	v_mfma_f32_16x16x32_bf16 v[88:91], v[160:163], v[200:203], v[88:91]
	v_mfma_f32_16x16x32_bf16 v[76:79], v[144:147], v[208:211], v[76:79]
	v_mfma_f32_16x16x32_bf16 v[72:75], v[160:163], v[208:211], v[72:75]
	v_mfma_f32_16x16x32_bf16 v[124:127], v[156:159], v[188:191], v[124:127]
	v_mfma_f32_16x16x32_bf16 v[120:123], v[164:167], v[188:191], v[120:123]
	v_mfma_f32_16x16x32_bf16 v[108:111], v[156:159], v[196:199], v[108:111]
	v_mfma_f32_16x16x32_bf16 v[104:107], v[164:167], v[196:199], v[104:107]
	v_mfma_f32_16x16x32_bf16 v[92:95], v[156:159], v[204:207], v[92:95]
	v_mfma_f32_16x16x32_bf16 v[88:91], v[164:167], v[204:207], v[88:91]
	v_mfma_f32_16x16x32_bf16 v[76:79], v[156:159], v[212:215], v[76:79]
	v_mfma_f32_16x16x32_bf16 v[72:75], v[164:167], v[212:215], v[72:75]
	v_mfma_f32_16x16x32_bf16 v[116:119], v[168:171], v[184:187], v[116:119]
	v_mfma_f32_16x16x32_bf16 v[112:115], v[176:179], v[184:187], v[112:115]
	v_mfma_f32_16x16x32_bf16 v[100:103], v[168:171], v[192:195], v[100:103]
	v_mfma_f32_16x16x32_bf16 v[96:99], v[176:179], v[192:195], v[96:99]
	v_mfma_f32_16x16x32_bf16 v[84:87], v[168:171], v[200:203], v[84:87]
	v_mfma_f32_16x16x32_bf16 v[80:83], v[176:179], v[200:203], v[80:83]
	v_mfma_f32_16x16x32_bf16 v[68:71], v[168:171], v[208:211], v[68:71]
	v_mfma_f32_16x16x32_bf16 v[64:67], v[176:179], v[208:211], v[64:67]
	v_mfma_f32_16x16x32_bf16 v[116:119], v[172:175], v[188:191], v[116:119]
	v_mfma_f32_16x16x32_bf16 v[112:115], v[180:183], v[188:191], v[112:115]
	v_mfma_f32_16x16x32_bf16 v[100:103], v[172:175], v[196:199], v[100:103]
	v_mfma_f32_16x16x32_bf16 v[96:99], v[180:183], v[196:199], v[96:99]
	v_mfma_f32_16x16x32_bf16 v[84:87], v[172:175], v[204:207], v[84:87]
	v_mfma_f32_16x16x32_bf16 v[80:83], v[180:183], v[204:207], v[80:83]
	v_mfma_f32_16x16x32_bf16 v[68:71], v[172:175], v[212:215], v[68:71]
	v_mfma_f32_16x16x32_bf16 v[64:67], v[180:183], v[212:215], v[64:67]
	s_barrier
; #define PG8_STAGE(bufoff, gbase, voff) do { _Pragma("unroll") for (int _i = 0; _i < 2; ++_i) \
;         __builtin_amdgcn_global_load_lds((const unsigned*)((const char*)(gbase) + (voff)[_i]), (PG8_LAS unsigned*)(lds + (bufoff) + ldsw + _i * 8192), 16, 0, 0); } while (0)
; #define PG8_LDA(dst, b, h) do { _Pragma("unroll") for (int m = 0; m < 4; ++m) _Pragma("unroll") for (int k = 0; k < 2; ++k) dst[m][k] = *(const PG8_LAS bf16x8*)(lds + PG8_SA(b, h) + aoff + m * 2048 + k * 1024); } while (0)
; #define PG8_LDB(dst, b, h) do { _Pragma("unroll") for (int n = 0; n < 2; ++n) _Pragma("unroll") for (int k = 0; k < 2; ++k) dst[n][k] = *(const PG8_LAS bf16x8*)(lds + PG8_SB(b, h) + boff + n * 2048 + k * 1024); } while (0)
; #define PG8_MMA(ai, bj, At, Bt) do { __builtin_amdgcn_s_setprio(1); _Pragma("unroll") for (int m = 0; m < 4; ++m) _Pragma("unroll") for (int n = 0; n < 2; ++n) _Pragma("unroll") for (int k = 0; k < 2; ++k) \
;         acc[ai][bj][m][n] = __builtin_amdgcn_mfma_f32_16x16x32_bf16(Bt[n][k], At[m][k], acc[ai][bj][m][n], 0, 0, 0); __builtin_amdgcn_s_setprio(0); } while (0)
; #define PG8_WAIT_V(n) asm volatile("s_waitcnt vmcnt(" #n ")" ::: "memory")
; #define PG8_BAR __builtin_amdgcn_s_barrier()
; template <class Epi, class Sched, bool ALIGN_EPI = false, bool SP2 = false>
; __device__ __forceinline__ void gemm_phase(PG8_LAS unsigned char* lds, const Gemm g, const Sched& S, const Epi& E) {
;     ...
;         for (int t = 0; t < nt; t += 2) {
;             const bool last = (t == nt - 2);
;             const char* a1 = cA + (size_t)(t + 1) * kstep;
;             const char* a2 = last ? nA : cA + (size_t)(t + 2) * kstep; const char* b2 = last ? nB : cB + (size_t)(t + 2) * kstep;
;             const char* a3 = a2 + kstep; const char* b3 = b2 + kstep;
;             if (last && has_next) S.a_ready(nxt);
;             if constexpr (SP2) {
;             PG8_LDB(B0, 0, 0); PG8_LDB(B1, 0, 1); PG8_SCHED; PG8_LDA(At, 0, 0); PG8_STAGE(PG8_SA(1, 1), a1 + hstep, voffA);
;             PG8_WAIT_V(8); PG8_WAIT_L(0); PG8_BAR; PG8_MMA(0, 0, At, B0); PG8_MMA(0, 1, At, B1); PG8_BAR; PG8_SCHED;
;     ...
;             PG8_LDA(At, 1, 1); PG8_STAGE(PG8_SB(1, 0), b3, voffB); PG8_STAGE(PG8_SB(1, 1), b3 + hstep, voffB); PG8_STAGE(PG8_SA(1, 0), a3, voffA);
;             PG8_WAIT_V(8); PG8_WAIT_L(0); PG8_BAR; PG8_MMA(1, 0, At, B0); PG8_MMA(1, 1, At, B1); PG8_BAR; PG8_SCHED;
	s_add_i32 s34, s64, s16
	v_lshl_add_u64 v[216:217], v[216:217], 0, s[22:23]
	s_mov_b32 m0, s34
	ds_read_b128 v[184:187], v153 offset:49152
	ds_read_b128 v[188:191], v153 offset:50176
	ds_read_b128 v[192:195], v153 offset:51200
	ds_read_b128 v[196:199], v153 offset:52224
	ds_read_b128 v[200:203], v153 offset:53248
	ds_read_b128 v[204:207], v153 offset:54272
	ds_read_b128 v[208:211], v153 offset:55296
	ds_read_b128 v[212:215], v153 offset:56320
	global_load_lds_dwordx4 v[216:217], off
	v_lshl_add_u64 v[216:217], v[218:219], 0, s[22:23]
	s_add_i32 m0, s34, 0x2000
	s_add_i32 s34, s65, s16
	global_load_lds_dwordx4 v[216:217], off
	v_lshl_add_u64 v[216:217], v[220:221], 0, s[22:23]
	s_mov_b32 m0, s34
	s_nop 0
	global_load_lds_dwordx4 v[216:217], off
	v_lshl_add_u64 v[216:217], v[222:223], 0, s[22:23]
	s_add_i32 m0, s34, 0x2000
	s_nop 0
	global_load_lds_dwordx4 v[216:217], off
	v_lshl_add_u64 v[216:217], v[224:225], 0, s[22:23]
	s_mov_b32 m0, s37
	s_nop 0
	global_load_lds_dwordx4 v[216:217], off
	v_lshl_add_u64 v[216:217], v[226:227], 0, s[22:23]
	s_mov_b32 m0, s38
	s_nop 0
	global_load_lds_dwordx4 v[216:217], off
	s_waitcnt vmcnt(8)
	s_waitcnt lgkmcnt(0)
	s_barrier
	s_waitcnt lgkmcnt(0)
	v_mfma_f32_16x16x32_bf16 v[60:63], v[144:147], v[184:187], v[60:63]
	v_mfma_f32_16x16x32_bf16 v[56:59], v[160:163], v[184:187], v[56:59]
	v_mfma_f32_16x16x32_bf16 v[44:47], v[144:147], v[192:195], v[44:47]
	v_mfma_f32_16x16x32_bf16 v[40:43], v[160:163], v[192:195], v[40:43]
	v_mfma_f32_16x16x32_bf16 v[28:31], v[144:147], v[200:203], v[28:31]
	v_mfma_f32_16x16x32_bf16 v[24:27], v[160:163], v[200:203], v[24:27]
	v_mfma_f32_16x16x32_bf16 v[12:15], v[144:147], v[208:211], v[12:15]
	v_mfma_f32_16x16x32_bf16 v[8:11], v[160:163], v[208:211], v[8:11]
	v_mfma_f32_16x16x32_bf16 v[60:63], v[156:159], v[188:191], v[60:63]
	v_mfma_f32_16x16x32_bf16 v[56:59], v[164:167], v[188:191], v[56:59]
	v_mfma_f32_16x16x32_bf16 v[44:47], v[156:159], v[196:199], v[44:47]
	v_mfma_f32_16x16x32_bf16 v[40:43], v[164:167], v[196:199], v[40:43]
	v_mfma_f32_16x16x32_bf16 v[28:31], v[156:159], v[204:207], v[28:31]
	v_mfma_f32_16x16x32_bf16 v[24:27], v[164:167], v[204:207], v[24:27]
	v_mfma_f32_16x16x32_bf16 v[12:15], v[156:159], v[212:215], v[12:15]
	v_mfma_f32_16x16x32_bf16 v[8:11], v[164:167], v[212:215], v[8:11]
	v_mfma_f32_16x16x32_bf16 v[52:55], v[168:171], v[184:187], v[52:55]
	v_mfma_f32_16x16x32_bf16 v[48:51], v[176:179], v[184:187], v[48:51]
	v_mfma_f32_16x16x32_bf16 v[36:39], v[168:171], v[192:195], v[36:39]
	v_mfma_f32_16x16x32_bf16 v[32:35], v[176:179], v[192:195], v[32:35]
	v_mfma_f32_16x16x32_bf16 v[20:23], v[168:171], v[200:203], v[20:23]
	v_mfma_f32_16x16x32_bf16 v[16:19], v[176:179], v[200:203], v[16:19]
	v_mfma_f32_16x16x32_bf16 v[4:7], v[168:171], v[208:211], v[4:7]
	v_mfma_f32_16x16x32_bf16 v[0:3], v[176:179], v[208:211], v[0:3]
	v_mfma_f32_16x16x32_bf16 v[52:55], v[172:175], v[188:191], v[52:55]
	v_mfma_f32_16x16x32_bf16 v[48:51], v[180:183], v[188:191], v[48:51]
	v_mfma_f32_16x16x32_bf16 v[36:39], v[172:175], v[196:199], v[36:39]
	v_mfma_f32_16x16x32_bf16 v[32:35], v[180:183], v[196:199], v[32:35]
	v_mfma_f32_16x16x32_bf16 v[20:23], v[172:175], v[204:207], v[20:23]
	v_mfma_f32_16x16x32_bf16 v[16:19], v[180:183], v[204:207], v[16:19]
	v_mfma_f32_16x16x32_bf16 v[4:7], v[172:175], v[212:215], v[4:7]
	v_mfma_f32_16x16x32_bf16 v[0:3], v[180:183], v[212:215], v[0:3]
	s_barrier
	s_add_u32 s30, s30, 0x100
	s_addc_u32 s31, s31, 0
	s_add_u32 s61, s61, 0x100
	s_addc_u32 s62, s62, 0
	s_cmp_ge_i32 s63, s40
	s_mov_b32 s34, s63
	s_cbranch_scc0 .LBB0_2386
	s_branch .Lpeel_x11
.LBB0_2386:
	ds_read_b128 v[144:147], v151
	ds_read_b128 v[156:159], v151 offset:1024
	ds_read_b128 v[160:163], v151 offset:2048
	ds_read_b128 v[164:167], v151 offset:3072
	ds_read_b128 v[168:171], v152
	ds_read_b128 v[172:175], v152 offset:1024
	ds_read_b128 v[176:179], v152 offset:2048
	ds_read_b128 v[180:183], v152 offset:3072
	s_add_i32 s63, s34, 2
	s_add_u32 s64, s30, 0x80
	s_addc_u32 s35, s31, 0
	s_cmp_eq_u32 s41, s34
	s_cselect_b32 s34, s0, s64
	s_cselect_b32 s35, s1, s35
	s_cselect_b32 s65, s29, s62
	s_cselect_b32 s64, s28, s61
	v_lshl_add_u64 v[216:217], s[30:31], 0, v[136:137]
	s_add_i32 m0, s17, 0xc000
	ds_read_b128 v[184:187], v153
	ds_read_b128 v[188:191], v153 offset:1024
	ds_read_b128 v[192:195], v153 offset:2048
	ds_read_b128 v[196:199], v153 offset:3072
	ds_read_b128 v[200:203], v153 offset:4096
	ds_read_b128 v[204:207], v153 offset:5120
	ds_read_b128 v[208:211], v153 offset:6144
	ds_read_b128 v[212:215], v153 offset:7168
	global_load_lds_dwordx4 v[216:217], off
	v_lshl_add_u64 v[216:217], s[30:31], 0, v[138:139]
	s_add_i32 m0, s17, 0xe000
	s_nop 0
	global_load_lds_dwordx4 v[216:217], off
	s_waitcnt vmcnt(8)
	s_waitcnt lgkmcnt(0)
	s_barrier
; #define PG8_STAGE(bufoff, gbase, voff) do { _Pragma("unroll") for (int _i = 0; _i < 2; ++_i) \
;         __builtin_amdgcn_global_load_lds((const unsigned*)((const char*)(gbase) + (voff)[_i]), (PG8_LAS unsigned*)(lds + (bufoff) + ldsw + _i * 8192), 16, 0, 0); } while (0)
; #define PG8_LDA(dst, b, h) do { _Pragma("unroll") for (int m = 0; m < 4; ++m) _Pragma("unroll") for (int k = 0; k < 2; ++k) dst[m][k] = *(const PG8_LAS bf16x8*)(lds + PG8_SA(b, h) + aoff + m * 2048 + k * 1024); } while (0)
; #define PG8_MMA(ai, bj, At, Bt) do { __builtin_amdgcn_s_setprio(1); _Pragma("unroll") for (int m = 0; m < 4; ++m) _Pragma("unroll") for (int n = 0; n < 2; ++n) _Pragma("unroll") for (int k = 0; k < 2; ++k) \
;         acc[ai][bj][m][n] = __builtin_amdgcn_mfma_f32_16x16x32_bf16(Bt[n][k], At[m][k], acc[ai][bj][m][n], 0, 0, 0); __builtin_amdgcn_s_setprio(0); } while (0)
; #define PG8_WAIT_V(n) asm volatile("s_waitcnt vmcnt(" #n ")" ::: "memory")
; #define PG8_WAIT_L(n) asm volatile("s_waitcnt lgkmcnt(" #n ")" ::: "memory")
; #define PG8_BAR __builtin_amdgcn_s_barrier()
; #define PG8_SCHED __builtin_amdgcn_sched_barrier(0)
; template <class Epi, class Sched, bool ALIGN_EPI = false, bool SP2 = false>
; __device__ __forceinline__ void gemm_phase(PG8_LAS unsigned char* lds, const Gemm g, const Sched& S, const Epi& E) {
;     ...
;             PG8_WAIT_V(8); PG8_WAIT_L(0); PG8_BAR; PG8_MMA(0, 0, At, B0); PG8_MMA(0, 1, At, B1); PG8_BAR; PG8_SCHED;
;             PG8_LDA(At, 0, 1); PG8_STAGE(PG8_SB(0, 0), b2, voffB); PG8_STAGE(PG8_SB(0, 1), b2 + hstep, voffB); PG8_STAGE(PG8_SA(0, 0), a2, voffA);
;             PG8_WAIT_V(8); PG8_WAIT_L(0); PG8_BAR; PG8_MMA(1, 0, At, B0); PG8_MMA(1, 1, At, B1); PG8_BAR; PG8_SCHED;
	s_waitcnt lgkmcnt(0)
	v_mfma_f32_16x16x32_bf16 v[124:127], v[144:147], v[184:187], v[124:127]
	v_mfma_f32_16x16x32_bf16 v[120:123], v[160:163], v[184:187], v[120:123]
	v_mfma_f32_16x16x32_bf16 v[108:111], v[144:147], v[192:195], v[108:111]
	v_mfma_f32_16x16x32_bf16 v[104:107], v[160:163], v[192:195], v[104:107]
	v_mfma_f32_16x16x32_bf16 v[92:95], v[144:147], v[200:203], v[92:95]
	v_mfma_f32_16x16x32_bf16 v[88:91], v[160:163], v[200:203], v[88:91]
	v_mfma_f32_16x16x32_bf16 v[76:79], v[144:147], v[208:211], v[76:79]
	v_mfma_f32_16x16x32_bf16 v[72:75], v[160:163], v[208:211], v[72:75]
	v_mfma_f32_16x16x32_bf16 v[124:127], v[156:159], v[188:191], v[124:127]
	v_mfma_f32_16x16x32_bf16 v[120:123], v[164:167], v[188:191], v[120:123]
	v_mfma_f32_16x16x32_bf16 v[108:111], v[156:159], v[196:199], v[108:111]
	v_mfma_f32_16x16x32_bf16 v[104:107], v[164:167], v[196:199], v[104:107]
	v_mfma_f32_16x16x32_bf16 v[92:95], v[156:159], v[204:207], v[92:95]
	v_mfma_f32_16x16x32_bf16 v[88:91], v[164:167], v[204:207], v[88:91]
	v_mfma_f32_16x16x32_bf16 v[76:79], v[156:159], v[212:215], v[76:79]
	v_mfma_f32_16x16x32_bf16 v[72:75], v[164:167], v[212:215], v[72:75]
	v_mfma_f32_16x16x32_bf16 v[116:119], v[168:171], v[184:187], v[116:119]
	v_mfma_f32_16x16x32_bf16 v[112:115], v[176:179], v[184:187], v[112:115]
	v_mfma_f32_16x16x32_bf16 v[100:103], v[168:171], v[192:195], v[100:103]
	v_mfma_f32_16x16x32_bf16 v[96:99], v[176:179], v[192:195], v[96:99]
	v_mfma_f32_16x16x32_bf16 v[84:87], v[168:171], v[200:203], v[84:87]
	v_mfma_f32_16x16x32_bf16 v[80:83], v[176:179], v[200:203], v[80:83]
	v_mfma_f32_16x16x32_bf16 v[68:71], v[168:171], v[208:211], v[68:71]
	v_mfma_f32_16x16x32_bf16 v[64:67], v[176:179], v[208:211], v[64:67]
	v_mfma_f32_16x16x32_bf16 v[116:119], v[172:175], v[188:191], v[116:119]
	v_mfma_f32_16x16x32_bf16 v[112:115], v[180:183], v[188:191], v[112:115]
	v_mfma_f32_16x16x32_bf16 v[100:103], v[172:175], v[196:199], v[100:103]
	v_mfma_f32_16x16x32_bf16 v[96:99], v[180:183], v[196:199], v[96:99]
	v_mfma_f32_16x16x32_bf16 v[84:87], v[172:175], v[204:207], v[84:87]
	v_mfma_f32_16x16x32_bf16 v[80:83], v[180:183], v[204:207], v[80:83]
	v_mfma_f32_16x16x32_bf16 v[68:71], v[172:175], v[212:215], v[68:71]
	v_mfma_f32_16x16x32_bf16 v[64:67], v[180:183], v[212:215], v[64:67]
	s_barrier
	s_add_i32 s66, s51, s16
	v_lshl_add_u64 v[216:217], s[64:65], 0, v[130:131]
	s_mov_b32 m0, s66
	ds_read_b128 v[184:187], v153 offset:16384
	ds_read_b128 v[188:191], v153 offset:17408
	ds_read_b128 v[192:195], v153 offset:18432
	ds_read_b128 v[196:199], v153 offset:19456
	ds_read_b128 v[200:203], v153 offset:20480
	ds_read_b128 v[204:207], v153 offset:21504
	ds_read_b128 v[208:211], v153 offset:22528
	ds_read_b128 v[212:215], v153 offset:23552
	global_load_lds_dwordx4 v[216:217], off
	s_add_i32 m0, s66, 0x2000
	v_lshl_add_u64 v[218:219], s[64:65], 0, v[134:135]
	s_add_u32 s64, s64, s6
	s_addc_u32 s65, s65, s7
	s_add_i32 s66, s56, s16
	global_load_lds_dwordx4 v[218:219], off
	v_lshl_add_u64 v[220:221], s[64:65], 0, v[130:131]
	s_mov_b32 m0, s66
	v_lshl_add_u64 v[222:223], s[64:65], 0, v[134:135]
	global_load_lds_dwordx4 v[220:221], off
	s_add_i32 m0, s66, 0x2000
	v_lshl_add_u64 v[224:225], s[34:35], 0, v[128:129]
	global_load_lds_dwordx4 v[222:223], off
	s_mov_b32 m0, s17
	v_lshl_add_u64 v[226:227], s[34:35], 0, v[132:133]
	global_load_lds_dwordx4 v[224:225], off
	s_mov_b32 m0, s19
	s_nop 0
	global_load_lds_dwordx4 v[226:227], off
	s_waitcnt vmcnt(8)
	s_waitcnt lgkmcnt(0)
	s_barrier
	s_waitcnt lgkmcnt(0)
	v_mfma_f32_16x16x32_bf16 v[60:63], v[144:147], v[184:187], v[60:63]
	v_mfma_f32_16x16x32_bf16 v[56:59], v[160:163], v[184:187], v[56:59]
	v_mfma_f32_16x16x32_bf16 v[44:47], v[144:147], v[192:195], v[44:47]
	v_mfma_f32_16x16x32_bf16 v[40:43], v[160:163], v[192:195], v[40:43]
	v_mfma_f32_16x16x32_bf16 v[28:31], v[144:147], v[200:203], v[28:31]
	v_mfma_f32_16x16x32_bf16 v[24:27], v[160:163], v[200:203], v[24:27]
	v_mfma_f32_16x16x32_bf16 v[12:15], v[144:147], v[208:211], v[12:15]
	v_mfma_f32_16x16x32_bf16 v[8:11], v[160:163], v[208:211], v[8:11]
	v_mfma_f32_16x16x32_bf16 v[60:63], v[156:159], v[188:191], v[60:63]
	v_mfma_f32_16x16x32_bf16 v[56:59], v[164:167], v[188:191], v[56:59]
	v_mfma_f32_16x16x32_bf16 v[44:47], v[156:159], v[196:199], v[44:47]
	v_mfma_f32_16x16x32_bf16 v[40:43], v[164:167], v[196:199], v[40:43]
	v_mfma_f32_16x16x32_bf16 v[28:31], v[156:159], v[204:207], v[28:31]
	v_mfma_f32_16x16x32_bf16 v[24:27], v[164:167], v[204:207], v[24:27]
	v_mfma_f32_16x16x32_bf16 v[12:15], v[156:159], v[212:215], v[12:15]
	v_mfma_f32_16x16x32_bf16 v[8:11], v[164:167], v[212:215], v[8:11]
	v_mfma_f32_16x16x32_bf16 v[52:55], v[168:171], v[184:187], v[52:55]
	v_mfma_f32_16x16x32_bf16 v[48:51], v[176:179], v[184:187], v[48:51]
	v_mfma_f32_16x16x32_bf16 v[36:39], v[168:171], v[192:195], v[36:39]
	v_mfma_f32_16x16x32_bf16 v[32:35], v[176:179], v[192:195], v[32:35]
	v_mfma_f32_16x16x32_bf16 v[20:23], v[168:171], v[200:203], v[20:23]
	v_mfma_f32_16x16x32_bf16 v[16:19], v[176:179], v[200:203], v[16:19]
	v_mfma_f32_16x16x32_bf16 v[4:7], v[168:171], v[208:211], v[4:7]
	v_mfma_f32_16x16x32_bf16 v[0:3], v[176:179], v[208:211], v[0:3]
	v_mfma_f32_16x16x32_bf16 v[52:55], v[172:175], v[188:191], v[52:55]
	v_mfma_f32_16x16x32_bf16 v[48:51], v[180:183], v[188:191], v[48:51]
	v_mfma_f32_16x16x32_bf16 v[36:39], v[172:175], v[196:199], v[36:39]
	v_mfma_f32_16x16x32_bf16 v[32:35], v[180:183], v[196:199], v[32:35]
	v_mfma_f32_16x16x32_bf16 v[20:23], v[172:175], v[204:207], v[20:23]
	v_mfma_f32_16x16x32_bf16 v[16:19], v[180:183], v[204:207], v[16:19]
	v_mfma_f32_16x16x32_bf16 v[4:7], v[172:175], v[212:215], v[4:7]
	v_mfma_f32_16x16x32_bf16 v[0:3], v[180:183], v[212:215], v[0:3]
	s_barrier
; #define PG8_STAGE(bufoff, gbase, voff) do { _Pragma("unroll") for (int _i = 0; _i < 2; ++_i) \
;         __builtin_amdgcn_global_load_lds((const unsigned*)((const char*)(gbase) + (voff)[_i]), (PG8_LAS unsigned*)(lds + (bufoff) + ldsw + _i * 8192), 16, 0, 0); } while (0)
; #define PG8_LDA(dst, b, h) do { _Pragma("unroll") for (int m = 0; m < 4; ++m) _Pragma("unroll") for (int k = 0; k < 2; ++k) dst[m][k] = *(const PG8_LAS bf16x8*)(lds + PG8_SA(b, h) + aoff + m * 2048 + k * 1024); } while (0)
; #define PG8_LDB(dst, b, h) do { _Pragma("unroll") for (int n = 0; n < 2; ++n) _Pragma("unroll") for (int k = 0; k < 2; ++k) dst[n][k] = *(const PG8_LAS bf16x8*)(lds + PG8_SB(b, h) + boff + n * 2048 + k * 1024); } while (0)
; #define PG8_MMA(ai, bj, At, Bt) do { __builtin_amdgcn_s_setprio(1); _Pragma("unroll") for (int m = 0; m < 4; ++m) _Pragma("unroll") for (int n = 0; n < 2; ++n) _Pragma("unroll") for (int k = 0; k < 2; ++k) \
;         acc[ai][bj][m][n] = __builtin_amdgcn_mfma_f32_16x16x32_bf16(Bt[n][k], At[m][k], acc[ai][bj][m][n], 0, 0, 0); __builtin_amdgcn_s_setprio(0); } while (0)
; #define PG8_WAIT_V(n) asm volatile("s_waitcnt vmcnt(" #n ")" ::: "memory")
; #define PG8_WAIT_L(n) asm volatile("s_waitcnt lgkmcnt(" #n ")" ::: "memory")
; #define PG8_BAR __builtin_amdgcn_s_barrier()
; #define PG8_SCHED __builtin_amdgcn_sched_barrier(0)
; template <class Epi, class Sched, bool ALIGN_EPI = false, bool SP2 = false>
; __device__ __forceinline__ void gemm_phase(PG8_LAS unsigned char* lds, const Gemm g, const Sched& S, const Epi& E) {
;     ...
;             PG8_LDB(B0, 1, 0); PG8_LDB(B1, 1, 1); PG8_SCHED; PG8_LDA(At, 1, 0); PG8_STAGE(PG8_SA(0, 1), a2 + hstep, voffA);
;             PG8_WAIT_V(8); PG8_WAIT_L(0); PG8_BAR; PG8_MMA(0, 0, At, B0); PG8_MMA(0, 1, At, B1); PG8_BAR; PG8_SCHED;
;             PG8_LDA(At, 1, 1); PG8_STAGE(PG8_SB(1, 0), b3, voffB); PG8_STAGE(PG8_SB(1, 1), b3 + hstep, voffB); PG8_STAGE(PG8_SA(1, 0), a3, voffA);
;             PG8_WAIT_V(8); PG8_WAIT_L(0); PG8_BAR; PG8_MMA(1, 0, At, B0); PG8_MMA(1, 1, At, B1); PG8_BAR; PG8_SCHED;
	s_add_i32 s64, 0, 0x18000
	v_add_u32_e32 v155, s64, v149
	s_add_i32 s65, 0, 0x1c000
	ds_read_b128 v[144:147], v155
	ds_read_b128 v[156:159], v155 offset:1024
	ds_read_b128 v[160:163], v155 offset:2048
	ds_read_b128 v[164:167], v155 offset:3072
	v_add_u32_e32 v155, s65, v149
	ds_read_b128 v[168:171], v155
	ds_read_b128 v[172:175], v155 offset:1024
	ds_read_b128 v[176:179], v155 offset:2048
	ds_read_b128 v[180:183], v155 offset:3072
	s_add_u32 s34, s34, s6
	s_addc_u32 s35, s35, s7
	s_mov_b32 m0, s33
	v_lshl_add_u64 v[228:229], s[34:35], 0, v[128:129]
	ds_read_b128 v[184:187], v153 offset:32768
	ds_read_b128 v[188:191], v153 offset:33792
	ds_read_b128 v[192:195], v153 offset:34816
	ds_read_b128 v[196:199], v153 offset:35840
	ds_read_b128 v[200:203], v153 offset:36864
	ds_read_b128 v[204:207], v153 offset:37888
	ds_read_b128 v[208:211], v153 offset:38912
	ds_read_b128 v[212:215], v153 offset:39936
	global_load_lds_dwordx4 v[228:229], off
	v_lshl_add_u64 v[228:229], s[34:35], 0, v[132:133]
	s_mov_b32 m0, s36
	s_nop 0
	global_load_lds_dwordx4 v[228:229], off
	s_waitcnt vmcnt(8)
	s_waitcnt lgkmcnt(0)
	s_barrier
	s_waitcnt lgkmcnt(0)
	v_mfma_f32_16x16x32_bf16 v[124:127], v[144:147], v[184:187], v[124:127]
	v_mfma_f32_16x16x32_bf16 v[120:123], v[160:163], v[184:187], v[120:123]
	v_mfma_f32_16x16x32_bf16 v[108:111], v[144:147], v[192:195], v[108:111]
	v_mfma_f32_16x16x32_bf16 v[104:107], v[160:163], v[192:195], v[104:107]
	v_mfma_f32_16x16x32_bf16 v[92:95], v[144:147], v[200:203], v[92:95]
	v_mfma_f32_16x16x32_bf16 v[88:91], v[160:163], v[200:203], v[88:91]
	v_mfma_f32_16x16x32_bf16 v[76:79], v[144:147], v[208:211], v[76:79]
	v_mfma_f32_16x16x32_bf16 v[72:75], v[160:163], v[208:211], v[72:75]
	v_mfma_f32_16x16x32_bf16 v[124:127], v[156:159], v[188:191], v[124:127]
	v_mfma_f32_16x16x32_bf16 v[120:123], v[164:167], v[188:191], v[120:123]
	v_mfma_f32_16x16x32_bf16 v[108:111], v[156:159], v[196:199], v[108:111]
	v_mfma_f32_16x16x32_bf16 v[104:107], v[164:167], v[196:199], v[104:107]
	v_mfma_f32_16x16x32_bf16 v[92:95], v[156:159], v[204:207], v[92:95]
	v_mfma_f32_16x16x32_bf16 v[88:91], v[164:167], v[204:207], v[88:91]
	v_mfma_f32_16x16x32_bf16 v[76:79], v[156:159], v[212:215], v[76:79]
	v_mfma_f32_16x16x32_bf16 v[72:75], v[164:167], v[212:215], v[72:75]
	v_mfma_f32_16x16x32_bf16 v[116:119], v[168:171], v[184:187], v[116:119]
	v_mfma_f32_16x16x32_bf16 v[112:115], v[176:179], v[184:187], v[112:115]
	v_mfma_f32_16x16x32_bf16 v[100:103], v[168:171], v[192:195], v[100:103]
	v_mfma_f32_16x16x32_bf16 v[96:99], v[176:179], v[192:195], v[96:99]
	v_mfma_f32_16x16x32_bf16 v[84:87], v[168:171], v[200:203], v[84:87]
	v_mfma_f32_16x16x32_bf16 v[80:83], v[176:179], v[200:203], v[80:83]
	v_mfma_f32_16x16x32_bf16 v[68:71], v[168:171], v[208:211], v[68:71]
	v_mfma_f32_16x16x32_bf16 v[64:67], v[176:179], v[208:211], v[64:67]
	v_mfma_f32_16x16x32_bf16 v[116:119], v[172:175], v[188:191], v[116:119]
	v_mfma_f32_16x16x32_bf16 v[112:115], v[180:183], v[188:191], v[112:115]
	v_mfma_f32_16x16x32_bf16 v[100:103], v[172:175], v[196:199], v[100:103]
	v_mfma_f32_16x16x32_bf16 v[96:99], v[180:183], v[196:199], v[96:99]
	v_mfma_f32_16x16x32_bf16 v[84:87], v[172:175], v[204:207], v[84:87]
	v_mfma_f32_16x16x32_bf16 v[80:83], v[180:183], v[204:207], v[80:83]
	v_mfma_f32_16x16x32_bf16 v[68:71], v[172:175], v[212:215], v[68:71]
	v_mfma_f32_16x16x32_bf16 v[64:67], v[180:183], v[212:215], v[64:67]
	s_barrier
	s_add_i32 s34, s64, s16
	v_lshl_add_u64 v[216:217], v[216:217], 0, s[22:23]
	s_mov_b32 m0, s34
	ds_read_b128 v[184:187], v153 offset:49152
	ds_read_b128 v[188:191], v153 offset:50176
	ds_read_b128 v[192:195], v153 offset:51200
	ds_read_b128 v[196:199], v153 offset:52224
	ds_read_b128 v[200:203], v153 offset:53248
	ds_read_b128 v[204:207], v153 offset:54272
	ds_read_b128 v[208:211], v153 offset:55296
	ds_read_b128 v[212:215], v153 offset:56320
	global_load_lds_dwordx4 v[216:217], off
	v_lshl_add_u64 v[216:217], v[218:219], 0, s[22:23]
	s_add_i32 m0, s34, 0x2000
	s_add_i32 s34, s65, s16
	global_load_lds_dwordx4 v[216:217], off
	v_lshl_add_u64 v[216:217], v[220:221], 0, s[22:23]
	s_mov_b32 m0, s34
	s_nop 0
	global_load_lds_dwordx4 v[216:217], off
	v_lshl_add_u64 v[216:217], v[222:223], 0, s[22:23]
	s_add_i32 m0, s34, 0x2000
	s_nop 0
	global_load_lds_dwordx4 v[216:217], off
	v_lshl_add_u64 v[216:217], v[224:225], 0, s[22:23]
	s_mov_b32 m0, s37
	s_nop 0
	global_load_lds_dwordx4 v[216:217], off
	v_lshl_add_u64 v[216:217], v[226:227], 0, s[22:23]
	s_mov_b32 m0, s38
	s_nop 0
	global_load_lds_dwordx4 v[216:217], off
	s_waitcnt vmcnt(8)
	s_waitcnt lgkmcnt(0)
	s_barrier
	s_waitcnt lgkmcnt(0)
	v_mfma_f32_16x16x32_bf16 v[60:63], v[144:147], v[184:187], v[60:63]
	v_mfma_f32_16x16x32_bf16 v[56:59], v[160:163], v[184:187], v[56:59]
	v_mfma_f32_16x16x32_bf16 v[44:47], v[144:147], v[192:195], v[44:47]
	v_mfma_f32_16x16x32_bf16 v[40:43], v[160:163], v[192:195], v[40:43]
	v_mfma_f32_16x16x32_bf16 v[28:31], v[144:147], v[200:203], v[28:31]
	v_mfma_f32_16x16x32_bf16 v[24:27], v[160:163], v[200:203], v[24:27]
	v_mfma_f32_16x16x32_bf16 v[12:15], v[144:147], v[208:211], v[12:15]
	v_mfma_f32_16x16x32_bf16 v[8:11], v[160:163], v[208:211], v[8:11]
	v_mfma_f32_16x16x32_bf16 v[60:63], v[156:159], v[188:191], v[60:63]
	v_mfma_f32_16x16x32_bf16 v[56:59], v[164:167], v[188:191], v[56:59]
	v_mfma_f32_16x16x32_bf16 v[44:47], v[156:159], v[196:199], v[44:47]
	v_mfma_f32_16x16x32_bf16 v[40:43], v[164:167], v[196:199], v[40:43]
	v_mfma_f32_16x16x32_bf16 v[28:31], v[156:159], v[204:207], v[28:31]
	v_mfma_f32_16x16x32_bf16 v[24:27], v[164:167], v[204:207], v[24:27]
	v_mfma_f32_16x16x32_bf16 v[12:15], v[156:159], v[212:215], v[12:15]
	v_mfma_f32_16x16x32_bf16 v[8:11], v[164:167], v[212:215], v[8:11]
	v_mfma_f32_16x16x32_bf16 v[52:55], v[168:171], v[184:187], v[52:55]
	v_mfma_f32_16x16x32_bf16 v[48:51], v[176:179], v[184:187], v[48:51]
	v_mfma_f32_16x16x32_bf16 v[36:39], v[168:171], v[192:195], v[36:39]
	v_mfma_f32_16x16x32_bf16 v[32:35], v[176:179], v[192:195], v[32:35]
	v_mfma_f32_16x16x32_bf16 v[20:23], v[168:171], v[200:203], v[20:23]
	v_mfma_f32_16x16x32_bf16 v[16:19], v[176:179], v[200:203], v[16:19]
	v_mfma_f32_16x16x32_bf16 v[4:7], v[168:171], v[208:211], v[4:7]
	v_mfma_f32_16x16x32_bf16 v[0:3], v[176:179], v[208:211], v[0:3]
	v_mfma_f32_16x16x32_bf16 v[52:55], v[172:175], v[188:191], v[52:55]
	v_mfma_f32_16x16x32_bf16 v[48:51], v[180:183], v[188:191], v[48:51]
	v_mfma_f32_16x16x32_bf16 v[36:39], v[172:175], v[196:199], v[36:39]
	v_mfma_f32_16x16x32_bf16 v[32:35], v[180:183], v[196:199], v[32:35]
	v_mfma_f32_16x16x32_bf16 v[20:23], v[172:175], v[204:207], v[20:23]
	v_mfma_f32_16x16x32_bf16 v[16:19], v[180:183], v[204:207], v[16:19]
	v_mfma_f32_16x16x32_bf16 v[4:7], v[172:175], v[212:215], v[4:7]
	v_mfma_f32_16x16x32_bf16 v[0:3], v[180:183], v[212:215], v[0:3]
	s_barrier
	s_add_u32 s30, s30, 0x100
	s_addc_u32 s31, s31, 0
	s_add_u32 s61, s61, 0x100
	s_addc_u32 s62, s62, 0
	s_cmp_ge_i32 s63, s40
	s_mov_b32 s34, s63
	s_cbranch_scc0 .LBB0_2386

; #define PG8_STAGE(bufoff, gbase, voff) do { _Pragma("unroll") for (int _i = 0; _i < 2; ++_i) \
;         __builtin_amdgcn_global_load_lds((const unsigned*)((const char*)(gbase) + (voff)[_i]), (PG8_LAS unsigned*)(lds + (bufoff) + ldsw + _i * 8192), 16, 0, 0); } while (0)
; #define PG8_LDA(dst, b, h) do { _Pragma("unroll") for (int m = 0; m < 4; ++m) _Pragma("unroll") for (int k = 0; k < 2; ++k) dst[m][k] = *(const PG8_LAS bf16x8*)(lds + PG8_SA(b, h) + aoff + m * 2048 + k * 1024); } while (0)
; #define PG8_LDB(dst, b, h) do { _Pragma("unroll") for (int n = 0; n < 2; ++n) _Pragma("unroll") for (int k = 0; k < 2; ++k) dst[n][k] = *(const PG8_LAS bf16x8*)(lds + PG8_SB(b, h) + boff + n * 2048 + k * 1024); } while (0)
; #define PG8_WAIT_V(n) asm volatile("s_waitcnt vmcnt(" #n ")" ::: "memory")
; #define PG8_WAIT_L(n) asm volatile("s_waitcnt lgkmcnt(" #n ")" ::: "memory")
; template <class Epi, class Sched, bool ALIGN_EPI = false, bool SP2 = false>
; __device__ __forceinline__ void gemm_phase(PG8_LAS unsigned char* lds, const Gemm g, const Sched& S, const Epi& E) {
;     ...
;         for (int t = 0; t < nt; t += 2) {
;             const bool last = (t == nt - 2);
;             const char* a1 = cA + (size_t)(t + 1) * kstep;
;             const char* a2 = last ? nA : cA + (size_t)(t + 2) * kstep; const char* b2 = last ? nB : cB + (size_t)(t + 2) * kstep;
;             const char* a3 = a2 + kstep; const char* b3 = b2 + kstep;
;             if (last && has_next) S.a_ready(nxt);
;             if constexpr (SP2) {
;             PG8_LDB(B0, 0, 0); PG8_LDB(B1, 0, 1); PG8_SCHED; PG8_LDA(At, 0, 0); PG8_STAGE(PG8_SA(1, 1), a1 + hstep, voffA);
;             PG8_WAIT_V(8); PG8_WAIT_L(0); PG8_BAR; PG8_MMA(0, 0, At, B0); PG8_MMA(0, 1, At, B1); PG8_BAR; PG8_SCHED;
;             PG8_LDA(At, 0, 1); PG8_STAGE(PG8_SB(0, 0), b2, voffB); PG8_STAGE(PG8_SB(0, 1), b2 + hstep, voffB); PG8_STAGE(PG8_SA(0, 0), a2, voffA);
;             PG8_WAIT_V(8); PG8_WAIT_L(0); PG8_BAR; PG8_MMA(1, 0, At, B0); PG8_MMA(1, 1, At, B1); PG8_BAR; PG8_SCHED;
;     ...
; #pragma unroll
;         for (int a = 0; a < 2; ++a)
; #pragma unroll
;             for (int b = 0; b < 2; ++b)
; #pragma unroll
;                 for (int m = 0; m < 4; ++m)
; #pragma unroll
;                     for (int n = 0; n < 2; ++n) acc[a][b][m][n] = (f32x4){0.f, 0.f, 0.f, 0.f};
;         cur = nxt; cA = nA; cB = nB; ++ui;
.LBB0_2479:
	s_andn2_b64 vcc, exec, s[20:21]
	s_waitcnt vmcnt(0)
	s_cbranch_vccnz .LBB0_2482
	s_add_u32 s26, s26, 0x80
	s_addc_u32 s27, s27, 0
	s_add_u32 s60, s28, 0x100
	s_addc_u32 s61, s29, 0
	s_mov_b32 s28, 0
	ds_read_b128 v[154:157], v149
	ds_read_b128 v[158:161], v149 offset:1024
	ds_read_b128 v[162:165], v149 offset:2048
	ds_read_b128 v[166:169], v149 offset:3072
	ds_read_b128 v[170:173], v150
	ds_read_b128 v[174:177], v150 offset:1024
	ds_read_b128 v[178:181], v150 offset:2048
	ds_read_b128 v[182:185], v150 offset:3072
	s_add_i32 s62, s28, 2
	s_add_u32 s63, s26, 0x80
	s_addc_u32 s29, s27, 0
	s_cmp_eq_u32 s39, s28
	s_cselect_b32 s28, s0, s63
	s_cselect_b32 s29, s1, s29
	s_cselect_b32 s65, s25, s61
	s_cselect_b32 s64, s24, s60
	v_lshl_add_u64 v[144:145], s[26:27], 0, v[136:137]
	s_add_i32 m0, s30, 0xc000
	ds_read_b128 v[186:189], v151
	ds_read_b128 v[190:193], v151 offset:1024
	ds_read_b128 v[194:197], v151 offset:2048
	ds_read_b128 v[198:201], v151 offset:3072
	ds_read_b128 v[202:205], v151 offset:4096
	ds_read_b128 v[206:209], v151 offset:5120
	ds_read_b128 v[210:213], v151 offset:6144
	ds_read_b128 v[214:217], v151 offset:7168
	global_load_lds_dwordx4 v[144:145], off
	v_lshl_add_u64 v[144:145], s[26:27], 0, v[138:139]
	s_add_i32 m0, s30, 0xe000
	s_nop 0
	global_load_lds_dwordx4 v[144:145], off
	s_waitcnt vmcnt(8)
	s_waitcnt lgkmcnt(0)
	s_barrier
	s_waitcnt lgkmcnt(0)
	v_mfma_f32_16x16x32_bf16 v[116:119], v[154:157], v[186:189], 0
	v_mfma_f32_16x16x32_bf16 v[112:115], v[162:165], v[186:189], 0
	v_mfma_f32_16x16x32_bf16 v[100:103], v[154:157], v[194:197], 0
	v_mfma_f32_16x16x32_bf16 v[96:99], v[162:165], v[194:197], 0
	v_mfma_f32_16x16x32_bf16 v[84:87], v[154:157], v[202:205], 0
	v_mfma_f32_16x16x32_bf16 v[80:83], v[162:165], v[202:205], 0
	v_mfma_f32_16x16x32_bf16 v[68:71], v[154:157], v[210:213], 0
	v_mfma_f32_16x16x32_bf16 v[64:67], v[162:165], v[210:213], 0
	v_mfma_f32_16x16x32_bf16 v[116:119], v[158:161], v[190:193], v[116:119]
	v_mfma_f32_16x16x32_bf16 v[112:115], v[166:169], v[190:193], v[112:115]
	v_mfma_f32_16x16x32_bf16 v[100:103], v[158:161], v[198:201], v[100:103]
	v_mfma_f32_16x16x32_bf16 v[96:99], v[166:169], v[198:201], v[96:99]
	v_mfma_f32_16x16x32_bf16 v[84:87], v[158:161], v[206:209], v[84:87]
	v_mfma_f32_16x16x32_bf16 v[80:83], v[166:169], v[206:209], v[80:83]
	v_mfma_f32_16x16x32_bf16 v[68:71], v[158:161], v[214:217], v[68:71]
	v_mfma_f32_16x16x32_bf16 v[64:67], v[166:169], v[214:217], v[64:67]
	v_mfma_f32_16x16x32_bf16 v[124:127], v[170:173], v[186:189], 0
	v_mfma_f32_16x16x32_bf16 v[120:123], v[178:181], v[186:189], 0
	v_mfma_f32_16x16x32_bf16 v[108:111], v[170:173], v[194:197], 0
	v_mfma_f32_16x16x32_bf16 v[104:107], v[178:181], v[194:197], 0
	v_mfma_f32_16x16x32_bf16 v[92:95], v[170:173], v[202:205], 0
	v_mfma_f32_16x16x32_bf16 v[88:91], v[178:181], v[202:205], 0
	v_mfma_f32_16x16x32_bf16 v[76:79], v[170:173], v[210:213], 0
	v_mfma_f32_16x16x32_bf16 v[72:75], v[178:181], v[210:213], 0
	v_mfma_f32_16x16x32_bf16 v[124:127], v[174:177], v[190:193], v[124:127]
	v_mfma_f32_16x16x32_bf16 v[120:123], v[182:185], v[190:193], v[120:123]
	v_mfma_f32_16x16x32_bf16 v[108:111], v[174:177], v[198:201], v[108:111]
	v_mfma_f32_16x16x32_bf16 v[104:107], v[182:185], v[198:201], v[104:107]
	v_mfma_f32_16x16x32_bf16 v[92:95], v[174:177], v[206:209], v[92:95]
	v_mfma_f32_16x16x32_bf16 v[88:91], v[182:185], v[206:209], v[88:91]
	v_mfma_f32_16x16x32_bf16 v[76:79], v[174:177], v[214:217], v[76:79]
	v_mfma_f32_16x16x32_bf16 v[72:75], v[182:185], v[214:217], v[72:75]
	s_barrier
	s_add_i32 s63, s44, s16
	v_lshl_add_u64 v[144:145], s[64:65], 0, v[132:133]
	s_mov_b32 m0, s63
	ds_read_b128 v[186:189], v151 offset:16384
	ds_read_b128 v[190:193], v151 offset:17408
	ds_read_b128 v[194:197], v151 offset:18432
	ds_read_b128 v[198:201], v151 offset:19456
	ds_read_b128 v[202:205], v151 offset:20480
	ds_read_b128 v[206:209], v151 offset:21504
	ds_read_b128 v[210:213], v151 offset:22528
	ds_read_b128 v[214:217], v151 offset:23552
	global_load_lds_dwordx4 v[144:145], off
	s_add_i32 m0, s63, 0x2000
	v_lshl_add_u64 v[218:219], s[64:65], 0, v[128:129]
	s_add_u32 s64, s64, s8
	s_addc_u32 s65, s65, s9
	s_add_i32 s63, s45, s16
	global_load_lds_dwordx4 v[218:219], off
	v_lshl_add_u64 v[220:221], s[64:65], 0, v[132:133]
	s_mov_b32 m0, s63
	v_lshl_add_u64 v[222:223], s[64:65], 0, v[128:129]
	global_load_lds_dwordx4 v[220:221], off
	s_add_i32 m0, s63, 0x2000
	v_lshl_add_u64 v[224:225], s[28:29], 0, v[134:135]
	global_load_lds_dwordx4 v[222:223], off
	s_mov_b32 m0, s30
	v_lshl_add_u64 v[226:227], s[28:29], 0, v[130:131]
	global_load_lds_dwordx4 v[224:225], off
	s_mov_b32 m0, s31
	s_nop 0
	global_load_lds_dwordx4 v[226:227], off
	s_waitcnt vmcnt(8)
	s_waitcnt lgkmcnt(0)
	s_barrier
; #define PG8_STAGE(bufoff, gbase, voff) do { _Pragma("unroll") for (int _i = 0; _i < 2; ++_i) \
;         __builtin_amdgcn_global_load_lds((const unsigned*)((const char*)(gbase) + (voff)[_i]), (PG8_LAS unsigned*)(lds + (bufoff) + ldsw + _i * 8192), 16, 0, 0); } while (0)
; #define PG8_LDA(dst, b, h) do { _Pragma("unroll") for (int m = 0; m < 4; ++m) _Pragma("unroll") for (int k = 0; k < 2; ++k) dst[m][k] = *(const PG8_LAS bf16x8*)(lds + PG8_SA(b, h) + aoff + m * 2048 + k * 1024); } while (0)
; #define PG8_LDB(dst, b, h) do { _Pragma("unroll") for (int n = 0; n < 2; ++n) _Pragma("unroll") for (int k = 0; k < 2; ++k) dst[n][k] = *(const PG8_LAS bf16x8*)(lds + PG8_SB(b, h) + boff + n * 2048 + k * 1024); } while (0)
; #define PG8_MMA(ai, bj, At, Bt) do { __builtin_amdgcn_s_setprio(1); _Pragma("unroll") for (int m = 0; m < 4; ++m) _Pragma("unroll") for (int n = 0; n < 2; ++n) _Pragma("unroll") for (int k = 0; k < 2; ++k) \
;         acc[ai][bj][m][n] = __builtin_amdgcn_mfma_f32_16x16x32_bf16(Bt[n][k], At[m][k], acc[ai][bj][m][n], 0, 0, 0); __builtin_amdgcn_s_setprio(0); } while (0)
; #define PG8_WAIT_V(n) asm volatile("s_waitcnt vmcnt(" #n ")" ::: "memory")
; #define PG8_WAIT_L(n) asm volatile("s_waitcnt lgkmcnt(" #n ")" ::: "memory")
; #define PG8_BAR __builtin_amdgcn_s_barrier()
; #define PG8_SCHED __builtin_amdgcn_sched_barrier(0)
; template <class Epi, class Sched, bool ALIGN_EPI = false, bool SP2 = false>
; __device__ __forceinline__ void gemm_phase(PG8_LAS unsigned char* lds, const Gemm g, const Sched& S, const Epi& E) {
;     ...
;             PG8_WAIT_V(8); PG8_WAIT_L(0); PG8_BAR; PG8_MMA(1, 0, At, B0); PG8_MMA(1, 1, At, B1); PG8_BAR; PG8_SCHED;
;             PG8_LDB(B0, 1, 0); PG8_LDB(B1, 1, 1); PG8_SCHED; PG8_LDA(At, 1, 0); PG8_STAGE(PG8_SA(0, 1), a2 + hstep, voffA);
;             PG8_WAIT_V(8); PG8_WAIT_L(0); PG8_BAR; PG8_MMA(0, 0, At, B0); PG8_MMA(0, 1, At, B1); PG8_BAR; PG8_SCHED;
	s_waitcnt lgkmcnt(0)
	v_mfma_f32_16x16x32_bf16 v[52:55], v[154:157], v[186:189], 0
	v_mfma_f32_16x16x32_bf16 v[48:51], v[162:165], v[186:189], 0
	v_mfma_f32_16x16x32_bf16 v[36:39], v[154:157], v[194:197], 0
	v_mfma_f32_16x16x32_bf16 v[32:35], v[162:165], v[194:197], 0
	v_mfma_f32_16x16x32_bf16 v[20:23], v[154:157], v[202:205], 0
	v_mfma_f32_16x16x32_bf16 v[16:19], v[162:165], v[202:205], 0
	v_mfma_f32_16x16x32_bf16 v[4:7], v[154:157], v[210:213], 0
	v_mfma_f32_16x16x32_bf16 v[0:3], v[162:165], v[210:213], 0
	v_mfma_f32_16x16x32_bf16 v[52:55], v[158:161], v[190:193], v[52:55]
	v_mfma_f32_16x16x32_bf16 v[48:51], v[166:169], v[190:193], v[48:51]
	v_mfma_f32_16x16x32_bf16 v[36:39], v[158:161], v[198:201], v[36:39]
	v_mfma_f32_16x16x32_bf16 v[32:35], v[166:169], v[198:201], v[32:35]
	v_mfma_f32_16x16x32_bf16 v[20:23], v[158:161], v[206:209], v[20:23]
	v_mfma_f32_16x16x32_bf16 v[16:19], v[166:169], v[206:209], v[16:19]
	v_mfma_f32_16x16x32_bf16 v[4:7], v[158:161], v[214:217], v[4:7]
	v_mfma_f32_16x16x32_bf16 v[0:3], v[166:169], v[214:217], v[0:3]
	v_mfma_f32_16x16x32_bf16 v[60:63], v[170:173], v[186:189], 0
	v_mfma_f32_16x16x32_bf16 v[56:59], v[178:181], v[186:189], 0
	v_mfma_f32_16x16x32_bf16 v[44:47], v[170:173], v[194:197], 0
	v_mfma_f32_16x16x32_bf16 v[40:43], v[178:181], v[194:197], 0
	v_mfma_f32_16x16x32_bf16 v[28:31], v[170:173], v[202:205], 0
	v_mfma_f32_16x16x32_bf16 v[24:27], v[178:181], v[202:205], 0
	v_mfma_f32_16x16x32_bf16 v[12:15], v[170:173], v[210:213], 0
	v_mfma_f32_16x16x32_bf16 v[8:11], v[178:181], v[210:213], 0
	v_mfma_f32_16x16x32_bf16 v[60:63], v[174:177], v[190:193], v[60:63]
	v_mfma_f32_16x16x32_bf16 v[56:59], v[182:185], v[190:193], v[56:59]
	v_mfma_f32_16x16x32_bf16 v[44:47], v[174:177], v[198:201], v[44:47]
	v_mfma_f32_16x16x32_bf16 v[40:43], v[182:185], v[198:201], v[40:43]
	v_mfma_f32_16x16x32_bf16 v[28:31], v[174:177], v[206:209], v[28:31]
	v_mfma_f32_16x16x32_bf16 v[24:27], v[182:185], v[206:209], v[24:27]
	v_mfma_f32_16x16x32_bf16 v[12:15], v[174:177], v[214:217], v[12:15]
	v_mfma_f32_16x16x32_bf16 v[8:11], v[182:185], v[214:217], v[8:11]
	s_barrier
	s_add_i32 s63, 0, 0x18000
	v_add_u32_e32 v153, s63, v147
	s_add_i32 s64, 0, 0x1c000
	ds_read_b128 v[154:157], v153
	ds_read_b128 v[158:161], v153 offset:1024
	ds_read_b128 v[162:165], v153 offset:2048
	ds_read_b128 v[166:169], v153 offset:3072
	v_add_u32_e32 v153, s64, v147
	ds_read_b128 v[170:173], v153
	ds_read_b128 v[174:177], v153 offset:1024
	ds_read_b128 v[178:181], v153 offset:2048
	ds_read_b128 v[182:185], v153 offset:3072
	s_add_u32 s28, s28, s8
	s_addc_u32 s29, s29, s9
	s_mov_b32 m0, s33
	v_lshl_add_u64 v[228:229], s[28:29], 0, v[134:135]
	ds_read_b128 v[186:189], v151 offset:32768
	ds_read_b128 v[190:193], v151 offset:33792
	ds_read_b128 v[194:197], v151 offset:34816
	ds_read_b128 v[198:201], v151 offset:35840
	ds_read_b128 v[202:205], v151 offset:36864
	ds_read_b128 v[206:209], v151 offset:37888
	ds_read_b128 v[210:213], v151 offset:38912
	ds_read_b128 v[214:217], v151 offset:39936
	global_load_lds_dwordx4 v[228:229], off
	v_lshl_add_u64 v[228:229], s[28:29], 0, v[130:131]
	s_mov_b32 m0, s34
	s_nop 0
	global_load_lds_dwordx4 v[228:229], off
	s_waitcnt vmcnt(8)
	s_waitcnt lgkmcnt(0)
	s_barrier
	s_waitcnt lgkmcnt(0)
	v_mfma_f32_16x16x32_bf16 v[116:119], v[154:157], v[186:189], v[116:119]
	v_mfma_f32_16x16x32_bf16 v[112:115], v[162:165], v[186:189], v[112:115]
	v_mfma_f32_16x16x32_bf16 v[100:103], v[154:157], v[194:197], v[100:103]
	v_mfma_f32_16x16x32_bf16 v[96:99], v[162:165], v[194:197], v[96:99]
	v_mfma_f32_16x16x32_bf16 v[84:87], v[154:157], v[202:205], v[84:87]
	v_mfma_f32_16x16x32_bf16 v[80:83], v[162:165], v[202:205], v[80:83]
	v_mfma_f32_16x16x32_bf16 v[68:71], v[154:157], v[210:213], v[68:71]
	v_mfma_f32_16x16x32_bf16 v[64:67], v[162:165], v[210:213], v[64:67]
	v_mfma_f32_16x16x32_bf16 v[116:119], v[158:161], v[190:193], v[116:119]
	v_mfma_f32_16x16x32_bf16 v[112:115], v[166:169], v[190:193], v[112:115]
	v_mfma_f32_16x16x32_bf16 v[100:103], v[158:161], v[198:201], v[100:103]
	v_mfma_f32_16x16x32_bf16 v[96:99], v[166:169], v[198:201], v[96:99]
	v_mfma_f32_16x16x32_bf16 v[84:87], v[158:161], v[206:209], v[84:87]
	v_mfma_f32_16x16x32_bf16 v[80:83], v[166:169], v[206:209], v[80:83]
	v_mfma_f32_16x16x32_bf16 v[68:71], v[158:161], v[214:217], v[68:71]
	v_mfma_f32_16x16x32_bf16 v[64:67], v[166:169], v[214:217], v[64:67]
	v_mfma_f32_16x16x32_bf16 v[124:127], v[170:173], v[186:189], v[124:127]
	v_mfma_f32_16x16x32_bf16 v[120:123], v[178:181], v[186:189], v[120:123]
	v_mfma_f32_16x16x32_bf16 v[108:111], v[170:173], v[194:197], v[108:111]
	v_mfma_f32_16x16x32_bf16 v[104:107], v[178:181], v[194:197], v[104:107]
	v_mfma_f32_16x16x32_bf16 v[92:95], v[170:173], v[202:205], v[92:95]
	v_mfma_f32_16x16x32_bf16 v[88:91], v[178:181], v[202:205], v[88:91]
	v_mfma_f32_16x16x32_bf16 v[76:79], v[170:173], v[210:213], v[76:79]
	v_mfma_f32_16x16x32_bf16 v[72:75], v[178:181], v[210:213], v[72:75]
	v_mfma_f32_16x16x32_bf16 v[124:127], v[174:177], v[190:193], v[124:127]
	v_mfma_f32_16x16x32_bf16 v[120:123], v[182:185], v[190:193], v[120:123]
	v_mfma_f32_16x16x32_bf16 v[108:111], v[174:177], v[198:201], v[108:111]
	v_mfma_f32_16x16x32_bf16 v[104:107], v[182:185], v[198:201], v[104:107]
	v_mfma_f32_16x16x32_bf16 v[92:95], v[174:177], v[206:209], v[92:95]
	v_mfma_f32_16x16x32_bf16 v[88:91], v[182:185], v[206:209], v[88:91]
	v_mfma_f32_16x16x32_bf16 v[76:79], v[174:177], v[214:217], v[76:79]
	v_mfma_f32_16x16x32_bf16 v[72:75], v[182:185], v[214:217], v[72:75]
	s_barrier
; #define PG8_STAGE(bufoff, gbase, voff) do { _Pragma("unroll") for (int _i = 0; _i < 2; ++_i) \
;         __builtin_amdgcn_global_load_lds((const unsigned*)((const char*)(gbase) + (voff)[_i]), (PG8_LAS unsigned*)(lds + (bufoff) + ldsw + _i * 8192), 16, 0, 0); } while (0)
; #define PG8_LDA(dst, b, h) do { _Pragma("unroll") for (int m = 0; m < 4; ++m) _Pragma("unroll") for (int k = 0; k < 2; ++k) dst[m][k] = *(const PG8_LAS bf16x8*)(lds + PG8_SA(b, h) + aoff + m * 2048 + k * 1024); } while (0)
; #define PG8_LDB(dst, b, h) do { _Pragma("unroll") for (int n = 0; n < 2; ++n) _Pragma("unroll") for (int k = 0; k < 2; ++k) dst[n][k] = *(const PG8_LAS bf16x8*)(lds + PG8_SB(b, h) + boff + n * 2048 + k * 1024); } while (0)
; #define PG8_MMA(ai, bj, At, Bt) do { __builtin_amdgcn_s_setprio(1); _Pragma("unroll") for (int m = 0; m < 4; ++m) _Pragma("unroll") for (int n = 0; n < 2; ++n) _Pragma("unroll") for (int k = 0; k < 2; ++k) \
;         acc[ai][bj][m][n] = __builtin_amdgcn_mfma_f32_16x16x32_bf16(Bt[n][k], At[m][k], acc[ai][bj][m][n], 0, 0, 0); __builtin_amdgcn_s_setprio(0); } while (0)
; #define PG8_WAIT_V(n) asm volatile("s_waitcnt vmcnt(" #n ")" ::: "memory")
; #define PG8_BAR __builtin_amdgcn_s_barrier()
; template <class Epi, class Sched, bool ALIGN_EPI = false, bool SP2 = false>
; __device__ __forceinline__ void gemm_phase(PG8_LAS unsigned char* lds, const Gemm g, const Sched& S, const Epi& E) {
;     ...
;         for (int t = 0; t < nt; t += 2) {
;             const bool last = (t == nt - 2);
;             const char* a1 = cA + (size_t)(t + 1) * kstep;
;             const char* a2 = last ? nA : cA + (size_t)(t + 2) * kstep; const char* b2 = last ? nB : cB + (size_t)(t + 2) * kstep;
;             const char* a3 = a2 + kstep; const char* b3 = b2 + kstep;
;             if (last && has_next) S.a_ready(nxt);
;             if constexpr (SP2) {
;             PG8_LDB(B0, 0, 0); PG8_LDB(B1, 0, 1); PG8_SCHED; PG8_LDA(At, 0, 0); PG8_STAGE(PG8_SA(1, 1), a1 + hstep, voffA);
;             PG8_WAIT_V(8); PG8_WAIT_L(0); PG8_BAR; PG8_MMA(0, 0, At, B0); PG8_MMA(0, 1, At, B1); PG8_BAR; PG8_SCHED;
;     ...
;             PG8_LDA(At, 1, 1); PG8_STAGE(PG8_SB(1, 0), b3, voffB); PG8_STAGE(PG8_SB(1, 1), b3 + hstep, voffB); PG8_STAGE(PG8_SA(1, 0), a3, voffA);
;             PG8_WAIT_V(8); PG8_WAIT_L(0); PG8_BAR; PG8_MMA(1, 0, At, B0); PG8_MMA(1, 1, At, B1); PG8_BAR; PG8_SCHED;
	s_add_i32 s28, s63, s16
	v_lshl_add_u64 v[144:145], v[144:145], 0, s[14:15]
	s_mov_b32 m0, s28
	ds_read_b128 v[186:189], v151 offset:49152
	ds_read_b128 v[190:193], v151 offset:50176
	ds_read_b128 v[194:197], v151 offset:51200
	ds_read_b128 v[198:201], v151 offset:52224
	ds_read_b128 v[202:205], v151 offset:53248
	ds_read_b128 v[206:209], v151 offset:54272
	ds_read_b128 v[210:213], v151 offset:55296
	ds_read_b128 v[214:217], v151 offset:56320
	global_load_lds_dwordx4 v[144:145], off
	v_lshl_add_u64 v[144:145], v[218:219], 0, s[14:15]
	s_add_i32 m0, s28, 0x2000
	s_add_i32 s28, s64, s16
	global_load_lds_dwordx4 v[144:145], off
	v_lshl_add_u64 v[144:145], v[220:221], 0, s[14:15]
	s_mov_b32 m0, s28
	s_nop 0
	global_load_lds_dwordx4 v[144:145], off
	v_lshl_add_u64 v[144:145], v[222:223], 0, s[14:15]
	s_add_i32 m0, s28, 0x2000
	s_nop 0
	global_load_lds_dwordx4 v[144:145], off
	v_lshl_add_u64 v[144:145], v[224:225], 0, s[14:15]
	s_mov_b32 m0, s36
	s_nop 0
	global_load_lds_dwordx4 v[144:145], off
	v_lshl_add_u64 v[144:145], v[226:227], 0, s[14:15]
	s_mov_b32 m0, s37
	s_nop 0
	global_load_lds_dwordx4 v[144:145], off
	s_waitcnt vmcnt(8)
	s_waitcnt lgkmcnt(0)
	s_barrier
	s_waitcnt lgkmcnt(0)
	v_mfma_f32_16x16x32_bf16 v[52:55], v[154:157], v[186:189], v[52:55]
	v_mfma_f32_16x16x32_bf16 v[48:51], v[162:165], v[186:189], v[48:51]
	v_mfma_f32_16x16x32_bf16 v[36:39], v[154:157], v[194:197], v[36:39]
	v_mfma_f32_16x16x32_bf16 v[32:35], v[162:165], v[194:197], v[32:35]
	v_mfma_f32_16x16x32_bf16 v[20:23], v[154:157], v[202:205], v[20:23]
	v_mfma_f32_16x16x32_bf16 v[16:19], v[162:165], v[202:205], v[16:19]
	v_mfma_f32_16x16x32_bf16 v[4:7], v[154:157], v[210:213], v[4:7]
	v_mfma_f32_16x16x32_bf16 v[0:3], v[162:165], v[210:213], v[0:3]
	v_mfma_f32_16x16x32_bf16 v[52:55], v[158:161], v[190:193], v[52:55]
	v_mfma_f32_16x16x32_bf16 v[48:51], v[166:169], v[190:193], v[48:51]
	v_mfma_f32_16x16x32_bf16 v[36:39], v[158:161], v[198:201], v[36:39]
	v_mfma_f32_16x16x32_bf16 v[32:35], v[166:169], v[198:201], v[32:35]
	v_mfma_f32_16x16x32_bf16 v[20:23], v[158:161], v[206:209], v[20:23]
	v_mfma_f32_16x16x32_bf16 v[16:19], v[166:169], v[206:209], v[16:19]
	v_mfma_f32_16x16x32_bf16 v[4:7], v[158:161], v[214:217], v[4:7]
	v_mfma_f32_16x16x32_bf16 v[0:3], v[166:169], v[214:217], v[0:3]
	v_mfma_f32_16x16x32_bf16 v[60:63], v[170:173], v[186:189], v[60:63]
	v_mfma_f32_16x16x32_bf16 v[56:59], v[178:181], v[186:189], v[56:59]
	v_mfma_f32_16x16x32_bf16 v[44:47], v[170:173], v[194:197], v[44:47]
	v_mfma_f32_16x16x32_bf16 v[40:43], v[178:181], v[194:197], v[40:43]
	v_mfma_f32_16x16x32_bf16 v[28:31], v[170:173], v[202:205], v[28:31]
	v_mfma_f32_16x16x32_bf16 v[24:27], v[178:181], v[202:205], v[24:27]
	v_mfma_f32_16x16x32_bf16 v[12:15], v[170:173], v[210:213], v[12:15]
	v_mfma_f32_16x16x32_bf16 v[8:11], v[178:181], v[210:213], v[8:11]
	v_mfma_f32_16x16x32_bf16 v[60:63], v[174:177], v[190:193], v[60:63]
	v_mfma_f32_16x16x32_bf16 v[56:59], v[182:185], v[190:193], v[56:59]
	v_mfma_f32_16x16x32_bf16 v[44:47], v[174:177], v[198:201], v[44:47]
	v_mfma_f32_16x16x32_bf16 v[40:43], v[182:185], v[198:201], v[40:43]
	v_mfma_f32_16x16x32_bf16 v[28:31], v[174:177], v[206:209], v[28:31]
	v_mfma_f32_16x16x32_bf16 v[24:27], v[182:185], v[206:209], v[24:27]
	v_mfma_f32_16x16x32_bf16 v[12:15], v[174:177], v[214:217], v[12:15]
	v_mfma_f32_16x16x32_bf16 v[8:11], v[182:185], v[214:217], v[8:11]
	s_barrier
	s_add_u32 s26, s26, 0x100
	s_addc_u32 s27, s27, 0
	s_add_u32 s60, s60, 0x100
	s_addc_u32 s61, s61, 0
	s_cmp_ge_i32 s62, s38
	s_mov_b32 s28, s62
	s_cbranch_scc0 .LBB0_2481
	s_branch .Lpeel_x12
.LBB0_2481:
	ds_read_b128 v[154:157], v149
	ds_read_b128 v[158:161], v149 offset:1024
	ds_read_b128 v[162:165], v149 offset:2048
	ds_read_b128 v[166:169], v149 offset:3072
	ds_read_b128 v[170:173], v150
	ds_read_b128 v[174:177], v150 offset:1024
	ds_read_b128 v[178:181], v150 offset:2048
	ds_read_b128 v[182:185], v150 offset:3072
	s_add_i32 s62, s28, 2
	s_add_u32 s63, s26, 0x80
	s_addc_u32 s29, s27, 0
	s_cmp_eq_u32 s39, s28
	s_cselect_b32 s28, s0, s63
	s_cselect_b32 s29, s1, s29
	s_cselect_b32 s65, s25, s61
	s_cselect_b32 s64, s24, s60
	v_lshl_add_u64 v[144:145], s[26:27], 0, v[136:137]
	s_add_i32 m0, s30, 0xc000
	ds_read_b128 v[186:189], v151
	ds_read_b128 v[190:193], v151 offset:1024
	ds_read_b128 v[194:197], v151 offset:2048
	ds_read_b128 v[198:201], v151 offset:3072
	ds_read_b128 v[202:205], v151 offset:4096
	ds_read_b128 v[206:209], v151 offset:5120
	ds_read_b128 v[210:213], v151 offset:6144
	ds_read_b128 v[214:217], v151 offset:7168
	global_load_lds_dwordx4 v[144:145], off
	v_lshl_add_u64 v[144:145], s[26:27], 0, v[138:139]
	s_add_i32 m0, s30, 0xe000
	s_nop 0
	global_load_lds_dwordx4 v[144:145], off
	s_waitcnt vmcnt(8)
	s_waitcnt lgkmcnt(0)
	s_barrier
; #define PG8_STAGE(bufoff, gbase, voff) do { _Pragma("unroll") for (int _i = 0; _i < 2; ++_i) \
;         __builtin_amdgcn_global_load_lds((const unsigned*)((const char*)(gbase) + (voff)[_i]), (PG8_LAS unsigned*)(lds + (bufoff) + ldsw + _i * 8192), 16, 0, 0); } while (0)
; #define PG8_LDA(dst, b, h) do { _Pragma("unroll") for (int m = 0; m < 4; ++m) _Pragma("unroll") for (int k = 0; k < 2; ++k) dst[m][k] = *(const PG8_LAS bf16x8*)(lds + PG8_SA(b, h) + aoff + m * 2048 + k * 1024); } while (0)
; #define PG8_MMA(ai, bj, At, Bt) do { __builtin_amdgcn_s_setprio(1); _Pragma("unroll") for (int m = 0; m < 4; ++m) _Pragma("unroll") for (int n = 0; n < 2; ++n) _Pragma("unroll") for (int k = 0; k < 2; ++k) \
;         acc[ai][bj][m][n] = __builtin_amdgcn_mfma_f32_16x16x32_bf16(Bt[n][k], At[m][k], acc[ai][bj][m][n], 0, 0, 0); __builtin_amdgcn_s_setprio(0); } while (0)
; #define PG8_WAIT_V(n) asm volatile("s_waitcnt vmcnt(" #n ")" ::: "memory")
; #define PG8_WAIT_L(n) asm volatile("s_waitcnt lgkmcnt(" #n ")" ::: "memory")
; #define PG8_BAR __builtin_amdgcn_s_barrier()
; #define PG8_SCHED __builtin_amdgcn_sched_barrier(0)
; template <class Epi, class Sched, bool ALIGN_EPI = false, bool SP2 = false>
; __device__ __forceinline__ void gemm_phase(PG8_LAS unsigned char* lds, const Gemm g, const Sched& S, const Epi& E) {
;     ...
;             PG8_WAIT_V(8); PG8_WAIT_L(0); PG8_BAR; PG8_MMA(0, 0, At, B0); PG8_MMA(0, 1, At, B1); PG8_BAR; PG8_SCHED;
;             PG8_LDA(At, 0, 1); PG8_STAGE(PG8_SB(0, 0), b2, voffB); PG8_STAGE(PG8_SB(0, 1), b2 + hstep, voffB); PG8_STAGE(PG8_SA(0, 0), a2, voffA);
;             PG8_WAIT_V(8); PG8_WAIT_L(0); PG8_BAR; PG8_MMA(1, 0, At, B0); PG8_MMA(1, 1, At, B1); PG8_BAR; PG8_SCHED;
	s_waitcnt lgkmcnt(0)
	v_mfma_f32_16x16x32_bf16 v[116:119], v[154:157], v[186:189], v[116:119]
	v_mfma_f32_16x16x32_bf16 v[112:115], v[162:165], v[186:189], v[112:115]
	v_mfma_f32_16x16x32_bf16 v[100:103], v[154:157], v[194:197], v[100:103]
	v_mfma_f32_16x16x32_bf16 v[96:99], v[162:165], v[194:197], v[96:99]
	v_mfma_f32_16x16x32_bf16 v[84:87], v[154:157], v[202:205], v[84:87]
	v_mfma_f32_16x16x32_bf16 v[80:83], v[162:165], v[202:205], v[80:83]
	v_mfma_f32_16x16x32_bf16 v[68:71], v[154:157], v[210:213], v[68:71]
	v_mfma_f32_16x16x32_bf16 v[64:67], v[162:165], v[210:213], v[64:67]
	v_mfma_f32_16x16x32_bf16 v[116:119], v[158:161], v[190:193], v[116:119]
	v_mfma_f32_16x16x32_bf16 v[112:115], v[166:169], v[190:193], v[112:115]
	v_mfma_f32_16x16x32_bf16 v[100:103], v[158:161], v[198:201], v[100:103]
	v_mfma_f32_16x16x32_bf16 v[96:99], v[166:169], v[198:201], v[96:99]
	v_mfma_f32_16x16x32_bf16 v[84:87], v[158:161], v[206:209], v[84:87]
	v_mfma_f32_16x16x32_bf16 v[80:83], v[166:169], v[206:209], v[80:83]
	v_mfma_f32_16x16x32_bf16 v[68:71], v[158:161], v[214:217], v[68:71]
	v_mfma_f32_16x16x32_bf16 v[64:67], v[166:169], v[214:217], v[64:67]
	v_mfma_f32_16x16x32_bf16 v[124:127], v[170:173], v[186:189], v[124:127]
	v_mfma_f32_16x16x32_bf16 v[120:123], v[178:181], v[186:189], v[120:123]
	v_mfma_f32_16x16x32_bf16 v[108:111], v[170:173], v[194:197], v[108:111]
	v_mfma_f32_16x16x32_bf16 v[104:107], v[178:181], v[194:197], v[104:107]
	v_mfma_f32_16x16x32_bf16 v[92:95], v[170:173], v[202:205], v[92:95]
	v_mfma_f32_16x16x32_bf16 v[88:91], v[178:181], v[202:205], v[88:91]
	v_mfma_f32_16x16x32_bf16 v[76:79], v[170:173], v[210:213], v[76:79]
	v_mfma_f32_16x16x32_bf16 v[72:75], v[178:181], v[210:213], v[72:75]
	v_mfma_f32_16x16x32_bf16 v[124:127], v[174:177], v[190:193], v[124:127]
	v_mfma_f32_16x16x32_bf16 v[120:123], v[182:185], v[190:193], v[120:123]
	v_mfma_f32_16x16x32_bf16 v[108:111], v[174:177], v[198:201], v[108:111]
	v_mfma_f32_16x16x32_bf16 v[104:107], v[182:185], v[198:201], v[104:107]
	v_mfma_f32_16x16x32_bf16 v[92:95], v[174:177], v[206:209], v[92:95]
	v_mfma_f32_16x16x32_bf16 v[88:91], v[182:185], v[206:209], v[88:91]
	v_mfma_f32_16x16x32_bf16 v[76:79], v[174:177], v[214:217], v[76:79]
	v_mfma_f32_16x16x32_bf16 v[72:75], v[182:185], v[214:217], v[72:75]
	s_barrier
	s_add_i32 s63, s44, s16
	v_lshl_add_u64 v[144:145], s[64:65], 0, v[132:133]
	s_mov_b32 m0, s63
	ds_read_b128 v[186:189], v151 offset:16384
	ds_read_b128 v[190:193], v151 offset:17408
	ds_read_b128 v[194:197], v151 offset:18432
	ds_read_b128 v[198:201], v151 offset:19456
	ds_read_b128 v[202:205], v151 offset:20480
	ds_read_b128 v[206:209], v151 offset:21504
	ds_read_b128 v[210:213], v151 offset:22528
	ds_read_b128 v[214:217], v151 offset:23552
	global_load_lds_dwordx4 v[144:145], off
	s_add_i32 m0, s63, 0x2000
	v_lshl_add_u64 v[218:219], s[64:65], 0, v[128:129]
	s_add_u32 s64, s64, s8
	s_addc_u32 s65, s65, s9
	s_add_i32 s63, s45, s16
	global_load_lds_dwordx4 v[218:219], off
	v_lshl_add_u64 v[220:221], s[64:65], 0, v[132:133]
	s_mov_b32 m0, s63
	v_lshl_add_u64 v[222:223], s[64:65], 0, v[128:129]
	global_load_lds_dwordx4 v[220:221], off
	s_add_i32 m0, s63, 0x2000
	v_lshl_add_u64 v[224:225], s[28:29], 0, v[134:135]
	global_load_lds_dwordx4 v[222:223], off
	s_mov_b32 m0, s30
	v_lshl_add_u64 v[226:227], s[28:29], 0, v[130:131]
	global_load_lds_dwordx4 v[224:225], off
	s_mov_b32 m0, s31
	s_nop 0
	global_load_lds_dwordx4 v[226:227], off
	s_waitcnt vmcnt(8)
	s_waitcnt lgkmcnt(0)
	s_barrier
	s_waitcnt lgkmcnt(0)
	v_mfma_f32_16x16x32_bf16 v[52:55], v[154:157], v[186:189], v[52:55]
	v_mfma_f32_16x16x32_bf16 v[48:51], v[162:165], v[186:189], v[48:51]
	v_mfma_f32_16x16x32_bf16 v[36:39], v[154:157], v[194:197], v[36:39]
	v_mfma_f32_16x16x32_bf16 v[32:35], v[162:165], v[194:197], v[32:35]
	v_mfma_f32_16x16x32_bf16 v[20:23], v[154:157], v[202:205], v[20:23]
	v_mfma_f32_16x16x32_bf16 v[16:19], v[162:165], v[202:205], v[16:19]
	v_mfma_f32_16x16x32_bf16 v[4:7], v[154:157], v[210:213], v[4:7]
	v_mfma_f32_16x16x32_bf16 v[0:3], v[162:165], v[210:213], v[0:3]
	v_mfma_f32_16x16x32_bf16 v[52:55], v[158:161], v[190:193], v[52:55]
	v_mfma_f32_16x16x32_bf16 v[48:51], v[166:169], v[190:193], v[48:51]
	v_mfma_f32_16x16x32_bf16 v[36:39], v[158:161], v[198:201], v[36:39]
	v_mfma_f32_16x16x32_bf16 v[32:35], v[166:169], v[198:201], v[32:35]
	v_mfma_f32_16x16x32_bf16 v[20:23], v[158:161], v[206:209], v[20:23]
	v_mfma_f32_16x16x32_bf16 v[16:19], v[166:169], v[206:209], v[16:19]
	v_mfma_f32_16x16x32_bf16 v[4:7], v[158:161], v[214:217], v[4:7]
	v_mfma_f32_16x16x32_bf16 v[0:3], v[166:169], v[214:217], v[0:3]
	v_mfma_f32_16x16x32_bf16 v[60:63], v[170:173], v[186:189], v[60:63]
	v_mfma_f32_16x16x32_bf16 v[56:59], v[178:181], v[186:189], v[56:59]
	v_mfma_f32_16x16x32_bf16 v[44:47], v[170:173], v[194:197], v[44:47]
	v_mfma_f32_16x16x32_bf16 v[40:43], v[178:181], v[194:197], v[40:43]
	v_mfma_f32_16x16x32_bf16 v[28:31], v[170:173], v[202:205], v[28:31]
	v_mfma_f32_16x16x32_bf16 v[24:27], v[178:181], v[202:205], v[24:27]
	v_mfma_f32_16x16x32_bf16 v[12:15], v[170:173], v[210:213], v[12:15]
	v_mfma_f32_16x16x32_bf16 v[8:11], v[178:181], v[210:213], v[8:11]
	v_mfma_f32_16x16x32_bf16 v[60:63], v[174:177], v[190:193], v[60:63]
	v_mfma_f32_16x16x32_bf16 v[56:59], v[182:185], v[190:193], v[56:59]
	v_mfma_f32_16x16x32_bf16 v[44:47], v[174:177], v[198:201], v[44:47]
	v_mfma_f32_16x16x32_bf16 v[40:43], v[182:185], v[198:201], v[40:43]
	v_mfma_f32_16x16x32_bf16 v[28:31], v[174:177], v[206:209], v[28:31]
	v_mfma_f32_16x16x32_bf16 v[24:27], v[182:185], v[206:209], v[24:27]
	v_mfma_f32_16x16x32_bf16 v[12:15], v[174:177], v[214:217], v[12:15]
	v_mfma_f32_16x16x32_bf16 v[8:11], v[182:185], v[214:217], v[8:11]
	s_barrier
; #define PG8_STAGE(bufoff, gbase, voff) do { _Pragma("unroll") for (int _i = 0; _i < 2; ++_i) \
;         __builtin_amdgcn_global_load_lds((const unsigned*)((const char*)(gbase) + (voff)[_i]), (PG8_LAS unsigned*)(lds + (bufoff) + ldsw + _i * 8192), 16, 0, 0); } while (0)
; #define PG8_LDA(dst, b, h) do { _Pragma("unroll") for (int m = 0; m < 4; ++m) _Pragma("unroll") for (int k = 0; k < 2; ++k) dst[m][k] = *(const PG8_LAS bf16x8*)(lds + PG8_SA(b, h) + aoff + m * 2048 + k * 1024); } while (0)
; #define PG8_LDB(dst, b, h) do { _Pragma("unroll") for (int n = 0; n < 2; ++n) _Pragma("unroll") for (int k = 0; k < 2; ++k) dst[n][k] = *(const PG8_LAS bf16x8*)(lds + PG8_SB(b, h) + boff + n * 2048 + k * 1024); } while (0)
; #define PG8_MMA(ai, bj, At, Bt) do { __builtin_amdgcn_s_setprio(1); _Pragma("unroll") for (int m = 0; m < 4; ++m) _Pragma("unroll") for (int n = 0; n < 2; ++n) _Pragma("unroll") for (int k = 0; k < 2; ++k) \
;         acc[ai][bj][m][n] = __builtin_amdgcn_mfma_f32_16x16x32_bf16(Bt[n][k], At[m][k], acc[ai][bj][m][n], 0, 0, 0); __builtin_amdgcn_s_setprio(0); } while (0)
; #define PG8_WAIT_V(n) asm volatile("s_waitcnt vmcnt(" #n ")" ::: "memory")
; #define PG8_WAIT_L(n) asm volatile("s_waitcnt lgkmcnt(" #n ")" ::: "memory")
; #define PG8_BAR __builtin_amdgcn_s_barrier()
; #define PG8_SCHED __builtin_amdgcn_sched_barrier(0)
; template <class Epi, class Sched, bool ALIGN_EPI = false, bool SP2 = false>
; __device__ __forceinline__ void gemm_phase(PG8_LAS unsigned char* lds, const Gemm g, const Sched& S, const Epi& E) {
;     ...
;             PG8_LDB(B0, 1, 0); PG8_LDB(B1, 1, 1); PG8_SCHED; PG8_LDA(At, 1, 0); PG8_STAGE(PG8_SA(0, 1), a2 + hstep, voffA);
;             PG8_WAIT_V(8); PG8_WAIT_L(0); PG8_BAR; PG8_MMA(0, 0, At, B0); PG8_MMA(0, 1, At, B1); PG8_BAR; PG8_SCHED;
;             PG8_LDA(At, 1, 1); PG8_STAGE(PG8_SB(1, 0), b3, voffB); PG8_STAGE(PG8_SB(1, 1), b3 + hstep, voffB); PG8_STAGE(PG8_SA(1, 0), a3, voffA);
;             PG8_WAIT_V(8); PG8_WAIT_L(0); PG8_BAR; PG8_MMA(1, 0, At, B0); PG8_MMA(1, 1, At, B1); PG8_BAR; PG8_SCHED;
	s_add_i32 s63, 0, 0x18000
	v_add_u32_e32 v153, s63, v147
	s_add_i32 s64, 0, 0x1c000
	ds_read_b128 v[154:157], v153
	ds_read_b128 v[158:161], v153 offset:1024
	ds_read_b128 v[162:165], v153 offset:2048
	ds_read_b128 v[166:169], v153 offset:3072
	v_add_u32_e32 v153, s64, v147
	ds_read_b128 v[170:173], v153
	ds_read_b128 v[174:177], v153 offset:1024
	ds_read_b128 v[178:181], v153 offset:2048
	ds_read_b128 v[182:185], v153 offset:3072
	s_add_u32 s28, s28, s8
	s_addc_u32 s29, s29, s9
	s_mov_b32 m0, s33
	v_lshl_add_u64 v[228:229], s[28:29], 0, v[134:135]
	ds_read_b128 v[186:189], v151 offset:32768
	ds_read_b128 v[190:193], v151 offset:33792
	ds_read_b128 v[194:197], v151 offset:34816
	ds_read_b128 v[198:201], v151 offset:35840
	ds_read_b128 v[202:205], v151 offset:36864
	ds_read_b128 v[206:209], v151 offset:37888
	ds_read_b128 v[210:213], v151 offset:38912
	ds_read_b128 v[214:217], v151 offset:39936
	global_load_lds_dwordx4 v[228:229], off
	v_lshl_add_u64 v[228:229], s[28:29], 0, v[130:131]
	s_mov_b32 m0, s34
	s_nop 0
	global_load_lds_dwordx4 v[228:229], off
	s_waitcnt vmcnt(8)
	s_waitcnt lgkmcnt(0)
	s_barrier
	s_waitcnt lgkmcnt(0)
	v_mfma_f32_16x16x32_bf16 v[116:119], v[154:157], v[186:189], v[116:119]
	v_mfma_f32_16x16x32_bf16 v[112:115], v[162:165], v[186:189], v[112:115]
	v_mfma_f32_16x16x32_bf16 v[100:103], v[154:157], v[194:197], v[100:103]
	v_mfma_f32_16x16x32_bf16 v[96:99], v[162:165], v[194:197], v[96:99]
	v_mfma_f32_16x16x32_bf16 v[84:87], v[154:157], v[202:205], v[84:87]
	v_mfma_f32_16x16x32_bf16 v[80:83], v[162:165], v[202:205], v[80:83]
	v_mfma_f32_16x16x32_bf16 v[68:71], v[154:157], v[210:213], v[68:71]
	v_mfma_f32_16x16x32_bf16 v[64:67], v[162:165], v[210:213], v[64:67]
	v_mfma_f32_16x16x32_bf16 v[116:119], v[158:161], v[190:193], v[116:119]
	v_mfma_f32_16x16x32_bf16 v[112:115], v[166:169], v[190:193], v[112:115]
	v_mfma_f32_16x16x32_bf16 v[100:103], v[158:161], v[198:201], v[100:103]
	v_mfma_f32_16x16x32_bf16 v[96:99], v[166:169], v[198:201], v[96:99]
	v_mfma_f32_16x16x32_bf16 v[84:87], v[158:161], v[206:209], v[84:87]
	v_mfma_f32_16x16x32_bf16 v[80:83], v[166:169], v[206:209], v[80:83]
	v_mfma_f32_16x16x32_bf16 v[68:71], v[158:161], v[214:217], v[68:71]
	v_mfma_f32_16x16x32_bf16 v[64:67], v[166:169], v[214:217], v[64:67]
	v_mfma_f32_16x16x32_bf16 v[124:127], v[170:173], v[186:189], v[124:127]
	v_mfma_f32_16x16x32_bf16 v[120:123], v[178:181], v[186:189], v[120:123]
	v_mfma_f32_16x16x32_bf16 v[108:111], v[170:173], v[194:197], v[108:111]
	v_mfma_f32_16x16x32_bf16 v[104:107], v[178:181], v[194:197], v[104:107]
	v_mfma_f32_16x16x32_bf16 v[92:95], v[170:173], v[202:205], v[92:95]
	v_mfma_f32_16x16x32_bf16 v[88:91], v[178:181], v[202:205], v[88:91]
	v_mfma_f32_16x16x32_bf16 v[76:79], v[170:173], v[210:213], v[76:79]
	v_mfma_f32_16x16x32_bf16 v[72:75], v[178:181], v[210:213], v[72:75]
	v_mfma_f32_16x16x32_bf16 v[124:127], v[174:177], v[190:193], v[124:127]
	v_mfma_f32_16x16x32_bf16 v[120:123], v[182:185], v[190:193], v[120:123]
	v_mfma_f32_16x16x32_bf16 v[108:111], v[174:177], v[198:201], v[108:111]
	v_mfma_f32_16x16x32_bf16 v[104:107], v[182:185], v[198:201], v[104:107]
	v_mfma_f32_16x16x32_bf16 v[92:95], v[174:177], v[206:209], v[92:95]
	v_mfma_f32_16x16x32_bf16 v[88:91], v[182:185], v[206:209], v[88:91]
	v_mfma_f32_16x16x32_bf16 v[76:79], v[174:177], v[214:217], v[76:79]
	v_mfma_f32_16x16x32_bf16 v[72:75], v[182:185], v[214:217], v[72:75]
	s_barrier
	s_add_i32 s28, s63, s16
	v_lshl_add_u64 v[144:145], v[144:145], 0, s[14:15]
	s_mov_b32 m0, s28
	ds_read_b128 v[186:189], v151 offset:49152
	ds_read_b128 v[190:193], v151 offset:50176
	ds_read_b128 v[194:197], v151 offset:51200
	ds_read_b128 v[198:201], v151 offset:52224
	ds_read_b128 v[202:205], v151 offset:53248
	ds_read_b128 v[206:209], v151 offset:54272
	ds_read_b128 v[210:213], v151 offset:55296
	ds_read_b128 v[214:217], v151 offset:56320
	global_load_lds_dwordx4 v[144:145], off
	v_lshl_add_u64 v[144:145], v[218:219], 0, s[14:15]
	s_add_i32 m0, s28, 0x2000
	s_add_i32 s28, s64, s16
	global_load_lds_dwordx4 v[144:145], off
	v_lshl_add_u64 v[144:145], v[220:221], 0, s[14:15]
	s_mov_b32 m0, s28
	s_nop 0
	global_load_lds_dwordx4 v[144:145], off
	v_lshl_add_u64 v[144:145], v[222:223], 0, s[14:15]
	s_add_i32 m0, s28, 0x2000
	s_nop 0
	global_load_lds_dwordx4 v[144:145], off
	v_lshl_add_u64 v[144:145], v[224:225], 0, s[14:15]
	s_mov_b32 m0, s36
	s_nop 0
	global_load_lds_dwordx4 v[144:145], off
	v_lshl_add_u64 v[144:145], v[226:227], 0, s[14:15]
	s_mov_b32 m0, s37
	s_nop 0
	global_load_lds_dwordx4 v[144:145], off
	s_waitcnt vmcnt(8)
	s_waitcnt lgkmcnt(0)
	s_barrier
	s_waitcnt lgkmcnt(0)
	v_mfma_f32_16x16x32_bf16 v[52:55], v[154:157], v[186:189], v[52:55]
	v_mfma_f32_16x16x32_bf16 v[48:51], v[162:165], v[186:189], v[48:51]
	v_mfma_f32_16x16x32_bf16 v[36:39], v[154:157], v[194:197], v[36:39]
	v_mfma_f32_16x16x32_bf16 v[32:35], v[162:165], v[194:197], v[32:35]
	v_mfma_f32_16x16x32_bf16 v[20:23], v[154:157], v[202:205], v[20:23]
	v_mfma_f32_16x16x32_bf16 v[16:19], v[162:165], v[202:205], v[16:19]
	v_mfma_f32_16x16x32_bf16 v[4:7], v[154:157], v[210:213], v[4:7]
	v_mfma_f32_16x16x32_bf16 v[0:3], v[162:165], v[210:213], v[0:3]
	v_mfma_f32_16x16x32_bf16 v[52:55], v[158:161], v[190:193], v[52:55]
	v_mfma_f32_16x16x32_bf16 v[48:51], v[166:169], v[190:193], v[48:51]
	v_mfma_f32_16x16x32_bf16 v[36:39], v[158:161], v[198:201], v[36:39]
	v_mfma_f32_16x16x32_bf16 v[32:35], v[166:169], v[198:201], v[32:35]
	v_mfma_f32_16x16x32_bf16 v[20:23], v[158:161], v[206:209], v[20:23]
	v_mfma_f32_16x16x32_bf16 v[16:19], v[166:169], v[206:209], v[16:19]
	v_mfma_f32_16x16x32_bf16 v[4:7], v[158:161], v[214:217], v[4:7]
	v_mfma_f32_16x16x32_bf16 v[0:3], v[166:169], v[214:217], v[0:3]
	v_mfma_f32_16x16x32_bf16 v[60:63], v[170:173], v[186:189], v[60:63]
	v_mfma_f32_16x16x32_bf16 v[56:59], v[178:181], v[186:189], v[56:59]
	v_mfma_f32_16x16x32_bf16 v[44:47], v[170:173], v[194:197], v[44:47]
	v_mfma_f32_16x16x32_bf16 v[40:43], v[178:181], v[194:197], v[40:43]
	v_mfma_f32_16x16x32_bf16 v[28:31], v[170:173], v[202:205], v[28:31]
	v_mfma_f32_16x16x32_bf16 v[24:27], v[178:181], v[202:205], v[24:27]
	v_mfma_f32_16x16x32_bf16 v[12:15], v[170:173], v[210:213], v[12:15]
	v_mfma_f32_16x16x32_bf16 v[8:11], v[178:181], v[210:213], v[8:11]
	v_mfma_f32_16x16x32_bf16 v[60:63], v[174:177], v[190:193], v[60:63]
	v_mfma_f32_16x16x32_bf16 v[56:59], v[182:185], v[190:193], v[56:59]
	v_mfma_f32_16x16x32_bf16 v[44:47], v[174:177], v[198:201], v[44:47]
	v_mfma_f32_16x16x32_bf16 v[40:43], v[182:185], v[198:201], v[40:43]
	v_mfma_f32_16x16x32_bf16 v[28:31], v[174:177], v[206:209], v[28:31]
	v_mfma_f32_16x16x32_bf16 v[24:27], v[182:185], v[206:209], v[24:27]
	v_mfma_f32_16x16x32_bf16 v[12:15], v[174:177], v[214:217], v[12:15]
	v_mfma_f32_16x16x32_bf16 v[8:11], v[182:185], v[214:217], v[8:11]
	s_barrier
	s_add_u32 s26, s26, 0x100
	s_addc_u32 s27, s27, 0
	s_add_u32 s60, s60, 0x100
	s_addc_u32 s61, s61, 0
	s_cmp_ge_i32 s62, s38
	s_mov_b32 s28, s62
	s_cbranch_scc0 .LBB0_2481

; #define PG8_STAGE(bufoff, gbase, voff) do { _Pragma("unroll") for (int _i = 0; _i < 2; ++_i) \
;         __builtin_amdgcn_global_load_lds((const unsigned*)((const char*)(gbase) + (voff)[_i]), (PG8_LAS unsigned*)(lds + (bufoff) + ldsw + _i * 8192), 16, 0, 0); } while (0)
; #define PG8_LDA(dst, b, h) do { _Pragma("unroll") for (int m = 0; m < 4; ++m) _Pragma("unroll") for (int k = 0; k < 2; ++k) dst[m][k] = *(const PG8_LAS bf16x8*)(lds + PG8_SA(b, h) + aoff + m * 2048 + k * 1024); } while (0)
; #define PG8_LDB(dst, b, h) do { _Pragma("unroll") for (int n = 0; n < 2; ++n) _Pragma("unroll") for (int k = 0; k < 2; ++k) dst[n][k] = *(const PG8_LAS bf16x8*)(lds + PG8_SB(b, h) + boff + n * 2048 + k * 1024); } while (0)
; #define PG8_WAIT_V(n) asm volatile("s_waitcnt vmcnt(" #n ")" ::: "memory")
; #define PG8_WAIT_L(n) asm volatile("s_waitcnt lgkmcnt(" #n ")" ::: "memory")
; template <class Epi, class Sched, bool ALIGN_EPI = false, bool SP2 = false>
; __device__ __forceinline__ void gemm_phase(PG8_LAS unsigned char* lds, const Gemm g, const Sched& S, const Epi& E) {
;     ...
;         for (int t = 0; t < nt; t += 2) {
;             const bool last = (t == nt - 2);
;             const char* a1 = cA + (size_t)(t + 1) * kstep;
;             const char* a2 = last ? nA : cA + (size_t)(t + 2) * kstep; const char* b2 = last ? nB : cB + (size_t)(t + 2) * kstep;
;             const char* a3 = a2 + kstep; const char* b3 = b2 + kstep;
;             if (last && has_next) S.a_ready(nxt);
;             if constexpr (SP2) {
;             PG8_LDB(B0, 0, 0); PG8_LDB(B1, 0, 1); PG8_SCHED; PG8_LDA(At, 0, 0); PG8_STAGE(PG8_SA(1, 1), a1 + hstep, voffA);
;             PG8_WAIT_V(8); PG8_WAIT_L(0); PG8_BAR; PG8_MMA(0, 0, At, B0); PG8_MMA(0, 1, At, B1); PG8_BAR; PG8_SCHED;
;             PG8_LDA(At, 0, 1); PG8_STAGE(PG8_SB(0, 0), b2, voffB); PG8_STAGE(PG8_SB(0, 1), b2 + hstep, voffB); PG8_STAGE(PG8_SA(0, 0), a2, voffA);
;             PG8_WAIT_V(8); PG8_WAIT_L(0); PG8_BAR; PG8_MMA(1, 0, At, B0); PG8_MMA(1, 1, At, B1); PG8_BAR; PG8_SCHED;
;     ...
; #pragma unroll
;         for (int a = 0; a < 2; ++a)
; #pragma unroll
;             for (int b = 0; b < 2; ++b)
; #pragma unroll
;                 for (int m = 0; m < 4; ++m)
; #pragma unroll
;                     for (int n = 0; n < 2; ++n) acc[a][b][m][n] = (f32x4){0.f, 0.f, 0.f, 0.f};
;         cur = nxt; cA = nA; cB = nB; ++ui;
.LBB0_2573:
	v_mov_b32_e32 v151, 0
	s_andn2_b64 vcc, exec, s[24:25]
	v_mov_b32_e32 v150, 0
	v_mov_b32_e32 v155, 0
	v_mov_b32_e32 v154, 0
	v_mov_b32_e32 v153, 0
	v_mov_b32_e32 v152, 0
	v_mov_b32_e32 v149, 0
	v_mov_b32_e32 v148, 0
	s_waitcnt vmcnt(0)
	v_mov_b32_e32 v145, 0
	v_mov_b32_e32 v144, 0
	v_mov_b32_e32 v147, 0
	v_mov_b32_e32 v146, 0
	s_waitcnt lgkmcnt(0)
	s_cbranch_vccnz .LBB0_2577
	s_add_u32 s30, s30, 0x80
	s_addc_u32 s31, s31, 0
	s_add_u32 s61, s34, 0x100
	s_addc_u32 s62, s35, 0
	s_mov_b32 s34, 0
	ds_read_b128 v[144:147], v159
	ds_read_b128 v[148:151], v159 offset:1024
	ds_read_b128 v[152:155], v159 offset:2048
	ds_read_b128 v[164:167], v159 offset:3072
	ds_read_b128 v[168:171], v160
	ds_read_b128 v[172:175], v160 offset:1024
	ds_read_b128 v[176:179], v160 offset:2048
	ds_read_b128 v[180:183], v160 offset:3072
	s_add_i32 s63, s34, 2
	s_add_u32 s64, s30, 0x80
	s_addc_u32 s35, s31, 0
	s_cmp_eq_u32 s41, s34
	s_cselect_b32 s34, s0, s64
	s_cselect_b32 s35, s1, s35
	s_cselect_b32 s65, s29, s62
	s_cselect_b32 s64, s28, s61
	v_lshl_add_u64 v[216:217], s[30:31], 0, v[136:137]
	s_add_i32 m0, s17, 0xc000
	ds_read_b128 v[184:187], v161
	ds_read_b128 v[188:191], v161 offset:1024
	ds_read_b128 v[192:195], v161 offset:2048
	ds_read_b128 v[196:199], v161 offset:3072
	ds_read_b128 v[200:203], v161 offset:4096
	ds_read_b128 v[204:207], v161 offset:5120
	ds_read_b128 v[208:211], v161 offset:6144
	ds_read_b128 v[212:215], v161 offset:7168
	global_load_lds_dwordx4 v[216:217], off
	v_lshl_add_u64 v[216:217], s[30:31], 0, v[138:139]
	s_add_i32 m0, s17, 0xe000
	s_nop 0
	global_load_lds_dwordx4 v[216:217], off
	s_waitcnt vmcnt(8)
	s_waitcnt lgkmcnt(0)
	s_barrier
	s_waitcnt lgkmcnt(0)
	v_mfma_f32_16x16x32_bf16 v[124:127], v[144:147], v[184:187], 0
	v_mfma_f32_16x16x32_bf16 v[120:123], v[152:155], v[184:187], 0
	v_mfma_f32_16x16x32_bf16 v[116:119], v[144:147], v[192:195], 0
	v_mfma_f32_16x16x32_bf16 v[112:115], v[152:155], v[192:195], 0
	v_mfma_f32_16x16x32_bf16 v[104:107], v[144:147], v[200:203], 0
	v_mfma_f32_16x16x32_bf16 v[96:99], v[152:155], v[200:203], 0
	v_mfma_f32_16x16x32_bf16 v[88:91], v[144:147], v[208:211], 0
	v_mfma_f32_16x16x32_bf16 v[80:83], v[152:155], v[208:211], 0
	v_mfma_f32_16x16x32_bf16 v[124:127], v[148:151], v[188:191], v[124:127]
	v_mfma_f32_16x16x32_bf16 v[120:123], v[164:167], v[188:191], v[120:123]
	v_mfma_f32_16x16x32_bf16 v[116:119], v[148:151], v[196:199], v[116:119]
	v_mfma_f32_16x16x32_bf16 v[112:115], v[164:167], v[196:199], v[112:115]
	v_mfma_f32_16x16x32_bf16 v[104:107], v[148:151], v[204:207], v[104:107]
	v_mfma_f32_16x16x32_bf16 v[96:99], v[164:167], v[204:207], v[96:99]
	v_mfma_f32_16x16x32_bf16 v[88:91], v[148:151], v[212:215], v[88:91]
	v_mfma_f32_16x16x32_bf16 v[80:83], v[164:167], v[212:215], v[80:83]
	v_mfma_f32_16x16x32_bf16 v[108:111], v[168:171], v[184:187], 0
	v_mfma_f32_16x16x32_bf16 v[100:103], v[176:179], v[184:187], 0
	v_mfma_f32_16x16x32_bf16 v[92:95], v[168:171], v[192:195], 0
	v_mfma_f32_16x16x32_bf16 v[84:87], v[176:179], v[192:195], 0
	v_mfma_f32_16x16x32_bf16 v[76:79], v[168:171], v[200:203], 0
	v_mfma_f32_16x16x32_bf16 v[72:75], v[176:179], v[200:203], 0
	v_mfma_f32_16x16x32_bf16 v[68:71], v[168:171], v[208:211], 0
	v_mfma_f32_16x16x32_bf16 v[64:67], v[176:179], v[208:211], 0
	v_mfma_f32_16x16x32_bf16 v[108:111], v[172:175], v[188:191], v[108:111]
	v_mfma_f32_16x16x32_bf16 v[100:103], v[180:183], v[188:191], v[100:103]
	v_mfma_f32_16x16x32_bf16 v[92:95], v[172:175], v[196:199], v[92:95]
	v_mfma_f32_16x16x32_bf16 v[84:87], v[180:183], v[196:199], v[84:87]
	v_mfma_f32_16x16x32_bf16 v[76:79], v[172:175], v[204:207], v[76:79]
	v_mfma_f32_16x16x32_bf16 v[72:75], v[180:183], v[204:207], v[72:75]
	v_mfma_f32_16x16x32_bf16 v[68:71], v[172:175], v[212:215], v[68:71]
	v_mfma_f32_16x16x32_bf16 v[64:67], v[180:183], v[212:215], v[64:67]
	s_barrier
	s_add_i32 s66, s51, s16
	v_lshl_add_u64 v[216:217], s[64:65], 0, v[130:131]
	s_mov_b32 m0, s66
	ds_read_b128 v[184:187], v161 offset:16384
	ds_read_b128 v[188:191], v161 offset:17408
	ds_read_b128 v[192:195], v161 offset:18432
	ds_read_b128 v[196:199], v161 offset:19456
	ds_read_b128 v[200:203], v161 offset:20480
	ds_read_b128 v[204:207], v161 offset:21504
	ds_read_b128 v[208:211], v161 offset:22528
	ds_read_b128 v[212:215], v161 offset:23552
	global_load_lds_dwordx4 v[216:217], off
	s_add_i32 m0, s66, 0x2000
	v_lshl_add_u64 v[218:219], s[64:65], 0, v[134:135]
	s_add_u32 s64, s64, s6
	s_addc_u32 s65, s65, s7
	s_add_i32 s66, s56, s16
	global_load_lds_dwordx4 v[218:219], off
	v_lshl_add_u64 v[220:221], s[64:65], 0, v[130:131]
	s_mov_b32 m0, s66
	v_lshl_add_u64 v[222:223], s[64:65], 0, v[134:135]
	global_load_lds_dwordx4 v[220:221], off
	s_add_i32 m0, s66, 0x2000
	v_lshl_add_u64 v[224:225], s[34:35], 0, v[128:129]
	global_load_lds_dwordx4 v[222:223], off
	s_mov_b32 m0, s17
	v_lshl_add_u64 v[226:227], s[34:35], 0, v[132:133]
	global_load_lds_dwordx4 v[224:225], off
	s_mov_b32 m0, s19
	s_nop 0
	global_load_lds_dwordx4 v[226:227], off
	s_waitcnt vmcnt(8)
	s_waitcnt lgkmcnt(0)
	s_barrier
; #define PG8_STAGE(bufoff, gbase, voff) do { _Pragma("unroll") for (int _i = 0; _i < 2; ++_i) \
;         __builtin_amdgcn_global_load_lds((const unsigned*)((const char*)(gbase) + (voff)[_i]), (PG8_LAS unsigned*)(lds + (bufoff) + ldsw + _i * 8192), 16, 0, 0); } while (0)
; #define PG8_LDA(dst, b, h) do { _Pragma("unroll") for (int m = 0; m < 4; ++m) _Pragma("unroll") for (int k = 0; k < 2; ++k) dst[m][k] = *(const PG8_LAS bf16x8*)(lds + PG8_SA(b, h) + aoff + m * 2048 + k * 1024); } while (0)
; #define PG8_LDB(dst, b, h) do { _Pragma("unroll") for (int n = 0; n < 2; ++n) _Pragma("unroll") for (int k = 0; k < 2; ++k) dst[n][k] = *(const PG8_LAS bf16x8*)(lds + PG8_SB(b, h) + boff + n * 2048 + k * 1024); } while (0)
; #define PG8_MMA(ai, bj, At, Bt) do { __builtin_amdgcn_s_setprio(1); _Pragma("unroll") for (int m = 0; m < 4; ++m) _Pragma("unroll") for (int n = 0; n < 2; ++n) _Pragma("unroll") for (int k = 0; k < 2; ++k) \
;         acc[ai][bj][m][n] = __builtin_amdgcn_mfma_f32_16x16x32_bf16(Bt[n][k], At[m][k], acc[ai][bj][m][n], 0, 0, 0); __builtin_amdgcn_s_setprio(0); } while (0)
; #define PG8_WAIT_V(n) asm volatile("s_waitcnt vmcnt(" #n ")" ::: "memory")
; #define PG8_WAIT_L(n) asm volatile("s_waitcnt lgkmcnt(" #n ")" ::: "memory")
; #define PG8_BAR __builtin_amdgcn_s_barrier()
; #define PG8_SCHED __builtin_amdgcn_sched_barrier(0)
; template <class Epi, class Sched, bool ALIGN_EPI = false, bool SP2 = false>
; __device__ __forceinline__ void gemm_phase(PG8_LAS unsigned char* lds, const Gemm g, const Sched& S, const Epi& E) {
;     ...
;             PG8_WAIT_V(8); PG8_WAIT_L(0); PG8_BAR; PG8_MMA(1, 0, At, B0); PG8_MMA(1, 1, At, B1); PG8_BAR; PG8_SCHED;
;             PG8_LDB(B0, 1, 0); PG8_LDB(B1, 1, 1); PG8_SCHED; PG8_LDA(At, 1, 0); PG8_STAGE(PG8_SA(0, 1), a2 + hstep, voffA);
;             PG8_WAIT_V(8); PG8_WAIT_L(0); PG8_BAR; PG8_MMA(0, 0, At, B0); PG8_MMA(0, 1, At, B1); PG8_BAR; PG8_SCHED;
	s_waitcnt lgkmcnt(0)
	v_mfma_f32_16x16x32_bf16 v[60:63], v[144:147], v[184:187], 0
	v_mfma_f32_16x16x32_bf16 v[56:59], v[152:155], v[184:187], 0
	v_mfma_f32_16x16x32_bf16 v[52:55], v[144:147], v[192:195], 0
	v_mfma_f32_16x16x32_bf16 v[48:51], v[152:155], v[192:195], 0
	v_mfma_f32_16x16x32_bf16 v[40:43], v[144:147], v[200:203], 0
	v_mfma_f32_16x16x32_bf16 v[32:35], v[152:155], v[200:203], 0
	v_mfma_f32_16x16x32_bf16 v[24:27], v[144:147], v[208:211], 0
	v_mfma_f32_16x16x32_bf16 v[16:19], v[152:155], v[208:211], 0
	v_mfma_f32_16x16x32_bf16 v[60:63], v[148:151], v[188:191], v[60:63]
	v_mfma_f32_16x16x32_bf16 v[56:59], v[164:167], v[188:191], v[56:59]
	v_mfma_f32_16x16x32_bf16 v[52:55], v[148:151], v[196:199], v[52:55]
	v_mfma_f32_16x16x32_bf16 v[48:51], v[164:167], v[196:199], v[48:51]
	v_mfma_f32_16x16x32_bf16 v[40:43], v[148:151], v[204:207], v[40:43]
	v_mfma_f32_16x16x32_bf16 v[32:35], v[164:167], v[204:207], v[32:35]
	v_mfma_f32_16x16x32_bf16 v[24:27], v[148:151], v[212:215], v[24:27]
	v_mfma_f32_16x16x32_bf16 v[16:19], v[164:167], v[212:215], v[16:19]
	v_mfma_f32_16x16x32_bf16 v[44:47], v[168:171], v[184:187], 0
	v_mfma_f32_16x16x32_bf16 v[36:39], v[176:179], v[184:187], 0
	v_mfma_f32_16x16x32_bf16 v[28:31], v[168:171], v[192:195], 0
	v_mfma_f32_16x16x32_bf16 v[20:23], v[176:179], v[192:195], 0
	v_mfma_f32_16x16x32_bf16 v[12:15], v[168:171], v[200:203], 0
	v_mfma_f32_16x16x32_bf16 v[8:11], v[176:179], v[200:203], 0
	v_mfma_f32_16x16x32_bf16 v[4:7], v[168:171], v[208:211], 0
	v_mfma_f32_16x16x32_bf16 v[0:3], v[176:179], v[208:211], 0
	v_mfma_f32_16x16x32_bf16 v[44:47], v[172:175], v[188:191], v[44:47]
	v_mfma_f32_16x16x32_bf16 v[36:39], v[180:183], v[188:191], v[36:39]
	v_mfma_f32_16x16x32_bf16 v[28:31], v[172:175], v[196:199], v[28:31]
	v_mfma_f32_16x16x32_bf16 v[20:23], v[180:183], v[196:199], v[20:23]
	v_mfma_f32_16x16x32_bf16 v[12:15], v[172:175], v[204:207], v[12:15]
	v_mfma_f32_16x16x32_bf16 v[8:11], v[180:183], v[204:207], v[8:11]
	v_mfma_f32_16x16x32_bf16 v[4:7], v[172:175], v[212:215], v[4:7]
	v_mfma_f32_16x16x32_bf16 v[0:3], v[180:183], v[212:215], v[0:3]
	s_barrier
	s_add_i32 s64, 0, 0x18000
	v_add_u32_e32 v163, s64, v157
	s_add_i32 s65, 0, 0x1c000
	ds_read_b128 v[144:147], v163
	ds_read_b128 v[148:151], v163 offset:1024
	ds_read_b128 v[152:155], v163 offset:2048
	ds_read_b128 v[164:167], v163 offset:3072
	v_add_u32_e32 v163, s65, v157
	ds_read_b128 v[168:171], v163
	ds_read_b128 v[172:175], v163 offset:1024
	ds_read_b128 v[176:179], v163 offset:2048
	ds_read_b128 v[180:183], v163 offset:3072
	s_add_u32 s34, s34, s6
	s_addc_u32 s35, s35, s7
	s_mov_b32 m0, s33
	v_lshl_add_u64 v[228:229], s[34:35], 0, v[128:129]
	ds_read_b128 v[184:187], v161 offset:32768
	ds_read_b128 v[188:191], v161 offset:33792
	ds_read_b128 v[192:195], v161 offset:34816
	ds_read_b128 v[196:199], v161 offset:35840
	ds_read_b128 v[200:203], v161 offset:36864
	ds_read_b128 v[204:207], v161 offset:37888
	ds_read_b128 v[208:211], v161 offset:38912
	ds_read_b128 v[212:215], v161 offset:39936
	global_load_lds_dwordx4 v[228:229], off
	v_lshl_add_u64 v[228:229], s[34:35], 0, v[132:133]
	s_mov_b32 m0, s36
	s_nop 0
	global_load_lds_dwordx4 v[228:229], off
	s_waitcnt vmcnt(8)
	s_waitcnt lgkmcnt(0)
	s_barrier
	s_waitcnt lgkmcnt(0)
	v_mfma_f32_16x16x32_bf16 v[124:127], v[144:147], v[184:187], v[124:127]
	v_mfma_f32_16x16x32_bf16 v[120:123], v[152:155], v[184:187], v[120:123]
	v_mfma_f32_16x16x32_bf16 v[116:119], v[144:147], v[192:195], v[116:119]
	v_mfma_f32_16x16x32_bf16 v[112:115], v[152:155], v[192:195], v[112:115]
	v_mfma_f32_16x16x32_bf16 v[104:107], v[144:147], v[200:203], v[104:107]
	v_mfma_f32_16x16x32_bf16 v[96:99], v[152:155], v[200:203], v[96:99]
	v_mfma_f32_16x16x32_bf16 v[88:91], v[144:147], v[208:211], v[88:91]
	v_mfma_f32_16x16x32_bf16 v[80:83], v[152:155], v[208:211], v[80:83]
	v_mfma_f32_16x16x32_bf16 v[124:127], v[148:151], v[188:191], v[124:127]
	v_mfma_f32_16x16x32_bf16 v[120:123], v[164:167], v[188:191], v[120:123]
	v_mfma_f32_16x16x32_bf16 v[116:119], v[148:151], v[196:199], v[116:119]
	v_mfma_f32_16x16x32_bf16 v[112:115], v[164:167], v[196:199], v[112:115]
	v_mfma_f32_16x16x32_bf16 v[104:107], v[148:151], v[204:207], v[104:107]
	v_mfma_f32_16x16x32_bf16 v[96:99], v[164:167], v[204:207], v[96:99]
	v_mfma_f32_16x16x32_bf16 v[88:91], v[148:151], v[212:215], v[88:91]
	v_mfma_f32_16x16x32_bf16 v[80:83], v[164:167], v[212:215], v[80:83]
	v_mfma_f32_16x16x32_bf16 v[108:111], v[168:171], v[184:187], v[108:111]
	v_mfma_f32_16x16x32_bf16 v[100:103], v[176:179], v[184:187], v[100:103]
	v_mfma_f32_16x16x32_bf16 v[92:95], v[168:171], v[192:195], v[92:95]
	v_mfma_f32_16x16x32_bf16 v[84:87], v[176:179], v[192:195], v[84:87]
	v_mfma_f32_16x16x32_bf16 v[76:79], v[168:171], v[200:203], v[76:79]
	v_mfma_f32_16x16x32_bf16 v[72:75], v[176:179], v[200:203], v[72:75]
	v_mfma_f32_16x16x32_bf16 v[68:71], v[168:171], v[208:211], v[68:71]
	v_mfma_f32_16x16x32_bf16 v[64:67], v[176:179], v[208:211], v[64:67]
	v_mfma_f32_16x16x32_bf16 v[108:111], v[172:175], v[188:191], v[108:111]
	v_mfma_f32_16x16x32_bf16 v[100:103], v[180:183], v[188:191], v[100:103]
	v_mfma_f32_16x16x32_bf16 v[92:95], v[172:175], v[196:199], v[92:95]
	v_mfma_f32_16x16x32_bf16 v[84:87], v[180:183], v[196:199], v[84:87]
	v_mfma_f32_16x16x32_bf16 v[76:79], v[172:175], v[204:207], v[76:79]
	v_mfma_f32_16x16x32_bf16 v[72:75], v[180:183], v[204:207], v[72:75]
	v_mfma_f32_16x16x32_bf16 v[68:71], v[172:175], v[212:215], v[68:71]
	v_mfma_f32_16x16x32_bf16 v[64:67], v[180:183], v[212:215], v[64:67]
	s_barrier
; #define PG8_STAGE(bufoff, gbase, voff) do { _Pragma("unroll") for (int _i = 0; _i < 2; ++_i) \
;         __builtin_amdgcn_global_load_lds((const unsigned*)((const char*)(gbase) + (voff)[_i]), (PG8_LAS unsigned*)(lds + (bufoff) + ldsw + _i * 8192), 16, 0, 0); } while (0)
; #define PG8_LDA(dst, b, h) do { _Pragma("unroll") for (int m = 0; m < 4; ++m) _Pragma("unroll") for (int k = 0; k < 2; ++k) dst[m][k] = *(const PG8_LAS bf16x8*)(lds + PG8_SA(b, h) + aoff + m * 2048 + k * 1024); } while (0)
; #define PG8_LDB(dst, b, h) do { _Pragma("unroll") for (int n = 0; n < 2; ++n) _Pragma("unroll") for (int k = 0; k < 2; ++k) dst[n][k] = *(const PG8_LAS bf16x8*)(lds + PG8_SB(b, h) + boff + n * 2048 + k * 1024); } while (0)
; #define PG8_MMA(ai, bj, At, Bt) do { __builtin_amdgcn_s_setprio(1); _Pragma("unroll") for (int m = 0; m < 4; ++m) _Pragma("unroll") for (int n = 0; n < 2; ++n) _Pragma("unroll") for (int k = 0; k < 2; ++k) \
;         acc[ai][bj][m][n] = __builtin_amdgcn_mfma_f32_16x16x32_bf16(Bt[n][k], At[m][k], acc[ai][bj][m][n], 0, 0, 0); __builtin_amdgcn_s_setprio(0); } while (0)
; #define PG8_WAIT_V(n) asm volatile("s_waitcnt vmcnt(" #n ")" ::: "memory")
; #define PG8_BAR __builtin_amdgcn_s_barrier()
; template <class Epi, class Sched, bool ALIGN_EPI = false, bool SP2 = false>
; __device__ __forceinline__ void gemm_phase(PG8_LAS unsigned char* lds, const Gemm g, const Sched& S, const Epi& E) {
;     ...
;         for (int t = 0; t < nt; t += 2) {
;             const bool last = (t == nt - 2);
;             const char* a1 = cA + (size_t)(t + 1) * kstep;
;             const char* a2 = last ? nA : cA + (size_t)(t + 2) * kstep; const char* b2 = last ? nB : cB + (size_t)(t + 2) * kstep;
;             const char* a3 = a2 + kstep; const char* b3 = b2 + kstep;
;             if (last && has_next) S.a_ready(nxt);
;             if constexpr (SP2) {
;             PG8_LDB(B0, 0, 0); PG8_LDB(B1, 0, 1); PG8_SCHED; PG8_LDA(At, 0, 0); PG8_STAGE(PG8_SA(1, 1), a1 + hstep, voffA);
;             PG8_WAIT_V(8); PG8_WAIT_L(0); PG8_BAR; PG8_MMA(0, 0, At, B0); PG8_MMA(0, 1, At, B1); PG8_BAR; PG8_SCHED;
;     ...
;             PG8_LDA(At, 1, 1); PG8_STAGE(PG8_SB(1, 0), b3, voffB); PG8_STAGE(PG8_SB(1, 1), b3 + hstep, voffB); PG8_STAGE(PG8_SA(1, 0), a3, voffA);
;             PG8_WAIT_V(8); PG8_WAIT_L(0); PG8_BAR; PG8_MMA(1, 0, At, B0); PG8_MMA(1, 1, At, B1); PG8_BAR; PG8_SCHED;
	s_add_i32 s34, s64, s16
	v_lshl_add_u64 v[216:217], v[216:217], 0, s[22:23]
	s_mov_b32 m0, s34
	ds_read_b128 v[184:187], v161 offset:49152
	ds_read_b128 v[188:191], v161 offset:50176
	ds_read_b128 v[192:195], v161 offset:51200
	ds_read_b128 v[196:199], v161 offset:52224
	ds_read_b128 v[200:203], v161 offset:53248
	ds_read_b128 v[204:207], v161 offset:54272
	ds_read_b128 v[208:211], v161 offset:55296
	ds_read_b128 v[212:215], v161 offset:56320
	global_load_lds_dwordx4 v[216:217], off
	v_lshl_add_u64 v[216:217], v[218:219], 0, s[22:23]
	s_add_i32 m0, s34, 0x2000
	s_add_i32 s34, s65, s16
	global_load_lds_dwordx4 v[216:217], off
	v_lshl_add_u64 v[216:217], v[220:221], 0, s[22:23]
	s_mov_b32 m0, s34
	s_nop 0
	global_load_lds_dwordx4 v[216:217], off
	v_lshl_add_u64 v[216:217], v[222:223], 0, s[22:23]
	s_add_i32 m0, s34, 0x2000
	s_nop 0
	global_load_lds_dwordx4 v[216:217], off
	v_lshl_add_u64 v[216:217], v[224:225], 0, s[22:23]
	s_mov_b32 m0, s37
	s_nop 0
	global_load_lds_dwordx4 v[216:217], off
	v_lshl_add_u64 v[216:217], v[226:227], 0, s[22:23]
	s_mov_b32 m0, s38
	s_nop 0
	global_load_lds_dwordx4 v[216:217], off
	s_waitcnt vmcnt(8)
	s_waitcnt lgkmcnt(0)
	s_barrier
	s_waitcnt lgkmcnt(0)
	v_mfma_f32_16x16x32_bf16 v[60:63], v[144:147], v[184:187], v[60:63]
	v_mfma_f32_16x16x32_bf16 v[56:59], v[152:155], v[184:187], v[56:59]
	v_mfma_f32_16x16x32_bf16 v[52:55], v[144:147], v[192:195], v[52:55]
	v_mfma_f32_16x16x32_bf16 v[48:51], v[152:155], v[192:195], v[48:51]
	v_mfma_f32_16x16x32_bf16 v[40:43], v[144:147], v[200:203], v[40:43]
	v_mfma_f32_16x16x32_bf16 v[32:35], v[152:155], v[200:203], v[32:35]
	v_mfma_f32_16x16x32_bf16 v[24:27], v[144:147], v[208:211], v[24:27]
	v_mfma_f32_16x16x32_bf16 v[16:19], v[152:155], v[208:211], v[16:19]
	v_mfma_f32_16x16x32_bf16 v[60:63], v[148:151], v[188:191], v[60:63]
	v_mfma_f32_16x16x32_bf16 v[56:59], v[164:167], v[188:191], v[56:59]
	v_mfma_f32_16x16x32_bf16 v[52:55], v[148:151], v[196:199], v[52:55]
	v_mfma_f32_16x16x32_bf16 v[48:51], v[164:167], v[196:199], v[48:51]
	v_mfma_f32_16x16x32_bf16 v[40:43], v[148:151], v[204:207], v[40:43]
	v_mfma_f32_16x16x32_bf16 v[32:35], v[164:167], v[204:207], v[32:35]
	v_mfma_f32_16x16x32_bf16 v[24:27], v[148:151], v[212:215], v[24:27]
	v_mfma_f32_16x16x32_bf16 v[16:19], v[164:167], v[212:215], v[16:19]
	v_mfma_f32_16x16x32_bf16 v[44:47], v[168:171], v[184:187], v[44:47]
	v_mfma_f32_16x16x32_bf16 v[36:39], v[176:179], v[184:187], v[36:39]
	v_mfma_f32_16x16x32_bf16 v[28:31], v[168:171], v[192:195], v[28:31]
	v_mfma_f32_16x16x32_bf16 v[20:23], v[176:179], v[192:195], v[20:23]
	v_mfma_f32_16x16x32_bf16 v[12:15], v[168:171], v[200:203], v[12:15]
	v_mfma_f32_16x16x32_bf16 v[8:11], v[176:179], v[200:203], v[8:11]
	v_mfma_f32_16x16x32_bf16 v[4:7], v[168:171], v[208:211], v[4:7]
	v_mfma_f32_16x16x32_bf16 v[0:3], v[176:179], v[208:211], v[0:3]
	v_mfma_f32_16x16x32_bf16 v[44:47], v[172:175], v[188:191], v[44:47]
	v_mfma_f32_16x16x32_bf16 v[36:39], v[180:183], v[188:191], v[36:39]
	v_mfma_f32_16x16x32_bf16 v[28:31], v[172:175], v[196:199], v[28:31]
	v_mfma_f32_16x16x32_bf16 v[20:23], v[180:183], v[196:199], v[20:23]
	v_mfma_f32_16x16x32_bf16 v[12:15], v[172:175], v[204:207], v[12:15]
	v_mfma_f32_16x16x32_bf16 v[8:11], v[180:183], v[204:207], v[8:11]
	v_mfma_f32_16x16x32_bf16 v[4:7], v[172:175], v[212:215], v[4:7]
	v_mfma_f32_16x16x32_bf16 v[0:3], v[180:183], v[212:215], v[0:3]
	s_barrier
	s_add_u32 s30, s30, 0x100
	s_addc_u32 s31, s31, 0
	s_add_u32 s61, s61, 0x100
	s_addc_u32 s62, s62, 0
	s_cmp_ge_i32 s63, s40
	s_mov_b32 s34, s63
	s_cbranch_scc0 .LBB0_2575
	s_branch .Lpeel_x13
.LBB0_2575:
	ds_read_b128 v[144:147], v159
	ds_read_b128 v[148:151], v159 offset:1024
	ds_read_b128 v[152:155], v159 offset:2048
	ds_read_b128 v[164:167], v159 offset:3072
	ds_read_b128 v[168:171], v160
	ds_read_b128 v[172:175], v160 offset:1024
	ds_read_b128 v[176:179], v160 offset:2048
	ds_read_b128 v[180:183], v160 offset:3072
	s_add_i32 s63, s34, 2
	s_add_u32 s64, s30, 0x80
	s_addc_u32 s35, s31, 0
	s_cmp_eq_u32 s41, s34
	s_cselect_b32 s34, s0, s64
	s_cselect_b32 s35, s1, s35
	s_cselect_b32 s65, s29, s62
	s_cselect_b32 s64, s28, s61
	v_lshl_add_u64 v[216:217], s[30:31], 0, v[136:137]
	s_add_i32 m0, s17, 0xc000
	ds_read_b128 v[184:187], v161
	ds_read_b128 v[188:191], v161 offset:1024
	ds_read_b128 v[192:195], v161 offset:2048
	ds_read_b128 v[196:199], v161 offset:3072
	ds_read_b128 v[200:203], v161 offset:4096
	ds_read_b128 v[204:207], v161 offset:5120
	ds_read_b128 v[208:211], v161 offset:6144
	ds_read_b128 v[212:215], v161 offset:7168
	global_load_lds_dwordx4 v[216:217], off
	v_lshl_add_u64 v[216:217], s[30:31], 0, v[138:139]
	s_add_i32 m0, s17, 0xe000
	s_nop 0
	global_load_lds_dwordx4 v[216:217], off
	s_waitcnt vmcnt(8)
	s_waitcnt lgkmcnt(0)
	s_barrier
; #define PG8_STAGE(bufoff, gbase, voff) do { _Pragma("unroll") for (int _i = 0; _i < 2; ++_i) \
;         __builtin_amdgcn_global_load_lds((const unsigned*)((const char*)(gbase) + (voff)[_i]), (PG8_LAS unsigned*)(lds + (bufoff) + ldsw + _i * 8192), 16, 0, 0); } while (0)
; #define PG8_LDA(dst, b, h) do { _Pragma("unroll") for (int m = 0; m < 4; ++m) _Pragma("unroll") for (int k = 0; k < 2; ++k) dst[m][k] = *(const PG8_LAS bf16x8*)(lds + PG8_SA(b, h) + aoff + m * 2048 + k * 1024); } while (0)
; #define PG8_MMA(ai, bj, At, Bt) do { __builtin_amdgcn_s_setprio(1); _Pragma("unroll") for (int m = 0; m < 4; ++m) _Pragma("unroll") for (int n = 0; n < 2; ++n) _Pragma("unroll") for (int k = 0; k < 2; ++k) \
;         acc[ai][bj][m][n] = __builtin_amdgcn_mfma_f32_16x16x32_bf16(Bt[n][k], At[m][k], acc[ai][bj][m][n], 0, 0, 0); __builtin_amdgcn_s_setprio(0); } while (0)
; #define PG8_WAIT_V(n) asm volatile("s_waitcnt vmcnt(" #n ")" ::: "memory")
; #define PG8_WAIT_L(n) asm volatile("s_waitcnt lgkmcnt(" #n ")" ::: "memory")
; #define PG8_BAR __builtin_amdgcn_s_barrier()
; #define PG8_SCHED __builtin_amdgcn_sched_barrier(0)
; template <class Epi, class Sched, bool ALIGN_EPI = false, bool SP2 = false>
; __device__ __forceinline__ void gemm_phase(PG8_LAS unsigned char* lds, const Gemm g, const Sched& S, const Epi& E) {
;     ...
;             PG8_WAIT_V(8); PG8_WAIT_L(0); PG8_BAR; PG8_MMA(0, 0, At, B0); PG8_MMA(0, 1, At, B1); PG8_BAR; PG8_SCHED;
;             PG8_LDA(At, 0, 1); PG8_STAGE(PG8_SB(0, 0), b2, voffB); PG8_STAGE(PG8_SB(0, 1), b2 + hstep, voffB); PG8_STAGE(PG8_SA(0, 0), a2, voffA);
;             PG8_WAIT_V(8); PG8_WAIT_L(0); PG8_BAR; PG8_MMA(1, 0, At, B0); PG8_MMA(1, 1, At, B1); PG8_BAR; PG8_SCHED;
	s_waitcnt lgkmcnt(0)
	v_mfma_f32_16x16x32_bf16 v[124:127], v[144:147], v[184:187], v[124:127]
	v_mfma_f32_16x16x32_bf16 v[120:123], v[152:155], v[184:187], v[120:123]
	v_mfma_f32_16x16x32_bf16 v[116:119], v[144:147], v[192:195], v[116:119]
	v_mfma_f32_16x16x32_bf16 v[112:115], v[152:155], v[192:195], v[112:115]
	v_mfma_f32_16x16x32_bf16 v[104:107], v[144:147], v[200:203], v[104:107]
	v_mfma_f32_16x16x32_bf16 v[96:99], v[152:155], v[200:203], v[96:99]
	v_mfma_f32_16x16x32_bf16 v[88:91], v[144:147], v[208:211], v[88:91]
	v_mfma_f32_16x16x32_bf16 v[80:83], v[152:155], v[208:211], v[80:83]
	v_mfma_f32_16x16x32_bf16 v[124:127], v[148:151], v[188:191], v[124:127]
	v_mfma_f32_16x16x32_bf16 v[120:123], v[164:167], v[188:191], v[120:123]
	v_mfma_f32_16x16x32_bf16 v[116:119], v[148:151], v[196:199], v[116:119]
	v_mfma_f32_16x16x32_bf16 v[112:115], v[164:167], v[196:199], v[112:115]
	v_mfma_f32_16x16x32_bf16 v[104:107], v[148:151], v[204:207], v[104:107]
	v_mfma_f32_16x16x32_bf16 v[96:99], v[164:167], v[204:207], v[96:99]
	v_mfma_f32_16x16x32_bf16 v[88:91], v[148:151], v[212:215], v[88:91]
	v_mfma_f32_16x16x32_bf16 v[80:83], v[164:167], v[212:215], v[80:83]
	v_mfma_f32_16x16x32_bf16 v[108:111], v[168:171], v[184:187], v[108:111]
	v_mfma_f32_16x16x32_bf16 v[100:103], v[176:179], v[184:187], v[100:103]
	v_mfma_f32_16x16x32_bf16 v[92:95], v[168:171], v[192:195], v[92:95]
	v_mfma_f32_16x16x32_bf16 v[84:87], v[176:179], v[192:195], v[84:87]
	v_mfma_f32_16x16x32_bf16 v[76:79], v[168:171], v[200:203], v[76:79]
	v_mfma_f32_16x16x32_bf16 v[72:75], v[176:179], v[200:203], v[72:75]
	v_mfma_f32_16x16x32_bf16 v[68:71], v[168:171], v[208:211], v[68:71]
	v_mfma_f32_16x16x32_bf16 v[64:67], v[176:179], v[208:211], v[64:67]
	v_mfma_f32_16x16x32_bf16 v[108:111], v[172:175], v[188:191], v[108:111]
	v_mfma_f32_16x16x32_bf16 v[100:103], v[180:183], v[188:191], v[100:103]
	v_mfma_f32_16x16x32_bf16 v[92:95], v[172:175], v[196:199], v[92:95]
	v_mfma_f32_16x16x32_bf16 v[84:87], v[180:183], v[196:199], v[84:87]
	v_mfma_f32_16x16x32_bf16 v[76:79], v[172:175], v[204:207], v[76:79]
	v_mfma_f32_16x16x32_bf16 v[72:75], v[180:183], v[204:207], v[72:75]
	v_mfma_f32_16x16x32_bf16 v[68:71], v[172:175], v[212:215], v[68:71]
	v_mfma_f32_16x16x32_bf16 v[64:67], v[180:183], v[212:215], v[64:67]
	s_barrier
	s_add_i32 s66, s51, s16
	v_lshl_add_u64 v[216:217], s[64:65], 0, v[130:131]
	s_mov_b32 m0, s66
	ds_read_b128 v[184:187], v161 offset:16384
	ds_read_b128 v[188:191], v161 offset:17408
	ds_read_b128 v[192:195], v161 offset:18432
	ds_read_b128 v[196:199], v161 offset:19456
	ds_read_b128 v[200:203], v161 offset:20480
	ds_read_b128 v[204:207], v161 offset:21504
	ds_read_b128 v[208:211], v161 offset:22528
	ds_read_b128 v[212:215], v161 offset:23552
	global_load_lds_dwordx4 v[216:217], off
	s_add_i32 m0, s66, 0x2000
	v_lshl_add_u64 v[218:219], s[64:65], 0, v[134:135]
	s_add_u32 s64, s64, s6
	s_addc_u32 s65, s65, s7
	s_add_i32 s66, s56, s16
	global_load_lds_dwordx4 v[218:219], off
	v_lshl_add_u64 v[220:221], s[64:65], 0, v[130:131]
	s_mov_b32 m0, s66
	v_lshl_add_u64 v[222:223], s[64:65], 0, v[134:135]
	global_load_lds_dwordx4 v[220:221], off
	s_add_i32 m0, s66, 0x2000
	v_lshl_add_u64 v[224:225], s[34:35], 0, v[128:129]
	global_load_lds_dwordx4 v[222:223], off
	s_mov_b32 m0, s17
	v_lshl_add_u64 v[226:227], s[34:35], 0, v[132:133]
	global_load_lds_dwordx4 v[224:225], off
	s_mov_b32 m0, s19
	s_nop 0
	global_load_lds_dwordx4 v[226:227], off
	s_waitcnt vmcnt(8)
	s_waitcnt lgkmcnt(0)
	s_barrier
	s_waitcnt lgkmcnt(0)
	v_mfma_f32_16x16x32_bf16 v[60:63], v[144:147], v[184:187], v[60:63]
	v_mfma_f32_16x16x32_bf16 v[56:59], v[152:155], v[184:187], v[56:59]
	v_mfma_f32_16x16x32_bf16 v[52:55], v[144:147], v[192:195], v[52:55]
	v_mfma_f32_16x16x32_bf16 v[48:51], v[152:155], v[192:195], v[48:51]
	v_mfma_f32_16x16x32_bf16 v[40:43], v[144:147], v[200:203], v[40:43]
	v_mfma_f32_16x16x32_bf16 v[32:35], v[152:155], v[200:203], v[32:35]
	v_mfma_f32_16x16x32_bf16 v[24:27], v[144:147], v[208:211], v[24:27]
	v_mfma_f32_16x16x32_bf16 v[16:19], v[152:155], v[208:211], v[16:19]
	v_mfma_f32_16x16x32_bf16 v[60:63], v[148:151], v[188:191], v[60:63]
	v_mfma_f32_16x16x32_bf16 v[56:59], v[164:167], v[188:191], v[56:59]
	v_mfma_f32_16x16x32_bf16 v[52:55], v[148:151], v[196:199], v[52:55]
	v_mfma_f32_16x16x32_bf16 v[48:51], v[164:167], v[196:199], v[48:51]
	v_mfma_f32_16x16x32_bf16 v[40:43], v[148:151], v[204:207], v[40:43]
	v_mfma_f32_16x16x32_bf16 v[32:35], v[164:167], v[204:207], v[32:35]
	v_mfma_f32_16x16x32_bf16 v[24:27], v[148:151], v[212:215], v[24:27]
	v_mfma_f32_16x16x32_bf16 v[16:19], v[164:167], v[212:215], v[16:19]
	v_mfma_f32_16x16x32_bf16 v[44:47], v[168:171], v[184:187], v[44:47]
	v_mfma_f32_16x16x32_bf16 v[36:39], v[176:179], v[184:187], v[36:39]
	v_mfma_f32_16x16x32_bf16 v[28:31], v[168:171], v[192:195], v[28:31]
	v_mfma_f32_16x16x32_bf16 v[20:23], v[176:179], v[192:195], v[20:23]
	v_mfma_f32_16x16x32_bf16 v[12:15], v[168:171], v[200:203], v[12:15]
	v_mfma_f32_16x16x32_bf16 v[8:11], v[176:179], v[200:203], v[8:11]
	v_mfma_f32_16x16x32_bf16 v[4:7], v[168:171], v[208:211], v[4:7]
	v_mfma_f32_16x16x32_bf16 v[0:3], v[176:179], v[208:211], v[0:3]
	v_mfma_f32_16x16x32_bf16 v[44:47], v[172:175], v[188:191], v[44:47]
	v_mfma_f32_16x16x32_bf16 v[36:39], v[180:183], v[188:191], v[36:39]
	v_mfma_f32_16x16x32_bf16 v[28:31], v[172:175], v[196:199], v[28:31]
	v_mfma_f32_16x16x32_bf16 v[20:23], v[180:183], v[196:199], v[20:23]
	v_mfma_f32_16x16x32_bf16 v[12:15], v[172:175], v[204:207], v[12:15]
	v_mfma_f32_16x16x32_bf16 v[8:11], v[180:183], v[204:207], v[8:11]
	v_mfma_f32_16x16x32_bf16 v[4:7], v[172:175], v[212:215], v[4:7]
	v_mfma_f32_16x16x32_bf16 v[0:3], v[180:183], v[212:215], v[0:3]
	s_barrier
; #define PG8_STAGE(bufoff, gbase, voff) do { _Pragma("unroll") for (int _i = 0; _i < 2; ++_i) \
;         __builtin_amdgcn_global_load_lds((const unsigned*)((const char*)(gbase) + (voff)[_i]), (PG8_LAS unsigned*)(lds + (bufoff) + ldsw + _i * 8192), 16, 0, 0); } while (0)
; #define PG8_LDA(dst, b, h) do { _Pragma("unroll") for (int m = 0; m < 4; ++m) _Pragma("unroll") for (int k = 0; k < 2; ++k) dst[m][k] = *(const PG8_LAS bf16x8*)(lds + PG8_SA(b, h) + aoff + m * 2048 + k * 1024); } while (0)
; #define PG8_LDB(dst, b, h) do { _Pragma("unroll") for (int n = 0; n < 2; ++n) _Pragma("unroll") for (int k = 0; k < 2; ++k) dst[n][k] = *(const PG8_LAS bf16x8*)(lds + PG8_SB(b, h) + boff + n * 2048 + k * 1024); } while (0)
; #define PG8_MMA(ai, bj, At, Bt) do { __builtin_amdgcn_s_setprio(1); _Pragma("unroll") for (int m = 0; m < 4; ++m) _Pragma("unroll") for (int n = 0; n < 2; ++n) _Pragma("unroll") for (int k = 0; k < 2; ++k) \
;         acc[ai][bj][m][n] = __builtin_amdgcn_mfma_f32_16x16x32_bf16(Bt[n][k], At[m][k], acc[ai][bj][m][n], 0, 0, 0); __builtin_amdgcn_s_setprio(0); } while (0)
; #define PG8_WAIT_V(n) asm volatile("s_waitcnt vmcnt(" #n ")" ::: "memory")
; #define PG8_WAIT_L(n) asm volatile("s_waitcnt lgkmcnt(" #n ")" ::: "memory")
; #define PG8_BAR __builtin_amdgcn_s_barrier()
; template <class Epi, class Sched, bool ALIGN_EPI = false, bool SP2 = false>
; __device__ __forceinline__ void gemm_phase(PG8_LAS unsigned char* lds, const Gemm g, const Sched& S, const Epi& E) {
;     ...
;         for (int t = 0; t < nt; t += 2) {
;             const bool last = (t == nt - 2);
;             const char* a1 = cA + (size_t)(t + 1) * kstep;
;             const char* a2 = last ? nA : cA + (size_t)(t + 2) * kstep; const char* b2 = last ? nB : cB + (size_t)(t + 2) * kstep;
;             const char* a3 = a2 + kstep; const char* b3 = b2 + kstep;
;     ...
;             PG8_LDB(B0, 1, 0); PG8_LDB(B1, 1, 1); PG8_SCHED; PG8_LDA(At, 1, 0); PG8_STAGE(PG8_SA(0, 1), a2 + hstep, voffA);
;             PG8_WAIT_V(8); PG8_WAIT_L(0); PG8_BAR; PG8_MMA(0, 0, At, B0); PG8_MMA(0, 1, At, B1); PG8_BAR; PG8_SCHED;
;             PG8_LDA(At, 1, 1); PG8_STAGE(PG8_SB(1, 0), b3, voffB); PG8_STAGE(PG8_SB(1, 1), b3 + hstep, voffB); PG8_STAGE(PG8_SA(1, 0), a3, voffA);
;             PG8_WAIT_V(8); PG8_WAIT_L(0); PG8_BAR; PG8_MMA(1, 0, At, B0); PG8_MMA(1, 1, At, B1); PG8_BAR; PG8_SCHED;
	s_add_i32 s64, 0, 0x18000
	v_add_u32_e32 v163, s64, v157
	s_add_i32 s65, 0, 0x1c000
	ds_read_b128 v[144:147], v163
	ds_read_b128 v[148:151], v163 offset:1024
	ds_read_b128 v[152:155], v163 offset:2048
	ds_read_b128 v[164:167], v163 offset:3072
	v_add_u32_e32 v163, s65, v157
	ds_read_b128 v[168:171], v163
	ds_read_b128 v[172:175], v163 offset:1024
	ds_read_b128 v[176:179], v163 offset:2048
	ds_read_b128 v[180:183], v163 offset:3072
	s_add_u32 s34, s34, s6
	s_addc_u32 s35, s35, s7
	s_mov_b32 m0, s33
	v_lshl_add_u64 v[228:229], s[34:35], 0, v[128:129]
	ds_read_b128 v[184:187], v161 offset:32768
	ds_read_b128 v[188:191], v161 offset:33792
	ds_read_b128 v[192:195], v161 offset:34816
	ds_read_b128 v[196:199], v161 offset:35840
	ds_read_b128 v[200:203], v161 offset:36864
	ds_read_b128 v[204:207], v161 offset:37888
	ds_read_b128 v[208:211], v161 offset:38912
	ds_read_b128 v[212:215], v161 offset:39936
	global_load_lds_dwordx4 v[228:229], off
	v_lshl_add_u64 v[228:229], s[34:35], 0, v[132:133]
	s_mov_b32 m0, s36
	s_nop 0
	global_load_lds_dwordx4 v[228:229], off
	s_waitcnt vmcnt(8)
	s_waitcnt lgkmcnt(0)
	s_barrier
	s_waitcnt lgkmcnt(0)
	v_mfma_f32_16x16x32_bf16 v[124:127], v[144:147], v[184:187], v[124:127]
	v_mfma_f32_16x16x32_bf16 v[120:123], v[152:155], v[184:187], v[120:123]
	v_mfma_f32_16x16x32_bf16 v[116:119], v[144:147], v[192:195], v[116:119]
	v_mfma_f32_16x16x32_bf16 v[112:115], v[152:155], v[192:195], v[112:115]
	v_mfma_f32_16x16x32_bf16 v[104:107], v[144:147], v[200:203], v[104:107]
	v_mfma_f32_16x16x32_bf16 v[96:99], v[152:155], v[200:203], v[96:99]
	v_mfma_f32_16x16x32_bf16 v[88:91], v[144:147], v[208:211], v[88:91]
	v_mfma_f32_16x16x32_bf16 v[80:83], v[152:155], v[208:211], v[80:83]
	v_mfma_f32_16x16x32_bf16 v[124:127], v[148:151], v[188:191], v[124:127]
	v_mfma_f32_16x16x32_bf16 v[120:123], v[164:167], v[188:191], v[120:123]
	v_mfma_f32_16x16x32_bf16 v[116:119], v[148:151], v[196:199], v[116:119]
	v_mfma_f32_16x16x32_bf16 v[112:115], v[164:167], v[196:199], v[112:115]
	v_mfma_f32_16x16x32_bf16 v[104:107], v[148:151], v[204:207], v[104:107]
	v_mfma_f32_16x16x32_bf16 v[96:99], v[164:167], v[204:207], v[96:99]
	v_mfma_f32_16x16x32_bf16 v[88:91], v[148:151], v[212:215], v[88:91]
	v_mfma_f32_16x16x32_bf16 v[80:83], v[164:167], v[212:215], v[80:83]
	v_mfma_f32_16x16x32_bf16 v[108:111], v[168:171], v[184:187], v[108:111]
	v_mfma_f32_16x16x32_bf16 v[100:103], v[176:179], v[184:187], v[100:103]
	v_mfma_f32_16x16x32_bf16 v[92:95], v[168:171], v[192:195], v[92:95]
	v_mfma_f32_16x16x32_bf16 v[84:87], v[176:179], v[192:195], v[84:87]
	v_mfma_f32_16x16x32_bf16 v[76:79], v[168:171], v[200:203], v[76:79]
	v_mfma_f32_16x16x32_bf16 v[72:75], v[176:179], v[200:203], v[72:75]
	v_mfma_f32_16x16x32_bf16 v[68:71], v[168:171], v[208:211], v[68:71]
	v_mfma_f32_16x16x32_bf16 v[64:67], v[176:179], v[208:211], v[64:67]
	v_mfma_f32_16x16x32_bf16 v[108:111], v[172:175], v[188:191], v[108:111]
	v_mfma_f32_16x16x32_bf16 v[100:103], v[180:183], v[188:191], v[100:103]
	v_mfma_f32_16x16x32_bf16 v[92:95], v[172:175], v[196:199], v[92:95]
	v_mfma_f32_16x16x32_bf16 v[84:87], v[180:183], v[196:199], v[84:87]
	v_mfma_f32_16x16x32_bf16 v[76:79], v[172:175], v[204:207], v[76:79]
	v_mfma_f32_16x16x32_bf16 v[72:75], v[180:183], v[204:207], v[72:75]
	v_mfma_f32_16x16x32_bf16 v[68:71], v[172:175], v[212:215], v[68:71]
	v_mfma_f32_16x16x32_bf16 v[64:67], v[180:183], v[212:215], v[64:67]
	s_barrier
	s_add_i32 s34, s64, s16
	v_lshl_add_u64 v[216:217], v[216:217], 0, s[22:23]
	s_mov_b32 m0, s34
	ds_read_b128 v[184:187], v161 offset:49152
	ds_read_b128 v[188:191], v161 offset:50176
	ds_read_b128 v[192:195], v161 offset:51200
	ds_read_b128 v[196:199], v161 offset:52224
	ds_read_b128 v[200:203], v161 offset:53248
	ds_read_b128 v[204:207], v161 offset:54272
	ds_read_b128 v[208:211], v161 offset:55296
	ds_read_b128 v[212:215], v161 offset:56320
	global_load_lds_dwordx4 v[216:217], off
	v_lshl_add_u64 v[216:217], v[218:219], 0, s[22:23]
	s_add_i32 m0, s34, 0x2000
	s_add_i32 s34, s65, s16
	global_load_lds_dwordx4 v[216:217], off
	v_lshl_add_u64 v[216:217], v[220:221], 0, s[22:23]
	s_mov_b32 m0, s34
	s_nop 0
	global_load_lds_dwordx4 v[216:217], off
	v_lshl_add_u64 v[216:217], v[222:223], 0, s[22:23]
	s_add_i32 m0, s34, 0x2000
	s_nop 0
	global_load_lds_dwordx4 v[216:217], off
	v_lshl_add_u64 v[216:217], v[224:225], 0, s[22:23]
	s_mov_b32 m0, s37
	s_nop 0
	global_load_lds_dwordx4 v[216:217], off
	v_lshl_add_u64 v[216:217], v[226:227], 0, s[22:23]
	s_mov_b32 m0, s38
	s_nop 0
	global_load_lds_dwordx4 v[216:217], off
	s_waitcnt vmcnt(8)
	s_waitcnt lgkmcnt(0)
	s_barrier
	s_waitcnt lgkmcnt(0)
	v_mfma_f32_16x16x32_bf16 v[60:63], v[144:147], v[184:187], v[60:63]
	v_mfma_f32_16x16x32_bf16 v[56:59], v[152:155], v[184:187], v[56:59]
	v_mfma_f32_16x16x32_bf16 v[52:55], v[144:147], v[192:195], v[52:55]
	v_mfma_f32_16x16x32_bf16 v[48:51], v[152:155], v[192:195], v[48:51]
	v_mfma_f32_16x16x32_bf16 v[40:43], v[144:147], v[200:203], v[40:43]
	v_mfma_f32_16x16x32_bf16 v[32:35], v[152:155], v[200:203], v[32:35]
	v_mfma_f32_16x16x32_bf16 v[24:27], v[144:147], v[208:211], v[24:27]
	v_mfma_f32_16x16x32_bf16 v[16:19], v[152:155], v[208:211], v[16:19]
	v_mfma_f32_16x16x32_bf16 v[60:63], v[148:151], v[188:191], v[60:63]
	v_mfma_f32_16x16x32_bf16 v[56:59], v[164:167], v[188:191], v[56:59]
	v_mfma_f32_16x16x32_bf16 v[52:55], v[148:151], v[196:199], v[52:55]
	v_mfma_f32_16x16x32_bf16 v[48:51], v[164:167], v[196:199], v[48:51]
	v_mfma_f32_16x16x32_bf16 v[40:43], v[148:151], v[204:207], v[40:43]
	v_mfma_f32_16x16x32_bf16 v[32:35], v[164:167], v[204:207], v[32:35]
	v_mfma_f32_16x16x32_bf16 v[24:27], v[148:151], v[212:215], v[24:27]
	v_mfma_f32_16x16x32_bf16 v[16:19], v[164:167], v[212:215], v[16:19]
	v_mfma_f32_16x16x32_bf16 v[44:47], v[168:171], v[184:187], v[44:47]
	v_mfma_f32_16x16x32_bf16 v[36:39], v[176:179], v[184:187], v[36:39]
	v_mfma_f32_16x16x32_bf16 v[28:31], v[168:171], v[192:195], v[28:31]
	v_mfma_f32_16x16x32_bf16 v[20:23], v[176:179], v[192:195], v[20:23]
	v_mfma_f32_16x16x32_bf16 v[12:15], v[168:171], v[200:203], v[12:15]
	v_mfma_f32_16x16x32_bf16 v[8:11], v[176:179], v[200:203], v[8:11]
	v_mfma_f32_16x16x32_bf16 v[4:7], v[168:171], v[208:211], v[4:7]
	v_mfma_f32_16x16x32_bf16 v[0:3], v[176:179], v[208:211], v[0:3]
	v_mfma_f32_16x16x32_bf16 v[44:47], v[172:175], v[188:191], v[44:47]
	v_mfma_f32_16x16x32_bf16 v[36:39], v[180:183], v[188:191], v[36:39]
	v_mfma_f32_16x16x32_bf16 v[28:31], v[172:175], v[196:199], v[28:31]
	v_mfma_f32_16x16x32_bf16 v[20:23], v[180:183], v[196:199], v[20:23]
	v_mfma_f32_16x16x32_bf16 v[12:15], v[172:175], v[204:207], v[12:15]
	v_mfma_f32_16x16x32_bf16 v[8:11], v[180:183], v[204:207], v[8:11]
	v_mfma_f32_16x16x32_bf16 v[4:7], v[172:175], v[212:215], v[4:7]
	v_mfma_f32_16x16x32_bf16 v[0:3], v[180:183], v[212:215], v[0:3]
	s_barrier
	s_add_u32 s30, s30, 0x100
	s_addc_u32 s31, s31, 0
	s_add_u32 s61, s61, 0x100
	s_addc_u32 s62, s62, 0
	s_cmp_ge_i32 s63, s40
	s_mov_b32 s34, s63
	s_cbranch_scc0 .LBB0_2575
